# one static s_setprio 1 for waves 4-7 at kernel entry, per-phase priority flips deleted from the K-loops
# speedup vs baseline: 1.0179x; 1.0179x over previous
_Z14fwd_megakernel6Params:
	s_load_dwordx16 s[36:51], s[0:1], 0x0
	s_load_dwordx16 s[72:87], s[0:1], 0x40
	s_load_dwordx8 s[88:95], s[0:1], 0x80
	s_load_dword s69, s[0:1], 0xa0
	s_add_u32 s4, s0, 0x98
	v_and_b32_e32 v222, 0x3ff, v0
	s_addc_u32 s5, s1, 0
	v_readfirstlane_b32 s16, v222
	v_cmp_gt_u32_e32 vcc, 2, v222
	s_and_saveexec_b64 s[0:1], vcc
	v_lshl_add_u32 v1, v222, 2, 0
	v_add_u32_e32 v1, 0x20000, v1
	v_mov_b32_e32 v2, 0
	ds_write_b32 v1, v2
	s_or_b64 exec, exec, s[0:1]
	s_lshr_b32 s66, s16, 6
	s_cmp_lt_u32 s66, 4
	s_cbranch_scc1 .Lprio_done
	s_setprio 1
.Lprio_done:
	s_cmpk_lt_i32 s2, 0x1780
	s_cselect_b64 s[8:9], -1, 0
	s_cmpk_gt_i32 s2, 0x177f
	v_and_b32_e32 v154, 63, v222
	s_cbranch_scc1 .LBB0_11
	s_cmpk_gt_i32 s2, 0x2ff
	s_cbranch_scc0 .LBB0_12
	s_cmpk_gt_u32 s2, 0x3ff
	s_cbranch_scc0 .LBB0_13
	s_cmpk_gt_u32 s2, 0x97f
	s_cbranch_scc0 .LBB0_14
	s_cmpk_gt_u32 s2, 0xc3f
	s_cbranch_scc0 .LBB0_15
	s_cmpk_gt_u32 s2, 0xe3f
	s_cbranch_scc0 .LBB0_16
	s_cmpk_gt_u32 s2, 0xf3f
	s_cbranch_scc0 .LBB0_17
	s_cmpk_gt_u32 s2, 0x14bf
	s_cbranch_scc0 .LBB0_18
	s_add_i32 s17, s2, 0xffffeb40
	s_waitcnt lgkmcnt(0)
	s_add_u32 s10, s86, 0x2c00000
	s_addc_u32 s11, s87, 0
	s_add_u32 s6, s92, 0xa700000
	s_addc_u32 s7, s93, 0
	s_mov_b64 s[0:1], 0
	s_branch .LBB0_19

.LBB0_147:
	ds_read_b128 v[144:147], v165
	ds_read_b128 v[148:151], v220
	ds_read_b128 v[170:173], v165 offset:2048
	ds_read_b128 v[174:177], v220 offset:2048
	s_add_u32 s18, s16, 0xfff80080
	s_addc_u32 s19, s17, -1
	s_cmp_eq_u32 s47, 28
	s_cselect_b32 s21, s11, s19
	s_cselect_b32 s20, s41, s18
	s_cselect_b32 s19, s9, s46
	s_cselect_b32 s18, s44, s45
	s_add_i32 m0, s1, 0xc000
	ds_read_b128 v[178:181], v166
	ds_read_b128 v[182:185], v221
	ds_read_b128 v[186:189], v166 offset:2048
	ds_read_b128 v[190:193], v221 offset:2048
	ds_read_b128 v[194:197], v166 offset:4096
	ds_read_b128 v[198:201], v221 offset:4096
	ds_read_b128 v[202:205], v166 offset:6144
	ds_read_b128 v[206:209], v221 offset:6144
	global_load_lds_dwordx4 v136, s[16:17]
	s_add_i32 m0, s1, 0xe000
	s_nop 0
	global_load_lds_dwordx4 v138, s[16:17]
	s_waitcnt lgkmcnt(8)
	s_barrier
	s_waitcnt lgkmcnt(0)
	s_waitcnt lgkmcnt(0)
	v_mfma_f32_16x16x32_bf16 v[124:127], v[144:147], v[178:181], v[124:127]
	v_mfma_f32_16x16x32_bf16 v[124:127], v[148:151], v[182:185], v[124:127]
	v_mfma_f32_16x16x32_bf16 v[120:123], v[174:177], v[182:185], v[120:123]
	v_mfma_f32_16x16x32_bf16 v[120:123], v[170:173], v[178:181], v[120:123]
	v_mfma_f32_16x16x32_bf16 v[104:107], v[170:173], v[186:189], v[104:107]
	v_mfma_f32_16x16x32_bf16 v[104:107], v[174:177], v[190:193], v[104:107]
	v_mfma_f32_16x16x32_bf16 v[108:111], v[148:151], v[190:193], v[108:111]
	v_mfma_f32_16x16x32_bf16 v[108:111], v[144:147], v[186:189], v[108:111]
	v_mfma_f32_16x16x32_bf16 v[92:95], v[144:147], v[194:197], v[92:95]
	v_mfma_f32_16x16x32_bf16 v[92:95], v[148:151], v[198:201], v[92:95]
	v_mfma_f32_16x16x32_bf16 v[88:91], v[174:177], v[198:201], v[88:91]
	v_mfma_f32_16x16x32_bf16 v[88:91], v[170:173], v[194:197], v[88:91]
	v_mfma_f32_16x16x32_bf16 v[72:75], v[170:173], v[202:205], v[72:75]
	v_mfma_f32_16x16x32_bf16 v[72:75], v[174:177], v[206:209], v[72:75]
	v_mfma_f32_16x16x32_bf16 v[76:79], v[148:151], v[206:209], v[76:79]
	v_mfma_f32_16x16x32_bf16 v[76:79], v[144:147], v[202:205], v[76:79]
	s_barrier
	s_add_i32 s48, s35, s24
	s_add_u32 s98, s18, s6
	s_addc_u32 s99, s19, s7
	s_mov_b32 m0, s48
	ds_read_b128 v[210:213], v167
	ds_read_b128 v[214:217], v234
	ds_read_b128 v[226:229], v167 offset:2048
	ds_read_b128 v[230:233], v234 offset:2048
	global_load_lds_dwordx4 v132, s[18:19]
	s_add_i32 m0, s48, 0x2000
	s_nop 0
	global_load_lds_dwordx4 v128, s[18:19]
	s_barrier
	s_waitcnt lgkmcnt(0)
	s_waitcnt lgkmcnt(0)
	v_mfma_f32_16x16x32_bf16 v[116:119], v[210:213], v[178:181], v[116:119]
	v_mfma_f32_16x16x32_bf16 v[116:119], v[214:217], v[182:185], v[116:119]
	v_mfma_f32_16x16x32_bf16 v[112:115], v[230:233], v[182:185], v[112:115]
	v_mfma_f32_16x16x32_bf16 v[112:115], v[226:229], v[178:181], v[112:115]
	v_mfma_f32_16x16x32_bf16 v[96:99], v[226:229], v[186:189], v[96:99]
	v_mfma_f32_16x16x32_bf16 v[96:99], v[230:233], v[190:193], v[96:99]
	v_mfma_f32_16x16x32_bf16 v[100:103], v[214:217], v[190:193], v[100:103]
	v_mfma_f32_16x16x32_bf16 v[100:103], v[210:213], v[186:189], v[100:103]
	v_mfma_f32_16x16x32_bf16 v[84:87], v[210:213], v[194:197], v[84:87]
	v_mfma_f32_16x16x32_bf16 v[84:87], v[214:217], v[198:201], v[84:87]
	v_mfma_f32_16x16x32_bf16 v[80:83], v[230:233], v[198:201], v[80:83]
	v_mfma_f32_16x16x32_bf16 v[80:83], v[226:229], v[194:197], v[80:83]
	v_mfma_f32_16x16x32_bf16 v[64:67], v[226:229], v[202:205], v[64:67]
	v_mfma_f32_16x16x32_bf16 v[64:67], v[230:233], v[206:209], v[64:67]
	v_mfma_f32_16x16x32_bf16 v[68:71], v[214:217], v[206:209], v[68:71]
	v_mfma_f32_16x16x32_bf16 v[68:71], v[210:213], v[202:205], v[68:71]
	s_mov_b32 m0, s1
	s_add_u32 s100, s20, s6
	s_addc_u32 s101, s21, s7
	s_barrier
	ds_read_b128 v[178:181], v166 offset:16384
	ds_read_b128 v[182:185], v221 offset:16384
	ds_read_b128 v[186:189], v166 offset:18432
	ds_read_b128 v[190:193], v221 offset:18432
	ds_read_b128 v[194:197], v166 offset:20480
	ds_read_b128 v[198:201], v221 offset:20480
	ds_read_b128 v[202:205], v166 offset:22528
	ds_read_b128 v[206:209], v221 offset:22528
	global_load_lds_dwordx4 v134, s[20:21]
	s_mov_b32 m0, s26
	s_nop 0
	global_load_lds_dwordx4 v130, s[20:21]
	s_barrier
	s_waitcnt lgkmcnt(0)
	s_waitcnt lgkmcnt(0)
	v_mfma_f32_16x16x32_bf16 v[60:63], v[144:147], v[178:181], v[60:63]
	v_mfma_f32_16x16x32_bf16 v[60:63], v[148:151], v[182:185], v[60:63]
	v_mfma_f32_16x16x32_bf16 v[56:59], v[174:177], v[182:185], v[56:59]
	v_mfma_f32_16x16x32_bf16 v[56:59], v[170:173], v[178:181], v[56:59]
	v_mfma_f32_16x16x32_bf16 v[40:43], v[170:173], v[186:189], v[40:43]
	v_mfma_f32_16x16x32_bf16 v[40:43], v[174:177], v[190:193], v[40:43]
	v_mfma_f32_16x16x32_bf16 v[44:47], v[148:151], v[190:193], v[44:47]
	v_mfma_f32_16x16x32_bf16 v[44:47], v[144:147], v[186:189], v[44:47]
	v_mfma_f32_16x16x32_bf16 v[28:31], v[144:147], v[194:197], v[28:31]
	v_mfma_f32_16x16x32_bf16 v[28:31], v[148:151], v[198:201], v[28:31]
	v_mfma_f32_16x16x32_bf16 v[24:27], v[174:177], v[198:201], v[24:27]
	v_mfma_f32_16x16x32_bf16 v[24:27], v[170:173], v[194:197], v[24:27]
	v_mfma_f32_16x16x32_bf16 v[8:11], v[170:173], v[202:205], v[8:11]
	v_mfma_f32_16x16x32_bf16 v[8:11], v[174:177], v[206:209], v[8:11]
	v_mfma_f32_16x16x32_bf16 v[12:15], v[148:151], v[206:209], v[12:15]
	v_mfma_f32_16x16x32_bf16 v[12:15], v[144:147], v[202:205], v[12:15]
	s_barrier
	s_add_u32 s48, s18, 0x80000
	s_addc_u32 s49, s19, 0
	s_add_i32 s52, s38, s24
	s_mov_b32 m0, s52
	s_nop 0
	global_load_lds_dwordx4 v132, s[48:49]
	s_add_i32 m0, s52, 0x2000
	s_nop 0
	global_load_lds_dwordx4 v128, s[48:49]
	s_waitcnt vmcnt(6)
	s_barrier
	v_mfma_f32_16x16x32_bf16 v[52:55], v[210:213], v[178:181], v[52:55]
	v_mfma_f32_16x16x32_bf16 v[52:55], v[214:217], v[182:185], v[52:55]
	v_mfma_f32_16x16x32_bf16 v[48:51], v[230:233], v[182:185], v[48:51]
	v_mfma_f32_16x16x32_bf16 v[48:51], v[226:229], v[178:181], v[48:51]
	v_mfma_f32_16x16x32_bf16 v[32:35], v[226:229], v[186:189], v[32:35]
	v_mfma_f32_16x16x32_bf16 v[32:35], v[230:233], v[190:193], v[32:35]
	v_mfma_f32_16x16x32_bf16 v[36:39], v[214:217], v[190:193], v[36:39]
	v_mfma_f32_16x16x32_bf16 v[36:39], v[210:213], v[186:189], v[36:39]
	v_mfma_f32_16x16x32_bf16 v[20:23], v[210:213], v[194:197], v[20:23]
	v_mfma_f32_16x16x32_bf16 v[20:23], v[214:217], v[198:201], v[20:23]
	v_mfma_f32_16x16x32_bf16 v[16:19], v[230:233], v[198:201], v[16:19]
	v_mfma_f32_16x16x32_bf16 v[16:19], v[226:229], v[194:197], v[16:19]
	v_mfma_f32_16x16x32_bf16 v[0:3], v[226:229], v[202:205], v[0:3]
	v_mfma_f32_16x16x32_bf16 v[0:3], v[230:233], v[206:209], v[0:3]
	v_mfma_f32_16x16x32_bf16 v[4:7], v[214:217], v[206:209], v[4:7]
	v_mfma_f32_16x16x32_bf16 v[4:7], v[210:213], v[202:205], v[4:7]
	s_add_i32 s48, 0, 0x18000
	s_barrier
	ds_read_b128 v[144:147], v235
	ds_read_b128 v[148:151], v236
	ds_read_b128 v[170:173], v235 offset:2048
	ds_read_b128 v[174:177], v236 offset:2048
	s_add_u32 s20, s20, 0x80000
	s_addc_u32 s21, s21, 0
	s_mov_b32 m0, s27
	ds_read_b128 v[178:181], v166 offset:32768
	ds_read_b128 v[182:185], v221 offset:32768
	ds_read_b128 v[186:189], v166 offset:34816
	ds_read_b128 v[190:193], v221 offset:34816
	ds_read_b128 v[194:197], v166 offset:36864
	ds_read_b128 v[198:201], v221 offset:36864
	ds_read_b128 v[202:205], v166 offset:38912
	ds_read_b128 v[206:209], v221 offset:38912
	global_load_lds_dwordx4 v134, s[20:21]
	s_mov_b32 m0, s28
	s_nop 0
	global_load_lds_dwordx4 v130, s[20:21]
	s_waitcnt lgkmcnt(8)
	s_barrier
	s_waitcnt lgkmcnt(0)
	s_waitcnt lgkmcnt(0)
	v_mfma_f32_16x16x32_bf16 v[124:127], v[144:147], v[178:181], v[124:127]
	v_mfma_f32_16x16x32_bf16 v[124:127], v[148:151], v[182:185], v[124:127]
	v_mfma_f32_16x16x32_bf16 v[120:123], v[174:177], v[182:185], v[120:123]
	v_mfma_f32_16x16x32_bf16 v[120:123], v[170:173], v[178:181], v[120:123]
	v_mfma_f32_16x16x32_bf16 v[104:107], v[170:173], v[186:189], v[104:107]
	v_mfma_f32_16x16x32_bf16 v[104:107], v[174:177], v[190:193], v[104:107]
	v_mfma_f32_16x16x32_bf16 v[108:111], v[148:151], v[190:193], v[108:111]
	v_mfma_f32_16x16x32_bf16 v[108:111], v[144:147], v[186:189], v[108:111]
	v_mfma_f32_16x16x32_bf16 v[92:95], v[144:147], v[194:197], v[92:95]
	v_mfma_f32_16x16x32_bf16 v[92:95], v[148:151], v[198:201], v[92:95]
	v_mfma_f32_16x16x32_bf16 v[88:91], v[174:177], v[198:201], v[88:91]
	v_mfma_f32_16x16x32_bf16 v[88:91], v[170:173], v[194:197], v[88:91]
	v_mfma_f32_16x16x32_bf16 v[72:75], v[170:173], v[202:205], v[72:75]
	v_mfma_f32_16x16x32_bf16 v[72:75], v[174:177], v[206:209], v[72:75]
	v_mfma_f32_16x16x32_bf16 v[76:79], v[148:151], v[206:209], v[76:79]
	v_mfma_f32_16x16x32_bf16 v[76:79], v[144:147], v[202:205], v[76:79]
	s_barrier
	s_add_i32 s20, 0, 0x1c000
	s_add_i32 s21, s48, s24
	v_add_u32_e32 v169, s20, v161
	s_mov_b32 m0, s21
	ds_read_b128 v[210:213], v169
	v_xor_b32_e32 v233, 64, v169
	ds_read_b128 v[214:217], v233
	ds_read_b128 v[226:229], v169 offset:2048
	ds_read_b128 v[230:233], v233 offset:2048
	global_load_lds_dwordx4 v132, s[98:99]
	s_add_i32 m0, s21, 0x2000
	s_nop 0
	global_load_lds_dwordx4 v128, s[98:99]
	s_barrier
	s_waitcnt lgkmcnt(0)
	s_waitcnt lgkmcnt(0)
	v_mfma_f32_16x16x32_bf16 v[116:119], v[210:213], v[178:181], v[116:119]
	v_mfma_f32_16x16x32_bf16 v[116:119], v[214:217], v[182:185], v[116:119]
	v_mfma_f32_16x16x32_bf16 v[112:115], v[230:233], v[182:185], v[112:115]
	v_mfma_f32_16x16x32_bf16 v[112:115], v[226:229], v[178:181], v[112:115]
	v_mfma_f32_16x16x32_bf16 v[96:99], v[226:229], v[186:189], v[96:99]
	v_mfma_f32_16x16x32_bf16 v[96:99], v[230:233], v[190:193], v[96:99]
	v_mfma_f32_16x16x32_bf16 v[100:103], v[214:217], v[190:193], v[100:103]
	v_mfma_f32_16x16x32_bf16 v[100:103], v[210:213], v[186:189], v[100:103]
	v_mfma_f32_16x16x32_bf16 v[84:87], v[210:213], v[194:197], v[84:87]
	v_mfma_f32_16x16x32_bf16 v[84:87], v[214:217], v[198:201], v[84:87]
	v_mfma_f32_16x16x32_bf16 v[80:83], v[230:233], v[198:201], v[80:83]
	v_mfma_f32_16x16x32_bf16 v[80:83], v[226:229], v[194:197], v[80:83]
	v_mfma_f32_16x16x32_bf16 v[64:67], v[226:229], v[202:205], v[64:67]
	v_mfma_f32_16x16x32_bf16 v[64:67], v[230:233], v[206:209], v[64:67]
	v_mfma_f32_16x16x32_bf16 v[68:71], v[214:217], v[206:209], v[68:71]
	v_mfma_f32_16x16x32_bf16 v[68:71], v[210:213], v[202:205], v[68:71]
	s_mov_b32 m0, s30
	s_barrier
	ds_read_b128 v[178:181], v166 offset:49152
	ds_read_b128 v[182:185], v221 offset:49152
	ds_read_b128 v[186:189], v166 offset:51200
	ds_read_b128 v[190:193], v221 offset:51200
	ds_read_b128 v[194:197], v166 offset:53248
	ds_read_b128 v[198:201], v221 offset:53248
	ds_read_b128 v[202:205], v166 offset:55296
	ds_read_b128 v[206:209], v221 offset:55296
	global_load_lds_dwordx4 v134, s[100:101]
	s_mov_b32 m0, s31
	s_nop 0
	global_load_lds_dwordx4 v130, s[100:101]
	s_barrier
	s_waitcnt lgkmcnt(0)
	s_waitcnt lgkmcnt(0)
	v_mfma_f32_16x16x32_bf16 v[60:63], v[144:147], v[178:181], v[60:63]
	v_mfma_f32_16x16x32_bf16 v[60:63], v[148:151], v[182:185], v[60:63]
	v_mfma_f32_16x16x32_bf16 v[56:59], v[174:177], v[182:185], v[56:59]
	v_mfma_f32_16x16x32_bf16 v[56:59], v[170:173], v[178:181], v[56:59]
	v_mfma_f32_16x16x32_bf16 v[40:43], v[170:173], v[186:189], v[40:43]
	v_mfma_f32_16x16x32_bf16 v[40:43], v[174:177], v[190:193], v[40:43]
	v_mfma_f32_16x16x32_bf16 v[44:47], v[148:151], v[190:193], v[44:47]
	v_mfma_f32_16x16x32_bf16 v[44:47], v[144:147], v[186:189], v[44:47]
	v_mfma_f32_16x16x32_bf16 v[28:31], v[144:147], v[194:197], v[28:31]
	v_mfma_f32_16x16x32_bf16 v[28:31], v[148:151], v[198:201], v[28:31]
	v_mfma_f32_16x16x32_bf16 v[24:27], v[174:177], v[198:201], v[24:27]
	v_mfma_f32_16x16x32_bf16 v[24:27], v[170:173], v[194:197], v[24:27]
	v_mfma_f32_16x16x32_bf16 v[8:11], v[170:173], v[202:205], v[8:11]
	v_mfma_f32_16x16x32_bf16 v[8:11], v[174:177], v[206:209], v[8:11]
	v_mfma_f32_16x16x32_bf16 v[12:15], v[148:151], v[206:209], v[12:15]
	v_mfma_f32_16x16x32_bf16 v[12:15], v[144:147], v[202:205], v[12:15]
	s_barrier
	s_add_u32 s18, s18, 0x80080
	s_addc_u32 s19, s19, 0
	s_add_i32 s20, s20, s24
	s_mov_b32 m0, s20
	s_nop 0
	global_load_lds_dwordx4 v132, s[18:19]
	s_add_i32 m0, s20, 0x2000
	s_nop 0
	global_load_lds_dwordx4 v128, s[18:19]
	s_waitcnt vmcnt(6)
	s_barrier
	v_mfma_f32_16x16x32_bf16 v[52:55], v[210:213], v[178:181], v[52:55]
	v_mfma_f32_16x16x32_bf16 v[52:55], v[214:217], v[182:185], v[52:55]
	v_mfma_f32_16x16x32_bf16 v[48:51], v[230:233], v[182:185], v[48:51]
	v_mfma_f32_16x16x32_bf16 v[48:51], v[226:229], v[178:181], v[48:51]
	v_mfma_f32_16x16x32_bf16 v[32:35], v[226:229], v[186:189], v[32:35]
	v_mfma_f32_16x16x32_bf16 v[32:35], v[230:233], v[190:193], v[32:35]
	v_mfma_f32_16x16x32_bf16 v[36:39], v[214:217], v[190:193], v[36:39]
	v_mfma_f32_16x16x32_bf16 v[36:39], v[210:213], v[186:189], v[36:39]
	v_mfma_f32_16x16x32_bf16 v[20:23], v[210:213], v[194:197], v[20:23]
	v_mfma_f32_16x16x32_bf16 v[20:23], v[214:217], v[198:201], v[20:23]
	v_mfma_f32_16x16x32_bf16 v[16:19], v[230:233], v[198:201], v[16:19]
	v_mfma_f32_16x16x32_bf16 v[16:19], v[226:229], v[194:197], v[16:19]
	v_mfma_f32_16x16x32_bf16 v[0:3], v[226:229], v[202:205], v[0:3]
	v_mfma_f32_16x16x32_bf16 v[0:3], v[230:233], v[206:209], v[0:3]
	v_mfma_f32_16x16x32_bf16 v[4:7], v[214:217], v[206:209], v[4:7]
	v_mfma_f32_16x16x32_bf16 v[4:7], v[210:213], v[202:205], v[4:7]
	s_add_i32 s47, s47, 2
	s_add_u32 s16, s16, 0x100
	s_addc_u32 s17, s17, 0
	s_add_u32 s45, s45, 0x100
	s_addc_u32 s46, s46, 0
	s_cmp_gt_u32 s47, 29
	s_barrier
	s_cbranch_scc0 .LBB0_147
	v_lshl_add_u32 v144, s0, 8, v160
	v_ashrrev_i32_e32 v145, 31, v144
	v_lshl_add_u64 v[150:151], v[144:145], 2, s[92:93]
	global_load_dword v176, v[150:151], off
	global_load_dword v177, v[150:151], off offset:64
	global_load_dword v178, v[150:151], off offset:128
	global_load_dword v179, v[150:151], off offset:192
	global_load_dword v180, v[150:151], off offset:512
	global_load_dword v181, v[150:151], off offset:576
	global_load_dword v182, v[150:151], off offset:640
	global_load_dword v183, v[150:151], off offset:704
	v_lshl_or_b32 v148, s40, 8, v164
	v_mov_b64_e32 v[146:147], s[96:97]
	v_ashrrev_i32_e32 v149, 31, v148
	v_mad_i64_i32 v[172:173], s[16:17], v144, s39, v[146:147]
	v_lshlrev_b64 v[148:149], 1, v[148:149]
	v_lshl_add_u64 v[172:173], v[172:173], 0, v[148:149]
	s_and_b64 vcc, exec, s[4:5]
	s_mov_b32 s40, s8
	s_mov_b32 s0, s10
	s_mov_b64 s[18:19], s[14:15]
	s_waitcnt vmcnt(0)
	v_fmamk_f32 v145, v176, 0x3a000000, v168
	v_rsq_f32_e32 v170, v145
	s_nop 0
	v_pk_mul_f32 v[126:127], v[126:127], v[170:171] op_sel_hi:[1,0]
	v_pk_mul_f32 v[124:125], v[124:125], v[170:171] op_sel_hi:[1,0]
	v_pk_mul_f32 v[122:123], v[122:123], v[170:171] op_sel_hi:[1,0]
	v_pk_mul_f32 v[120:121], v[120:121], v[170:171] op_sel_hi:[1,0]
	v_pk_mul_f32 v[118:119], v[118:119], v[170:171] op_sel_hi:[1,0]
	v_pk_mul_f32 v[116:117], v[116:117], v[170:171] op_sel_hi:[1,0]
	v_pk_mul_f32 v[174:175], v[114:115], v[170:171] op_sel_hi:[1,0]
	v_pk_mul_f32 v[170:171], v[112:113], v[170:171] op_sel_hi:[1,0]
	v_cvt_pk_bf16_f32 v112, v124, v125
	v_cvt_pk_bf16_f32 v113, v126, v127
	v_cvt_pk_bf16_f32 v114, v120, v121
	v_cvt_pk_bf16_f32 v115, v122, v123
	global_store_dwordx4 v[172:173], v[112:115], off
	s_nop 1
	v_cvt_pk_bf16_f32 v112, v116, v117
	v_cvt_pk_bf16_f32 v113, v118, v119
	v_cvt_pk_bf16_f32 v114, v170, v171
	v_cvt_pk_bf16_f32 v115, v174, v175
	global_store_dwordx4 v[172:173], v[112:115], off offset:256
	s_nop 0
	s_nop 0
	v_or_b32_e32 v113, 16, v144
	v_mad_i64_i32 v[114:115], s[16:17], v113, s39, v[146:147]
	v_lshl_add_u64 v[114:115], v[114:115], 0, v[148:149]
	s_nop 0
	v_fmamk_f32 v112, v177, 0x3a000000, v168
	v_rsq_f32_e32 v112, v112
	s_nop 0
	v_pk_mul_f32 v[110:111], v[110:111], v[112:113] op_sel_hi:[1,0]
	v_pk_mul_f32 v[108:109], v[108:109], v[112:113] op_sel_hi:[1,0]
	v_pk_mul_f32 v[106:107], v[106:107], v[112:113] op_sel_hi:[1,0]
	v_pk_mul_f32 v[104:105], v[104:105], v[112:113] op_sel_hi:[1,0]
	v_pk_mul_f32 v[102:103], v[102:103], v[112:113] op_sel_hi:[1,0]
	v_pk_mul_f32 v[100:101], v[100:101], v[112:113] op_sel_hi:[1,0]
	v_pk_mul_f32 v[116:117], v[98:99], v[112:113] op_sel_hi:[1,0]
	v_pk_mul_f32 v[112:113], v[96:97], v[112:113] op_sel_hi:[1,0]
	v_cvt_pk_bf16_f32 v96, v108, v109
	v_cvt_pk_bf16_f32 v97, v110, v111
	v_cvt_pk_bf16_f32 v98, v104, v105
	v_cvt_pk_bf16_f32 v99, v106, v107
	global_store_dwordx4 v[114:115], v[96:99], off
	s_nop 1
	v_cvt_pk_bf16_f32 v96, v100, v101
	v_cvt_pk_bf16_f32 v97, v102, v103
	v_cvt_pk_bf16_f32 v98, v112, v113
	v_cvt_pk_bf16_f32 v99, v116, v117
	global_store_dwordx4 v[114:115], v[96:99], off offset:256
	s_nop 0
	s_nop 0
	v_or_b32_e32 v97, 32, v144
	v_mad_i64_i32 v[98:99], s[16:17], v97, s39, v[146:147]
	v_lshl_add_u64 v[98:99], v[98:99], 0, v[148:149]
	s_nop 0
	v_fmamk_f32 v96, v178, 0x3a000000, v168
	v_rsq_f32_e32 v96, v96
	s_nop 0
	v_pk_mul_f32 v[94:95], v[94:95], v[96:97] op_sel_hi:[1,0]
	v_pk_mul_f32 v[92:93], v[92:93], v[96:97] op_sel_hi:[1,0]
	v_pk_mul_f32 v[90:91], v[90:91], v[96:97] op_sel_hi:[1,0]
	v_pk_mul_f32 v[88:89], v[88:89], v[96:97] op_sel_hi:[1,0]
	v_pk_mul_f32 v[86:87], v[86:87], v[96:97] op_sel_hi:[1,0]
	v_pk_mul_f32 v[84:85], v[84:85], v[96:97] op_sel_hi:[1,0]
	v_pk_mul_f32 v[100:101], v[82:83], v[96:97] op_sel_hi:[1,0]
	v_pk_mul_f32 v[96:97], v[80:81], v[96:97] op_sel_hi:[1,0]
	v_cvt_pk_bf16_f32 v80, v92, v93
	v_cvt_pk_bf16_f32 v81, v94, v95
	v_cvt_pk_bf16_f32 v82, v88, v89
	v_cvt_pk_bf16_f32 v83, v90, v91
	global_store_dwordx4 v[98:99], v[80:83], off
	s_nop 1
	v_cvt_pk_bf16_f32 v80, v84, v85
	v_cvt_pk_bf16_f32 v81, v86, v87
	v_cvt_pk_bf16_f32 v82, v96, v97
	v_cvt_pk_bf16_f32 v83, v100, v101
	global_store_dwordx4 v[98:99], v[80:83], off offset:256
	s_nop 0
	s_nop 0
	v_or_b32_e32 v81, 48, v144
	v_mad_i64_i32 v[82:83], s[16:17], v81, s39, v[146:147]
	v_lshl_add_u64 v[82:83], v[82:83], 0, v[148:149]
	s_nop 0
	v_fmamk_f32 v80, v179, 0x3a000000, v168
	v_rsq_f32_e32 v80, v80
	s_nop 0
	v_pk_mul_f32 v[78:79], v[78:79], v[80:81] op_sel_hi:[1,0]
	v_pk_mul_f32 v[76:77], v[76:77], v[80:81] op_sel_hi:[1,0]
	v_pk_mul_f32 v[74:75], v[74:75], v[80:81] op_sel_hi:[1,0]
	v_pk_mul_f32 v[72:73], v[72:73], v[80:81] op_sel_hi:[1,0]
	v_pk_mul_f32 v[70:71], v[70:71], v[80:81] op_sel_hi:[1,0]
	v_pk_mul_f32 v[68:69], v[68:69], v[80:81] op_sel_hi:[1,0]
	v_pk_mul_f32 v[84:85], v[66:67], v[80:81] op_sel_hi:[1,0]
	v_pk_mul_f32 v[80:81], v[64:65], v[80:81] op_sel_hi:[1,0]
	v_cvt_pk_bf16_f32 v64, v76, v77
	v_cvt_pk_bf16_f32 v65, v78, v79
	v_cvt_pk_bf16_f32 v66, v72, v73
	v_cvt_pk_bf16_f32 v67, v74, v75
	global_store_dwordx4 v[82:83], v[64:67], off
	s_nop 1
	v_cvt_pk_bf16_f32 v64, v68, v69
	v_cvt_pk_bf16_f32 v65, v70, v71
	v_cvt_pk_bf16_f32 v66, v80, v81
	v_cvt_pk_bf16_f32 v67, v84, v85
	global_store_dwordx4 v[82:83], v[64:67], off offset:256
	s_nop 0
	s_nop 0
	v_add_u32_e32 v65, 0x80, v144
	v_mad_i64_i32 v[66:67], s[16:17], v65, s39, v[146:147]
	v_lshl_add_u64 v[66:67], v[66:67], 0, v[148:149]
	s_nop 0
	v_fmamk_f32 v64, v180, 0x3a000000, v168
	v_rsq_f32_e32 v64, v64
	s_nop 0
	v_pk_mul_f32 v[62:63], v[62:63], v[64:65] op_sel_hi:[1,0]
	v_pk_mul_f32 v[60:61], v[60:61], v[64:65] op_sel_hi:[1,0]
	v_pk_mul_f32 v[58:59], v[58:59], v[64:65] op_sel_hi:[1,0]
	v_pk_mul_f32 v[56:57], v[56:57], v[64:65] op_sel_hi:[1,0]
	v_pk_mul_f32 v[54:55], v[54:55], v[64:65] op_sel_hi:[1,0]
	v_pk_mul_f32 v[52:53], v[52:53], v[64:65] op_sel_hi:[1,0]
	v_pk_mul_f32 v[68:69], v[50:51], v[64:65] op_sel_hi:[1,0]
	v_pk_mul_f32 v[64:65], v[48:49], v[64:65] op_sel_hi:[1,0]
	v_cvt_pk_bf16_f32 v48, v60, v61
	v_cvt_pk_bf16_f32 v49, v62, v63
	v_cvt_pk_bf16_f32 v50, v56, v57
	v_cvt_pk_bf16_f32 v51, v58, v59
	global_store_dwordx4 v[66:67], v[48:51], off
	s_nop 1
	v_cvt_pk_bf16_f32 v48, v52, v53
	v_cvt_pk_bf16_f32 v49, v54, v55
	v_cvt_pk_bf16_f32 v50, v64, v65
	v_cvt_pk_bf16_f32 v51, v68, v69
	global_store_dwordx4 v[66:67], v[48:51], off offset:256
	s_nop 0
	s_nop 0
	v_add_u32_e32 v49, 0x90, v144
	v_mad_i64_i32 v[50:51], s[16:17], v49, s39, v[146:147]
	v_lshl_add_u64 v[50:51], v[50:51], 0, v[148:149]
	s_nop 0
	v_fmamk_f32 v48, v181, 0x3a000000, v168
	v_rsq_f32_e32 v48, v48
	s_nop 0
	v_pk_mul_f32 v[46:47], v[46:47], v[48:49] op_sel_hi:[1,0]
	v_pk_mul_f32 v[44:45], v[44:45], v[48:49] op_sel_hi:[1,0]
	v_pk_mul_f32 v[42:43], v[42:43], v[48:49] op_sel_hi:[1,0]
	v_pk_mul_f32 v[40:41], v[40:41], v[48:49] op_sel_hi:[1,0]
	v_pk_mul_f32 v[38:39], v[38:39], v[48:49] op_sel_hi:[1,0]
	v_pk_mul_f32 v[36:37], v[36:37], v[48:49] op_sel_hi:[1,0]
	v_pk_mul_f32 v[52:53], v[34:35], v[48:49] op_sel_hi:[1,0]
	v_pk_mul_f32 v[48:49], v[32:33], v[48:49] op_sel_hi:[1,0]
	v_cvt_pk_bf16_f32 v32, v44, v45
	v_cvt_pk_bf16_f32 v33, v46, v47
	v_cvt_pk_bf16_f32 v34, v40, v41
	v_cvt_pk_bf16_f32 v35, v42, v43
	global_store_dwordx4 v[50:51], v[32:35], off
	s_nop 1
	v_cvt_pk_bf16_f32 v32, v36, v37
	v_cvt_pk_bf16_f32 v33, v38, v39
	v_cvt_pk_bf16_f32 v34, v48, v49
	v_cvt_pk_bf16_f32 v35, v52, v53
	global_store_dwordx4 v[50:51], v[32:35], off offset:256
	s_nop 0
	s_nop 0
	v_add_u32_e32 v33, 0xa0, v144
	v_mad_i64_i32 v[34:35], s[16:17], v33, s39, v[146:147]
	v_lshl_add_u64 v[34:35], v[34:35], 0, v[148:149]
	s_mov_b64 s[16:17], s[12:13]
	s_nop 0
	v_fmamk_f32 v32, v182, 0x3a000000, v168
	v_rsq_f32_e32 v32, v32
	s_nop 0
	v_pk_mul_f32 v[30:31], v[30:31], v[32:33] op_sel_hi:[1,0]
	v_pk_mul_f32 v[28:29], v[28:29], v[32:33] op_sel_hi:[1,0]
	v_pk_mul_f32 v[26:27], v[26:27], v[32:33] op_sel_hi:[1,0]
	v_pk_mul_f32 v[24:25], v[24:25], v[32:33] op_sel_hi:[1,0]
	v_pk_mul_f32 v[22:23], v[22:23], v[32:33] op_sel_hi:[1,0]
	v_pk_mul_f32 v[20:21], v[20:21], v[32:33] op_sel_hi:[1,0]
	v_pk_mul_f32 v[36:37], v[18:19], v[32:33] op_sel_hi:[1,0]
	v_pk_mul_f32 v[32:33], v[16:17], v[32:33] op_sel_hi:[1,0]
	v_cvt_pk_bf16_f32 v16, v28, v29
	v_cvt_pk_bf16_f32 v17, v30, v31
	v_cvt_pk_bf16_f32 v18, v24, v25
	v_cvt_pk_bf16_f32 v19, v26, v27
	global_store_dwordx4 v[34:35], v[16:19], off
	s_nop 1
	v_cvt_pk_bf16_f32 v16, v20, v21
	v_cvt_pk_bf16_f32 v17, v22, v23
	v_cvt_pk_bf16_f32 v18, v32, v33
	v_cvt_pk_bf16_f32 v19, v36, v37
	global_store_dwordx4 v[34:35], v[16:19], off offset:256
	s_nop 0
	s_nop 0
	v_add_u32_e32 v17, 0xb0, v144
	v_mad_i64_i32 v[18:19], s[4:5], v17, s39, v[146:147]
	v_lshl_add_u64 v[18:19], v[18:19], 0, v[148:149]
	s_nop 0
	v_fmamk_f32 v16, v183, 0x3a000000, v168
	v_rsq_f32_e32 v16, v16
	s_nop 0
	v_pk_mul_f32 v[14:15], v[14:15], v[16:17] op_sel_hi:[1,0]
	v_pk_mul_f32 v[12:13], v[12:13], v[16:17] op_sel_hi:[1,0]
	v_pk_mul_f32 v[10:11], v[10:11], v[16:17] op_sel_hi:[1,0]
	v_pk_mul_f32 v[8:9], v[8:9], v[16:17] op_sel_hi:[1,0]
	v_pk_mul_f32 v[6:7], v[6:7], v[16:17] op_sel_hi:[1,0]
	v_pk_mul_f32 v[4:5], v[4:5], v[16:17] op_sel_hi:[1,0]
	v_pk_mul_f32 v[20:21], v[2:3], v[16:17] op_sel_hi:[1,0]
	v_pk_mul_f32 v[16:17], v[0:1], v[16:17] op_sel_hi:[1,0]
	v_cvt_pk_bf16_f32 v0, v12, v13
	v_cvt_pk_bf16_f32 v1, v14, v15
	v_cvt_pk_bf16_f32 v2, v8, v9
	v_cvt_pk_bf16_f32 v3, v10, v11
	global_store_dwordx4 v[18:19], v[0:3], off
	s_nop 1
	v_cvt_pk_bf16_f32 v0, v4, v5
	v_cvt_pk_bf16_f32 v1, v6, v7
	v_cvt_pk_bf16_f32 v2, v16, v17
	v_cvt_pk_bf16_f32 v3, v20, v21
	global_store_dwordx4 v[18:19], v[0:3], off offset:256
	s_cbranch_vccz .LBB0_144
	s_waitcnt vmcnt(0)
	s_cmpk_gt_u32 s3, 0xff
	s_cbranch_scc1 .LBB0_151
	s_barrier

.LBB0_283:
	ds_read_b128 v[140:143], v146
	ds_read_b128 v[154:157], v150
	ds_read_b128 v[158:161], v146 offset:2048
	ds_read_b128 v[168:171], v150 offset:2048
	s_add_u32 s18, s6, 0xffe80080
	s_addc_u32 s19, s7, -1
	s_cmp_eq_u32 s45, 28
	s_cselect_b32 s21, s15, s19
	s_cselect_b32 s20, s14, s18
	s_cselect_b32 s19, s1, s44
	s_cselect_b32 s18, s11, s43
	s_add_i32 m0, s25, 0xc000
	ds_read_b128 v[172:175], v147
	ds_read_b128 v[176:179], v151
	ds_read_b128 v[180:183], v147 offset:2048
	ds_read_b128 v[184:187], v151 offset:2048
	ds_read_b128 v[188:191], v147 offset:4096
	ds_read_b128 v[192:195], v151 offset:4096
	ds_read_b128 v[196:199], v147 offset:6144
	ds_read_b128 v[200:203], v151 offset:6144
	global_load_lds_dwordx4 v132, s[6:7]
	s_add_i32 m0, s25, 0xe000
	s_nop 0
	global_load_lds_dwordx4 v134, s[6:7]
	s_waitcnt lgkmcnt(8)
	s_barrier
	s_waitcnt lgkmcnt(0)
	s_waitcnt lgkmcnt(0)
	v_mfma_f32_16x16x32_bf16 v[124:127], v[140:143], v[172:175], v[124:127]
	v_mfma_f32_16x16x32_bf16 v[124:127], v[154:157], v[176:179], v[124:127]
	v_mfma_f32_16x16x32_bf16 v[120:123], v[168:171], v[176:179], v[120:123]
	v_mfma_f32_16x16x32_bf16 v[120:123], v[158:161], v[172:175], v[120:123]
	v_mfma_f32_16x16x32_bf16 v[104:107], v[158:161], v[180:183], v[104:107]
	v_mfma_f32_16x16x32_bf16 v[104:107], v[168:171], v[184:187], v[104:107]
	v_mfma_f32_16x16x32_bf16 v[108:111], v[154:157], v[184:187], v[108:111]
	v_mfma_f32_16x16x32_bf16 v[108:111], v[140:143], v[180:183], v[108:111]
	v_mfma_f32_16x16x32_bf16 v[92:95], v[140:143], v[188:191], v[92:95]
	v_mfma_f32_16x16x32_bf16 v[92:95], v[154:157], v[192:195], v[92:95]
	v_mfma_f32_16x16x32_bf16 v[88:91], v[168:171], v[192:195], v[88:91]
	v_mfma_f32_16x16x32_bf16 v[88:91], v[158:161], v[188:191], v[88:91]
	v_mfma_f32_16x16x32_bf16 v[72:75], v[158:161], v[196:199], v[72:75]
	v_mfma_f32_16x16x32_bf16 v[72:75], v[168:171], v[200:203], v[72:75]
	v_mfma_f32_16x16x32_bf16 v[76:79], v[154:157], v[200:203], v[76:79]
	v_mfma_f32_16x16x32_bf16 v[76:79], v[140:143], v[196:199], v[76:79]
	s_barrier
	s_add_i32 s46, s39, s24
	s_add_u32 s98, s18, s8
	s_addc_u32 s99, s19, s9
	s_mov_b32 m0, s46
	ds_read_b128 v[204:207], v148
	ds_read_b128 v[208:211], v216
	ds_read_b128 v[212:215], v148 offset:2048
	ds_read_b128 v[242:245], v216 offset:2048
	global_load_lds_dwordx4 v164, s[18:19]
	s_add_i32 m0, s46, 0x2000
	s_nop 0
	global_load_lds_dwordx4 v166, s[18:19]
	s_barrier
	s_waitcnt lgkmcnt(0)
	s_waitcnt lgkmcnt(0)
	v_mfma_f32_16x16x32_bf16 v[116:119], v[204:207], v[172:175], v[116:119]
	v_mfma_f32_16x16x32_bf16 v[116:119], v[208:211], v[176:179], v[116:119]
	v_mfma_f32_16x16x32_bf16 v[112:115], v[242:245], v[176:179], v[112:115]
	v_mfma_f32_16x16x32_bf16 v[112:115], v[212:215], v[172:175], v[112:115]
	v_mfma_f32_16x16x32_bf16 v[96:99], v[212:215], v[180:183], v[96:99]
	v_mfma_f32_16x16x32_bf16 v[96:99], v[242:245], v[184:187], v[96:99]
	v_mfma_f32_16x16x32_bf16 v[100:103], v[208:211], v[184:187], v[100:103]
	v_mfma_f32_16x16x32_bf16 v[100:103], v[204:207], v[180:183], v[100:103]
	v_mfma_f32_16x16x32_bf16 v[84:87], v[204:207], v[188:191], v[84:87]
	v_mfma_f32_16x16x32_bf16 v[84:87], v[208:211], v[192:195], v[84:87]
	v_mfma_f32_16x16x32_bf16 v[80:83], v[242:245], v[192:195], v[80:83]
	v_mfma_f32_16x16x32_bf16 v[80:83], v[212:215], v[188:191], v[80:83]
	v_mfma_f32_16x16x32_bf16 v[64:67], v[212:215], v[196:199], v[64:67]
	v_mfma_f32_16x16x32_bf16 v[64:67], v[242:245], v[200:203], v[64:67]
	v_mfma_f32_16x16x32_bf16 v[68:71], v[208:211], v[200:203], v[68:71]
	v_mfma_f32_16x16x32_bf16 v[68:71], v[204:207], v[196:199], v[68:71]
	s_mov_b32 m0, s25
	s_add_u32 s100, s20, s8
	s_addc_u32 s101, s21, s9
	s_barrier
	ds_read_b128 v[172:175], v147 offset:16384
	ds_read_b128 v[176:179], v151 offset:16384
	ds_read_b128 v[180:183], v147 offset:18432
	ds_read_b128 v[184:187], v151 offset:18432
	ds_read_b128 v[188:191], v147 offset:20480
	ds_read_b128 v[192:195], v151 offset:20480
	ds_read_b128 v[196:199], v147 offset:22528
	ds_read_b128 v[200:203], v151 offset:22528
	global_load_lds_dwordx4 v128, s[20:21]
	s_mov_b32 m0, s26
	s_nop 0
	global_load_lds_dwordx4 v130, s[20:21]
	s_barrier
	s_waitcnt lgkmcnt(0)
	s_waitcnt lgkmcnt(0)
	v_mfma_f32_16x16x32_bf16 v[60:63], v[140:143], v[172:175], v[60:63]
	v_mfma_f32_16x16x32_bf16 v[60:63], v[154:157], v[176:179], v[60:63]
	v_mfma_f32_16x16x32_bf16 v[56:59], v[168:171], v[176:179], v[56:59]
	v_mfma_f32_16x16x32_bf16 v[56:59], v[158:161], v[172:175], v[56:59]
	v_mfma_f32_16x16x32_bf16 v[40:43], v[158:161], v[180:183], v[40:43]
	v_mfma_f32_16x16x32_bf16 v[40:43], v[168:171], v[184:187], v[40:43]
	v_mfma_f32_16x16x32_bf16 v[44:47], v[154:157], v[184:187], v[44:47]
	v_mfma_f32_16x16x32_bf16 v[44:47], v[140:143], v[180:183], v[44:47]
	v_mfma_f32_16x16x32_bf16 v[28:31], v[140:143], v[188:191], v[28:31]
	v_mfma_f32_16x16x32_bf16 v[28:31], v[154:157], v[192:195], v[28:31]
	v_mfma_f32_16x16x32_bf16 v[24:27], v[168:171], v[192:195], v[24:27]
	v_mfma_f32_16x16x32_bf16 v[24:27], v[158:161], v[188:191], v[24:27]
	v_mfma_f32_16x16x32_bf16 v[8:11], v[158:161], v[196:199], v[8:11]
	v_mfma_f32_16x16x32_bf16 v[8:11], v[168:171], v[200:203], v[8:11]
	v_mfma_f32_16x16x32_bf16 v[12:15], v[154:157], v[200:203], v[12:15]
	v_mfma_f32_16x16x32_bf16 v[12:15], v[140:143], v[196:199], v[12:15]
	s_barrier
	s_add_u32 s46, s18, 0x80000
	s_addc_u32 s47, s19, 0
	s_add_i32 s48, s40, s24
	s_mov_b32 m0, s48
	s_nop 0
	global_load_lds_dwordx4 v164, s[46:47]
	s_add_i32 m0, s48, 0x2000
	s_nop 0
	global_load_lds_dwordx4 v166, s[46:47]
	s_waitcnt vmcnt(6)
	s_barrier
	v_mfma_f32_16x16x32_bf16 v[52:55], v[204:207], v[172:175], v[52:55]
	v_mfma_f32_16x16x32_bf16 v[52:55], v[208:211], v[176:179], v[52:55]
	v_mfma_f32_16x16x32_bf16 v[48:51], v[242:245], v[176:179], v[48:51]
	v_mfma_f32_16x16x32_bf16 v[48:51], v[212:215], v[172:175], v[48:51]
	v_mfma_f32_16x16x32_bf16 v[32:35], v[212:215], v[180:183], v[32:35]
	v_mfma_f32_16x16x32_bf16 v[32:35], v[242:245], v[184:187], v[32:35]
	v_mfma_f32_16x16x32_bf16 v[36:39], v[208:211], v[184:187], v[36:39]
	v_mfma_f32_16x16x32_bf16 v[36:39], v[204:207], v[180:183], v[36:39]
	v_mfma_f32_16x16x32_bf16 v[20:23], v[204:207], v[188:191], v[20:23]
	v_mfma_f32_16x16x32_bf16 v[20:23], v[208:211], v[192:195], v[20:23]
	v_mfma_f32_16x16x32_bf16 v[16:19], v[242:245], v[192:195], v[16:19]
	v_mfma_f32_16x16x32_bf16 v[16:19], v[212:215], v[188:191], v[16:19]
	v_mfma_f32_16x16x32_bf16 v[0:3], v[212:215], v[196:199], v[0:3]
	v_mfma_f32_16x16x32_bf16 v[0:3], v[242:245], v[200:203], v[0:3]
	v_mfma_f32_16x16x32_bf16 v[4:7], v[208:211], v[200:203], v[4:7]
	v_mfma_f32_16x16x32_bf16 v[4:7], v[204:207], v[196:199], v[4:7]
	s_add_i32 s46, 0, 0x18000
	s_barrier
	ds_read_b128 v[140:143], v217
	ds_read_b128 v[154:157], v220
	ds_read_b128 v[158:161], v217 offset:2048
	ds_read_b128 v[168:171], v220 offset:2048
	s_add_u32 s20, s20, 0x180000
	s_addc_u32 s21, s21, 0
	s_mov_b32 m0, s27
	ds_read_b128 v[172:175], v147 offset:32768
	ds_read_b128 v[176:179], v151 offset:32768
	ds_read_b128 v[180:183], v147 offset:34816
	ds_read_b128 v[184:187], v151 offset:34816
	ds_read_b128 v[188:191], v147 offset:36864
	ds_read_b128 v[192:195], v151 offset:36864
	ds_read_b128 v[196:199], v147 offset:38912
	ds_read_b128 v[200:203], v151 offset:38912
	global_load_lds_dwordx4 v128, s[20:21]
	s_mov_b32 m0, s28
	s_nop 0
	global_load_lds_dwordx4 v130, s[20:21]
	s_waitcnt lgkmcnt(8)
	s_barrier
	s_waitcnt lgkmcnt(0)
	s_waitcnt lgkmcnt(0)
	v_mfma_f32_16x16x32_bf16 v[124:127], v[140:143], v[172:175], v[124:127]
	v_mfma_f32_16x16x32_bf16 v[124:127], v[154:157], v[176:179], v[124:127]
	v_mfma_f32_16x16x32_bf16 v[120:123], v[168:171], v[176:179], v[120:123]
	v_mfma_f32_16x16x32_bf16 v[120:123], v[158:161], v[172:175], v[120:123]
	v_mfma_f32_16x16x32_bf16 v[104:107], v[158:161], v[180:183], v[104:107]
	v_mfma_f32_16x16x32_bf16 v[104:107], v[168:171], v[184:187], v[104:107]
	v_mfma_f32_16x16x32_bf16 v[108:111], v[154:157], v[184:187], v[108:111]
	v_mfma_f32_16x16x32_bf16 v[108:111], v[140:143], v[180:183], v[108:111]
	v_mfma_f32_16x16x32_bf16 v[92:95], v[140:143], v[188:191], v[92:95]
	v_mfma_f32_16x16x32_bf16 v[92:95], v[154:157], v[192:195], v[92:95]
	v_mfma_f32_16x16x32_bf16 v[88:91], v[168:171], v[192:195], v[88:91]
	v_mfma_f32_16x16x32_bf16 v[88:91], v[158:161], v[188:191], v[88:91]
	v_mfma_f32_16x16x32_bf16 v[72:75], v[158:161], v[196:199], v[72:75]
	v_mfma_f32_16x16x32_bf16 v[72:75], v[168:171], v[200:203], v[72:75]
	v_mfma_f32_16x16x32_bf16 v[76:79], v[154:157], v[200:203], v[76:79]
	v_mfma_f32_16x16x32_bf16 v[76:79], v[140:143], v[196:199], v[76:79]
	s_barrier
	s_add_i32 s20, 0, 0x1c000
	s_add_i32 s21, s46, s24
	v_add_u32_e32 v223, s20, v145
	s_mov_b32 m0, s21
	ds_read_b128 v[204:207], v223
	v_xor_b32_e32 v245, 64, v223
	ds_read_b128 v[208:211], v245
	ds_read_b128 v[212:215], v223 offset:2048
	ds_read_b128 v[242:245], v245 offset:2048
	global_load_lds_dwordx4 v164, s[98:99]
	s_add_i32 m0, s21, 0x2000
	s_nop 0
	global_load_lds_dwordx4 v166, s[98:99]
	s_barrier
	s_waitcnt lgkmcnt(0)
	s_waitcnt lgkmcnt(0)
	v_mfma_f32_16x16x32_bf16 v[116:119], v[204:207], v[172:175], v[116:119]
	v_mfma_f32_16x16x32_bf16 v[116:119], v[208:211], v[176:179], v[116:119]
	v_mfma_f32_16x16x32_bf16 v[112:115], v[242:245], v[176:179], v[112:115]
	v_mfma_f32_16x16x32_bf16 v[112:115], v[212:215], v[172:175], v[112:115]
	v_mfma_f32_16x16x32_bf16 v[96:99], v[212:215], v[180:183], v[96:99]
	v_mfma_f32_16x16x32_bf16 v[96:99], v[242:245], v[184:187], v[96:99]
	v_mfma_f32_16x16x32_bf16 v[100:103], v[208:211], v[184:187], v[100:103]
	v_mfma_f32_16x16x32_bf16 v[100:103], v[204:207], v[180:183], v[100:103]
	v_mfma_f32_16x16x32_bf16 v[84:87], v[204:207], v[188:191], v[84:87]
	v_mfma_f32_16x16x32_bf16 v[84:87], v[208:211], v[192:195], v[84:87]
	v_mfma_f32_16x16x32_bf16 v[80:83], v[242:245], v[192:195], v[80:83]
	v_mfma_f32_16x16x32_bf16 v[80:83], v[212:215], v[188:191], v[80:83]
	v_mfma_f32_16x16x32_bf16 v[64:67], v[212:215], v[196:199], v[64:67]
	v_mfma_f32_16x16x32_bf16 v[64:67], v[242:245], v[200:203], v[64:67]
	v_mfma_f32_16x16x32_bf16 v[68:71], v[208:211], v[200:203], v[68:71]
	v_mfma_f32_16x16x32_bf16 v[68:71], v[204:207], v[196:199], v[68:71]
	s_mov_b32 m0, s33
	s_barrier
	ds_read_b128 v[172:175], v147 offset:49152
	ds_read_b128 v[176:179], v151 offset:49152
	ds_read_b128 v[180:183], v147 offset:51200
	ds_read_b128 v[184:187], v151 offset:51200
	ds_read_b128 v[188:191], v147 offset:53248
	ds_read_b128 v[192:195], v151 offset:53248
	ds_read_b128 v[196:199], v147 offset:55296
	ds_read_b128 v[200:203], v151 offset:55296
	global_load_lds_dwordx4 v128, s[100:101]
	s_mov_b32 m0, s34
	s_nop 0
	global_load_lds_dwordx4 v130, s[100:101]
	s_barrier
	s_waitcnt lgkmcnt(0)
	s_waitcnt lgkmcnt(0)
	v_mfma_f32_16x16x32_bf16 v[60:63], v[140:143], v[172:175], v[60:63]
	v_mfma_f32_16x16x32_bf16 v[60:63], v[154:157], v[176:179], v[60:63]
	v_mfma_f32_16x16x32_bf16 v[56:59], v[168:171], v[176:179], v[56:59]
	v_mfma_f32_16x16x32_bf16 v[56:59], v[158:161], v[172:175], v[56:59]
	v_mfma_f32_16x16x32_bf16 v[40:43], v[158:161], v[180:183], v[40:43]
	v_mfma_f32_16x16x32_bf16 v[40:43], v[168:171], v[184:187], v[40:43]
	v_mfma_f32_16x16x32_bf16 v[44:47], v[154:157], v[184:187], v[44:47]
	v_mfma_f32_16x16x32_bf16 v[44:47], v[140:143], v[180:183], v[44:47]
	v_mfma_f32_16x16x32_bf16 v[28:31], v[140:143], v[188:191], v[28:31]
	v_mfma_f32_16x16x32_bf16 v[28:31], v[154:157], v[192:195], v[28:31]
	v_mfma_f32_16x16x32_bf16 v[24:27], v[168:171], v[192:195], v[24:27]
	v_mfma_f32_16x16x32_bf16 v[24:27], v[158:161], v[188:191], v[24:27]
	v_mfma_f32_16x16x32_bf16 v[8:11], v[158:161], v[196:199], v[8:11]
	v_mfma_f32_16x16x32_bf16 v[8:11], v[168:171], v[200:203], v[8:11]
	v_mfma_f32_16x16x32_bf16 v[12:15], v[154:157], v[200:203], v[12:15]
	v_mfma_f32_16x16x32_bf16 v[12:15], v[140:143], v[196:199], v[12:15]
	s_barrier
	s_add_u32 s18, s18, 0x80080
	s_addc_u32 s19, s19, 0
	s_add_i32 s20, s20, s24
	s_mov_b32 m0, s20
	s_nop 0
	global_load_lds_dwordx4 v164, s[18:19]
	s_add_i32 m0, s20, 0x2000
	s_nop 0
	global_load_lds_dwordx4 v166, s[18:19]
	s_waitcnt vmcnt(6)
	s_barrier
	v_mfma_f32_16x16x32_bf16 v[52:55], v[204:207], v[172:175], v[52:55]
	v_mfma_f32_16x16x32_bf16 v[52:55], v[208:211], v[176:179], v[52:55]
	v_mfma_f32_16x16x32_bf16 v[48:51], v[242:245], v[176:179], v[48:51]
	v_mfma_f32_16x16x32_bf16 v[48:51], v[212:215], v[172:175], v[48:51]
	v_mfma_f32_16x16x32_bf16 v[32:35], v[212:215], v[180:183], v[32:35]
	v_mfma_f32_16x16x32_bf16 v[32:35], v[242:245], v[184:187], v[32:35]
	v_mfma_f32_16x16x32_bf16 v[36:39], v[208:211], v[184:187], v[36:39]
	v_mfma_f32_16x16x32_bf16 v[36:39], v[204:207], v[180:183], v[36:39]
	v_mfma_f32_16x16x32_bf16 v[20:23], v[204:207], v[188:191], v[20:23]
	v_mfma_f32_16x16x32_bf16 v[20:23], v[208:211], v[192:195], v[20:23]
	v_mfma_f32_16x16x32_bf16 v[16:19], v[242:245], v[192:195], v[16:19]
	v_mfma_f32_16x16x32_bf16 v[16:19], v[212:215], v[188:191], v[16:19]
	v_mfma_f32_16x16x32_bf16 v[0:3], v[212:215], v[196:199], v[0:3]
	v_mfma_f32_16x16x32_bf16 v[0:3], v[242:245], v[200:203], v[0:3]
	v_mfma_f32_16x16x32_bf16 v[4:7], v[208:211], v[200:203], v[4:7]
	v_mfma_f32_16x16x32_bf16 v[4:7], v[204:207], v[196:199], v[4:7]
	s_add_i32 s45, s45, 2
	s_add_u32 s6, s6, 0x100
	s_addc_u32 s7, s7, 0
	s_add_u32 s43, s43, 0x100
	s_addc_u32 s44, s44, 0
	s_cmp_gt_u32 s45, 29
	s_barrier
	s_cbranch_scc0 .LBB0_283
	v_lshl_add_u32 v217, s42, 8, v163
	v_add_u32_e32 v217, s30, v217
	v_lshlrev_b32_e32 v208, 2, v217
	v_lshl_add_u32 v214, v225, 3, s31
	v_lshl_add_u32 v214, s0, 8, v214
	v_lshl_add_u32 v209, v217, 11, v214
	v_lshlrev_b32_e32 v209, 1, v209
	v_lshlrev_b32_e32 v210, 1, v209
	v_lshl_add_u32 v217, v225, 4, v163
	v_xor_b32_e32 v215, 16, v217
	v_lshlrev_b32_e32 v215, 2, v215
	v_xor_b32_e32 v216, 32, v217
	v_lshlrev_b32_e32 v216, 2, v216
	v_add_u32_e32 v212, 0x0, v210
	global_load_dwordx4 v[176:179], v212, s[36:37]
	global_load_dwordx4 v[180:183], v212, s[36:37] offset:16
	global_load_dwordx4 v[184:187], v212, s[36:37] offset:512
	global_load_dwordx4 v[188:191], v212, s[36:37] offset:528
	v_add_u32_e32 v212, 0x20000, v210
	global_load_dwordx4 v[192:195], v212, s[36:37]
	global_load_dwordx4 v[196:199], v212, s[36:37] offset:16
	global_load_dwordx4 v[200:203], v212, s[36:37] offset:512
	global_load_dwordx4 v[204:207], v212, s[36:37] offset:528
	s_waitcnt vmcnt(4)
	v_pk_add_f32 v[124:125], v[124:125], v[176:177]
	v_pk_add_f32 v[126:127], v[126:127], v[178:179]
	v_pk_add_f32 v[120:121], v[120:121], v[180:181]
	v_pk_add_f32 v[122:123], v[122:123], v[182:183]
	v_mul_f32_e32 v213, v124, v124
	v_fmac_f32_e32 v213, v125, v125
	v_fmac_f32_e32 v213, v126, v126
	v_fmac_f32_e32 v213, v127, v127
	v_fmac_f32_e32 v213, v120, v120
	v_fmac_f32_e32 v213, v121, v121
	v_fmac_f32_e32 v213, v122, v122
	v_fmac_f32_e32 v213, v123, v123
	v_cvt_pk_bf16_f32 v176, v124, v125
	v_cvt_pk_bf16_f32 v177, v126, v127
	v_cvt_pk_bf16_f32 v178, v120, v121
	v_cvt_pk_bf16_f32 v179, v122, v123
	v_add_u32_e32 v217, 0x0, v209
	global_store_dwordx4 v217, v[176:179], s[80:81]
	v_pk_add_f32 v[116:117], v[116:117], v[184:185]
	v_pk_add_f32 v[118:119], v[118:119], v[186:187]
	v_pk_add_f32 v[112:113], v[112:113], v[188:189]
	v_pk_add_f32 v[114:115], v[114:115], v[190:191]
	v_fmac_f32_e32 v213, v116, v116
	v_fmac_f32_e32 v213, v117, v117
	v_fmac_f32_e32 v213, v118, v118
	v_fmac_f32_e32 v213, v119, v119
	v_fmac_f32_e32 v213, v112, v112
	v_fmac_f32_e32 v213, v113, v113
	v_fmac_f32_e32 v213, v114, v114
	v_fmac_f32_e32 v213, v115, v115
	v_cvt_pk_bf16_f32 v184, v116, v117
	v_cvt_pk_bf16_f32 v185, v118, v119
	v_cvt_pk_bf16_f32 v186, v112, v113
	v_cvt_pk_bf16_f32 v187, v114, v115
	global_store_dwordx4 v217, v[184:187], s[80:81] offset:256
	ds_bpermute_b32 v214, v215, v213
	s_waitcnt lgkmcnt(0)
	v_add_f32_e32 v213, v213, v214
	ds_bpermute_b32 v214, v216, v213
	s_waitcnt lgkmcnt(0)
	v_add_f32_e32 v213, v213, v214
	s_mov_b64 exec, 0xffff
	global_atomic_add_f32 v208, v213, s[12:13]
	s_mov_b64 exec, -1
	v_add_u32_e32 v212, 0x40000, v210
	global_load_dwordx4 v[176:179], v212, s[36:37]
	global_load_dwordx4 v[180:183], v212, s[36:37] offset:16
	global_load_dwordx4 v[184:187], v212, s[36:37] offset:512
	global_load_dwordx4 v[188:191], v212, s[36:37] offset:528
	s_waitcnt vmcnt(7)
	v_pk_add_f32 v[108:109], v[108:109], v[192:193]
	v_pk_add_f32 v[110:111], v[110:111], v[194:195]
	v_pk_add_f32 v[104:105], v[104:105], v[196:197]
	v_pk_add_f32 v[106:107], v[106:107], v[198:199]
	v_mul_f32_e32 v213, v108, v108
	v_fmac_f32_e32 v213, v109, v109
	v_fmac_f32_e32 v213, v110, v110
	v_fmac_f32_e32 v213, v111, v111
	v_fmac_f32_e32 v213, v104, v104
	v_fmac_f32_e32 v213, v105, v105
	v_fmac_f32_e32 v213, v106, v106
	v_fmac_f32_e32 v213, v107, v107
	v_cvt_pk_bf16_f32 v192, v108, v109
	v_cvt_pk_bf16_f32 v193, v110, v111
	v_cvt_pk_bf16_f32 v194, v104, v105
	v_cvt_pk_bf16_f32 v195, v106, v107
	v_add_u32_e32 v217, 0x10000, v209
	global_store_dwordx4 v217, v[192:195], s[80:81]
	v_pk_add_f32 v[100:101], v[100:101], v[200:201]
	v_pk_add_f32 v[102:103], v[102:103], v[202:203]
	v_pk_add_f32 v[96:97], v[96:97], v[204:205]
	v_pk_add_f32 v[98:99], v[98:99], v[206:207]
	v_fmac_f32_e32 v213, v100, v100
	v_fmac_f32_e32 v213, v101, v101
	v_fmac_f32_e32 v213, v102, v102
	v_fmac_f32_e32 v213, v103, v103
	v_fmac_f32_e32 v213, v96, v96
	v_fmac_f32_e32 v213, v97, v97
	v_fmac_f32_e32 v213, v98, v98
	v_fmac_f32_e32 v213, v99, v99
	v_cvt_pk_bf16_f32 v200, v100, v101
	v_cvt_pk_bf16_f32 v201, v102, v103
	v_cvt_pk_bf16_f32 v202, v96, v97
	v_cvt_pk_bf16_f32 v203, v98, v99
	global_store_dwordx4 v217, v[200:203], s[80:81] offset:256
	ds_bpermute_b32 v214, v215, v213
	s_waitcnt lgkmcnt(0)
	v_add_f32_e32 v213, v213, v214
	ds_bpermute_b32 v214, v216, v213
	s_waitcnt lgkmcnt(0)
	v_add_f32_e32 v213, v213, v214
	s_mov_b64 exec, 0xffff
	global_atomic_add_f32 v208, v213, s[12:13] offset:64
	s_mov_b64 exec, -1
	v_add_u32_e32 v212, 0x60000, v210
	global_load_dwordx4 v[192:195], v212, s[36:37]
	global_load_dwordx4 v[196:199], v212, s[36:37] offset:16
	global_load_dwordx4 v[200:203], v212, s[36:37] offset:512
	global_load_dwordx4 v[204:207], v212, s[36:37] offset:528
	s_waitcnt vmcnt(7)
	v_pk_add_f32 v[92:93], v[92:93], v[176:177]
	v_pk_add_f32 v[94:95], v[94:95], v[178:179]
	v_pk_add_f32 v[88:89], v[88:89], v[180:181]
	v_pk_add_f32 v[90:91], v[90:91], v[182:183]
	v_mul_f32_e32 v213, v92, v92
	v_fmac_f32_e32 v213, v93, v93
	v_fmac_f32_e32 v213, v94, v94
	v_fmac_f32_e32 v213, v95, v95
	v_fmac_f32_e32 v213, v88, v88
	v_fmac_f32_e32 v213, v89, v89
	v_fmac_f32_e32 v213, v90, v90
	v_fmac_f32_e32 v213, v91, v91
	v_cvt_pk_bf16_f32 v176, v92, v93
	v_cvt_pk_bf16_f32 v177, v94, v95
	v_cvt_pk_bf16_f32 v178, v88, v89
	v_cvt_pk_bf16_f32 v179, v90, v91
	v_add_u32_e32 v217, 0x20000, v209
	global_store_dwordx4 v217, v[176:179], s[80:81]
	v_pk_add_f32 v[84:85], v[84:85], v[184:185]
	v_pk_add_f32 v[86:87], v[86:87], v[186:187]
	v_pk_add_f32 v[80:81], v[80:81], v[188:189]
	v_pk_add_f32 v[82:83], v[82:83], v[190:191]
	v_fmac_f32_e32 v213, v84, v84
	v_fmac_f32_e32 v213, v85, v85
	v_fmac_f32_e32 v213, v86, v86
	v_fmac_f32_e32 v213, v87, v87
	v_fmac_f32_e32 v213, v80, v80
	v_fmac_f32_e32 v213, v81, v81
	v_fmac_f32_e32 v213, v82, v82
	v_fmac_f32_e32 v213, v83, v83
	v_cvt_pk_bf16_f32 v184, v84, v85
	v_cvt_pk_bf16_f32 v185, v86, v87
	v_cvt_pk_bf16_f32 v186, v80, v81
	v_cvt_pk_bf16_f32 v187, v82, v83
	global_store_dwordx4 v217, v[184:187], s[80:81] offset:256
	ds_bpermute_b32 v214, v215, v213
	s_waitcnt lgkmcnt(0)
	v_add_f32_e32 v213, v213, v214
	ds_bpermute_b32 v214, v216, v213
	s_waitcnt lgkmcnt(0)
	v_add_f32_e32 v213, v213, v214
	s_mov_b64 exec, 0xffff
	global_atomic_add_f32 v208, v213, s[12:13] offset:128
	s_mov_b64 exec, -1
	v_add_u32_e32 v212, 0x100000, v210
	global_load_dwordx4 v[176:179], v212, s[36:37]
	global_load_dwordx4 v[180:183], v212, s[36:37] offset:16
	global_load_dwordx4 v[184:187], v212, s[36:37] offset:512
	global_load_dwordx4 v[188:191], v212, s[36:37] offset:528
	s_waitcnt vmcnt(7)
	v_pk_add_f32 v[76:77], v[76:77], v[192:193]
	v_pk_add_f32 v[78:79], v[78:79], v[194:195]
	v_pk_add_f32 v[72:73], v[72:73], v[196:197]
	v_pk_add_f32 v[74:75], v[74:75], v[198:199]
	v_mul_f32_e32 v213, v76, v76
	v_fmac_f32_e32 v213, v77, v77
	v_fmac_f32_e32 v213, v78, v78
	v_fmac_f32_e32 v213, v79, v79
	v_fmac_f32_e32 v213, v72, v72
	v_fmac_f32_e32 v213, v73, v73
	v_fmac_f32_e32 v213, v74, v74
	v_fmac_f32_e32 v213, v75, v75
	v_cvt_pk_bf16_f32 v192, v76, v77
	v_cvt_pk_bf16_f32 v193, v78, v79
	v_cvt_pk_bf16_f32 v194, v72, v73
	v_cvt_pk_bf16_f32 v195, v74, v75
	v_add_u32_e32 v217, 0x30000, v209
	global_store_dwordx4 v217, v[192:195], s[80:81]
	v_pk_add_f32 v[68:69], v[68:69], v[200:201]
	v_pk_add_f32 v[70:71], v[70:71], v[202:203]
	v_pk_add_f32 v[64:65], v[64:65], v[204:205]
	v_pk_add_f32 v[66:67], v[66:67], v[206:207]
	v_fmac_f32_e32 v213, v68, v68
	v_fmac_f32_e32 v213, v69, v69
	v_fmac_f32_e32 v213, v70, v70
	v_fmac_f32_e32 v213, v71, v71
	v_fmac_f32_e32 v213, v64, v64
	v_fmac_f32_e32 v213, v65, v65
	v_fmac_f32_e32 v213, v66, v66
	v_fmac_f32_e32 v213, v67, v67
	v_cvt_pk_bf16_f32 v200, v68, v69
	v_cvt_pk_bf16_f32 v201, v70, v71
	v_cvt_pk_bf16_f32 v202, v64, v65
	v_cvt_pk_bf16_f32 v203, v66, v67
	global_store_dwordx4 v217, v[200:203], s[80:81] offset:256
	ds_bpermute_b32 v214, v215, v213
	s_waitcnt lgkmcnt(0)
	v_add_f32_e32 v213, v213, v214
	ds_bpermute_b32 v214, v216, v213
	s_waitcnt lgkmcnt(0)
	v_add_f32_e32 v213, v213, v214
	s_mov_b64 exec, 0xffff
	global_atomic_add_f32 v208, v213, s[12:13] offset:192
	s_mov_b64 exec, -1
	v_add_u32_e32 v212, 0x120000, v210
	global_load_dwordx4 v[192:195], v212, s[36:37]
	global_load_dwordx4 v[196:199], v212, s[36:37] offset:16
	global_load_dwordx4 v[200:203], v212, s[36:37] offset:512
	global_load_dwordx4 v[204:207], v212, s[36:37] offset:528
	s_waitcnt vmcnt(7)
	v_pk_add_f32 v[60:61], v[60:61], v[176:177]
	v_pk_add_f32 v[62:63], v[62:63], v[178:179]
	v_pk_add_f32 v[56:57], v[56:57], v[180:181]
	v_pk_add_f32 v[58:59], v[58:59], v[182:183]
	v_mul_f32_e32 v213, v60, v60
	v_fmac_f32_e32 v213, v61, v61
	v_fmac_f32_e32 v213, v62, v62
	v_fmac_f32_e32 v213, v63, v63
	v_fmac_f32_e32 v213, v56, v56
	v_fmac_f32_e32 v213, v57, v57
	v_fmac_f32_e32 v213, v58, v58
	v_fmac_f32_e32 v213, v59, v59
	v_cvt_pk_bf16_f32 v176, v60, v61
	v_cvt_pk_bf16_f32 v177, v62, v63
	v_cvt_pk_bf16_f32 v178, v56, v57
	v_cvt_pk_bf16_f32 v179, v58, v59
	v_add_u32_e32 v217, 0x80000, v209
	global_store_dwordx4 v217, v[176:179], s[80:81]
	v_pk_add_f32 v[52:53], v[52:53], v[184:185]
	v_pk_add_f32 v[54:55], v[54:55], v[186:187]
	v_pk_add_f32 v[48:49], v[48:49], v[188:189]
	v_pk_add_f32 v[50:51], v[50:51], v[190:191]
	v_fmac_f32_e32 v213, v52, v52
	v_fmac_f32_e32 v213, v53, v53
	v_fmac_f32_e32 v213, v54, v54
	v_fmac_f32_e32 v213, v55, v55
	v_fmac_f32_e32 v213, v48, v48
	v_fmac_f32_e32 v213, v49, v49
	v_fmac_f32_e32 v213, v50, v50
	v_fmac_f32_e32 v213, v51, v51
	v_cvt_pk_bf16_f32 v184, v52, v53
	v_cvt_pk_bf16_f32 v185, v54, v55
	v_cvt_pk_bf16_f32 v186, v48, v49
	v_cvt_pk_bf16_f32 v187, v50, v51
	global_store_dwordx4 v217, v[184:187], s[80:81] offset:256
	ds_bpermute_b32 v214, v215, v213
	s_waitcnt lgkmcnt(0)
	v_add_f32_e32 v213, v213, v214
	ds_bpermute_b32 v214, v216, v213
	s_waitcnt lgkmcnt(0)
	v_add_f32_e32 v213, v213, v214
	s_mov_b64 exec, 0xffff
	global_atomic_add_f32 v208, v213, s[12:13] offset:512
	s_mov_b64 exec, -1
	v_add_u32_e32 v212, 0x140000, v210
	global_load_dwordx4 v[176:179], v212, s[36:37]
	global_load_dwordx4 v[180:183], v212, s[36:37] offset:16
	global_load_dwordx4 v[184:187], v212, s[36:37] offset:512
	global_load_dwordx4 v[188:191], v212, s[36:37] offset:528
	s_waitcnt vmcnt(7)
	v_pk_add_f32 v[44:45], v[44:45], v[192:193]
	v_pk_add_f32 v[46:47], v[46:47], v[194:195]
	v_pk_add_f32 v[40:41], v[40:41], v[196:197]
	v_pk_add_f32 v[42:43], v[42:43], v[198:199]
	v_mul_f32_e32 v213, v44, v44
	v_fmac_f32_e32 v213, v45, v45
	v_fmac_f32_e32 v213, v46, v46
	v_fmac_f32_e32 v213, v47, v47
	v_fmac_f32_e32 v213, v40, v40
	v_fmac_f32_e32 v213, v41, v41
	v_fmac_f32_e32 v213, v42, v42
	v_fmac_f32_e32 v213, v43, v43
	v_cvt_pk_bf16_f32 v192, v44, v45
	v_cvt_pk_bf16_f32 v193, v46, v47
	v_cvt_pk_bf16_f32 v194, v40, v41
	v_cvt_pk_bf16_f32 v195, v42, v43
	v_add_u32_e32 v217, 0x90000, v209
	global_store_dwordx4 v217, v[192:195], s[80:81]
	v_pk_add_f32 v[36:37], v[36:37], v[200:201]
	v_pk_add_f32 v[38:39], v[38:39], v[202:203]
	v_pk_add_f32 v[32:33], v[32:33], v[204:205]
	v_pk_add_f32 v[34:35], v[34:35], v[206:207]
	v_fmac_f32_e32 v213, v36, v36
	v_fmac_f32_e32 v213, v37, v37
	v_fmac_f32_e32 v213, v38, v38
	v_fmac_f32_e32 v213, v39, v39
	v_fmac_f32_e32 v213, v32, v32
	v_fmac_f32_e32 v213, v33, v33
	v_fmac_f32_e32 v213, v34, v34
	v_fmac_f32_e32 v213, v35, v35
	v_cvt_pk_bf16_f32 v200, v36, v37
	v_cvt_pk_bf16_f32 v201, v38, v39
	v_cvt_pk_bf16_f32 v202, v32, v33
	v_cvt_pk_bf16_f32 v203, v34, v35
	global_store_dwordx4 v217, v[200:203], s[80:81] offset:256
	ds_bpermute_b32 v214, v215, v213
	s_waitcnt lgkmcnt(0)
	v_add_f32_e32 v213, v213, v214
	ds_bpermute_b32 v214, v216, v213
	s_waitcnt lgkmcnt(0)
	v_add_f32_e32 v213, v213, v214
	s_mov_b64 exec, 0xffff
	global_atomic_add_f32 v208, v213, s[12:13] offset:576
	s_mov_b64 exec, -1
	v_add_u32_e32 v212, 0x160000, v210
	global_load_dwordx4 v[192:195], v212, s[36:37]
	global_load_dwordx4 v[196:199], v212, s[36:37] offset:16
	global_load_dwordx4 v[200:203], v212, s[36:37] offset:512
	global_load_dwordx4 v[204:207], v212, s[36:37] offset:528
	s_waitcnt vmcnt(7)
	v_pk_add_f32 v[28:29], v[28:29], v[176:177]
	v_pk_add_f32 v[30:31], v[30:31], v[178:179]
	v_pk_add_f32 v[24:25], v[24:25], v[180:181]
	v_pk_add_f32 v[26:27], v[26:27], v[182:183]
	v_mul_f32_e32 v213, v28, v28
	v_fmac_f32_e32 v213, v29, v29
	v_fmac_f32_e32 v213, v30, v30
	v_fmac_f32_e32 v213, v31, v31
	v_fmac_f32_e32 v213, v24, v24
	v_fmac_f32_e32 v213, v25, v25
	v_fmac_f32_e32 v213, v26, v26
	v_fmac_f32_e32 v213, v27, v27
	v_cvt_pk_bf16_f32 v176, v28, v29
	v_cvt_pk_bf16_f32 v177, v30, v31
	v_cvt_pk_bf16_f32 v178, v24, v25
	v_cvt_pk_bf16_f32 v179, v26, v27
	v_add_u32_e32 v217, 0xa0000, v209
	global_store_dwordx4 v217, v[176:179], s[80:81]
	v_pk_add_f32 v[20:21], v[20:21], v[184:185]
	v_pk_add_f32 v[22:23], v[22:23], v[186:187]
	v_pk_add_f32 v[16:17], v[16:17], v[188:189]
	v_pk_add_f32 v[18:19], v[18:19], v[190:191]
	v_fmac_f32_e32 v213, v20, v20
	v_fmac_f32_e32 v213, v21, v21
	v_fmac_f32_e32 v213, v22, v22
	v_fmac_f32_e32 v213, v23, v23
	v_fmac_f32_e32 v213, v16, v16
	v_fmac_f32_e32 v213, v17, v17
	v_fmac_f32_e32 v213, v18, v18
	v_fmac_f32_e32 v213, v19, v19
	v_cvt_pk_bf16_f32 v184, v20, v21
	v_cvt_pk_bf16_f32 v185, v22, v23
	v_cvt_pk_bf16_f32 v186, v16, v17
	v_cvt_pk_bf16_f32 v187, v18, v19
	global_store_dwordx4 v217, v[184:187], s[80:81] offset:256
	ds_bpermute_b32 v214, v215, v213
	s_waitcnt lgkmcnt(0)
	v_add_f32_e32 v213, v213, v214
	ds_bpermute_b32 v214, v216, v213
	s_waitcnt lgkmcnt(0)
	v_add_f32_e32 v213, v213, v214
	s_mov_b64 exec, 0xffff
	global_atomic_add_f32 v208, v213, s[12:13] offset:640
	s_mov_b64 exec, -1
	s_waitcnt vmcnt(3)
	v_pk_add_f32 v[12:13], v[12:13], v[192:193]
	v_pk_add_f32 v[14:15], v[14:15], v[194:195]
	v_pk_add_f32 v[8:9], v[8:9], v[196:197]
	v_pk_add_f32 v[10:11], v[10:11], v[198:199]
	v_mul_f32_e32 v213, v12, v12
	v_fmac_f32_e32 v213, v13, v13
	v_fmac_f32_e32 v213, v14, v14
	v_fmac_f32_e32 v213, v15, v15
	v_fmac_f32_e32 v213, v8, v8
	v_fmac_f32_e32 v213, v9, v9
	v_fmac_f32_e32 v213, v10, v10
	v_fmac_f32_e32 v213, v11, v11
	v_cvt_pk_bf16_f32 v192, v12, v13
	v_cvt_pk_bf16_f32 v193, v14, v15
	v_cvt_pk_bf16_f32 v194, v8, v9
	v_cvt_pk_bf16_f32 v195, v10, v11
	v_add_u32_e32 v217, 0xb0000, v209
	global_store_dwordx4 v217, v[192:195], s[80:81]
	v_pk_add_f32 v[4:5], v[4:5], v[200:201]
	v_pk_add_f32 v[6:7], v[6:7], v[202:203]
	v_pk_add_f32 v[0:1], v[0:1], v[204:205]
	v_pk_add_f32 v[2:3], v[2:3], v[206:207]
	v_fmac_f32_e32 v213, v4, v4
	v_fmac_f32_e32 v213, v5, v5
	v_fmac_f32_e32 v213, v6, v6
	v_fmac_f32_e32 v213, v7, v7
	v_fmac_f32_e32 v213, v0, v0
	v_fmac_f32_e32 v213, v1, v1
	v_fmac_f32_e32 v213, v2, v2
	v_fmac_f32_e32 v213, v3, v3
	v_cvt_pk_bf16_f32 v200, v4, v5
	v_cvt_pk_bf16_f32 v201, v6, v7
	v_cvt_pk_bf16_f32 v202, v0, v1
	v_cvt_pk_bf16_f32 v203, v2, v3
	global_store_dwordx4 v217, v[200:203], s[80:81] offset:256
	ds_bpermute_b32 v214, v215, v213
	s_waitcnt lgkmcnt(0)
	v_add_f32_e32 v213, v213, v214
	ds_bpermute_b32 v214, v216, v213
	s_waitcnt lgkmcnt(0)
	v_add_f32_e32 v213, v213, v214
	s_mov_b64 exec, 0xffff
	global_atomic_add_f32 v208, v213, s[12:13] offset:704
	s_mov_b64 exec, -1
	s_branch .LBB0_273

.LBB0_363:
	ds_read_b128 v[76:79], v231
	ds_read_b128 v[80:83], v216
	ds_read_b128 v[84:87], v231 offset:2048
	ds_read_b128 v[88:91], v216 offset:2048
	s_add_u32 s8, s6, 0x100
	s_addc_u32 s9, s7, 0
	s_cmp_eq_u32 s65, 28
	s_cselect_b32 s39, s31, s9
	s_cselect_b32 s38, s33, s8
	s_cselect_b32 s11, s29, s64
	s_cselect_b32 s10, s62, s63
	s_add_i32 m0, s44, 0xc000
	ds_read_b128 v[92:95], v241
	ds_read_b128 v[96:99], v217
	ds_read_b128 v[100:103], v241 offset:2048
	ds_read_b128 v[104:107], v217 offset:2048
	ds_read_b128 v[180:183], v241 offset:4096
	ds_read_b128 v[184:187], v217 offset:4096
	ds_read_b128 v[188:191], v241 offset:6144
	ds_read_b128 v[192:195], v217 offset:6144
	global_load_lds_dwordx4 v172, s[6:7]
	s_add_i32 m0, s44, 0xe000
	s_nop 0
	global_load_lds_dwordx4 v174, s[6:7]
	s_waitcnt lgkmcnt(8)
	s_barrier
	s_waitcnt lgkmcnt(0)
	s_waitcnt lgkmcnt(0)
	v_mfma_f32_16x16x32_bf16 v[158:161], v[76:79], v[92:95], v[158:161]
	v_mfma_f32_16x16x32_bf16 v[158:161], v[80:83], v[96:99], v[158:161]
	v_mfma_f32_16x16x32_bf16 v[60:63], v[88:91], v[96:99], v[60:63]
	v_mfma_f32_16x16x32_bf16 v[60:63], v[84:87], v[92:95], v[60:63]
	v_mfma_f32_16x16x32_bf16 v[52:55], v[84:87], v[100:103], v[52:55]
	v_mfma_f32_16x16x32_bf16 v[52:55], v[88:91], v[104:107], v[52:55]
	v_mfma_f32_16x16x32_bf16 v[150:153], v[80:83], v[104:107], v[150:153]
	v_mfma_f32_16x16x32_bf16 v[150:153], v[76:79], v[100:103], v[150:153]
	v_mfma_f32_16x16x32_bf16 v[146:149], v[76:79], v[180:183], v[146:149]
	v_mfma_f32_16x16x32_bf16 v[146:149], v[80:83], v[184:187], v[146:149]
	v_mfma_f32_16x16x32_bf16 v[48:51], v[88:91], v[184:187], v[48:51]
	v_mfma_f32_16x16x32_bf16 v[48:51], v[84:87], v[180:183], v[48:51]
	v_mfma_f32_16x16x32_bf16 v[40:43], v[84:87], v[188:191], v[40:43]
	v_mfma_f32_16x16x32_bf16 v[40:43], v[88:91], v[192:195], v[40:43]
	v_mfma_f32_16x16x32_bf16 v[138:141], v[80:83], v[192:195], v[138:141]
	v_mfma_f32_16x16x32_bf16 v[138:141], v[76:79], v[188:191], v[138:141]
	s_barrier
	s_add_i32 s6, s58, s42
	s_add_u32 s98, s10, s14
	s_addc_u32 s99, s11, s15
	s_mov_b32 m0, s6
	ds_read_b128 v[196:199], v242
	ds_read_b128 v[200:203], v244
	ds_read_b128 v[204:207], v242 offset:2048
	ds_read_b128 v[208:211], v244 offset:2048
	global_load_lds_dwordx4 v164, s[10:11]
	s_add_i32 m0, s6, 0x2000
	s_nop 0
	global_load_lds_dwordx4 v166, s[10:11]
	s_barrier
	s_waitcnt lgkmcnt(0)
	s_waitcnt lgkmcnt(0)
	v_mfma_f32_16x16x32_bf16 v[154:157], v[196:199], v[92:95], v[154:157]
	v_mfma_f32_16x16x32_bf16 v[154:157], v[200:203], v[96:99], v[154:157]
	v_mfma_f32_16x16x32_bf16 v[56:59], v[208:211], v[96:99], v[56:59]
	v_mfma_f32_16x16x32_bf16 v[56:59], v[204:207], v[92:95], v[56:59]
	v_mfma_f32_16x16x32_bf16 v[44:47], v[204:207], v[100:103], v[44:47]
	v_mfma_f32_16x16x32_bf16 v[44:47], v[208:211], v[104:107], v[44:47]
	v_mfma_f32_16x16x32_bf16 v[36:39], v[208:211], v[184:187], v[36:39]
	v_mfma_f32_16x16x32_bf16 v[36:39], v[204:207], v[180:183], v[36:39]
	v_mfma_f32_16x16x32_bf16 v[32:35], v[204:207], v[188:191], v[32:35]
	v_mfma_f32_16x16x32_bf16 v[32:35], v[208:211], v[192:195], v[32:35]
	v_mfma_f32_16x16x32_bf16 v[92:95], v[196:199], v[100:103], v[142:145]
	v_mfma_f32_16x16x32_bf16 v[92:95], v[200:203], v[104:107], v[92:95]
	v_mfma_f32_16x16x32_bf16 v[96:99], v[200:203], v[184:187], v[134:137]
	v_mfma_f32_16x16x32_bf16 v[96:99], v[196:199], v[180:183], v[96:99]
	v_mfma_f32_16x16x32_bf16 v[100:103], v[196:199], v[188:191], v[130:133]
	v_mfma_f32_16x16x32_bf16 v[100:103], v[200:203], v[192:195], v[100:103]
	s_mov_b32 m0, s44
	s_add_u32 s100, s38, s14
	s_addc_u32 s101, s39, s15
	s_barrier
	ds_read_b128 v[104:107], v241 offset:16384
	ds_read_b128 v[130:133], v217 offset:16384
	ds_read_b128 v[134:137], v241 offset:18432
	ds_read_b128 v[142:145], v217 offset:18432
	ds_read_b128 v[180:183], v241 offset:20480
	ds_read_b128 v[184:187], v217 offset:20480
	ds_read_b128 v[188:191], v241 offset:22528
	ds_read_b128 v[192:195], v217 offset:22528
	global_load_lds_dwordx4 v170, s[38:39]
	s_mov_b32 m0, s45
	s_nop 0
	global_load_lds_dwordx4 v168, s[38:39]
	s_barrier
	s_waitcnt lgkmcnt(0)
	s_waitcnt lgkmcnt(0)
	v_mfma_f32_16x16x32_bf16 v[126:129], v[76:79], v[104:107], v[126:129]
	v_mfma_f32_16x16x32_bf16 v[126:129], v[80:83], v[130:133], v[126:129]
	v_mfma_f32_16x16x32_bf16 v[28:31], v[88:91], v[130:133], v[28:31]
	v_mfma_f32_16x16x32_bf16 v[28:31], v[84:87], v[104:107], v[28:31]
	v_mfma_f32_16x16x32_bf16 v[24:27], v[84:87], v[134:137], v[24:27]
	v_mfma_f32_16x16x32_bf16 v[24:27], v[88:91], v[142:145], v[24:27]
	v_mfma_f32_16x16x32_bf16 v[122:125], v[80:83], v[142:145], v[122:125]
	v_mfma_f32_16x16x32_bf16 v[122:125], v[76:79], v[134:137], v[122:125]
	v_mfma_f32_16x16x32_bf16 v[114:117], v[76:79], v[180:183], v[114:117]
	v_mfma_f32_16x16x32_bf16 v[114:117], v[80:83], v[184:187], v[114:117]
	v_mfma_f32_16x16x32_bf16 v[20:23], v[88:91], v[184:187], v[20:23]
	v_mfma_f32_16x16x32_bf16 v[20:23], v[84:87], v[180:183], v[20:23]
	v_mfma_f32_16x16x32_bf16 v[4:7], v[84:87], v[188:191], v[4:7]
	v_mfma_f32_16x16x32_bf16 v[4:7], v[88:91], v[192:195], v[4:7]
	v_mfma_f32_16x16x32_bf16 v[72:75], v[80:83], v[192:195], v[72:75]
	v_mfma_f32_16x16x32_bf16 v[72:75], v[76:79], v[188:191], v[72:75]
	s_barrier
	s_add_u32 s6, s10, 0x1600000
	s_addc_u32 s7, s11, 0
	s_add_i32 s66, s59, s42
	s_mov_b32 m0, s66
	s_nop 0
	global_load_lds_dwordx4 v164, s[6:7]
	s_add_i32 m0, s66, 0x2000
	s_nop 0
	global_load_lds_dwordx4 v166, s[6:7]
	s_waitcnt vmcnt(6)
	s_barrier
	v_mfma_f32_16x16x32_bf16 v[16:19], v[204:207], v[104:107], v[16:19]
	v_mfma_f32_16x16x32_bf16 v[16:19], v[208:211], v[130:133], v[16:19]
	v_mfma_f32_16x16x32_bf16 v[12:15], v[208:211], v[142:145], v[12:15]
	v_mfma_f32_16x16x32_bf16 v[12:15], v[204:207], v[134:137], v[12:15]
	v_mfma_f32_16x16x32_bf16 v[8:11], v[204:207], v[180:183], v[8:11]
	v_mfma_f32_16x16x32_bf16 v[8:11], v[208:211], v[184:187], v[8:11]
	v_mfma_f32_16x16x32_bf16 v[68:71], v[200:203], v[184:187], v[68:71]
	v_mfma_f32_16x16x32_bf16 v[68:71], v[196:199], v[180:183], v[68:71]
	v_mfma_f32_16x16x32_bf16 v[64:67], v[196:199], v[188:191], v[64:67]
	v_mfma_f32_16x16x32_bf16 v[64:67], v[200:203], v[192:195], v[64:67]
	v_mfma_f32_16x16x32_bf16 v[0:3], v[208:211], v[192:195], v[0:3]
	v_mfma_f32_16x16x32_bf16 v[0:3], v[204:207], v[188:191], v[0:3]
	v_mfma_f32_16x16x32_bf16 v[76:79], v[196:199], v[104:107], v[118:121]
	v_mfma_f32_16x16x32_bf16 v[76:79], v[200:203], v[130:133], v[76:79]
	v_mfma_f32_16x16x32_bf16 v[80:83], v[200:203], v[142:145], v[110:113]
	v_mfma_f32_16x16x32_bf16 v[80:83], v[196:199], v[134:137], v[80:83]
	s_add_i32 s66, 0, 0x18000
	s_barrier
	ds_read_b128 v[84:87], v245
	ds_read_b128 v[88:91], v246
	ds_read_b128 v[104:107], v245 offset:2048
	ds_read_b128 v[108:111], v246 offset:2048
	s_add_u32 s6, s38, 0x40000
	s_addc_u32 s7, s39, 0
	s_mov_b32 m0, s46
	ds_read_b128 v[118:121], v241 offset:32768
	ds_read_b128 v[130:133], v217 offset:32768
	ds_read_b128 v[134:137], v241 offset:34816
	ds_read_b128 v[180:183], v217 offset:34816
	ds_read_b128 v[184:187], v241 offset:36864
	ds_read_b128 v[188:191], v217 offset:36864
	ds_read_b128 v[192:195], v241 offset:38912
	ds_read_b128 v[196:199], v217 offset:38912
	global_load_lds_dwordx4 v170, s[6:7]
	s_mov_b32 m0, s47
	s_nop 0
	global_load_lds_dwordx4 v168, s[6:7]
	s_waitcnt lgkmcnt(8)
	s_barrier
	s_waitcnt lgkmcnt(0)
	s_waitcnt lgkmcnt(0)
	v_mfma_f32_16x16x32_bf16 v[142:145], v[84:87], v[118:121], v[158:161]
	v_mfma_f32_16x16x32_bf16 v[158:161], v[88:91], v[130:133], v[142:145]
	v_mfma_f32_16x16x32_bf16 v[60:63], v[108:111], v[130:133], v[60:63]
	v_mfma_f32_16x16x32_bf16 v[60:63], v[104:107], v[118:121], v[60:63]
	v_mfma_f32_16x16x32_bf16 v[52:55], v[104:107], v[134:137], v[52:55]
	v_mfma_f32_16x16x32_bf16 v[52:55], v[108:111], v[180:183], v[52:55]
	v_mfma_f32_16x16x32_bf16 v[48:51], v[108:111], v[188:191], v[48:51]
	v_mfma_f32_16x16x32_bf16 v[48:51], v[104:107], v[184:187], v[48:51]
	v_mfma_f32_16x16x32_bf16 v[40:43], v[104:107], v[192:195], v[40:43]
	v_mfma_f32_16x16x32_bf16 v[40:43], v[108:111], v[196:199], v[40:43]
	v_mfma_f32_16x16x32_bf16 v[138:141], v[88:91], v[196:199], v[138:141]
	v_mfma_f32_16x16x32_bf16 v[138:141], v[84:87], v[192:195], v[138:141]
	v_mfma_f32_16x16x32_bf16 v[142:145], v[84:87], v[134:137], v[150:153]
	v_mfma_f32_16x16x32_bf16 v[150:153], v[88:91], v[180:183], v[142:145]
	v_mfma_f32_16x16x32_bf16 v[142:145], v[84:87], v[184:187], v[146:149]
	v_mfma_f32_16x16x32_bf16 v[146:149], v[88:91], v[188:191], v[142:145]
	s_barrier
	s_add_i32 s38, 0, 0x1c000
	s_add_i32 s6, s66, s42
	ds_read_b128 v[200:203], v247
	ds_read_b128 v[204:207], v248
	ds_read_b128 v[208:211], v247 offset:2048
	ds_read_b128 v[212:215], v248 offset:2048
	s_mov_b32 m0, s6
	s_nop 0
	global_load_lds_dwordx4 v164, s[98:99]
	s_add_i32 m0, s6, 0x2000
	s_nop 0
	global_load_lds_dwordx4 v166, s[98:99]
	s_barrier
	s_waitcnt lgkmcnt(0)
	s_waitcnt lgkmcnt(0)
	v_mfma_f32_16x16x32_bf16 v[142:145], v[200:203], v[118:121], v[154:157]
	v_mfma_f32_16x16x32_bf16 v[154:157], v[204:207], v[130:133], v[142:145]
	v_mfma_f32_16x16x32_bf16 v[56:59], v[212:215], v[130:133], v[56:59]
	v_mfma_f32_16x16x32_bf16 v[56:59], v[208:211], v[118:121], v[56:59]
	v_mfma_f32_16x16x32_bf16 v[44:47], v[208:211], v[134:137], v[44:47]
	v_mfma_f32_16x16x32_bf16 v[44:47], v[212:215], v[180:183], v[44:47]
	v_mfma_f32_16x16x32_bf16 v[36:39], v[212:215], v[188:191], v[36:39]
	v_mfma_f32_16x16x32_bf16 v[36:39], v[208:211], v[184:187], v[36:39]
	v_mfma_f32_16x16x32_bf16 v[32:35], v[208:211], v[192:195], v[32:35]
	v_mfma_f32_16x16x32_bf16 v[32:35], v[212:215], v[196:199], v[32:35]
	v_mfma_f32_16x16x32_bf16 v[92:95], v[200:203], v[134:137], v[92:95]
	v_mfma_f32_16x16x32_bf16 v[142:145], v[204:207], v[180:183], v[92:95]
	v_mfma_f32_16x16x32_bf16 v[92:95], v[200:203], v[184:187], v[96:99]
	v_mfma_f32_16x16x32_bf16 v[134:137], v[204:207], v[188:191], v[92:95]
	v_mfma_f32_16x16x32_bf16 v[92:95], v[200:203], v[192:195], v[100:103]
	v_mfma_f32_16x16x32_bf16 v[130:133], v[204:207], v[196:199], v[92:95]
	s_mov_b32 m0, s52
	s_barrier
	ds_read_b128 v[92:95], v241 offset:49152
	ds_read_b128 v[96:99], v217 offset:49152
	ds_read_b128 v[100:103], v241 offset:51200
	ds_read_b128 v[180:183], v217 offset:51200
	ds_read_b128 v[184:187], v241 offset:53248
	ds_read_b128 v[188:191], v217 offset:53248
	ds_read_b128 v[192:195], v241 offset:55296
	ds_read_b128 v[196:199], v217 offset:55296
	global_load_lds_dwordx4 v170, s[100:101]
	s_mov_b32 m0, s53
	s_nop 0
	global_load_lds_dwordx4 v168, s[100:101]
	s_barrier
	s_waitcnt lgkmcnt(0)
	s_waitcnt lgkmcnt(0)
	v_mfma_f32_16x16x32_bf16 v[118:121], v[84:87], v[92:95], v[126:129]
	v_mfma_f32_16x16x32_bf16 v[126:129], v[88:91], v[96:99], v[118:121]
	v_mfma_f32_16x16x32_bf16 v[28:31], v[108:111], v[96:99], v[28:31]
	v_mfma_f32_16x16x32_bf16 v[28:31], v[104:107], v[92:95], v[28:31]
	v_mfma_f32_16x16x32_bf16 v[24:27], v[104:107], v[100:103], v[24:27]
	v_mfma_f32_16x16x32_bf16 v[24:27], v[108:111], v[180:183], v[24:27]
	v_mfma_f32_16x16x32_bf16 v[20:23], v[108:111], v[188:191], v[20:23]
	v_mfma_f32_16x16x32_bf16 v[20:23], v[104:107], v[184:187], v[20:23]
	v_mfma_f32_16x16x32_bf16 v[112:115], v[84:87], v[184:187], v[114:117]
	v_mfma_f32_16x16x32_bf16 v[114:117], v[88:91], v[188:191], v[112:115]
	v_mfma_f32_16x16x32_bf16 v[72:75], v[88:91], v[196:199], v[72:75]
	v_mfma_f32_16x16x32_bf16 v[72:75], v[84:87], v[192:195], v[72:75]
	v_mfma_f32_16x16x32_bf16 v[118:121], v[84:87], v[100:103], v[122:125]
	v_mfma_f32_16x16x32_bf16 v[122:125], v[88:91], v[180:183], v[118:121]
	v_mfma_f32_16x16x32_bf16 v[4:7], v[104:107], v[192:195], v[4:7]
	v_mfma_f32_16x16x32_bf16 v[4:7], v[108:111], v[196:199], v[4:7]
	s_barrier
	s_add_u32 s6, s10, 0x1600080
	s_addc_u32 s7, s11, 0
	s_add_i32 s10, s38, s42
	s_mov_b32 m0, s10
	s_nop 0
	global_load_lds_dwordx4 v164, s[6:7]
	s_add_i32 m0, s10, 0x2000
	s_nop 0
	global_load_lds_dwordx4 v166, s[6:7]
	s_waitcnt vmcnt(6)
	s_barrier
	v_mfma_f32_16x16x32_bf16 v[76:79], v[200:203], v[92:95], v[76:79]
	v_mfma_f32_16x16x32_bf16 v[118:121], v[204:207], v[96:99], v[76:79]
	v_mfma_f32_16x16x32_bf16 v[16:19], v[212:215], v[96:99], v[16:19]
	v_mfma_f32_16x16x32_bf16 v[16:19], v[208:211], v[92:95], v[16:19]
	v_mfma_f32_16x16x32_bf16 v[12:15], v[208:211], v[100:103], v[12:15]
	v_mfma_f32_16x16x32_bf16 v[12:15], v[212:215], v[180:183], v[12:15]
	v_mfma_f32_16x16x32_bf16 v[8:11], v[212:215], v[188:191], v[8:11]
	v_mfma_f32_16x16x32_bf16 v[8:11], v[208:211], v[184:187], v[8:11]
	v_mfma_f32_16x16x32_bf16 v[68:71], v[200:203], v[184:187], v[68:71]
	v_mfma_f32_16x16x32_bf16 v[68:71], v[204:207], v[188:191], v[68:71]
	v_mfma_f32_16x16x32_bf16 v[64:67], v[204:207], v[196:199], v[64:67]
	v_mfma_f32_16x16x32_bf16 v[64:67], v[200:203], v[192:195], v[64:67]
	v_mfma_f32_16x16x32_bf16 v[76:79], v[200:203], v[100:103], v[80:83]
	v_mfma_f32_16x16x32_bf16 v[110:113], v[204:207], v[180:183], v[76:79]
	v_mfma_f32_16x16x32_bf16 v[0:3], v[208:211], v[192:195], v[0:3]
	v_mfma_f32_16x16x32_bf16 v[0:3], v[212:215], v[196:199], v[0:3]
	s_add_i32 s65, s65, 2
	s_add_u32 s63, s63, 0x100
	s_addc_u32 s64, s64, 0
	s_cmp_gt_u32 s65, 29
	s_mov_b64 s[6:7], s[8:9]
	s_barrier
	s_cbranch_scc0 .LBB0_363
	s_lshl_b32 s8, s0, 8
	s_add_i32 s8, s8, s56
	s_lshl_b32 s9, s1, 7
	s_add_i32 s9, s9, s49
	s_lshl_b32 s10, s0, 3
	s_lshr_b32 s11, s56, 5
	s_add_i32 s10, s10, s11
	v_add_u32_e32 v200, s8, v163
	v_lshlrev_b32_e32 v213, 2, v200
	global_load_dword v188, v213, s[12:13]
	global_load_dword v189, v213, s[12:13] offset:64
	global_load_dword v190, v213, s[12:13] offset:128
	global_load_dword v191, v213, s[12:13] offset:192
	global_load_dword v192, v213, s[12:13] offset:256
	global_load_dword v193, v213, s[12:13] offset:320
	global_load_dword v194, v213, s[12:13] offset:384
	global_load_dword v195, v213, s[12:13] offset:448
	v_lshl_add_u32 v201, v225, 3, s9
	v_lshlrev_b32_e32 v212, 2, v201
	global_load_dwordx4 v[76:79], v212, s[82:83]
	v_add_u32_e32 v213, 0xb000, v212
	global_load_dwordx4 v[80:83], v213, s[82:83]
	v_add_u32_e32 v213, 0x16000, v212
	global_load_dwordx4 v[84:87], v213, s[82:83]
	global_load_dwordx4 v[88:91], v212, s[84:85]
	v_add_u32_e32 v213, 0x5800, v212
	global_load_dwordx4 v[92:95], v213, s[82:83]
	v_add_u32_e32 v213, 0x10800, v212
	global_load_dwordx4 v[96:99], v213, s[82:83]
	v_add_u32_e32 v213, 0x1b800, v212
	global_load_dwordx4 v[100:103], v213, s[82:83]
	v_add_u32_e32 v213, 0x5800, v212
	global_load_dwordx4 v[104:107], v213, s[84:85]
	v_mul_u32_u24_e32 v215, 0x2c00, v200
	v_lshl_add_u32 v215, v201, 1, v215
	v_add_u32_e32 v213, s10, v163
	v_mul_u32_u24_e32 v217, 0xb000, v213
	v_add_u32_e32 v217, v217, v212
	v_cmp_gt_u32_e64 s[8:9], 2, v163
	v_cmp_lt_u32_e64 s[10:11], 13, v163
	v_cmp_lt_u32_e32 vcc, 1, v163
	v_mov_b32_e32 v214, 1.0
	v_mov_b32_e32 v216, 0xbfb8aa3b
	v_mov_b32_e32 v108, 0x3727c5ac
	s_waitcnt vmcnt(8)
	v_fmamk_f32 v188, v188, 0x3a000000, v108
	v_fmamk_f32 v189, v189, 0x3a000000, v108
	v_fmamk_f32 v190, v190, 0x3a000000, v108
	v_fmamk_f32 v191, v191, 0x3a000000, v108
	v_fmamk_f32 v192, v192, 0x3a000000, v108
	v_fmamk_f32 v193, v193, 0x3a000000, v108
	v_fmamk_f32 v194, v194, 0x3a000000, v108
	v_fmamk_f32 v195, v195, 0x3a000000, v108
	v_rsq_f32_e32 v188, v188
	v_rsq_f32_e32 v189, v189
	v_rsq_f32_e32 v190, v190
	v_rsq_f32_e32 v191, v191
	v_rsq_f32_e32 v192, v192
	v_rsq_f32_e32 v193, v193
	v_rsq_f32_e32 v194, v194
	v_rsq_f32_e32 v195, v195
	v_pk_mul_f32 v[158:159], v[158:159], v[188:189] op_sel_hi:[1,0]
	v_pk_mul_f32 v[160:161], v[160:161], v[188:189] op_sel_hi:[1,0]
	v_pk_mul_f32 v[60:61], v[60:61], v[188:189] op_sel_hi:[1,0]
	v_pk_mul_f32 v[62:63], v[62:63], v[188:189] op_sel_hi:[1,0]
	v_pk_mul_f32 v[154:155], v[154:155], v[188:189] op_sel_hi:[1,0]
	v_pk_mul_f32 v[156:157], v[156:157], v[188:189] op_sel_hi:[1,0]
	v_pk_mul_f32 v[56:57], v[56:57], v[188:189] op_sel_hi:[1,0]
	v_pk_mul_f32 v[58:59], v[58:59], v[188:189] op_sel_hi:[1,0]
	v_pk_mul_f32 v[150:151], v[150:151], v[188:189] op_sel:[0,1] op_sel_hi:[1,1]
	v_pk_mul_f32 v[152:153], v[152:153], v[188:189] op_sel:[0,1] op_sel_hi:[1,1]
	v_pk_mul_f32 v[52:53], v[52:53], v[188:189] op_sel:[0,1] op_sel_hi:[1,1]
	v_pk_mul_f32 v[54:55], v[54:55], v[188:189] op_sel:[0,1] op_sel_hi:[1,1]
	v_pk_mul_f32 v[142:143], v[142:143], v[188:189] op_sel:[0,1] op_sel_hi:[1,1]
	v_pk_mul_f32 v[144:145], v[144:145], v[188:189] op_sel:[0,1] op_sel_hi:[1,1]
	v_pk_mul_f32 v[44:45], v[44:45], v[188:189] op_sel:[0,1] op_sel_hi:[1,1]
	v_pk_mul_f32 v[46:47], v[46:47], v[188:189] op_sel:[0,1] op_sel_hi:[1,1]
	v_pk_mul_f32 v[146:147], v[146:147], v[190:191] op_sel_hi:[1,0]
	v_pk_mul_f32 v[148:149], v[148:149], v[190:191] op_sel_hi:[1,0]
	v_pk_mul_f32 v[48:49], v[48:49], v[190:191] op_sel_hi:[1,0]
	v_pk_mul_f32 v[50:51], v[50:51], v[190:191] op_sel_hi:[1,0]
	v_pk_mul_f32 v[134:135], v[134:135], v[190:191] op_sel_hi:[1,0]
	v_pk_mul_f32 v[136:137], v[136:137], v[190:191] op_sel_hi:[1,0]
	v_pk_mul_f32 v[36:37], v[36:37], v[190:191] op_sel_hi:[1,0]
	v_pk_mul_f32 v[38:39], v[38:39], v[190:191] op_sel_hi:[1,0]
	v_pk_mul_f32 v[138:139], v[138:139], v[190:191] op_sel:[0,1] op_sel_hi:[1,1]
	v_pk_mul_f32 v[140:141], v[140:141], v[190:191] op_sel:[0,1] op_sel_hi:[1,1]
	v_pk_mul_f32 v[40:41], v[40:41], v[190:191] op_sel:[0,1] op_sel_hi:[1,1]
	v_pk_mul_f32 v[42:43], v[42:43], v[190:191] op_sel:[0,1] op_sel_hi:[1,1]
	v_pk_mul_f32 v[130:131], v[130:131], v[190:191] op_sel:[0,1] op_sel_hi:[1,1]
	v_pk_mul_f32 v[132:133], v[132:133], v[190:191] op_sel:[0,1] op_sel_hi:[1,1]
	v_pk_mul_f32 v[32:33], v[32:33], v[190:191] op_sel:[0,1] op_sel_hi:[1,1]
	v_pk_mul_f32 v[34:35], v[34:35], v[190:191] op_sel:[0,1] op_sel_hi:[1,1]
	v_pk_mul_f32 v[126:127], v[126:127], v[192:193] op_sel_hi:[1,0]
	v_pk_mul_f32 v[128:129], v[128:129], v[192:193] op_sel_hi:[1,0]
	v_pk_mul_f32 v[28:29], v[28:29], v[192:193] op_sel_hi:[1,0]
	v_pk_mul_f32 v[30:31], v[30:31], v[192:193] op_sel_hi:[1,0]
	v_pk_mul_f32 v[118:119], v[118:119], v[192:193] op_sel_hi:[1,0]
	v_pk_mul_f32 v[120:121], v[120:121], v[192:193] op_sel_hi:[1,0]
	v_pk_mul_f32 v[16:17], v[16:17], v[192:193] op_sel_hi:[1,0]
	v_pk_mul_f32 v[18:19], v[18:19], v[192:193] op_sel_hi:[1,0]
	v_pk_mul_f32 v[122:123], v[122:123], v[192:193] op_sel:[0,1] op_sel_hi:[1,1]
	v_pk_mul_f32 v[124:125], v[124:125], v[192:193] op_sel:[0,1] op_sel_hi:[1,1]
	v_pk_mul_f32 v[24:25], v[24:25], v[192:193] op_sel:[0,1] op_sel_hi:[1,1]
	v_pk_mul_f32 v[26:27], v[26:27], v[192:193] op_sel:[0,1] op_sel_hi:[1,1]
	v_pk_mul_f32 v[110:111], v[110:111], v[192:193] op_sel:[0,1] op_sel_hi:[1,1]
	v_pk_mul_f32 v[112:113], v[112:113], v[192:193] op_sel:[0,1] op_sel_hi:[1,1]
	v_pk_mul_f32 v[12:13], v[12:13], v[192:193] op_sel:[0,1] op_sel_hi:[1,1]
	v_pk_mul_f32 v[14:15], v[14:15], v[192:193] op_sel:[0,1] op_sel_hi:[1,1]
	v_pk_mul_f32 v[114:115], v[114:115], v[194:195] op_sel_hi:[1,0]
	v_pk_mul_f32 v[116:117], v[116:117], v[194:195] op_sel_hi:[1,0]
	v_pk_mul_f32 v[20:21], v[20:21], v[194:195] op_sel_hi:[1,0]
	v_pk_mul_f32 v[22:23], v[22:23], v[194:195] op_sel_hi:[1,0]
	v_pk_mul_f32 v[68:69], v[68:69], v[194:195] op_sel_hi:[1,0]
	v_pk_mul_f32 v[70:71], v[70:71], v[194:195] op_sel_hi:[1,0]
	v_pk_mul_f32 v[8:9], v[8:9], v[194:195] op_sel_hi:[1,0]
	v_pk_mul_f32 v[10:11], v[10:11], v[194:195] op_sel_hi:[1,0]
	v_pk_mul_f32 v[72:73], v[72:73], v[194:195] op_sel:[0,1] op_sel_hi:[1,1]
	v_pk_mul_f32 v[74:75], v[74:75], v[194:195] op_sel:[0,1] op_sel_hi:[1,1]
	v_pk_mul_f32 v[4:5], v[4:5], v[194:195] op_sel:[0,1] op_sel_hi:[1,1]
	v_pk_mul_f32 v[6:7], v[6:7], v[194:195] op_sel:[0,1] op_sel_hi:[1,1]
	v_pk_mul_f32 v[64:65], v[64:65], v[194:195] op_sel:[0,1] op_sel_hi:[1,1]
	v_pk_mul_f32 v[66:67], v[66:67], v[194:195] op_sel:[0,1] op_sel_hi:[1,1]
	v_pk_mul_f32 v[0:1], v[0:1], v[194:195] op_sel:[0,1] op_sel_hi:[1,1]
	v_pk_mul_f32 v[2:3], v[2:3], v[194:195] op_sel:[0,1] op_sel_hi:[1,1]
	s_nop 1
	s_mov_b64 exec, s[8:9]
	v_add_u32_e32 v213, 0x5800, v217
	global_store_dwordx4 v217, v[158:161], s[70:71]
	global_store_dwordx4 v213, v[154:157], s[70:71]
	global_store_dwordx4 v217, v[60:63], s[70:71] offset:16
	global_store_dwordx4 v213, v[56:59], s[70:71] offset:16
	s_mov_b64 exec, s[10:11]
	v_add_u32_e32 v213, 0xfff7c000, v217
	global_store_dwordx4 v213, v[72:75], s[70:71]
	global_store_dwordx4 v213, v[4:7], s[70:71] offset:16
	v_add_u32_e32 v213, 0xfff81800, v217
	global_store_dwordx4 v213, v[64:67], s[70:71]
	global_store_dwordx4 v213, v[0:3], s[70:71] offset:16
	s_mov_b64 exec, -1
	v_add_u32_e32 v213, 0x1b800, v212
	global_load_dwordx4 v[204:207], v213, s[82:83] offset:16
	v_add_u32_e32 v213, 0x5800, v212
	global_load_dwordx4 v[208:211], v213, s[84:85] offset:16
	s_waitcnt vmcnt(10)
	v_pk_fma_f32 v[188:189], v[158:159], v[84:85], v[88:89]
	v_pk_fma_f32 v[190:191], v[160:161], v[86:87], v[90:91]
	v_pk_fma_f32 v[192:193], v[154:155], v[100:101], v[104:105]
	v_pk_fma_f32 v[194:195], v[156:157], v[102:103], v[106:107]
	v_fmac_f32_dpp v188, v158, v80 row_shr:1 row_mask:0xf bank_mask:0xf
	v_fmac_f32_dpp v189, v159, v81 row_shr:1 row_mask:0xf bank_mask:0xf
	v_fmac_f32_dpp v190, v160, v82 row_shr:1 row_mask:0xf bank_mask:0xf
	v_fmac_f32_dpp v191, v161, v83 row_shr:1 row_mask:0xf bank_mask:0xf
	v_fmac_f32_dpp v192, v154, v96 row_shr:1 row_mask:0xf bank_mask:0xf
	v_fmac_f32_dpp v193, v155, v97 row_shr:1 row_mask:0xf bank_mask:0xf
	v_fmac_f32_dpp v194, v156, v98 row_shr:1 row_mask:0xf bank_mask:0xf
	v_fmac_f32_dpp v195, v157, v99 row_shr:1 row_mask:0xf bank_mask:0xf
	v_fmac_f32_dpp v188, v158, v76 row_shr:2 row_mask:0xf bank_mask:0xf
	v_fmac_f32_dpp v189, v159, v77 row_shr:2 row_mask:0xf bank_mask:0xf
	v_fmac_f32_dpp v190, v160, v78 row_shr:2 row_mask:0xf bank_mask:0xf
	v_fmac_f32_dpp v191, v161, v79 row_shr:2 row_mask:0xf bank_mask:0xf
	v_fmac_f32_dpp v192, v154, v92 row_shr:2 row_mask:0xf bank_mask:0xf
	v_fmac_f32_dpp v193, v155, v93 row_shr:2 row_mask:0xf bank_mask:0xf
	v_fmac_f32_dpp v194, v156, v94 row_shr:2 row_mask:0xf bank_mask:0xf
	v_fmac_f32_dpp v195, v157, v95 row_shr:2 row_mask:0xf bank_mask:0xf
	v_pk_mul_f32 v[196:197], v[188:189], v[216:217] op_sel_hi:[1,0]
	v_pk_mul_f32 v[198:199], v[190:191], v[216:217] op_sel_hi:[1,0]
	v_exp_f32_e32 v196, v196
	v_exp_f32_e32 v197, v197
	v_exp_f32_e32 v198, v198
	v_exp_f32_e32 v199, v199
	v_pk_add_f32 v[196:197], v[196:197], v[214:215] op_sel_hi:[1,0]
	v_pk_add_f32 v[198:199], v[198:199], v[214:215] op_sel_hi:[1,0]
	v_rcp_f32_e32 v196, v196
	v_rcp_f32_e32 v197, v197
	v_rcp_f32_e32 v198, v198
	v_rcp_f32_e32 v199, v199
	v_pk_mul_f32 v[188:189], v[188:189], v[196:197]
	v_pk_mul_f32 v[190:191], v[190:191], v[198:199]
	v_pk_mul_f32 v[188:189], v[188:189], v[192:193]
	v_pk_mul_f32 v[190:191], v[190:191], v[194:195]
	v_cvt_pk_bf16_f32 v200, v188, v189
	v_cvt_pk_bf16_f32 v201, v190, v191
	v_pk_fma_f32 v[188:189], v[150:151], v[84:85], v[88:89]
	v_pk_fma_f32 v[190:191], v[152:153], v[86:87], v[90:91]
	v_pk_fma_f32 v[192:193], v[142:143], v[100:101], v[104:105]
	v_pk_fma_f32 v[194:195], v[144:145], v[102:103], v[106:107]
	v_fmac_f32_dpp v188, v150, v80 row_shr:1 row_mask:0xf bank_mask:0xf
	v_fmac_f32_dpp v189, v151, v81 row_shr:1 row_mask:0xf bank_mask:0xf
	v_fmac_f32_dpp v190, v152, v82 row_shr:1 row_mask:0xf bank_mask:0xf
	v_fmac_f32_dpp v191, v153, v83 row_shr:1 row_mask:0xf bank_mask:0xf
	v_fmac_f32_dpp v192, v142, v96 row_shr:1 row_mask:0xf bank_mask:0xf
	v_fmac_f32_dpp v193, v143, v97 row_shr:1 row_mask:0xf bank_mask:0xf
	v_fmac_f32_dpp v194, v144, v98 row_shr:1 row_mask:0xf bank_mask:0xf
	v_fmac_f32_dpp v195, v145, v99 row_shr:1 row_mask:0xf bank_mask:0xf
	v_fmac_f32_dpp v188, v150, v76 row_shr:2 row_mask:0xf bank_mask:0xf
	v_fmac_f32_dpp v189, v151, v77 row_shr:2 row_mask:0xf bank_mask:0xf
	v_fmac_f32_dpp v190, v152, v78 row_shr:2 row_mask:0xf bank_mask:0xf
	v_fmac_f32_dpp v191, v153, v79 row_shr:2 row_mask:0xf bank_mask:0xf
	v_fmac_f32_dpp v192, v142, v92 row_shr:2 row_mask:0xf bank_mask:0xf
	v_fmac_f32_dpp v193, v143, v93 row_shr:2 row_mask:0xf bank_mask:0xf
	v_fmac_f32_dpp v194, v144, v94 row_shr:2 row_mask:0xf bank_mask:0xf
	v_fmac_f32_dpp v195, v145, v95 row_shr:2 row_mask:0xf bank_mask:0xf
	v_fmac_f32_dpp v188, v158, v80 row_shl:15 row_mask:0xf bank_mask:0xf
	v_fmac_f32_dpp v189, v159, v81 row_shl:15 row_mask:0xf bank_mask:0xf
	v_fmac_f32_dpp v190, v160, v82 row_shl:15 row_mask:0xf bank_mask:0xf
	v_fmac_f32_dpp v191, v161, v83 row_shl:15 row_mask:0xf bank_mask:0xf
	v_fmac_f32_dpp v192, v154, v96 row_shl:15 row_mask:0xf bank_mask:0xf
	v_fmac_f32_dpp v193, v155, v97 row_shl:15 row_mask:0xf bank_mask:0xf
	v_fmac_f32_dpp v194, v156, v98 row_shl:15 row_mask:0xf bank_mask:0xf
	v_fmac_f32_dpp v195, v157, v99 row_shl:15 row_mask:0xf bank_mask:0xf
	v_fmac_f32_dpp v188, v158, v76 row_shl:14 row_mask:0xf bank_mask:0xf
	v_fmac_f32_dpp v189, v159, v77 row_shl:14 row_mask:0xf bank_mask:0xf
	v_fmac_f32_dpp v190, v160, v78 row_shl:14 row_mask:0xf bank_mask:0xf
	v_fmac_f32_dpp v191, v161, v79 row_shl:14 row_mask:0xf bank_mask:0xf
	v_fmac_f32_dpp v192, v154, v92 row_shl:14 row_mask:0xf bank_mask:0xf
	v_fmac_f32_dpp v193, v155, v93 row_shl:14 row_mask:0xf bank_mask:0xf
	v_fmac_f32_dpp v194, v156, v94 row_shl:14 row_mask:0xf bank_mask:0xf
	v_fmac_f32_dpp v195, v157, v95 row_shl:14 row_mask:0xf bank_mask:0xf
	v_pk_mul_f32 v[196:197], v[188:189], v[216:217] op_sel_hi:[1,0]
	v_pk_mul_f32 v[198:199], v[190:191], v[216:217] op_sel_hi:[1,0]
	v_exp_f32_e32 v196, v196
	v_exp_f32_e32 v197, v197
	v_exp_f32_e32 v198, v198
	v_exp_f32_e32 v199, v199
	v_pk_add_f32 v[196:197], v[196:197], v[214:215] op_sel_hi:[1,0]
	v_pk_add_f32 v[198:199], v[198:199], v[214:215] op_sel_hi:[1,0]
	v_rcp_f32_e32 v196, v196
	v_rcp_f32_e32 v197, v197
	v_rcp_f32_e32 v198, v198
	v_rcp_f32_e32 v199, v199
	v_pk_mul_f32 v[188:189], v[188:189], v[196:197]
	v_pk_mul_f32 v[190:191], v[190:191], v[198:199]
	v_pk_mul_f32 v[188:189], v[188:189], v[192:193]
	v_pk_mul_f32 v[190:191], v[190:191], v[194:195]
	v_cvt_pk_bf16_f32 v158, v188, v189
	v_cvt_pk_bf16_f32 v159, v190, v191
	global_load_dwordx4 v[154:157], v212, s[82:83] offset:16
	v_pk_fma_f32 v[188:189], v[146:147], v[84:85], v[88:89]
	v_pk_fma_f32 v[190:191], v[148:149], v[86:87], v[90:91]
	v_pk_fma_f32 v[192:193], v[134:135], v[100:101], v[104:105]
	v_pk_fma_f32 v[194:195], v[136:137], v[102:103], v[106:107]
	v_fmac_f32_dpp v188, v146, v80 row_shr:1 row_mask:0xf bank_mask:0xf
	v_fmac_f32_dpp v189, v147, v81 row_shr:1 row_mask:0xf bank_mask:0xf
	v_fmac_f32_dpp v190, v148, v82 row_shr:1 row_mask:0xf bank_mask:0xf
	v_fmac_f32_dpp v191, v149, v83 row_shr:1 row_mask:0xf bank_mask:0xf
	v_fmac_f32_dpp v192, v134, v96 row_shr:1 row_mask:0xf bank_mask:0xf
	v_fmac_f32_dpp v193, v135, v97 row_shr:1 row_mask:0xf bank_mask:0xf
	v_fmac_f32_dpp v194, v136, v98 row_shr:1 row_mask:0xf bank_mask:0xf
	v_fmac_f32_dpp v195, v137, v99 row_shr:1 row_mask:0xf bank_mask:0xf
	v_fmac_f32_dpp v188, v146, v76 row_shr:2 row_mask:0xf bank_mask:0xf
	v_fmac_f32_dpp v189, v147, v77 row_shr:2 row_mask:0xf bank_mask:0xf
	v_fmac_f32_dpp v190, v148, v78 row_shr:2 row_mask:0xf bank_mask:0xf
	v_fmac_f32_dpp v191, v149, v79 row_shr:2 row_mask:0xf bank_mask:0xf
	v_fmac_f32_dpp v192, v134, v92 row_shr:2 row_mask:0xf bank_mask:0xf
	v_fmac_f32_dpp v193, v135, v93 row_shr:2 row_mask:0xf bank_mask:0xf
	v_fmac_f32_dpp v194, v136, v94 row_shr:2 row_mask:0xf bank_mask:0xf
	v_fmac_f32_dpp v195, v137, v95 row_shr:2 row_mask:0xf bank_mask:0xf
	v_fmac_f32_dpp v188, v150, v80 row_shl:15 row_mask:0xf bank_mask:0xf
	v_fmac_f32_dpp v189, v151, v81 row_shl:15 row_mask:0xf bank_mask:0xf
	v_fmac_f32_dpp v190, v152, v82 row_shl:15 row_mask:0xf bank_mask:0xf
	v_fmac_f32_dpp v191, v153, v83 row_shl:15 row_mask:0xf bank_mask:0xf
	v_fmac_f32_dpp v192, v142, v96 row_shl:15 row_mask:0xf bank_mask:0xf
	v_fmac_f32_dpp v193, v143, v97 row_shl:15 row_mask:0xf bank_mask:0xf
	v_fmac_f32_dpp v194, v144, v98 row_shl:15 row_mask:0xf bank_mask:0xf
	v_fmac_f32_dpp v195, v145, v99 row_shl:15 row_mask:0xf bank_mask:0xf
	v_fmac_f32_dpp v188, v150, v76 row_shl:14 row_mask:0xf bank_mask:0xf
	v_fmac_f32_dpp v189, v151, v77 row_shl:14 row_mask:0xf bank_mask:0xf
	v_fmac_f32_dpp v190, v152, v78 row_shl:14 row_mask:0xf bank_mask:0xf
	v_fmac_f32_dpp v191, v153, v79 row_shl:14 row_mask:0xf bank_mask:0xf
	v_fmac_f32_dpp v192, v142, v92 row_shl:14 row_mask:0xf bank_mask:0xf
	v_fmac_f32_dpp v193, v143, v93 row_shl:14 row_mask:0xf bank_mask:0xf
	v_fmac_f32_dpp v194, v144, v94 row_shl:14 row_mask:0xf bank_mask:0xf
	v_fmac_f32_dpp v195, v145, v95 row_shl:14 row_mask:0xf bank_mask:0xf
	v_pk_mul_f32 v[196:197], v[188:189], v[216:217] op_sel_hi:[1,0]
	v_pk_mul_f32 v[198:199], v[190:191], v[216:217] op_sel_hi:[1,0]
	v_exp_f32_e32 v196, v196
	v_exp_f32_e32 v197, v197
	v_exp_f32_e32 v198, v198
	v_exp_f32_e32 v199, v199
	v_pk_add_f32 v[196:197], v[196:197], v[214:215] op_sel_hi:[1,0]
	v_pk_add_f32 v[198:199], v[198:199], v[214:215] op_sel_hi:[1,0]
	v_rcp_f32_e32 v196, v196
	v_rcp_f32_e32 v197, v197
	v_rcp_f32_e32 v198, v198
	v_rcp_f32_e32 v199, v199
	v_pk_mul_f32 v[188:189], v[188:189], v[196:197]
	v_pk_mul_f32 v[190:191], v[190:191], v[198:199]
	v_pk_mul_f32 v[188:189], v[188:189], v[192:193]
	v_pk_mul_f32 v[190:191], v[190:191], v[194:195]
	v_cvt_pk_bf16_f32 v150, v188, v189
	v_cvt_pk_bf16_f32 v151, v190, v191
	v_add_u32_e32 v213, 0xb000, v212
	global_load_dwordx4 v[142:145], v213, s[82:83] offset:16
	v_pk_fma_f32 v[188:189], v[138:139], v[84:85], v[88:89]
	v_pk_fma_f32 v[190:191], v[140:141], v[86:87], v[90:91]
	v_pk_fma_f32 v[192:193], v[130:131], v[100:101], v[104:105]
	v_pk_fma_f32 v[194:195], v[132:133], v[102:103], v[106:107]
	v_fmac_f32_dpp v188, v138, v80 row_shr:1 row_mask:0xf bank_mask:0xf
	v_fmac_f32_dpp v189, v139, v81 row_shr:1 row_mask:0xf bank_mask:0xf
	v_fmac_f32_dpp v190, v140, v82 row_shr:1 row_mask:0xf bank_mask:0xf
	v_fmac_f32_dpp v191, v141, v83 row_shr:1 row_mask:0xf bank_mask:0xf
	v_fmac_f32_dpp v192, v130, v96 row_shr:1 row_mask:0xf bank_mask:0xf
	v_fmac_f32_dpp v193, v131, v97 row_shr:1 row_mask:0xf bank_mask:0xf
	v_fmac_f32_dpp v194, v132, v98 row_shr:1 row_mask:0xf bank_mask:0xf
	v_fmac_f32_dpp v195, v133, v99 row_shr:1 row_mask:0xf bank_mask:0xf
	v_fmac_f32_dpp v188, v138, v76 row_shr:2 row_mask:0xf bank_mask:0xf
	v_fmac_f32_dpp v189, v139, v77 row_shr:2 row_mask:0xf bank_mask:0xf
	v_fmac_f32_dpp v190, v140, v78 row_shr:2 row_mask:0xf bank_mask:0xf
	v_fmac_f32_dpp v191, v141, v79 row_shr:2 row_mask:0xf bank_mask:0xf
	v_fmac_f32_dpp v192, v130, v92 row_shr:2 row_mask:0xf bank_mask:0xf
	v_fmac_f32_dpp v193, v131, v93 row_shr:2 row_mask:0xf bank_mask:0xf
	v_fmac_f32_dpp v194, v132, v94 row_shr:2 row_mask:0xf bank_mask:0xf
	v_fmac_f32_dpp v195, v133, v95 row_shr:2 row_mask:0xf bank_mask:0xf
	v_fmac_f32_dpp v188, v146, v80 row_shl:15 row_mask:0xf bank_mask:0xf
	v_fmac_f32_dpp v189, v147, v81 row_shl:15 row_mask:0xf bank_mask:0xf
	v_fmac_f32_dpp v190, v148, v82 row_shl:15 row_mask:0xf bank_mask:0xf
	v_fmac_f32_dpp v191, v149, v83 row_shl:15 row_mask:0xf bank_mask:0xf
	v_fmac_f32_dpp v192, v134, v96 row_shl:15 row_mask:0xf bank_mask:0xf
	v_fmac_f32_dpp v193, v135, v97 row_shl:15 row_mask:0xf bank_mask:0xf
	v_fmac_f32_dpp v194, v136, v98 row_shl:15 row_mask:0xf bank_mask:0xf
	v_fmac_f32_dpp v195, v137, v99 row_shl:15 row_mask:0xf bank_mask:0xf
	v_fmac_f32_dpp v188, v146, v76 row_shl:14 row_mask:0xf bank_mask:0xf
	v_fmac_f32_dpp v189, v147, v77 row_shl:14 row_mask:0xf bank_mask:0xf
	v_fmac_f32_dpp v190, v148, v78 row_shl:14 row_mask:0xf bank_mask:0xf
	v_fmac_f32_dpp v191, v149, v79 row_shl:14 row_mask:0xf bank_mask:0xf
	v_fmac_f32_dpp v192, v134, v92 row_shl:14 row_mask:0xf bank_mask:0xf
	v_fmac_f32_dpp v193, v135, v93 row_shl:14 row_mask:0xf bank_mask:0xf
	v_fmac_f32_dpp v194, v136, v94 row_shl:14 row_mask:0xf bank_mask:0xf
	v_fmac_f32_dpp v195, v137, v95 row_shl:14 row_mask:0xf bank_mask:0xf
	v_pk_mul_f32 v[196:197], v[188:189], v[216:217] op_sel_hi:[1,0]
	v_pk_mul_f32 v[198:199], v[190:191], v[216:217] op_sel_hi:[1,0]
	v_exp_f32_e32 v196, v196
	v_exp_f32_e32 v197, v197
	v_exp_f32_e32 v198, v198
	v_exp_f32_e32 v199, v199
	v_pk_add_f32 v[196:197], v[196:197], v[214:215] op_sel_hi:[1,0]
	v_pk_add_f32 v[198:199], v[198:199], v[214:215] op_sel_hi:[1,0]
	v_rcp_f32_e32 v196, v196
	v_rcp_f32_e32 v197, v197
	v_rcp_f32_e32 v198, v198
	v_rcp_f32_e32 v199, v199
	v_pk_mul_f32 v[188:189], v[188:189], v[196:197]
	v_pk_mul_f32 v[190:191], v[190:191], v[198:199]
	v_pk_mul_f32 v[188:189], v[188:189], v[192:193]
	v_pk_mul_f32 v[190:191], v[190:191], v[194:195]
	v_cvt_pk_bf16_f32 v146, v188, v189
	v_cvt_pk_bf16_f32 v147, v190, v191
	v_add_u32_e32 v213, 0x16000, v212
	global_load_dwordx4 v[134:137], v213, s[82:83] offset:16
	v_pk_fma_f32 v[188:189], v[126:127], v[84:85], v[88:89]
	v_pk_fma_f32 v[190:191], v[128:129], v[86:87], v[90:91]
	v_pk_fma_f32 v[192:193], v[118:119], v[100:101], v[104:105]
	v_pk_fma_f32 v[194:195], v[120:121], v[102:103], v[106:107]
	v_fmac_f32_dpp v188, v126, v80 row_shr:1 row_mask:0xf bank_mask:0xf
	v_fmac_f32_dpp v189, v127, v81 row_shr:1 row_mask:0xf bank_mask:0xf
	v_fmac_f32_dpp v190, v128, v82 row_shr:1 row_mask:0xf bank_mask:0xf
	v_fmac_f32_dpp v191, v129, v83 row_shr:1 row_mask:0xf bank_mask:0xf
	v_fmac_f32_dpp v192, v118, v96 row_shr:1 row_mask:0xf bank_mask:0xf
	v_fmac_f32_dpp v193, v119, v97 row_shr:1 row_mask:0xf bank_mask:0xf
	v_fmac_f32_dpp v194, v120, v98 row_shr:1 row_mask:0xf bank_mask:0xf
	v_fmac_f32_dpp v195, v121, v99 row_shr:1 row_mask:0xf bank_mask:0xf
	v_fmac_f32_dpp v188, v126, v76 row_shr:2 row_mask:0xf bank_mask:0xf
	v_fmac_f32_dpp v189, v127, v77 row_shr:2 row_mask:0xf bank_mask:0xf
	v_fmac_f32_dpp v190, v128, v78 row_shr:2 row_mask:0xf bank_mask:0xf
	v_fmac_f32_dpp v191, v129, v79 row_shr:2 row_mask:0xf bank_mask:0xf
	v_fmac_f32_dpp v192, v118, v92 row_shr:2 row_mask:0xf bank_mask:0xf
	v_fmac_f32_dpp v193, v119, v93 row_shr:2 row_mask:0xf bank_mask:0xf
	v_fmac_f32_dpp v194, v120, v94 row_shr:2 row_mask:0xf bank_mask:0xf
	v_fmac_f32_dpp v195, v121, v95 row_shr:2 row_mask:0xf bank_mask:0xf
	v_fmac_f32_dpp v188, v138, v80 row_shl:15 row_mask:0xf bank_mask:0xf
	v_fmac_f32_dpp v189, v139, v81 row_shl:15 row_mask:0xf bank_mask:0xf
	v_fmac_f32_dpp v190, v140, v82 row_shl:15 row_mask:0xf bank_mask:0xf
	v_fmac_f32_dpp v191, v141, v83 row_shl:15 row_mask:0xf bank_mask:0xf
	v_fmac_f32_dpp v192, v130, v96 row_shl:15 row_mask:0xf bank_mask:0xf
	v_fmac_f32_dpp v193, v131, v97 row_shl:15 row_mask:0xf bank_mask:0xf
	v_fmac_f32_dpp v194, v132, v98 row_shl:15 row_mask:0xf bank_mask:0xf
	v_fmac_f32_dpp v195, v133, v99 row_shl:15 row_mask:0xf bank_mask:0xf
	v_fmac_f32_dpp v188, v138, v76 row_shl:14 row_mask:0xf bank_mask:0xf
	v_fmac_f32_dpp v189, v139, v77 row_shl:14 row_mask:0xf bank_mask:0xf
	v_fmac_f32_dpp v190, v140, v78 row_shl:14 row_mask:0xf bank_mask:0xf
	v_fmac_f32_dpp v191, v141, v79 row_shl:14 row_mask:0xf bank_mask:0xf
	v_fmac_f32_dpp v192, v130, v92 row_shl:14 row_mask:0xf bank_mask:0xf
	v_fmac_f32_dpp v193, v131, v93 row_shl:14 row_mask:0xf bank_mask:0xf
	v_fmac_f32_dpp v194, v132, v94 row_shl:14 row_mask:0xf bank_mask:0xf
	v_fmac_f32_dpp v195, v133, v95 row_shl:14 row_mask:0xf bank_mask:0xf
	v_pk_mul_f32 v[196:197], v[188:189], v[216:217] op_sel_hi:[1,0]
	v_pk_mul_f32 v[198:199], v[190:191], v[216:217] op_sel_hi:[1,0]
	v_exp_f32_e32 v196, v196
	v_exp_f32_e32 v197, v197
	v_exp_f32_e32 v198, v198
	v_exp_f32_e32 v199, v199
	v_pk_add_f32 v[196:197], v[196:197], v[214:215] op_sel_hi:[1,0]
	v_pk_add_f32 v[198:199], v[198:199], v[214:215] op_sel_hi:[1,0]
	v_rcp_f32_e32 v196, v196
	v_rcp_f32_e32 v197, v197
	v_rcp_f32_e32 v198, v198
	v_rcp_f32_e32 v199, v199
	v_pk_mul_f32 v[188:189], v[188:189], v[196:197]
	v_pk_mul_f32 v[190:191], v[190:191], v[198:199]
	v_pk_mul_f32 v[188:189], v[188:189], v[192:193]
	v_pk_mul_f32 v[190:191], v[190:191], v[194:195]
	v_cvt_pk_bf16_f32 v138, v188, v189
	v_cvt_pk_bf16_f32 v139, v190, v191
	global_load_dwordx4 v[130:133], v212, s[84:85] offset:16
	v_pk_fma_f32 v[188:189], v[122:123], v[84:85], v[88:89]
	v_pk_fma_f32 v[190:191], v[124:125], v[86:87], v[90:91]
	v_pk_fma_f32 v[192:193], v[110:111], v[100:101], v[104:105]
	v_pk_fma_f32 v[194:195], v[112:113], v[102:103], v[106:107]
	v_fmac_f32_dpp v188, v122, v80 row_shr:1 row_mask:0xf bank_mask:0xf
	v_fmac_f32_dpp v189, v123, v81 row_shr:1 row_mask:0xf bank_mask:0xf
	v_fmac_f32_dpp v190, v124, v82 row_shr:1 row_mask:0xf bank_mask:0xf
	v_fmac_f32_dpp v191, v125, v83 row_shr:1 row_mask:0xf bank_mask:0xf
	v_fmac_f32_dpp v192, v110, v96 row_shr:1 row_mask:0xf bank_mask:0xf
	v_fmac_f32_dpp v193, v111, v97 row_shr:1 row_mask:0xf bank_mask:0xf
	v_fmac_f32_dpp v194, v112, v98 row_shr:1 row_mask:0xf bank_mask:0xf
	v_fmac_f32_dpp v195, v113, v99 row_shr:1 row_mask:0xf bank_mask:0xf
	v_fmac_f32_dpp v188, v122, v76 row_shr:2 row_mask:0xf bank_mask:0xf
	v_fmac_f32_dpp v189, v123, v77 row_shr:2 row_mask:0xf bank_mask:0xf
	v_fmac_f32_dpp v190, v124, v78 row_shr:2 row_mask:0xf bank_mask:0xf
	v_fmac_f32_dpp v191, v125, v79 row_shr:2 row_mask:0xf bank_mask:0xf
	v_fmac_f32_dpp v192, v110, v92 row_shr:2 row_mask:0xf bank_mask:0xf
	v_fmac_f32_dpp v193, v111, v93 row_shr:2 row_mask:0xf bank_mask:0xf
	v_fmac_f32_dpp v194, v112, v94 row_shr:2 row_mask:0xf bank_mask:0xf
	v_fmac_f32_dpp v195, v113, v95 row_shr:2 row_mask:0xf bank_mask:0xf
	v_fmac_f32_dpp v188, v126, v80 row_shl:15 row_mask:0xf bank_mask:0xf
	v_fmac_f32_dpp v189, v127, v81 row_shl:15 row_mask:0xf bank_mask:0xf
	v_fmac_f32_dpp v190, v128, v82 row_shl:15 row_mask:0xf bank_mask:0xf
	v_fmac_f32_dpp v191, v129, v83 row_shl:15 row_mask:0xf bank_mask:0xf
	v_fmac_f32_dpp v192, v118, v96 row_shl:15 row_mask:0xf bank_mask:0xf
	v_fmac_f32_dpp v193, v119, v97 row_shl:15 row_mask:0xf bank_mask:0xf
	v_fmac_f32_dpp v194, v120, v98 row_shl:15 row_mask:0xf bank_mask:0xf
	v_fmac_f32_dpp v195, v121, v99 row_shl:15 row_mask:0xf bank_mask:0xf
	v_fmac_f32_dpp v188, v126, v76 row_shl:14 row_mask:0xf bank_mask:0xf
	v_fmac_f32_dpp v189, v127, v77 row_shl:14 row_mask:0xf bank_mask:0xf
	v_fmac_f32_dpp v190, v128, v78 row_shl:14 row_mask:0xf bank_mask:0xf
	v_fmac_f32_dpp v191, v129, v79 row_shl:14 row_mask:0xf bank_mask:0xf
	v_fmac_f32_dpp v192, v118, v92 row_shl:14 row_mask:0xf bank_mask:0xf
	v_fmac_f32_dpp v193, v119, v93 row_shl:14 row_mask:0xf bank_mask:0xf
	v_fmac_f32_dpp v194, v120, v94 row_shl:14 row_mask:0xf bank_mask:0xf
	v_fmac_f32_dpp v195, v121, v95 row_shl:14 row_mask:0xf bank_mask:0xf
	v_pk_mul_f32 v[196:197], v[188:189], v[216:217] op_sel_hi:[1,0]
	v_pk_mul_f32 v[198:199], v[190:191], v[216:217] op_sel_hi:[1,0]
	v_exp_f32_e32 v196, v196
	v_exp_f32_e32 v197, v197
	v_exp_f32_e32 v198, v198
	v_exp_f32_e32 v199, v199
	v_pk_add_f32 v[196:197], v[196:197], v[214:215] op_sel_hi:[1,0]
	v_pk_add_f32 v[198:199], v[198:199], v[214:215] op_sel_hi:[1,0]
	v_rcp_f32_e32 v196, v196
	v_rcp_f32_e32 v197, v197
	v_rcp_f32_e32 v198, v198
	v_rcp_f32_e32 v199, v199
	v_pk_mul_f32 v[188:189], v[188:189], v[196:197]
	v_pk_mul_f32 v[190:191], v[190:191], v[198:199]
	v_pk_mul_f32 v[188:189], v[188:189], v[192:193]
	v_pk_mul_f32 v[190:191], v[190:191], v[194:195]
	v_cvt_pk_bf16_f32 v126, v188, v189
	v_cvt_pk_bf16_f32 v127, v190, v191
	v_add_u32_e32 v213, 0x5800, v212
	global_load_dwordx4 v[118:121], v213, s[82:83] offset:16
	v_pk_fma_f32 v[188:189], v[114:115], v[84:85], v[88:89]
	v_pk_fma_f32 v[190:191], v[116:117], v[86:87], v[90:91]
	v_pk_fma_f32 v[192:193], v[68:69], v[100:101], v[104:105]
	v_pk_fma_f32 v[194:195], v[70:71], v[102:103], v[106:107]
	v_fmac_f32_dpp v188, v114, v80 row_shr:1 row_mask:0xf bank_mask:0xf
	v_fmac_f32_dpp v189, v115, v81 row_shr:1 row_mask:0xf bank_mask:0xf
	v_fmac_f32_dpp v190, v116, v82 row_shr:1 row_mask:0xf bank_mask:0xf
	v_fmac_f32_dpp v191, v117, v83 row_shr:1 row_mask:0xf bank_mask:0xf
	v_fmac_f32_dpp v192, v68, v96 row_shr:1 row_mask:0xf bank_mask:0xf
	v_fmac_f32_dpp v193, v69, v97 row_shr:1 row_mask:0xf bank_mask:0xf
	v_fmac_f32_dpp v194, v70, v98 row_shr:1 row_mask:0xf bank_mask:0xf
	v_fmac_f32_dpp v195, v71, v99 row_shr:1 row_mask:0xf bank_mask:0xf
	v_fmac_f32_dpp v188, v114, v76 row_shr:2 row_mask:0xf bank_mask:0xf
	v_fmac_f32_dpp v189, v115, v77 row_shr:2 row_mask:0xf bank_mask:0xf
	v_fmac_f32_dpp v190, v116, v78 row_shr:2 row_mask:0xf bank_mask:0xf
	v_fmac_f32_dpp v191, v117, v79 row_shr:2 row_mask:0xf bank_mask:0xf
	v_fmac_f32_dpp v192, v68, v92 row_shr:2 row_mask:0xf bank_mask:0xf
	v_fmac_f32_dpp v193, v69, v93 row_shr:2 row_mask:0xf bank_mask:0xf
	v_fmac_f32_dpp v194, v70, v94 row_shr:2 row_mask:0xf bank_mask:0xf
	v_fmac_f32_dpp v195, v71, v95 row_shr:2 row_mask:0xf bank_mask:0xf
	v_fmac_f32_dpp v188, v122, v80 row_shl:15 row_mask:0xf bank_mask:0xf
	v_fmac_f32_dpp v189, v123, v81 row_shl:15 row_mask:0xf bank_mask:0xf
	v_fmac_f32_dpp v190, v124, v82 row_shl:15 row_mask:0xf bank_mask:0xf
	v_fmac_f32_dpp v191, v125, v83 row_shl:15 row_mask:0xf bank_mask:0xf
	v_fmac_f32_dpp v192, v110, v96 row_shl:15 row_mask:0xf bank_mask:0xf
	v_fmac_f32_dpp v193, v111, v97 row_shl:15 row_mask:0xf bank_mask:0xf
	v_fmac_f32_dpp v194, v112, v98 row_shl:15 row_mask:0xf bank_mask:0xf
	v_fmac_f32_dpp v195, v113, v99 row_shl:15 row_mask:0xf bank_mask:0xf
	v_fmac_f32_dpp v188, v122, v76 row_shl:14 row_mask:0xf bank_mask:0xf
	v_fmac_f32_dpp v189, v123, v77 row_shl:14 row_mask:0xf bank_mask:0xf
	v_fmac_f32_dpp v190, v124, v78 row_shl:14 row_mask:0xf bank_mask:0xf
	v_fmac_f32_dpp v191, v125, v79 row_shl:14 row_mask:0xf bank_mask:0xf
	v_fmac_f32_dpp v192, v110, v92 row_shl:14 row_mask:0xf bank_mask:0xf
	v_fmac_f32_dpp v193, v111, v93 row_shl:14 row_mask:0xf bank_mask:0xf
	v_fmac_f32_dpp v194, v112, v94 row_shl:14 row_mask:0xf bank_mask:0xf
	v_fmac_f32_dpp v195, v113, v95 row_shl:14 row_mask:0xf bank_mask:0xf
	v_pk_mul_f32 v[196:197], v[188:189], v[216:217] op_sel_hi:[1,0]
	v_pk_mul_f32 v[198:199], v[190:191], v[216:217] op_sel_hi:[1,0]
	v_exp_f32_e32 v196, v196
	v_exp_f32_e32 v197, v197
	v_exp_f32_e32 v198, v198
	v_exp_f32_e32 v199, v199
	v_pk_add_f32 v[196:197], v[196:197], v[214:215] op_sel_hi:[1,0]
	v_pk_add_f32 v[198:199], v[198:199], v[214:215] op_sel_hi:[1,0]
	v_rcp_f32_e32 v196, v196
	v_rcp_f32_e32 v197, v197
	v_rcp_f32_e32 v198, v198
	v_rcp_f32_e32 v199, v199
	v_pk_mul_f32 v[188:189], v[188:189], v[196:197]
	v_pk_mul_f32 v[190:191], v[190:191], v[198:199]
	v_pk_mul_f32 v[188:189], v[188:189], v[192:193]
	v_pk_mul_f32 v[190:191], v[190:191], v[194:195]
	v_cvt_pk_bf16_f32 v122, v188, v189
	v_cvt_pk_bf16_f32 v123, v190, v191
	v_add_u32_e32 v213, 0x10800, v212
	global_load_dwordx4 v[110:113], v213, s[82:83] offset:16
	v_pk_fma_f32 v[188:189], v[72:73], v[84:85], v[88:89]
	v_pk_fma_f32 v[190:191], v[74:75], v[86:87], v[90:91]
	v_pk_fma_f32 v[192:193], v[64:65], v[100:101], v[104:105]
	v_pk_fma_f32 v[194:195], v[66:67], v[102:103], v[106:107]
	v_fmac_f32_dpp v188, v72, v80 row_shr:1 row_mask:0xf bank_mask:0xf
	v_fmac_f32_dpp v189, v73, v81 row_shr:1 row_mask:0xf bank_mask:0xf
	v_fmac_f32_dpp v190, v74, v82 row_shr:1 row_mask:0xf bank_mask:0xf
	v_fmac_f32_dpp v191, v75, v83 row_shr:1 row_mask:0xf bank_mask:0xf
	v_fmac_f32_dpp v192, v64, v96 row_shr:1 row_mask:0xf bank_mask:0xf
	v_fmac_f32_dpp v193, v65, v97 row_shr:1 row_mask:0xf bank_mask:0xf
	v_fmac_f32_dpp v194, v66, v98 row_shr:1 row_mask:0xf bank_mask:0xf
	v_fmac_f32_dpp v195, v67, v99 row_shr:1 row_mask:0xf bank_mask:0xf
	v_fmac_f32_dpp v188, v72, v76 row_shr:2 row_mask:0xf bank_mask:0xf
	v_fmac_f32_dpp v189, v73, v77 row_shr:2 row_mask:0xf bank_mask:0xf
	v_fmac_f32_dpp v190, v74, v78 row_shr:2 row_mask:0xf bank_mask:0xf
	v_fmac_f32_dpp v191, v75, v79 row_shr:2 row_mask:0xf bank_mask:0xf
	v_fmac_f32_dpp v192, v64, v92 row_shr:2 row_mask:0xf bank_mask:0xf
	v_fmac_f32_dpp v193, v65, v93 row_shr:2 row_mask:0xf bank_mask:0xf
	v_fmac_f32_dpp v194, v66, v94 row_shr:2 row_mask:0xf bank_mask:0xf
	v_fmac_f32_dpp v195, v67, v95 row_shr:2 row_mask:0xf bank_mask:0xf
	v_fmac_f32_dpp v188, v114, v80 row_shl:15 row_mask:0xf bank_mask:0xf
	v_fmac_f32_dpp v189, v115, v81 row_shl:15 row_mask:0xf bank_mask:0xf
	v_fmac_f32_dpp v190, v116, v82 row_shl:15 row_mask:0xf bank_mask:0xf
	v_fmac_f32_dpp v191, v117, v83 row_shl:15 row_mask:0xf bank_mask:0xf
	v_fmac_f32_dpp v192, v68, v96 row_shl:15 row_mask:0xf bank_mask:0xf
	v_fmac_f32_dpp v193, v69, v97 row_shl:15 row_mask:0xf bank_mask:0xf
	v_fmac_f32_dpp v194, v70, v98 row_shl:15 row_mask:0xf bank_mask:0xf
	v_fmac_f32_dpp v195, v71, v99 row_shl:15 row_mask:0xf bank_mask:0xf
	v_fmac_f32_dpp v188, v114, v76 row_shl:14 row_mask:0xf bank_mask:0xf
	v_fmac_f32_dpp v189, v115, v77 row_shl:14 row_mask:0xf bank_mask:0xf
	v_fmac_f32_dpp v190, v116, v78 row_shl:14 row_mask:0xf bank_mask:0xf
	v_fmac_f32_dpp v191, v117, v79 row_shl:14 row_mask:0xf bank_mask:0xf
	v_fmac_f32_dpp v192, v68, v92 row_shl:14 row_mask:0xf bank_mask:0xf
	v_fmac_f32_dpp v193, v69, v93 row_shl:14 row_mask:0xf bank_mask:0xf
	v_fmac_f32_dpp v194, v70, v94 row_shl:14 row_mask:0xf bank_mask:0xf
	v_fmac_f32_dpp v195, v71, v95 row_shl:14 row_mask:0xf bank_mask:0xf
	v_pk_mul_f32 v[196:197], v[188:189], v[216:217] op_sel_hi:[1,0]
	v_pk_mul_f32 v[198:199], v[190:191], v[216:217] op_sel_hi:[1,0]
	v_exp_f32_e32 v196, v196
	v_exp_f32_e32 v197, v197
	v_exp_f32_e32 v198, v198
	v_exp_f32_e32 v199, v199
	v_pk_add_f32 v[196:197], v[196:197], v[214:215] op_sel_hi:[1,0]
	v_pk_add_f32 v[198:199], v[198:199], v[214:215] op_sel_hi:[1,0]
	v_rcp_f32_e32 v196, v196
	v_rcp_f32_e32 v197, v197
	v_rcp_f32_e32 v198, v198
	v_rcp_f32_e32 v199, v199
	v_pk_mul_f32 v[188:189], v[188:189], v[196:197]
	v_pk_mul_f32 v[190:191], v[190:191], v[198:199]
	v_pk_mul_f32 v[188:189], v[188:189], v[192:193]
	v_pk_mul_f32 v[190:191], v[190:191], v[194:195]
	v_cvt_pk_bf16_f32 v114, v188, v189
	v_cvt_pk_bf16_f32 v115, v190, v191
	s_waitcnt vmcnt(0)
	v_pk_fma_f32 v[188:189], v[60:61], v[134:135], v[130:131]
	v_pk_fma_f32 v[190:191], v[62:63], v[136:137], v[132:133]
	v_pk_fma_f32 v[192:193], v[56:57], v[204:205], v[208:209]
	v_pk_fma_f32 v[194:195], v[58:59], v[206:207], v[210:211]
	v_fmac_f32_dpp v188, v60, v142 row_shr:1 row_mask:0xf bank_mask:0xf
	v_fmac_f32_dpp v189, v61, v143 row_shr:1 row_mask:0xf bank_mask:0xf
	v_fmac_f32_dpp v190, v62, v144 row_shr:1 row_mask:0xf bank_mask:0xf
	v_fmac_f32_dpp v191, v63, v145 row_shr:1 row_mask:0xf bank_mask:0xf
	v_fmac_f32_dpp v192, v56, v110 row_shr:1 row_mask:0xf bank_mask:0xf
	v_fmac_f32_dpp v193, v57, v111 row_shr:1 row_mask:0xf bank_mask:0xf
	v_fmac_f32_dpp v194, v58, v112 row_shr:1 row_mask:0xf bank_mask:0xf
	v_fmac_f32_dpp v195, v59, v113 row_shr:1 row_mask:0xf bank_mask:0xf
	v_fmac_f32_dpp v188, v60, v154 row_shr:2 row_mask:0xf bank_mask:0xf
	v_fmac_f32_dpp v189, v61, v155 row_shr:2 row_mask:0xf bank_mask:0xf
	v_fmac_f32_dpp v190, v62, v156 row_shr:2 row_mask:0xf bank_mask:0xf
	v_fmac_f32_dpp v191, v63, v157 row_shr:2 row_mask:0xf bank_mask:0xf
	v_fmac_f32_dpp v192, v56, v118 row_shr:2 row_mask:0xf bank_mask:0xf
	v_fmac_f32_dpp v193, v57, v119 row_shr:2 row_mask:0xf bank_mask:0xf
	v_fmac_f32_dpp v194, v58, v120 row_shr:2 row_mask:0xf bank_mask:0xf
	v_fmac_f32_dpp v195, v59, v121 row_shr:2 row_mask:0xf bank_mask:0xf
	v_pk_mul_f32 v[196:197], v[188:189], v[216:217] op_sel_hi:[1,0]
	v_pk_mul_f32 v[198:199], v[190:191], v[216:217] op_sel_hi:[1,0]
	v_exp_f32_e32 v196, v196
	v_exp_f32_e32 v197, v197
	v_exp_f32_e32 v198, v198
	v_exp_f32_e32 v199, v199
	v_pk_add_f32 v[196:197], v[196:197], v[214:215] op_sel_hi:[1,0]
	v_pk_add_f32 v[198:199], v[198:199], v[214:215] op_sel_hi:[1,0]
	v_rcp_f32_e32 v196, v196
	v_rcp_f32_e32 v197, v197
	v_rcp_f32_e32 v198, v198
	v_rcp_f32_e32 v199, v199
	v_pk_mul_f32 v[188:189], v[188:189], v[196:197]
	v_pk_mul_f32 v[190:191], v[190:191], v[198:199]
	v_pk_mul_f32 v[188:189], v[188:189], v[192:193]
	v_pk_mul_f32 v[190:191], v[190:191], v[194:195]
	v_cvt_pk_bf16_f32 v202, v188, v189
	v_cvt_pk_bf16_f32 v203, v190, v191
	s_mov_b64 exec, vcc
	global_store_dwordx4 v215, v[200:203], s[96:97]
	s_mov_b64 exec, -1
	v_pk_fma_f32 v[188:189], v[52:53], v[134:135], v[130:131]
	v_pk_fma_f32 v[190:191], v[54:55], v[136:137], v[132:133]
	v_pk_fma_f32 v[192:193], v[44:45], v[204:205], v[208:209]
	v_pk_fma_f32 v[194:195], v[46:47], v[206:207], v[210:211]
	v_fmac_f32_dpp v188, v52, v142 row_shr:1 row_mask:0xf bank_mask:0xf
	v_fmac_f32_dpp v189, v53, v143 row_shr:1 row_mask:0xf bank_mask:0xf
	v_fmac_f32_dpp v190, v54, v144 row_shr:1 row_mask:0xf bank_mask:0xf
	v_fmac_f32_dpp v191, v55, v145 row_shr:1 row_mask:0xf bank_mask:0xf
	v_fmac_f32_dpp v192, v44, v110 row_shr:1 row_mask:0xf bank_mask:0xf
	v_fmac_f32_dpp v193, v45, v111 row_shr:1 row_mask:0xf bank_mask:0xf
	v_fmac_f32_dpp v194, v46, v112 row_shr:1 row_mask:0xf bank_mask:0xf
	v_fmac_f32_dpp v195, v47, v113 row_shr:1 row_mask:0xf bank_mask:0xf
	v_fmac_f32_dpp v188, v52, v154 row_shr:2 row_mask:0xf bank_mask:0xf
	v_fmac_f32_dpp v189, v53, v155 row_shr:2 row_mask:0xf bank_mask:0xf
	v_fmac_f32_dpp v190, v54, v156 row_shr:2 row_mask:0xf bank_mask:0xf
	v_fmac_f32_dpp v191, v55, v157 row_shr:2 row_mask:0xf bank_mask:0xf
	v_fmac_f32_dpp v192, v44, v118 row_shr:2 row_mask:0xf bank_mask:0xf
	v_fmac_f32_dpp v193, v45, v119 row_shr:2 row_mask:0xf bank_mask:0xf
	v_fmac_f32_dpp v194, v46, v120 row_shr:2 row_mask:0xf bank_mask:0xf
	v_fmac_f32_dpp v195, v47, v121 row_shr:2 row_mask:0xf bank_mask:0xf
	v_fmac_f32_dpp v188, v60, v142 row_shl:15 row_mask:0xf bank_mask:0xf
	v_fmac_f32_dpp v189, v61, v143 row_shl:15 row_mask:0xf bank_mask:0xf
	v_fmac_f32_dpp v190, v62, v144 row_shl:15 row_mask:0xf bank_mask:0xf
	v_fmac_f32_dpp v191, v63, v145 row_shl:15 row_mask:0xf bank_mask:0xf
	v_fmac_f32_dpp v192, v56, v110 row_shl:15 row_mask:0xf bank_mask:0xf
	v_fmac_f32_dpp v193, v57, v111 row_shl:15 row_mask:0xf bank_mask:0xf
	v_fmac_f32_dpp v194, v58, v112 row_shl:15 row_mask:0xf bank_mask:0xf
	v_fmac_f32_dpp v195, v59, v113 row_shl:15 row_mask:0xf bank_mask:0xf
	v_fmac_f32_dpp v188, v60, v154 row_shl:14 row_mask:0xf bank_mask:0xf
	v_fmac_f32_dpp v189, v61, v155 row_shl:14 row_mask:0xf bank_mask:0xf
	v_fmac_f32_dpp v190, v62, v156 row_shl:14 row_mask:0xf bank_mask:0xf
	v_fmac_f32_dpp v191, v63, v157 row_shl:14 row_mask:0xf bank_mask:0xf
	v_fmac_f32_dpp v192, v56, v118 row_shl:14 row_mask:0xf bank_mask:0xf
	v_fmac_f32_dpp v193, v57, v119 row_shl:14 row_mask:0xf bank_mask:0xf
	v_fmac_f32_dpp v194, v58, v120 row_shl:14 row_mask:0xf bank_mask:0xf
	v_fmac_f32_dpp v195, v59, v121 row_shl:14 row_mask:0xf bank_mask:0xf
	v_pk_mul_f32 v[196:197], v[188:189], v[216:217] op_sel_hi:[1,0]
	v_pk_mul_f32 v[198:199], v[190:191], v[216:217] op_sel_hi:[1,0]
	v_exp_f32_e32 v196, v196
	v_exp_f32_e32 v197, v197
	v_exp_f32_e32 v198, v198
	v_exp_f32_e32 v199, v199
	v_pk_add_f32 v[196:197], v[196:197], v[214:215] op_sel_hi:[1,0]
	v_pk_add_f32 v[198:199], v[198:199], v[214:215] op_sel_hi:[1,0]
	v_rcp_f32_e32 v196, v196
	v_rcp_f32_e32 v197, v197
	v_rcp_f32_e32 v198, v198
	v_rcp_f32_e32 v199, v199
	v_pk_mul_f32 v[188:189], v[188:189], v[196:197]
	v_pk_mul_f32 v[190:191], v[190:191], v[198:199]
	v_pk_mul_f32 v[188:189], v[188:189], v[192:193]
	v_pk_mul_f32 v[190:191], v[190:191], v[194:195]
	v_cvt_pk_bf16_f32 v160, v188, v189
	v_cvt_pk_bf16_f32 v161, v190, v191
	v_add_u32_e32 v213, 0x2c000, v215
	global_store_dwordx4 v213, v[158:161], s[96:97]
	v_pk_fma_f32 v[188:189], v[48:49], v[134:135], v[130:131]
	v_pk_fma_f32 v[190:191], v[50:51], v[136:137], v[132:133]
	v_pk_fma_f32 v[192:193], v[36:37], v[204:205], v[208:209]
	v_pk_fma_f32 v[194:195], v[38:39], v[206:207], v[210:211]
	v_fmac_f32_dpp v188, v48, v142 row_shr:1 row_mask:0xf bank_mask:0xf
	v_fmac_f32_dpp v189, v49, v143 row_shr:1 row_mask:0xf bank_mask:0xf
	v_fmac_f32_dpp v190, v50, v144 row_shr:1 row_mask:0xf bank_mask:0xf
	v_fmac_f32_dpp v191, v51, v145 row_shr:1 row_mask:0xf bank_mask:0xf
	v_fmac_f32_dpp v192, v36, v110 row_shr:1 row_mask:0xf bank_mask:0xf
	v_fmac_f32_dpp v193, v37, v111 row_shr:1 row_mask:0xf bank_mask:0xf
	v_fmac_f32_dpp v194, v38, v112 row_shr:1 row_mask:0xf bank_mask:0xf
	v_fmac_f32_dpp v195, v39, v113 row_shr:1 row_mask:0xf bank_mask:0xf
	v_fmac_f32_dpp v188, v48, v154 row_shr:2 row_mask:0xf bank_mask:0xf
	v_fmac_f32_dpp v189, v49, v155 row_shr:2 row_mask:0xf bank_mask:0xf
	v_fmac_f32_dpp v190, v50, v156 row_shr:2 row_mask:0xf bank_mask:0xf
	v_fmac_f32_dpp v191, v51, v157 row_shr:2 row_mask:0xf bank_mask:0xf
	v_fmac_f32_dpp v192, v36, v118 row_shr:2 row_mask:0xf bank_mask:0xf
	v_fmac_f32_dpp v193, v37, v119 row_shr:2 row_mask:0xf bank_mask:0xf
	v_fmac_f32_dpp v194, v38, v120 row_shr:2 row_mask:0xf bank_mask:0xf
	v_fmac_f32_dpp v195, v39, v121 row_shr:2 row_mask:0xf bank_mask:0xf
	v_fmac_f32_dpp v188, v52, v142 row_shl:15 row_mask:0xf bank_mask:0xf
	v_fmac_f32_dpp v189, v53, v143 row_shl:15 row_mask:0xf bank_mask:0xf
	v_fmac_f32_dpp v190, v54, v144 row_shl:15 row_mask:0xf bank_mask:0xf
	v_fmac_f32_dpp v191, v55, v145 row_shl:15 row_mask:0xf bank_mask:0xf
	v_fmac_f32_dpp v192, v44, v110 row_shl:15 row_mask:0xf bank_mask:0xf
	v_fmac_f32_dpp v193, v45, v111 row_shl:15 row_mask:0xf bank_mask:0xf
	v_fmac_f32_dpp v194, v46, v112 row_shl:15 row_mask:0xf bank_mask:0xf
	v_fmac_f32_dpp v195, v47, v113 row_shl:15 row_mask:0xf bank_mask:0xf
	v_fmac_f32_dpp v188, v52, v154 row_shl:14 row_mask:0xf bank_mask:0xf
	v_fmac_f32_dpp v189, v53, v155 row_shl:14 row_mask:0xf bank_mask:0xf
	v_fmac_f32_dpp v190, v54, v156 row_shl:14 row_mask:0xf bank_mask:0xf
	v_fmac_f32_dpp v191, v55, v157 row_shl:14 row_mask:0xf bank_mask:0xf
	v_fmac_f32_dpp v192, v44, v118 row_shl:14 row_mask:0xf bank_mask:0xf
	v_fmac_f32_dpp v193, v45, v119 row_shl:14 row_mask:0xf bank_mask:0xf
	v_fmac_f32_dpp v194, v46, v120 row_shl:14 row_mask:0xf bank_mask:0xf
	v_fmac_f32_dpp v195, v47, v121 row_shl:14 row_mask:0xf bank_mask:0xf
	v_pk_mul_f32 v[196:197], v[188:189], v[216:217] op_sel_hi:[1,0]
	v_pk_mul_f32 v[198:199], v[190:191], v[216:217] op_sel_hi:[1,0]
	v_exp_f32_e32 v196, v196
	v_exp_f32_e32 v197, v197
	v_exp_f32_e32 v198, v198
	v_exp_f32_e32 v199, v199
	v_pk_add_f32 v[196:197], v[196:197], v[214:215] op_sel_hi:[1,0]
	v_pk_add_f32 v[198:199], v[198:199], v[214:215] op_sel_hi:[1,0]
	v_rcp_f32_e32 v196, v196
	v_rcp_f32_e32 v197, v197
	v_rcp_f32_e32 v198, v198
	v_rcp_f32_e32 v199, v199
	v_pk_mul_f32 v[188:189], v[188:189], v[196:197]
	v_pk_mul_f32 v[190:191], v[190:191], v[198:199]
	v_pk_mul_f32 v[188:189], v[188:189], v[192:193]
	v_pk_mul_f32 v[190:191], v[190:191], v[194:195]
	v_cvt_pk_bf16_f32 v152, v188, v189
	v_cvt_pk_bf16_f32 v153, v190, v191
	v_add_u32_e32 v213, 0x58000, v215
	global_store_dwordx4 v213, v[150:153], s[96:97]
	v_pk_fma_f32 v[188:189], v[40:41], v[134:135], v[130:131]
	v_pk_fma_f32 v[190:191], v[42:43], v[136:137], v[132:133]
	v_pk_fma_f32 v[192:193], v[32:33], v[204:205], v[208:209]
	v_pk_fma_f32 v[194:195], v[34:35], v[206:207], v[210:211]
	v_fmac_f32_dpp v188, v40, v142 row_shr:1 row_mask:0xf bank_mask:0xf
	v_fmac_f32_dpp v189, v41, v143 row_shr:1 row_mask:0xf bank_mask:0xf
	v_fmac_f32_dpp v190, v42, v144 row_shr:1 row_mask:0xf bank_mask:0xf
	v_fmac_f32_dpp v191, v43, v145 row_shr:1 row_mask:0xf bank_mask:0xf
	v_fmac_f32_dpp v192, v32, v110 row_shr:1 row_mask:0xf bank_mask:0xf
	v_fmac_f32_dpp v193, v33, v111 row_shr:1 row_mask:0xf bank_mask:0xf
	v_fmac_f32_dpp v194, v34, v112 row_shr:1 row_mask:0xf bank_mask:0xf
	v_fmac_f32_dpp v195, v35, v113 row_shr:1 row_mask:0xf bank_mask:0xf
	v_fmac_f32_dpp v188, v40, v154 row_shr:2 row_mask:0xf bank_mask:0xf
	v_fmac_f32_dpp v189, v41, v155 row_shr:2 row_mask:0xf bank_mask:0xf
	v_fmac_f32_dpp v190, v42, v156 row_shr:2 row_mask:0xf bank_mask:0xf
	v_fmac_f32_dpp v191, v43, v157 row_shr:2 row_mask:0xf bank_mask:0xf
	v_fmac_f32_dpp v192, v32, v118 row_shr:2 row_mask:0xf bank_mask:0xf
	v_fmac_f32_dpp v193, v33, v119 row_shr:2 row_mask:0xf bank_mask:0xf
	v_fmac_f32_dpp v194, v34, v120 row_shr:2 row_mask:0xf bank_mask:0xf
	v_fmac_f32_dpp v195, v35, v121 row_shr:2 row_mask:0xf bank_mask:0xf
	v_fmac_f32_dpp v188, v48, v142 row_shl:15 row_mask:0xf bank_mask:0xf
	v_fmac_f32_dpp v189, v49, v143 row_shl:15 row_mask:0xf bank_mask:0xf
	v_fmac_f32_dpp v190, v50, v144 row_shl:15 row_mask:0xf bank_mask:0xf
	v_fmac_f32_dpp v191, v51, v145 row_shl:15 row_mask:0xf bank_mask:0xf
	v_fmac_f32_dpp v192, v36, v110 row_shl:15 row_mask:0xf bank_mask:0xf
	v_fmac_f32_dpp v193, v37, v111 row_shl:15 row_mask:0xf bank_mask:0xf
	v_fmac_f32_dpp v194, v38, v112 row_shl:15 row_mask:0xf bank_mask:0xf
	v_fmac_f32_dpp v195, v39, v113 row_shl:15 row_mask:0xf bank_mask:0xf
	v_fmac_f32_dpp v188, v48, v154 row_shl:14 row_mask:0xf bank_mask:0xf
	v_fmac_f32_dpp v189, v49, v155 row_shl:14 row_mask:0xf bank_mask:0xf
	v_fmac_f32_dpp v190, v50, v156 row_shl:14 row_mask:0xf bank_mask:0xf
	v_fmac_f32_dpp v191, v51, v157 row_shl:14 row_mask:0xf bank_mask:0xf
	v_fmac_f32_dpp v192, v36, v118 row_shl:14 row_mask:0xf bank_mask:0xf
	v_fmac_f32_dpp v193, v37, v119 row_shl:14 row_mask:0xf bank_mask:0xf
	v_fmac_f32_dpp v194, v38, v120 row_shl:14 row_mask:0xf bank_mask:0xf
	v_fmac_f32_dpp v195, v39, v121 row_shl:14 row_mask:0xf bank_mask:0xf
	v_pk_mul_f32 v[196:197], v[188:189], v[216:217] op_sel_hi:[1,0]
	v_pk_mul_f32 v[198:199], v[190:191], v[216:217] op_sel_hi:[1,0]
	v_exp_f32_e32 v196, v196
	v_exp_f32_e32 v197, v197
	v_exp_f32_e32 v198, v198
	v_exp_f32_e32 v199, v199
	v_pk_add_f32 v[196:197], v[196:197], v[214:215] op_sel_hi:[1,0]
	v_pk_add_f32 v[198:199], v[198:199], v[214:215] op_sel_hi:[1,0]
	v_rcp_f32_e32 v196, v196
	v_rcp_f32_e32 v197, v197
	v_rcp_f32_e32 v198, v198
	v_rcp_f32_e32 v199, v199
	v_pk_mul_f32 v[188:189], v[188:189], v[196:197]
	v_pk_mul_f32 v[190:191], v[190:191], v[198:199]
	v_pk_mul_f32 v[188:189], v[188:189], v[192:193]
	v_pk_mul_f32 v[190:191], v[190:191], v[194:195]
	v_cvt_pk_bf16_f32 v148, v188, v189
	v_cvt_pk_bf16_f32 v149, v190, v191
	v_add_u32_e32 v213, 0x84000, v215
	global_store_dwordx4 v213, v[146:149], s[96:97]
	v_pk_fma_f32 v[188:189], v[28:29], v[134:135], v[130:131]
	v_pk_fma_f32 v[190:191], v[30:31], v[136:137], v[132:133]
	v_pk_fma_f32 v[192:193], v[16:17], v[204:205], v[208:209]
	v_pk_fma_f32 v[194:195], v[18:19], v[206:207], v[210:211]
	v_fmac_f32_dpp v188, v28, v142 row_shr:1 row_mask:0xf bank_mask:0xf
	v_fmac_f32_dpp v189, v29, v143 row_shr:1 row_mask:0xf bank_mask:0xf
	v_fmac_f32_dpp v190, v30, v144 row_shr:1 row_mask:0xf bank_mask:0xf
	v_fmac_f32_dpp v191, v31, v145 row_shr:1 row_mask:0xf bank_mask:0xf
	v_fmac_f32_dpp v192, v16, v110 row_shr:1 row_mask:0xf bank_mask:0xf
	v_fmac_f32_dpp v193, v17, v111 row_shr:1 row_mask:0xf bank_mask:0xf
	v_fmac_f32_dpp v194, v18, v112 row_shr:1 row_mask:0xf bank_mask:0xf
	v_fmac_f32_dpp v195, v19, v113 row_shr:1 row_mask:0xf bank_mask:0xf
	v_fmac_f32_dpp v188, v28, v154 row_shr:2 row_mask:0xf bank_mask:0xf
	v_fmac_f32_dpp v189, v29, v155 row_shr:2 row_mask:0xf bank_mask:0xf
	v_fmac_f32_dpp v190, v30, v156 row_shr:2 row_mask:0xf bank_mask:0xf
	v_fmac_f32_dpp v191, v31, v157 row_shr:2 row_mask:0xf bank_mask:0xf
	v_fmac_f32_dpp v192, v16, v118 row_shr:2 row_mask:0xf bank_mask:0xf
	v_fmac_f32_dpp v193, v17, v119 row_shr:2 row_mask:0xf bank_mask:0xf
	v_fmac_f32_dpp v194, v18, v120 row_shr:2 row_mask:0xf bank_mask:0xf
	v_fmac_f32_dpp v195, v19, v121 row_shr:2 row_mask:0xf bank_mask:0xf
	v_fmac_f32_dpp v188, v40, v142 row_shl:15 row_mask:0xf bank_mask:0xf
	v_fmac_f32_dpp v189, v41, v143 row_shl:15 row_mask:0xf bank_mask:0xf
	v_fmac_f32_dpp v190, v42, v144 row_shl:15 row_mask:0xf bank_mask:0xf
	v_fmac_f32_dpp v191, v43, v145 row_shl:15 row_mask:0xf bank_mask:0xf
	v_fmac_f32_dpp v192, v32, v110 row_shl:15 row_mask:0xf bank_mask:0xf
	v_fmac_f32_dpp v193, v33, v111 row_shl:15 row_mask:0xf bank_mask:0xf
	v_fmac_f32_dpp v194, v34, v112 row_shl:15 row_mask:0xf bank_mask:0xf
	v_fmac_f32_dpp v195, v35, v113 row_shl:15 row_mask:0xf bank_mask:0xf
	v_fmac_f32_dpp v188, v40, v154 row_shl:14 row_mask:0xf bank_mask:0xf
	v_fmac_f32_dpp v189, v41, v155 row_shl:14 row_mask:0xf bank_mask:0xf
	v_fmac_f32_dpp v190, v42, v156 row_shl:14 row_mask:0xf bank_mask:0xf
	v_fmac_f32_dpp v191, v43, v157 row_shl:14 row_mask:0xf bank_mask:0xf
	v_fmac_f32_dpp v192, v32, v118 row_shl:14 row_mask:0xf bank_mask:0xf
	v_fmac_f32_dpp v193, v33, v119 row_shl:14 row_mask:0xf bank_mask:0xf
	v_fmac_f32_dpp v194, v34, v120 row_shl:14 row_mask:0xf bank_mask:0xf
	v_fmac_f32_dpp v195, v35, v121 row_shl:14 row_mask:0xf bank_mask:0xf
	v_pk_mul_f32 v[196:197], v[188:189], v[216:217] op_sel_hi:[1,0]
	v_pk_mul_f32 v[198:199], v[190:191], v[216:217] op_sel_hi:[1,0]
	v_exp_f32_e32 v196, v196
	v_exp_f32_e32 v197, v197
	v_exp_f32_e32 v198, v198
	v_exp_f32_e32 v199, v199
	v_pk_add_f32 v[196:197], v[196:197], v[214:215] op_sel_hi:[1,0]
	v_pk_add_f32 v[198:199], v[198:199], v[214:215] op_sel_hi:[1,0]
	v_rcp_f32_e32 v196, v196
	v_rcp_f32_e32 v197, v197
	v_rcp_f32_e32 v198, v198
	v_rcp_f32_e32 v199, v199
	v_pk_mul_f32 v[188:189], v[188:189], v[196:197]
	v_pk_mul_f32 v[190:191], v[190:191], v[198:199]
	v_pk_mul_f32 v[188:189], v[188:189], v[192:193]
	v_pk_mul_f32 v[190:191], v[190:191], v[194:195]
	v_cvt_pk_bf16_f32 v140, v188, v189
	v_cvt_pk_bf16_f32 v141, v190, v191
	v_add_u32_e32 v213, 0xb0000, v215
	global_store_dwordx4 v213, v[138:141], s[96:97]
	v_pk_fma_f32 v[188:189], v[24:25], v[134:135], v[130:131]
	v_pk_fma_f32 v[190:191], v[26:27], v[136:137], v[132:133]
	v_pk_fma_f32 v[192:193], v[12:13], v[204:205], v[208:209]
	v_pk_fma_f32 v[194:195], v[14:15], v[206:207], v[210:211]
	v_fmac_f32_dpp v188, v24, v142 row_shr:1 row_mask:0xf bank_mask:0xf
	v_fmac_f32_dpp v189, v25, v143 row_shr:1 row_mask:0xf bank_mask:0xf
	v_fmac_f32_dpp v190, v26, v144 row_shr:1 row_mask:0xf bank_mask:0xf
	v_fmac_f32_dpp v191, v27, v145 row_shr:1 row_mask:0xf bank_mask:0xf
	v_fmac_f32_dpp v192, v12, v110 row_shr:1 row_mask:0xf bank_mask:0xf
	v_fmac_f32_dpp v193, v13, v111 row_shr:1 row_mask:0xf bank_mask:0xf
	v_fmac_f32_dpp v194, v14, v112 row_shr:1 row_mask:0xf bank_mask:0xf
	v_fmac_f32_dpp v195, v15, v113 row_shr:1 row_mask:0xf bank_mask:0xf
	v_fmac_f32_dpp v188, v24, v154 row_shr:2 row_mask:0xf bank_mask:0xf
	v_fmac_f32_dpp v189, v25, v155 row_shr:2 row_mask:0xf bank_mask:0xf
	v_fmac_f32_dpp v190, v26, v156 row_shr:2 row_mask:0xf bank_mask:0xf
	v_fmac_f32_dpp v191, v27, v157 row_shr:2 row_mask:0xf bank_mask:0xf
	v_fmac_f32_dpp v192, v12, v118 row_shr:2 row_mask:0xf bank_mask:0xf
	v_fmac_f32_dpp v193, v13, v119 row_shr:2 row_mask:0xf bank_mask:0xf
	v_fmac_f32_dpp v194, v14, v120 row_shr:2 row_mask:0xf bank_mask:0xf
	v_fmac_f32_dpp v195, v15, v121 row_shr:2 row_mask:0xf bank_mask:0xf
	v_fmac_f32_dpp v188, v28, v142 row_shl:15 row_mask:0xf bank_mask:0xf
	v_fmac_f32_dpp v189, v29, v143 row_shl:15 row_mask:0xf bank_mask:0xf
	v_fmac_f32_dpp v190, v30, v144 row_shl:15 row_mask:0xf bank_mask:0xf
	v_fmac_f32_dpp v191, v31, v145 row_shl:15 row_mask:0xf bank_mask:0xf
	v_fmac_f32_dpp v192, v16, v110 row_shl:15 row_mask:0xf bank_mask:0xf
	v_fmac_f32_dpp v193, v17, v111 row_shl:15 row_mask:0xf bank_mask:0xf
	v_fmac_f32_dpp v194, v18, v112 row_shl:15 row_mask:0xf bank_mask:0xf
	v_fmac_f32_dpp v195, v19, v113 row_shl:15 row_mask:0xf bank_mask:0xf
	v_fmac_f32_dpp v188, v28, v154 row_shl:14 row_mask:0xf bank_mask:0xf
	v_fmac_f32_dpp v189, v29, v155 row_shl:14 row_mask:0xf bank_mask:0xf
	v_fmac_f32_dpp v190, v30, v156 row_shl:14 row_mask:0xf bank_mask:0xf
	v_fmac_f32_dpp v191, v31, v157 row_shl:14 row_mask:0xf bank_mask:0xf
	v_fmac_f32_dpp v192, v16, v118 row_shl:14 row_mask:0xf bank_mask:0xf
	v_fmac_f32_dpp v193, v17, v119 row_shl:14 row_mask:0xf bank_mask:0xf
	v_fmac_f32_dpp v194, v18, v120 row_shl:14 row_mask:0xf bank_mask:0xf
	v_fmac_f32_dpp v195, v19, v121 row_shl:14 row_mask:0xf bank_mask:0xf
	v_pk_mul_f32 v[196:197], v[188:189], v[216:217] op_sel_hi:[1,0]
	v_pk_mul_f32 v[198:199], v[190:191], v[216:217] op_sel_hi:[1,0]
	v_exp_f32_e32 v196, v196
	v_exp_f32_e32 v197, v197
	v_exp_f32_e32 v198, v198
	v_exp_f32_e32 v199, v199
	v_pk_add_f32 v[196:197], v[196:197], v[214:215] op_sel_hi:[1,0]
	v_pk_add_f32 v[198:199], v[198:199], v[214:215] op_sel_hi:[1,0]
	v_rcp_f32_e32 v196, v196
	v_rcp_f32_e32 v197, v197
	v_rcp_f32_e32 v198, v198
	v_rcp_f32_e32 v199, v199
	v_pk_mul_f32 v[188:189], v[188:189], v[196:197]
	v_pk_mul_f32 v[190:191], v[190:191], v[198:199]
	v_pk_mul_f32 v[188:189], v[188:189], v[192:193]
	v_pk_mul_f32 v[190:191], v[190:191], v[194:195]
	v_cvt_pk_bf16_f32 v128, v188, v189
	v_cvt_pk_bf16_f32 v129, v190, v191
	v_add_u32_e32 v213, 0xdc000, v215
	global_store_dwordx4 v213, v[126:129], s[96:97]
	v_pk_fma_f32 v[188:189], v[20:21], v[134:135], v[130:131]
	v_pk_fma_f32 v[190:191], v[22:23], v[136:137], v[132:133]
	v_pk_fma_f32 v[192:193], v[8:9], v[204:205], v[208:209]
	v_pk_fma_f32 v[194:195], v[10:11], v[206:207], v[210:211]
	v_fmac_f32_dpp v188, v20, v142 row_shr:1 row_mask:0xf bank_mask:0xf
	v_fmac_f32_dpp v189, v21, v143 row_shr:1 row_mask:0xf bank_mask:0xf
	v_fmac_f32_dpp v190, v22, v144 row_shr:1 row_mask:0xf bank_mask:0xf
	v_fmac_f32_dpp v191, v23, v145 row_shr:1 row_mask:0xf bank_mask:0xf
	v_fmac_f32_dpp v192, v8, v110 row_shr:1 row_mask:0xf bank_mask:0xf
	v_fmac_f32_dpp v193, v9, v111 row_shr:1 row_mask:0xf bank_mask:0xf
	v_fmac_f32_dpp v194, v10, v112 row_shr:1 row_mask:0xf bank_mask:0xf
	v_fmac_f32_dpp v195, v11, v113 row_shr:1 row_mask:0xf bank_mask:0xf
	v_fmac_f32_dpp v188, v20, v154 row_shr:2 row_mask:0xf bank_mask:0xf
	v_fmac_f32_dpp v189, v21, v155 row_shr:2 row_mask:0xf bank_mask:0xf
	v_fmac_f32_dpp v190, v22, v156 row_shr:2 row_mask:0xf bank_mask:0xf
	v_fmac_f32_dpp v191, v23, v157 row_shr:2 row_mask:0xf bank_mask:0xf
	v_fmac_f32_dpp v192, v8, v118 row_shr:2 row_mask:0xf bank_mask:0xf
	v_fmac_f32_dpp v193, v9, v119 row_shr:2 row_mask:0xf bank_mask:0xf
	v_fmac_f32_dpp v194, v10, v120 row_shr:2 row_mask:0xf bank_mask:0xf
	v_fmac_f32_dpp v195, v11, v121 row_shr:2 row_mask:0xf bank_mask:0xf
	v_fmac_f32_dpp v188, v24, v142 row_shl:15 row_mask:0xf bank_mask:0xf
	v_fmac_f32_dpp v189, v25, v143 row_shl:15 row_mask:0xf bank_mask:0xf
	v_fmac_f32_dpp v190, v26, v144 row_shl:15 row_mask:0xf bank_mask:0xf
	v_fmac_f32_dpp v191, v27, v145 row_shl:15 row_mask:0xf bank_mask:0xf
	v_fmac_f32_dpp v192, v12, v110 row_shl:15 row_mask:0xf bank_mask:0xf
	v_fmac_f32_dpp v193, v13, v111 row_shl:15 row_mask:0xf bank_mask:0xf
	v_fmac_f32_dpp v194, v14, v112 row_shl:15 row_mask:0xf bank_mask:0xf
	v_fmac_f32_dpp v195, v15, v113 row_shl:15 row_mask:0xf bank_mask:0xf
	v_fmac_f32_dpp v188, v24, v154 row_shl:14 row_mask:0xf bank_mask:0xf
	v_fmac_f32_dpp v189, v25, v155 row_shl:14 row_mask:0xf bank_mask:0xf
	v_fmac_f32_dpp v190, v26, v156 row_shl:14 row_mask:0xf bank_mask:0xf
	v_fmac_f32_dpp v191, v27, v157 row_shl:14 row_mask:0xf bank_mask:0xf
	v_fmac_f32_dpp v192, v12, v118 row_shl:14 row_mask:0xf bank_mask:0xf
	v_fmac_f32_dpp v193, v13, v119 row_shl:14 row_mask:0xf bank_mask:0xf
	v_fmac_f32_dpp v194, v14, v120 row_shl:14 row_mask:0xf bank_mask:0xf
	v_fmac_f32_dpp v195, v15, v121 row_shl:14 row_mask:0xf bank_mask:0xf
	v_pk_mul_f32 v[196:197], v[188:189], v[216:217] op_sel_hi:[1,0]
	v_pk_mul_f32 v[198:199], v[190:191], v[216:217] op_sel_hi:[1,0]
	v_exp_f32_e32 v196, v196
	v_exp_f32_e32 v197, v197
	v_exp_f32_e32 v198, v198
	v_exp_f32_e32 v199, v199
	v_pk_add_f32 v[196:197], v[196:197], v[214:215] op_sel_hi:[1,0]
	v_pk_add_f32 v[198:199], v[198:199], v[214:215] op_sel_hi:[1,0]
	v_rcp_f32_e32 v196, v196
	v_rcp_f32_e32 v197, v197
	v_rcp_f32_e32 v198, v198
	v_rcp_f32_e32 v199, v199
	v_pk_mul_f32 v[188:189], v[188:189], v[196:197]
	v_pk_mul_f32 v[190:191], v[190:191], v[198:199]
	v_pk_mul_f32 v[188:189], v[188:189], v[192:193]
	v_pk_mul_f32 v[190:191], v[190:191], v[194:195]
	v_cvt_pk_bf16_f32 v124, v188, v189
	v_cvt_pk_bf16_f32 v125, v190, v191
	v_add_u32_e32 v213, 0x108000, v215
	global_store_dwordx4 v213, v[122:125], s[96:97]
	v_pk_fma_f32 v[188:189], v[4:5], v[134:135], v[130:131]
	v_pk_fma_f32 v[190:191], v[6:7], v[136:137], v[132:133]
	v_pk_fma_f32 v[192:193], v[0:1], v[204:205], v[208:209]
	v_pk_fma_f32 v[194:195], v[2:3], v[206:207], v[210:211]
	v_fmac_f32_dpp v188, v4, v142 row_shr:1 row_mask:0xf bank_mask:0xf
	v_fmac_f32_dpp v189, v5, v143 row_shr:1 row_mask:0xf bank_mask:0xf
	v_fmac_f32_dpp v190, v6, v144 row_shr:1 row_mask:0xf bank_mask:0xf
	v_fmac_f32_dpp v191, v7, v145 row_shr:1 row_mask:0xf bank_mask:0xf
	v_fmac_f32_dpp v192, v0, v110 row_shr:1 row_mask:0xf bank_mask:0xf
	v_fmac_f32_dpp v193, v1, v111 row_shr:1 row_mask:0xf bank_mask:0xf
	v_fmac_f32_dpp v194, v2, v112 row_shr:1 row_mask:0xf bank_mask:0xf
	v_fmac_f32_dpp v195, v3, v113 row_shr:1 row_mask:0xf bank_mask:0xf
	v_fmac_f32_dpp v188, v4, v154 row_shr:2 row_mask:0xf bank_mask:0xf
	v_fmac_f32_dpp v189, v5, v155 row_shr:2 row_mask:0xf bank_mask:0xf
	v_fmac_f32_dpp v190, v6, v156 row_shr:2 row_mask:0xf bank_mask:0xf
	v_fmac_f32_dpp v191, v7, v157 row_shr:2 row_mask:0xf bank_mask:0xf
	v_fmac_f32_dpp v192, v0, v118 row_shr:2 row_mask:0xf bank_mask:0xf
	v_fmac_f32_dpp v193, v1, v119 row_shr:2 row_mask:0xf bank_mask:0xf
	v_fmac_f32_dpp v194, v2, v120 row_shr:2 row_mask:0xf bank_mask:0xf
	v_fmac_f32_dpp v195, v3, v121 row_shr:2 row_mask:0xf bank_mask:0xf
	v_fmac_f32_dpp v188, v20, v142 row_shl:15 row_mask:0xf bank_mask:0xf
	v_fmac_f32_dpp v189, v21, v143 row_shl:15 row_mask:0xf bank_mask:0xf
	v_fmac_f32_dpp v190, v22, v144 row_shl:15 row_mask:0xf bank_mask:0xf
	v_fmac_f32_dpp v191, v23, v145 row_shl:15 row_mask:0xf bank_mask:0xf
	v_fmac_f32_dpp v192, v8, v110 row_shl:15 row_mask:0xf bank_mask:0xf
	v_fmac_f32_dpp v193, v9, v111 row_shl:15 row_mask:0xf bank_mask:0xf
	v_fmac_f32_dpp v194, v10, v112 row_shl:15 row_mask:0xf bank_mask:0xf
	v_fmac_f32_dpp v195, v11, v113 row_shl:15 row_mask:0xf bank_mask:0xf
	v_fmac_f32_dpp v188, v20, v154 row_shl:14 row_mask:0xf bank_mask:0xf
	v_fmac_f32_dpp v189, v21, v155 row_shl:14 row_mask:0xf bank_mask:0xf
	v_fmac_f32_dpp v190, v22, v156 row_shl:14 row_mask:0xf bank_mask:0xf
	v_fmac_f32_dpp v191, v23, v157 row_shl:14 row_mask:0xf bank_mask:0xf
	v_fmac_f32_dpp v192, v8, v118 row_shl:14 row_mask:0xf bank_mask:0xf
	v_fmac_f32_dpp v193, v9, v119 row_shl:14 row_mask:0xf bank_mask:0xf
	v_fmac_f32_dpp v194, v10, v120 row_shl:14 row_mask:0xf bank_mask:0xf
	v_fmac_f32_dpp v195, v11, v121 row_shl:14 row_mask:0xf bank_mask:0xf
	v_pk_mul_f32 v[196:197], v[188:189], v[216:217] op_sel_hi:[1,0]
	v_pk_mul_f32 v[198:199], v[190:191], v[216:217] op_sel_hi:[1,0]
	v_exp_f32_e32 v196, v196
	v_exp_f32_e32 v197, v197
	v_exp_f32_e32 v198, v198
	v_exp_f32_e32 v199, v199
	v_pk_add_f32 v[196:197], v[196:197], v[214:215] op_sel_hi:[1,0]
	v_pk_add_f32 v[198:199], v[198:199], v[214:215] op_sel_hi:[1,0]
	v_rcp_f32_e32 v196, v196
	v_rcp_f32_e32 v197, v197
	v_rcp_f32_e32 v198, v198
	v_rcp_f32_e32 v199, v199
	v_pk_mul_f32 v[188:189], v[188:189], v[196:197]
	v_pk_mul_f32 v[190:191], v[190:191], v[198:199]
	v_pk_mul_f32 v[188:189], v[188:189], v[192:193]
	v_pk_mul_f32 v[190:191], v[190:191], v[194:195]
	v_cvt_pk_bf16_f32 v116, v188, v189
	v_cvt_pk_bf16_f32 v117, v190, v191
	v_add_u32_e32 v213, 0x134000, v215
	global_store_dwordx4 v213, v[114:117], s[96:97]
	s_branch .LBB0_359

.LBB0_508:
	ds_read_b128 v[136:139], v141
	ds_read_b128 v[146:149], v216
	ds_read_b128 v[150:153], v141 offset:2048
	ds_read_b128 v[154:157], v216 offset:2048
	s_add_u32 s8, s0, 0xffea0080
	s_addc_u32 s9, s1, -1
	s_cmpk_eq_i32 s41, 0x54
	s_cselect_b32 s17, s13, s9
	s_cselect_b32 s16, s12, s8
	s_cselect_b32 s9, s11, s40
	s_cselect_b32 s8, s10, s39
	s_add_i32 m0, s21, 0xc000
	ds_read_b128 v[158:161], v142
	ds_read_b128 v[176:179], v217
	ds_read_b128 v[180:183], v142 offset:2048
	ds_read_b128 v[184:187], v217 offset:2048
	ds_read_b128 v[188:191], v142 offset:4096
	ds_read_b128 v[192:195], v217 offset:4096
	ds_read_b128 v[196:199], v142 offset:6144
	ds_read_b128 v[200:203], v217 offset:6144
	global_load_lds_dwordx4 v128, s[0:1]
	s_add_i32 m0, s21, 0xe000
	s_nop 0
	global_load_lds_dwordx4 v130, s[0:1]
	s_waitcnt lgkmcnt(8)
	s_barrier
	s_waitcnt lgkmcnt(0)
	s_waitcnt lgkmcnt(0)
	v_mfma_f32_16x16x32_bf16 v[124:127], v[136:139], v[158:161], v[124:127]
	v_mfma_f32_16x16x32_bf16 v[124:127], v[146:149], v[176:179], v[124:127]
	v_mfma_f32_16x16x32_bf16 v[120:123], v[154:157], v[176:179], v[120:123]
	v_mfma_f32_16x16x32_bf16 v[120:123], v[150:153], v[158:161], v[120:123]
	v_mfma_f32_16x16x32_bf16 v[104:107], v[150:153], v[180:183], v[104:107]
	v_mfma_f32_16x16x32_bf16 v[104:107], v[154:157], v[184:187], v[104:107]
	v_mfma_f32_16x16x32_bf16 v[108:111], v[146:149], v[184:187], v[108:111]
	v_mfma_f32_16x16x32_bf16 v[108:111], v[136:139], v[180:183], v[108:111]
	v_mfma_f32_16x16x32_bf16 v[92:95], v[136:139], v[188:191], v[92:95]
	v_mfma_f32_16x16x32_bf16 v[92:95], v[146:149], v[192:195], v[92:95]
	v_mfma_f32_16x16x32_bf16 v[88:91], v[154:157], v[192:195], v[88:91]
	v_mfma_f32_16x16x32_bf16 v[88:91], v[150:153], v[188:191], v[88:91]
	v_mfma_f32_16x16x32_bf16 v[72:75], v[150:153], v[196:199], v[72:75]
	v_mfma_f32_16x16x32_bf16 v[72:75], v[154:157], v[200:203], v[72:75]
	v_mfma_f32_16x16x32_bf16 v[76:79], v[146:149], v[200:203], v[76:79]
	v_mfma_f32_16x16x32_bf16 v[76:79], v[136:139], v[196:199], v[76:79]
	s_barrier
	s_add_i32 s42, s33, s20
	s_add_u32 s98, s8, s4
	s_addc_u32 s99, s9, s5
	s_mov_b32 m0, s42
	ds_read_b128 v[204:207], v143
	ds_read_b128 v[208:211], v244
	ds_read_b128 v[212:215], v143 offset:2048
	ds_read_b128 v[240:243], v244 offset:2048
	global_load_lds_dwordx4 v170, s[8:9]
	s_add_i32 m0, s42, 0x2000
	s_nop 0
	global_load_lds_dwordx4 v174, s[8:9]
	s_barrier
	s_waitcnt lgkmcnt(0)
	s_waitcnt lgkmcnt(0)
	v_mfma_f32_16x16x32_bf16 v[116:119], v[204:207], v[158:161], v[116:119]
	v_mfma_f32_16x16x32_bf16 v[116:119], v[208:211], v[176:179], v[116:119]
	v_mfma_f32_16x16x32_bf16 v[112:115], v[240:243], v[176:179], v[112:115]
	v_mfma_f32_16x16x32_bf16 v[112:115], v[212:215], v[158:161], v[112:115]
	v_mfma_f32_16x16x32_bf16 v[96:99], v[212:215], v[180:183], v[96:99]
	v_mfma_f32_16x16x32_bf16 v[96:99], v[240:243], v[184:187], v[96:99]
	v_mfma_f32_16x16x32_bf16 v[100:103], v[208:211], v[184:187], v[100:103]
	v_mfma_f32_16x16x32_bf16 v[100:103], v[204:207], v[180:183], v[100:103]
	v_mfma_f32_16x16x32_bf16 v[84:87], v[204:207], v[188:191], v[84:87]
	v_mfma_f32_16x16x32_bf16 v[84:87], v[208:211], v[192:195], v[84:87]
	v_mfma_f32_16x16x32_bf16 v[80:83], v[240:243], v[192:195], v[80:83]
	v_mfma_f32_16x16x32_bf16 v[80:83], v[212:215], v[188:191], v[80:83]
	v_mfma_f32_16x16x32_bf16 v[64:67], v[212:215], v[196:199], v[64:67]
	v_mfma_f32_16x16x32_bf16 v[64:67], v[240:243], v[200:203], v[64:67]
	v_mfma_f32_16x16x32_bf16 v[68:71], v[208:211], v[200:203], v[68:71]
	v_mfma_f32_16x16x32_bf16 v[68:71], v[204:207], v[196:199], v[68:71]
	s_mov_b32 m0, s21
	s_add_u32 s100, s16, s4
	s_addc_u32 s101, s17, s5
	s_barrier
	ds_read_b128 v[158:161], v142 offset:16384
	ds_read_b128 v[176:179], v217 offset:16384
	ds_read_b128 v[180:183], v142 offset:18432
	ds_read_b128 v[184:187], v217 offset:18432
	ds_read_b128 v[188:191], v142 offset:20480
	ds_read_b128 v[192:195], v217 offset:20480
	ds_read_b128 v[196:199], v142 offset:22528
	ds_read_b128 v[200:203], v217 offset:22528
	global_load_lds_dwordx4 v168, s[16:17]
	s_mov_b32 m0, s22
	s_nop 0
	global_load_lds_dwordx4 v172, s[16:17]
	s_barrier
	s_waitcnt lgkmcnt(0)
	s_waitcnt lgkmcnt(0)
	v_mfma_f32_16x16x32_bf16 v[60:63], v[136:139], v[158:161], v[60:63]
	v_mfma_f32_16x16x32_bf16 v[60:63], v[146:149], v[176:179], v[60:63]
	v_mfma_f32_16x16x32_bf16 v[56:59], v[154:157], v[176:179], v[56:59]
	v_mfma_f32_16x16x32_bf16 v[56:59], v[150:153], v[158:161], v[56:59]
	v_mfma_f32_16x16x32_bf16 v[40:43], v[150:153], v[180:183], v[40:43]
	v_mfma_f32_16x16x32_bf16 v[40:43], v[154:157], v[184:187], v[40:43]
	v_mfma_f32_16x16x32_bf16 v[44:47], v[146:149], v[184:187], v[44:47]
	v_mfma_f32_16x16x32_bf16 v[44:47], v[136:139], v[180:183], v[44:47]
	v_mfma_f32_16x16x32_bf16 v[28:31], v[136:139], v[188:191], v[28:31]
	v_mfma_f32_16x16x32_bf16 v[28:31], v[146:149], v[192:195], v[28:31]
	v_mfma_f32_16x16x32_bf16 v[24:27], v[154:157], v[192:195], v[24:27]
	v_mfma_f32_16x16x32_bf16 v[24:27], v[150:153], v[188:191], v[24:27]
	v_mfma_f32_16x16x32_bf16 v[8:11], v[150:153], v[196:199], v[8:11]
	v_mfma_f32_16x16x32_bf16 v[8:11], v[154:157], v[200:203], v[8:11]
	v_mfma_f32_16x16x32_bf16 v[12:15], v[146:149], v[200:203], v[12:15]
	v_mfma_f32_16x16x32_bf16 v[12:15], v[136:139], v[196:199], v[12:15]
	s_barrier
	s_add_u32 s42, s8, 0x160000
	s_addc_u32 s43, s9, 0
	s_add_i32 s44, s34, s20
	s_mov_b32 m0, s44
	s_nop 0
	global_load_lds_dwordx4 v170, s[42:43]
	s_add_i32 m0, s44, 0x2000
	s_nop 0
	global_load_lds_dwordx4 v174, s[42:43]
	s_waitcnt vmcnt(6)
	s_barrier
	v_mfma_f32_16x16x32_bf16 v[52:55], v[204:207], v[158:161], v[52:55]
	v_mfma_f32_16x16x32_bf16 v[52:55], v[208:211], v[176:179], v[52:55]
	v_mfma_f32_16x16x32_bf16 v[48:51], v[240:243], v[176:179], v[48:51]
	v_mfma_f32_16x16x32_bf16 v[48:51], v[212:215], v[158:161], v[48:51]
	v_mfma_f32_16x16x32_bf16 v[32:35], v[212:215], v[180:183], v[32:35]
	v_mfma_f32_16x16x32_bf16 v[32:35], v[240:243], v[184:187], v[32:35]
	v_mfma_f32_16x16x32_bf16 v[36:39], v[208:211], v[184:187], v[36:39]
	v_mfma_f32_16x16x32_bf16 v[36:39], v[204:207], v[180:183], v[36:39]
	v_mfma_f32_16x16x32_bf16 v[20:23], v[204:207], v[188:191], v[20:23]
	v_mfma_f32_16x16x32_bf16 v[20:23], v[208:211], v[192:195], v[20:23]
	v_mfma_f32_16x16x32_bf16 v[16:19], v[240:243], v[192:195], v[16:19]
	v_mfma_f32_16x16x32_bf16 v[16:19], v[212:215], v[188:191], v[16:19]
	v_mfma_f32_16x16x32_bf16 v[0:3], v[212:215], v[196:199], v[0:3]
	v_mfma_f32_16x16x32_bf16 v[0:3], v[240:243], v[200:203], v[0:3]
	v_mfma_f32_16x16x32_bf16 v[4:7], v[208:211], v[200:203], v[4:7]
	v_mfma_f32_16x16x32_bf16 v[4:7], v[204:207], v[196:199], v[4:7]
	s_add_i32 s42, 0, 0x18000
	s_barrier
	ds_read_b128 v[136:139], v245
	ds_read_b128 v[146:149], v246
	ds_read_b128 v[150:153], v245 offset:2048
	ds_read_b128 v[154:157], v246 offset:2048
	s_add_u32 s16, s16, 0x160000
	s_addc_u32 s17, s17, 0
	s_mov_b32 m0, s23
	ds_read_b128 v[158:161], v142 offset:32768
	ds_read_b128 v[176:179], v217 offset:32768
	ds_read_b128 v[180:183], v142 offset:34816
	ds_read_b128 v[184:187], v217 offset:34816
	ds_read_b128 v[188:191], v142 offset:36864
	ds_read_b128 v[192:195], v217 offset:36864
	ds_read_b128 v[196:199], v142 offset:38912
	ds_read_b128 v[200:203], v217 offset:38912
	global_load_lds_dwordx4 v168, s[16:17]
	s_mov_b32 m0, s24
	s_nop 0
	global_load_lds_dwordx4 v172, s[16:17]
	s_waitcnt lgkmcnt(8)
	s_barrier
	s_waitcnt lgkmcnt(0)
	s_waitcnt lgkmcnt(0)
	v_mfma_f32_16x16x32_bf16 v[124:127], v[136:139], v[158:161], v[124:127]
	v_mfma_f32_16x16x32_bf16 v[124:127], v[146:149], v[176:179], v[124:127]
	v_mfma_f32_16x16x32_bf16 v[120:123], v[154:157], v[176:179], v[120:123]
	v_mfma_f32_16x16x32_bf16 v[120:123], v[150:153], v[158:161], v[120:123]
	v_mfma_f32_16x16x32_bf16 v[104:107], v[150:153], v[180:183], v[104:107]
	v_mfma_f32_16x16x32_bf16 v[104:107], v[154:157], v[184:187], v[104:107]
	v_mfma_f32_16x16x32_bf16 v[108:111], v[146:149], v[184:187], v[108:111]
	v_mfma_f32_16x16x32_bf16 v[108:111], v[136:139], v[180:183], v[108:111]
	v_mfma_f32_16x16x32_bf16 v[92:95], v[136:139], v[188:191], v[92:95]
	v_mfma_f32_16x16x32_bf16 v[92:95], v[146:149], v[192:195], v[92:95]
	v_mfma_f32_16x16x32_bf16 v[88:91], v[154:157], v[192:195], v[88:91]
	v_mfma_f32_16x16x32_bf16 v[88:91], v[150:153], v[188:191], v[88:91]
	v_mfma_f32_16x16x32_bf16 v[72:75], v[150:153], v[196:199], v[72:75]
	v_mfma_f32_16x16x32_bf16 v[72:75], v[154:157], v[200:203], v[72:75]
	v_mfma_f32_16x16x32_bf16 v[76:79], v[146:149], v[200:203], v[76:79]
	v_mfma_f32_16x16x32_bf16 v[76:79], v[136:139], v[196:199], v[76:79]
	s_barrier
	s_add_i32 s16, 0, 0x1c000
	s_add_i32 s17, s42, s20
	v_add_u32_e32 v145, s16, v140
	s_mov_b32 m0, s17
	ds_read_b128 v[204:207], v145
	v_xor_b32_e32 v243, 64, v145
	ds_read_b128 v[208:211], v243
	ds_read_b128 v[212:215], v145 offset:2048
	ds_read_b128 v[240:243], v243 offset:2048
	global_load_lds_dwordx4 v170, s[98:99]
	s_add_i32 m0, s17, 0x2000
	s_nop 0
	global_load_lds_dwordx4 v174, s[98:99]
	s_barrier
	s_waitcnt lgkmcnt(0)
	s_waitcnt lgkmcnt(0)
	v_mfma_f32_16x16x32_bf16 v[116:119], v[204:207], v[158:161], v[116:119]
	v_mfma_f32_16x16x32_bf16 v[116:119], v[208:211], v[176:179], v[116:119]
	v_mfma_f32_16x16x32_bf16 v[112:115], v[240:243], v[176:179], v[112:115]
	v_mfma_f32_16x16x32_bf16 v[112:115], v[212:215], v[158:161], v[112:115]
	v_mfma_f32_16x16x32_bf16 v[96:99], v[212:215], v[180:183], v[96:99]
	v_mfma_f32_16x16x32_bf16 v[96:99], v[240:243], v[184:187], v[96:99]
	v_mfma_f32_16x16x32_bf16 v[100:103], v[208:211], v[184:187], v[100:103]
	v_mfma_f32_16x16x32_bf16 v[100:103], v[204:207], v[180:183], v[100:103]
	v_mfma_f32_16x16x32_bf16 v[84:87], v[204:207], v[188:191], v[84:87]
	v_mfma_f32_16x16x32_bf16 v[84:87], v[208:211], v[192:195], v[84:87]
	v_mfma_f32_16x16x32_bf16 v[80:83], v[240:243], v[192:195], v[80:83]
	v_mfma_f32_16x16x32_bf16 v[80:83], v[212:215], v[188:191], v[80:83]
	v_mfma_f32_16x16x32_bf16 v[64:67], v[212:215], v[196:199], v[64:67]
	v_mfma_f32_16x16x32_bf16 v[64:67], v[240:243], v[200:203], v[64:67]
	v_mfma_f32_16x16x32_bf16 v[68:71], v[208:211], v[200:203], v[68:71]
	v_mfma_f32_16x16x32_bf16 v[68:71], v[204:207], v[196:199], v[68:71]
	s_mov_b32 m0, s28
	s_barrier
	ds_read_b128 v[158:161], v142 offset:49152
	ds_read_b128 v[176:179], v217 offset:49152
	ds_read_b128 v[180:183], v142 offset:51200
	ds_read_b128 v[184:187], v217 offset:51200
	ds_read_b128 v[188:191], v142 offset:53248
	ds_read_b128 v[192:195], v217 offset:53248
	ds_read_b128 v[196:199], v142 offset:55296
	ds_read_b128 v[200:203], v217 offset:55296
	global_load_lds_dwordx4 v168, s[100:101]
	s_mov_b32 m0, s29
	s_nop 0
	global_load_lds_dwordx4 v172, s[100:101]
	s_barrier
	s_waitcnt lgkmcnt(0)
	s_waitcnt lgkmcnt(0)
	v_mfma_f32_16x16x32_bf16 v[60:63], v[136:139], v[158:161], v[60:63]
	v_mfma_f32_16x16x32_bf16 v[60:63], v[146:149], v[176:179], v[60:63]
	v_mfma_f32_16x16x32_bf16 v[56:59], v[154:157], v[176:179], v[56:59]
	v_mfma_f32_16x16x32_bf16 v[56:59], v[150:153], v[158:161], v[56:59]
	v_mfma_f32_16x16x32_bf16 v[40:43], v[150:153], v[180:183], v[40:43]
	v_mfma_f32_16x16x32_bf16 v[40:43], v[154:157], v[184:187], v[40:43]
	v_mfma_f32_16x16x32_bf16 v[44:47], v[146:149], v[184:187], v[44:47]
	v_mfma_f32_16x16x32_bf16 v[44:47], v[136:139], v[180:183], v[44:47]
	v_mfma_f32_16x16x32_bf16 v[28:31], v[136:139], v[188:191], v[28:31]
	v_mfma_f32_16x16x32_bf16 v[28:31], v[146:149], v[192:195], v[28:31]
	v_mfma_f32_16x16x32_bf16 v[24:27], v[154:157], v[192:195], v[24:27]
	v_mfma_f32_16x16x32_bf16 v[24:27], v[150:153], v[188:191], v[24:27]
	v_mfma_f32_16x16x32_bf16 v[8:11], v[150:153], v[196:199], v[8:11]
	v_mfma_f32_16x16x32_bf16 v[8:11], v[154:157], v[200:203], v[8:11]
	v_mfma_f32_16x16x32_bf16 v[12:15], v[146:149], v[200:203], v[12:15]
	v_mfma_f32_16x16x32_bf16 v[12:15], v[136:139], v[196:199], v[12:15]
	s_barrier
	s_add_u32 s8, s8, 0x160080
	s_addc_u32 s9, s9, 0
	s_add_i32 s16, s16, s20
	s_mov_b32 m0, s16
	s_nop 0
	global_load_lds_dwordx4 v170, s[8:9]
	s_add_i32 m0, s16, 0x2000
	s_nop 0
	global_load_lds_dwordx4 v174, s[8:9]
	s_waitcnt vmcnt(6)
	s_barrier
	v_mfma_f32_16x16x32_bf16 v[52:55], v[204:207], v[158:161], v[52:55]
	v_mfma_f32_16x16x32_bf16 v[52:55], v[208:211], v[176:179], v[52:55]
	v_mfma_f32_16x16x32_bf16 v[48:51], v[240:243], v[176:179], v[48:51]
	v_mfma_f32_16x16x32_bf16 v[48:51], v[212:215], v[158:161], v[48:51]
	v_mfma_f32_16x16x32_bf16 v[32:35], v[212:215], v[180:183], v[32:35]
	v_mfma_f32_16x16x32_bf16 v[32:35], v[240:243], v[184:187], v[32:35]
	v_mfma_f32_16x16x32_bf16 v[36:39], v[208:211], v[184:187], v[36:39]
	v_mfma_f32_16x16x32_bf16 v[36:39], v[204:207], v[180:183], v[36:39]
	v_mfma_f32_16x16x32_bf16 v[20:23], v[204:207], v[188:191], v[20:23]
	v_mfma_f32_16x16x32_bf16 v[20:23], v[208:211], v[192:195], v[20:23]
	v_mfma_f32_16x16x32_bf16 v[16:19], v[240:243], v[192:195], v[16:19]
	v_mfma_f32_16x16x32_bf16 v[16:19], v[212:215], v[188:191], v[16:19]
	v_mfma_f32_16x16x32_bf16 v[0:3], v[212:215], v[196:199], v[0:3]
	v_mfma_f32_16x16x32_bf16 v[0:3], v[240:243], v[200:203], v[0:3]
	v_mfma_f32_16x16x32_bf16 v[4:7], v[208:211], v[200:203], v[4:7]
	v_mfma_f32_16x16x32_bf16 v[4:7], v[204:207], v[196:199], v[4:7]
	s_add_i32 s41, s41, 2
	s_add_u32 s0, s0, 0x100
	s_addc_u32 s1, s1, 0
	s_add_u32 s39, s39, 0x100
	s_addc_u32 s40, s40, 0
	s_cmpk_gt_u32 s41, 0x55
	s_barrier
	s_cbranch_scc0 .LBB0_508
	v_lshl_add_u32 v217, s38, 8, v163
	v_add_u32_e32 v217, s26, v217
	v_lshlrev_b32_e32 v208, 2, v217
	v_lshl_add_u32 v214, v225, 3, s27
	v_lshl_add_u32 v214, s37, 8, v214
	v_lshl_add_u32 v209, v217, 11, v214
	v_lshlrev_b32_e32 v209, 1, v209
	v_lshlrev_b32_e32 v210, 1, v209
	v_lshl_add_u32 v217, v225, 4, v163
	v_xor_b32_e32 v215, 16, v217
	v_lshlrev_b32_e32 v215, 2, v215
	v_xor_b32_e32 v216, 32, v217
	v_lshlrev_b32_e32 v216, 2, v216
	v_add_u32_e32 v211, 0x0, v209
	global_load_dwordx4 v[176:179], v211, s[80:81]
	global_load_dwordx4 v[180:183], v211, s[80:81] offset:256
	v_add_u32_e32 v211, 0x10000, v209
	global_load_dwordx4 v[192:195], v211, s[80:81]
	global_load_dwordx4 v[196:199], v211, s[80:81] offset:256
	s_waitcnt vmcnt(2)
	v_lshlrev_b32_e32 v184, 16, v176
	v_and_b32_e32 v185, 0xffff0000, v176
	v_lshlrev_b32_e32 v186, 16, v177
	v_and_b32_e32 v187, 0xffff0000, v177
	v_lshlrev_b32_e32 v188, 16, v178
	v_and_b32_e32 v189, 0xffff0000, v178
	v_lshlrev_b32_e32 v190, 16, v179
	v_and_b32_e32 v191, 0xffff0000, v179
	v_pk_add_f32 v[124:125], v[124:125], v[184:185]
	v_pk_add_f32 v[126:127], v[126:127], v[186:187]
	v_pk_add_f32 v[120:121], v[120:121], v[188:189]
	v_pk_add_f32 v[122:123], v[122:123], v[190:191]
	v_mul_f32_e32 v213, v124, v124
	v_fmac_f32_e32 v213, v125, v125
	v_fmac_f32_e32 v213, v126, v126
	v_fmac_f32_e32 v213, v127, v127
	v_fmac_f32_e32 v213, v120, v120
	v_fmac_f32_e32 v213, v121, v121
	v_fmac_f32_e32 v213, v122, v122
	v_fmac_f32_e32 v213, v123, v123
	v_cvt_pk_bf16_f32 v176, v124, v125
	v_cvt_pk_bf16_f32 v177, v126, v127
	v_cvt_pk_bf16_f32 v178, v120, v121
	v_cvt_pk_bf16_f32 v179, v122, v123
	v_add_u32_e32 v217, 0x0, v209
	global_store_dwordx4 v217, v[176:179], s[80:81]
	v_lshlrev_b32_e32 v184, 16, v180
	v_and_b32_e32 v185, 0xffff0000, v180
	v_lshlrev_b32_e32 v186, 16, v181
	v_and_b32_e32 v187, 0xffff0000, v181
	v_lshlrev_b32_e32 v188, 16, v182
	v_and_b32_e32 v189, 0xffff0000, v182
	v_lshlrev_b32_e32 v190, 16, v183
	v_and_b32_e32 v191, 0xffff0000, v183
	v_pk_add_f32 v[116:117], v[116:117], v[184:185]
	v_pk_add_f32 v[118:119], v[118:119], v[186:187]
	v_pk_add_f32 v[112:113], v[112:113], v[188:189]
	v_pk_add_f32 v[114:115], v[114:115], v[190:191]
	v_fmac_f32_e32 v213, v116, v116
	v_fmac_f32_e32 v213, v117, v117
	v_fmac_f32_e32 v213, v118, v118
	v_fmac_f32_e32 v213, v119, v119
	v_fmac_f32_e32 v213, v112, v112
	v_fmac_f32_e32 v213, v113, v113
	v_fmac_f32_e32 v213, v114, v114
	v_fmac_f32_e32 v213, v115, v115
	v_cvt_pk_bf16_f32 v180, v116, v117
	v_cvt_pk_bf16_f32 v181, v118, v119
	v_cvt_pk_bf16_f32 v182, v112, v113
	v_cvt_pk_bf16_f32 v183, v114, v115
	global_store_dwordx4 v217, v[180:183], s[80:81] offset:256
	ds_bpermute_b32 v214, v215, v213
	s_waitcnt lgkmcnt(0)
	v_add_f32_e32 v213, v213, v214
	ds_bpermute_b32 v214, v216, v213
	s_waitcnt lgkmcnt(0)
	v_add_f32_e32 v213, v213, v214
	s_mov_b64 exec, 0xffff
	global_atomic_add_f32 v208, v213, s[14:15]
	s_mov_b64 exec, -1
	v_add_u32_e32 v211, 0x20000, v209
	global_load_dwordx4 v[176:179], v211, s[80:81]
	global_load_dwordx4 v[180:183], v211, s[80:81] offset:256
	s_waitcnt vmcnt(5)
	v_lshlrev_b32_e32 v200, 16, v192
	v_and_b32_e32 v201, 0xffff0000, v192
	v_lshlrev_b32_e32 v202, 16, v193
	v_and_b32_e32 v203, 0xffff0000, v193
	v_lshlrev_b32_e32 v204, 16, v194
	v_and_b32_e32 v205, 0xffff0000, v194
	v_lshlrev_b32_e32 v206, 16, v195
	v_and_b32_e32 v207, 0xffff0000, v195
	v_pk_add_f32 v[108:109], v[108:109], v[200:201]
	v_pk_add_f32 v[110:111], v[110:111], v[202:203]
	v_pk_add_f32 v[104:105], v[104:105], v[204:205]
	v_pk_add_f32 v[106:107], v[106:107], v[206:207]
	v_mul_f32_e32 v213, v108, v108
	v_fmac_f32_e32 v213, v109, v109
	v_fmac_f32_e32 v213, v110, v110
	v_fmac_f32_e32 v213, v111, v111
	v_fmac_f32_e32 v213, v104, v104
	v_fmac_f32_e32 v213, v105, v105
	v_fmac_f32_e32 v213, v106, v106
	v_fmac_f32_e32 v213, v107, v107
	v_cvt_pk_bf16_f32 v192, v108, v109
	v_cvt_pk_bf16_f32 v193, v110, v111
	v_cvt_pk_bf16_f32 v194, v104, v105
	v_cvt_pk_bf16_f32 v195, v106, v107
	v_add_u32_e32 v217, 0x10000, v209
	global_store_dwordx4 v217, v[192:195], s[80:81]
	v_lshlrev_b32_e32 v200, 16, v196
	v_and_b32_e32 v201, 0xffff0000, v196
	v_lshlrev_b32_e32 v202, 16, v197
	v_and_b32_e32 v203, 0xffff0000, v197
	v_lshlrev_b32_e32 v204, 16, v198
	v_and_b32_e32 v205, 0xffff0000, v198
	v_lshlrev_b32_e32 v206, 16, v199
	v_and_b32_e32 v207, 0xffff0000, v199
	v_pk_add_f32 v[100:101], v[100:101], v[200:201]
	v_pk_add_f32 v[102:103], v[102:103], v[202:203]
	v_pk_add_f32 v[96:97], v[96:97], v[204:205]
	v_pk_add_f32 v[98:99], v[98:99], v[206:207]
	v_fmac_f32_e32 v213, v100, v100
	v_fmac_f32_e32 v213, v101, v101
	v_fmac_f32_e32 v213, v102, v102
	v_fmac_f32_e32 v213, v103, v103
	v_fmac_f32_e32 v213, v96, v96
	v_fmac_f32_e32 v213, v97, v97
	v_fmac_f32_e32 v213, v98, v98
	v_fmac_f32_e32 v213, v99, v99
	v_cvt_pk_bf16_f32 v196, v100, v101
	v_cvt_pk_bf16_f32 v197, v102, v103
	v_cvt_pk_bf16_f32 v198, v96, v97
	v_cvt_pk_bf16_f32 v199, v98, v99
	global_store_dwordx4 v217, v[196:199], s[80:81] offset:256
	ds_bpermute_b32 v214, v215, v213
	s_waitcnt lgkmcnt(0)
	v_add_f32_e32 v213, v213, v214
	ds_bpermute_b32 v214, v216, v213
	s_waitcnt lgkmcnt(0)
	v_add_f32_e32 v213, v213, v214
	s_mov_b64 exec, 0xffff
	global_atomic_add_f32 v208, v213, s[14:15] offset:64
	s_mov_b64 exec, -1
	v_add_u32_e32 v211, 0x30000, v209
	global_load_dwordx4 v[192:195], v211, s[80:81]
	global_load_dwordx4 v[196:199], v211, s[80:81] offset:256
	s_waitcnt vmcnt(5)
	v_lshlrev_b32_e32 v184, 16, v176
	v_and_b32_e32 v185, 0xffff0000, v176
	v_lshlrev_b32_e32 v186, 16, v177
	v_and_b32_e32 v187, 0xffff0000, v177
	v_lshlrev_b32_e32 v188, 16, v178
	v_and_b32_e32 v189, 0xffff0000, v178
	v_lshlrev_b32_e32 v190, 16, v179
	v_and_b32_e32 v191, 0xffff0000, v179
	v_pk_add_f32 v[92:93], v[92:93], v[184:185]
	v_pk_add_f32 v[94:95], v[94:95], v[186:187]
	v_pk_add_f32 v[88:89], v[88:89], v[188:189]
	v_pk_add_f32 v[90:91], v[90:91], v[190:191]
	v_mul_f32_e32 v213, v92, v92
	v_fmac_f32_e32 v213, v93, v93
	v_fmac_f32_e32 v213, v94, v94
	v_fmac_f32_e32 v213, v95, v95
	v_fmac_f32_e32 v213, v88, v88
	v_fmac_f32_e32 v213, v89, v89
	v_fmac_f32_e32 v213, v90, v90
	v_fmac_f32_e32 v213, v91, v91
	v_cvt_pk_bf16_f32 v176, v92, v93
	v_cvt_pk_bf16_f32 v177, v94, v95
	v_cvt_pk_bf16_f32 v178, v88, v89
	v_cvt_pk_bf16_f32 v179, v90, v91
	v_add_u32_e32 v217, 0x20000, v209
	global_store_dwordx4 v217, v[176:179], s[80:81]
	v_lshlrev_b32_e32 v184, 16, v180
	v_and_b32_e32 v185, 0xffff0000, v180
	v_lshlrev_b32_e32 v186, 16, v181
	v_and_b32_e32 v187, 0xffff0000, v181
	v_lshlrev_b32_e32 v188, 16, v182
	v_and_b32_e32 v189, 0xffff0000, v182
	v_lshlrev_b32_e32 v190, 16, v183
	v_and_b32_e32 v191, 0xffff0000, v183
	v_pk_add_f32 v[84:85], v[84:85], v[184:185]
	v_pk_add_f32 v[86:87], v[86:87], v[186:187]
	v_pk_add_f32 v[80:81], v[80:81], v[188:189]
	v_pk_add_f32 v[82:83], v[82:83], v[190:191]
	v_fmac_f32_e32 v213, v84, v84
	v_fmac_f32_e32 v213, v85, v85
	v_fmac_f32_e32 v213, v86, v86
	v_fmac_f32_e32 v213, v87, v87
	v_fmac_f32_e32 v213, v80, v80
	v_fmac_f32_e32 v213, v81, v81
	v_fmac_f32_e32 v213, v82, v82
	v_fmac_f32_e32 v213, v83, v83
	v_cvt_pk_bf16_f32 v180, v84, v85
	v_cvt_pk_bf16_f32 v181, v86, v87
	v_cvt_pk_bf16_f32 v182, v80, v81
	v_cvt_pk_bf16_f32 v183, v82, v83
	global_store_dwordx4 v217, v[180:183], s[80:81] offset:256
	ds_bpermute_b32 v214, v215, v213
	s_waitcnt lgkmcnt(0)
	v_add_f32_e32 v213, v213, v214
	ds_bpermute_b32 v214, v216, v213
	s_waitcnt lgkmcnt(0)
	v_add_f32_e32 v213, v213, v214
	s_mov_b64 exec, 0xffff
	global_atomic_add_f32 v208, v213, s[14:15] offset:128
	s_mov_b64 exec, -1
	v_add_u32_e32 v211, 0x80000, v209
	global_load_dwordx4 v[176:179], v211, s[80:81]
	global_load_dwordx4 v[180:183], v211, s[80:81] offset:256
	s_waitcnt vmcnt(5)
	v_lshlrev_b32_e32 v200, 16, v192
	v_and_b32_e32 v201, 0xffff0000, v192
	v_lshlrev_b32_e32 v202, 16, v193
	v_and_b32_e32 v203, 0xffff0000, v193
	v_lshlrev_b32_e32 v204, 16, v194
	v_and_b32_e32 v205, 0xffff0000, v194
	v_lshlrev_b32_e32 v206, 16, v195
	v_and_b32_e32 v207, 0xffff0000, v195
	v_pk_add_f32 v[76:77], v[76:77], v[200:201]
	v_pk_add_f32 v[78:79], v[78:79], v[202:203]
	v_pk_add_f32 v[72:73], v[72:73], v[204:205]
	v_pk_add_f32 v[74:75], v[74:75], v[206:207]
	v_mul_f32_e32 v213, v76, v76
	v_fmac_f32_e32 v213, v77, v77
	v_fmac_f32_e32 v213, v78, v78
	v_fmac_f32_e32 v213, v79, v79
	v_fmac_f32_e32 v213, v72, v72
	v_fmac_f32_e32 v213, v73, v73
	v_fmac_f32_e32 v213, v74, v74
	v_fmac_f32_e32 v213, v75, v75
	v_cvt_pk_bf16_f32 v192, v76, v77
	v_cvt_pk_bf16_f32 v193, v78, v79
	v_cvt_pk_bf16_f32 v194, v72, v73
	v_cvt_pk_bf16_f32 v195, v74, v75
	v_add_u32_e32 v217, 0x30000, v209
	global_store_dwordx4 v217, v[192:195], s[80:81]
	v_lshlrev_b32_e32 v200, 16, v196
	v_and_b32_e32 v201, 0xffff0000, v196
	v_lshlrev_b32_e32 v202, 16, v197
	v_and_b32_e32 v203, 0xffff0000, v197
	v_lshlrev_b32_e32 v204, 16, v198
	v_and_b32_e32 v205, 0xffff0000, v198
	v_lshlrev_b32_e32 v206, 16, v199
	v_and_b32_e32 v207, 0xffff0000, v199
	v_pk_add_f32 v[68:69], v[68:69], v[200:201]
	v_pk_add_f32 v[70:71], v[70:71], v[202:203]
	v_pk_add_f32 v[64:65], v[64:65], v[204:205]
	v_pk_add_f32 v[66:67], v[66:67], v[206:207]
	v_fmac_f32_e32 v213, v68, v68
	v_fmac_f32_e32 v213, v69, v69
	v_fmac_f32_e32 v213, v70, v70
	v_fmac_f32_e32 v213, v71, v71
	v_fmac_f32_e32 v213, v64, v64
	v_fmac_f32_e32 v213, v65, v65
	v_fmac_f32_e32 v213, v66, v66
	v_fmac_f32_e32 v213, v67, v67
	v_cvt_pk_bf16_f32 v196, v68, v69
	v_cvt_pk_bf16_f32 v197, v70, v71
	v_cvt_pk_bf16_f32 v198, v64, v65
	v_cvt_pk_bf16_f32 v199, v66, v67
	global_store_dwordx4 v217, v[196:199], s[80:81] offset:256
	ds_bpermute_b32 v214, v215, v213
	s_waitcnt lgkmcnt(0)
	v_add_f32_e32 v213, v213, v214
	ds_bpermute_b32 v214, v216, v213
	s_waitcnt lgkmcnt(0)
	v_add_f32_e32 v213, v213, v214
	s_mov_b64 exec, 0xffff
	global_atomic_add_f32 v208, v213, s[14:15] offset:192
	s_mov_b64 exec, -1
	v_add_u32_e32 v211, 0x90000, v209
	global_load_dwordx4 v[192:195], v211, s[80:81]
	global_load_dwordx4 v[196:199], v211, s[80:81] offset:256
	s_waitcnt vmcnt(5)
	v_lshlrev_b32_e32 v184, 16, v176
	v_and_b32_e32 v185, 0xffff0000, v176
	v_lshlrev_b32_e32 v186, 16, v177
	v_and_b32_e32 v187, 0xffff0000, v177
	v_lshlrev_b32_e32 v188, 16, v178
	v_and_b32_e32 v189, 0xffff0000, v178
	v_lshlrev_b32_e32 v190, 16, v179
	v_and_b32_e32 v191, 0xffff0000, v179
	v_pk_add_f32 v[60:61], v[60:61], v[184:185]
	v_pk_add_f32 v[62:63], v[62:63], v[186:187]
	v_pk_add_f32 v[56:57], v[56:57], v[188:189]
	v_pk_add_f32 v[58:59], v[58:59], v[190:191]
	v_mul_f32_e32 v213, v60, v60
	v_fmac_f32_e32 v213, v61, v61
	v_fmac_f32_e32 v213, v62, v62
	v_fmac_f32_e32 v213, v63, v63
	v_fmac_f32_e32 v213, v56, v56
	v_fmac_f32_e32 v213, v57, v57
	v_fmac_f32_e32 v213, v58, v58
	v_fmac_f32_e32 v213, v59, v59
	v_cvt_pk_bf16_f32 v176, v60, v61
	v_cvt_pk_bf16_f32 v177, v62, v63
	v_cvt_pk_bf16_f32 v178, v56, v57
	v_cvt_pk_bf16_f32 v179, v58, v59
	v_add_u32_e32 v217, 0x80000, v209
	global_store_dwordx4 v217, v[176:179], s[80:81]
	v_lshlrev_b32_e32 v184, 16, v180
	v_and_b32_e32 v185, 0xffff0000, v180
	v_lshlrev_b32_e32 v186, 16, v181
	v_and_b32_e32 v187, 0xffff0000, v181
	v_lshlrev_b32_e32 v188, 16, v182
	v_and_b32_e32 v189, 0xffff0000, v182
	v_lshlrev_b32_e32 v190, 16, v183
	v_and_b32_e32 v191, 0xffff0000, v183
	v_pk_add_f32 v[52:53], v[52:53], v[184:185]
	v_pk_add_f32 v[54:55], v[54:55], v[186:187]
	v_pk_add_f32 v[48:49], v[48:49], v[188:189]
	v_pk_add_f32 v[50:51], v[50:51], v[190:191]
	v_fmac_f32_e32 v213, v52, v52
	v_fmac_f32_e32 v213, v53, v53
	v_fmac_f32_e32 v213, v54, v54
	v_fmac_f32_e32 v213, v55, v55
	v_fmac_f32_e32 v213, v48, v48
	v_fmac_f32_e32 v213, v49, v49
	v_fmac_f32_e32 v213, v50, v50
	v_fmac_f32_e32 v213, v51, v51
	v_cvt_pk_bf16_f32 v180, v52, v53
	v_cvt_pk_bf16_f32 v181, v54, v55
	v_cvt_pk_bf16_f32 v182, v48, v49
	v_cvt_pk_bf16_f32 v183, v50, v51
	global_store_dwordx4 v217, v[180:183], s[80:81] offset:256
	ds_bpermute_b32 v214, v215, v213
	s_waitcnt lgkmcnt(0)
	v_add_f32_e32 v213, v213, v214
	ds_bpermute_b32 v214, v216, v213
	s_waitcnt lgkmcnt(0)
	v_add_f32_e32 v213, v213, v214
	s_mov_b64 exec, 0xffff
	global_atomic_add_f32 v208, v213, s[14:15] offset:512
	s_mov_b64 exec, -1
	v_add_u32_e32 v211, 0xa0000, v209
	global_load_dwordx4 v[176:179], v211, s[80:81]
	global_load_dwordx4 v[180:183], v211, s[80:81] offset:256
	s_waitcnt vmcnt(5)
	v_lshlrev_b32_e32 v200, 16, v192
	v_and_b32_e32 v201, 0xffff0000, v192
	v_lshlrev_b32_e32 v202, 16, v193
	v_and_b32_e32 v203, 0xffff0000, v193
	v_lshlrev_b32_e32 v204, 16, v194
	v_and_b32_e32 v205, 0xffff0000, v194
	v_lshlrev_b32_e32 v206, 16, v195
	v_and_b32_e32 v207, 0xffff0000, v195
	v_pk_add_f32 v[44:45], v[44:45], v[200:201]
	v_pk_add_f32 v[46:47], v[46:47], v[202:203]
	v_pk_add_f32 v[40:41], v[40:41], v[204:205]
	v_pk_add_f32 v[42:43], v[42:43], v[206:207]
	v_mul_f32_e32 v213, v44, v44
	v_fmac_f32_e32 v213, v45, v45
	v_fmac_f32_e32 v213, v46, v46
	v_fmac_f32_e32 v213, v47, v47
	v_fmac_f32_e32 v213, v40, v40
	v_fmac_f32_e32 v213, v41, v41
	v_fmac_f32_e32 v213, v42, v42
	v_fmac_f32_e32 v213, v43, v43
	v_cvt_pk_bf16_f32 v192, v44, v45
	v_cvt_pk_bf16_f32 v193, v46, v47
	v_cvt_pk_bf16_f32 v194, v40, v41
	v_cvt_pk_bf16_f32 v195, v42, v43
	v_add_u32_e32 v217, 0x90000, v209
	global_store_dwordx4 v217, v[192:195], s[80:81]
	v_lshlrev_b32_e32 v200, 16, v196
	v_and_b32_e32 v201, 0xffff0000, v196
	v_lshlrev_b32_e32 v202, 16, v197
	v_and_b32_e32 v203, 0xffff0000, v197
	v_lshlrev_b32_e32 v204, 16, v198
	v_and_b32_e32 v205, 0xffff0000, v198
	v_lshlrev_b32_e32 v206, 16, v199
	v_and_b32_e32 v207, 0xffff0000, v199
	v_pk_add_f32 v[36:37], v[36:37], v[200:201]
	v_pk_add_f32 v[38:39], v[38:39], v[202:203]
	v_pk_add_f32 v[32:33], v[32:33], v[204:205]
	v_pk_add_f32 v[34:35], v[34:35], v[206:207]
	v_fmac_f32_e32 v213, v36, v36
	v_fmac_f32_e32 v213, v37, v37
	v_fmac_f32_e32 v213, v38, v38
	v_fmac_f32_e32 v213, v39, v39
	v_fmac_f32_e32 v213, v32, v32
	v_fmac_f32_e32 v213, v33, v33
	v_fmac_f32_e32 v213, v34, v34
	v_fmac_f32_e32 v213, v35, v35
	v_cvt_pk_bf16_f32 v196, v36, v37
	v_cvt_pk_bf16_f32 v197, v38, v39
	v_cvt_pk_bf16_f32 v198, v32, v33
	v_cvt_pk_bf16_f32 v199, v34, v35
	global_store_dwordx4 v217, v[196:199], s[80:81] offset:256
	ds_bpermute_b32 v214, v215, v213
	s_waitcnt lgkmcnt(0)
	v_add_f32_e32 v213, v213, v214
	ds_bpermute_b32 v214, v216, v213
	s_waitcnt lgkmcnt(0)
	v_add_f32_e32 v213, v213, v214
	s_mov_b64 exec, 0xffff
	global_atomic_add_f32 v208, v213, s[14:15] offset:576
	s_mov_b64 exec, -1
	v_add_u32_e32 v211, 0xb0000, v209
	global_load_dwordx4 v[192:195], v211, s[80:81]
	global_load_dwordx4 v[196:199], v211, s[80:81] offset:256
	s_waitcnt vmcnt(5)
	v_lshlrev_b32_e32 v184, 16, v176
	v_and_b32_e32 v185, 0xffff0000, v176
	v_lshlrev_b32_e32 v186, 16, v177
	v_and_b32_e32 v187, 0xffff0000, v177
	v_lshlrev_b32_e32 v188, 16, v178
	v_and_b32_e32 v189, 0xffff0000, v178
	v_lshlrev_b32_e32 v190, 16, v179
	v_and_b32_e32 v191, 0xffff0000, v179
	v_pk_add_f32 v[28:29], v[28:29], v[184:185]
	v_pk_add_f32 v[30:31], v[30:31], v[186:187]
	v_pk_add_f32 v[24:25], v[24:25], v[188:189]
	v_pk_add_f32 v[26:27], v[26:27], v[190:191]
	v_mul_f32_e32 v213, v28, v28
	v_fmac_f32_e32 v213, v29, v29
	v_fmac_f32_e32 v213, v30, v30
	v_fmac_f32_e32 v213, v31, v31
	v_fmac_f32_e32 v213, v24, v24
	v_fmac_f32_e32 v213, v25, v25
	v_fmac_f32_e32 v213, v26, v26
	v_fmac_f32_e32 v213, v27, v27
	v_cvt_pk_bf16_f32 v176, v28, v29
	v_cvt_pk_bf16_f32 v177, v30, v31
	v_cvt_pk_bf16_f32 v178, v24, v25
	v_cvt_pk_bf16_f32 v179, v26, v27
	v_add_u32_e32 v217, 0xa0000, v209
	global_store_dwordx4 v217, v[176:179], s[80:81]
	v_lshlrev_b32_e32 v184, 16, v180
	v_and_b32_e32 v185, 0xffff0000, v180
	v_lshlrev_b32_e32 v186, 16, v181
	v_and_b32_e32 v187, 0xffff0000, v181
	v_lshlrev_b32_e32 v188, 16, v182
	v_and_b32_e32 v189, 0xffff0000, v182
	v_lshlrev_b32_e32 v190, 16, v183
	v_and_b32_e32 v191, 0xffff0000, v183
	v_pk_add_f32 v[20:21], v[20:21], v[184:185]
	v_pk_add_f32 v[22:23], v[22:23], v[186:187]
	v_pk_add_f32 v[16:17], v[16:17], v[188:189]
	v_pk_add_f32 v[18:19], v[18:19], v[190:191]
	v_fmac_f32_e32 v213, v20, v20
	v_fmac_f32_e32 v213, v21, v21
	v_fmac_f32_e32 v213, v22, v22
	v_fmac_f32_e32 v213, v23, v23
	v_fmac_f32_e32 v213, v16, v16
	v_fmac_f32_e32 v213, v17, v17
	v_fmac_f32_e32 v213, v18, v18
	v_fmac_f32_e32 v213, v19, v19
	v_cvt_pk_bf16_f32 v180, v20, v21
	v_cvt_pk_bf16_f32 v181, v22, v23
	v_cvt_pk_bf16_f32 v182, v16, v17
	v_cvt_pk_bf16_f32 v183, v18, v19
	global_store_dwordx4 v217, v[180:183], s[80:81] offset:256
	ds_bpermute_b32 v214, v215, v213
	s_waitcnt lgkmcnt(0)
	v_add_f32_e32 v213, v213, v214
	ds_bpermute_b32 v214, v216, v213
	s_waitcnt lgkmcnt(0)
	v_add_f32_e32 v213, v213, v214
	s_mov_b64 exec, 0xffff
	global_atomic_add_f32 v208, v213, s[14:15] offset:640
	s_mov_b64 exec, -1
	s_waitcnt vmcnt(3)
	v_lshlrev_b32_e32 v200, 16, v192
	v_and_b32_e32 v201, 0xffff0000, v192
	v_lshlrev_b32_e32 v202, 16, v193
	v_and_b32_e32 v203, 0xffff0000, v193
	v_lshlrev_b32_e32 v204, 16, v194
	v_and_b32_e32 v205, 0xffff0000, v194
	v_lshlrev_b32_e32 v206, 16, v195
	v_and_b32_e32 v207, 0xffff0000, v195
	v_pk_add_f32 v[12:13], v[12:13], v[200:201]
	v_pk_add_f32 v[14:15], v[14:15], v[202:203]
	v_pk_add_f32 v[8:9], v[8:9], v[204:205]
	v_pk_add_f32 v[10:11], v[10:11], v[206:207]
	v_mul_f32_e32 v213, v12, v12
	v_fmac_f32_e32 v213, v13, v13
	v_fmac_f32_e32 v213, v14, v14
	v_fmac_f32_e32 v213, v15, v15
	v_fmac_f32_e32 v213, v8, v8
	v_fmac_f32_e32 v213, v9, v9
	v_fmac_f32_e32 v213, v10, v10
	v_fmac_f32_e32 v213, v11, v11
	v_cvt_pk_bf16_f32 v192, v12, v13
	v_cvt_pk_bf16_f32 v193, v14, v15
	v_cvt_pk_bf16_f32 v194, v8, v9
	v_cvt_pk_bf16_f32 v195, v10, v11
	v_add_u32_e32 v217, 0xb0000, v209
	global_store_dwordx4 v217, v[192:195], s[80:81]
	v_lshlrev_b32_e32 v200, 16, v196
	v_and_b32_e32 v201, 0xffff0000, v196
	v_lshlrev_b32_e32 v202, 16, v197
	v_and_b32_e32 v203, 0xffff0000, v197
	v_lshlrev_b32_e32 v204, 16, v198
	v_and_b32_e32 v205, 0xffff0000, v198
	v_lshlrev_b32_e32 v206, 16, v199
	v_and_b32_e32 v207, 0xffff0000, v199
	v_pk_add_f32 v[4:5], v[4:5], v[200:201]
	v_pk_add_f32 v[6:7], v[6:7], v[202:203]
	v_pk_add_f32 v[0:1], v[0:1], v[204:205]
	v_pk_add_f32 v[2:3], v[2:3], v[206:207]
	v_fmac_f32_e32 v213, v4, v4
	v_fmac_f32_e32 v213, v5, v5
	v_fmac_f32_e32 v213, v6, v6
	v_fmac_f32_e32 v213, v7, v7
	v_fmac_f32_e32 v213, v0, v0
	v_fmac_f32_e32 v213, v1, v1
	v_fmac_f32_e32 v213, v2, v2
	v_fmac_f32_e32 v213, v3, v3
	v_cvt_pk_bf16_f32 v196, v4, v5
	v_cvt_pk_bf16_f32 v197, v6, v7
	v_cvt_pk_bf16_f32 v198, v0, v1
	v_cvt_pk_bf16_f32 v199, v2, v3
	global_store_dwordx4 v217, v[196:199], s[80:81] offset:256
	ds_bpermute_b32 v214, v215, v213
	s_waitcnt lgkmcnt(0)
	v_add_f32_e32 v213, v213, v214
	ds_bpermute_b32 v214, v216, v213
	s_waitcnt lgkmcnt(0)
	v_add_f32_e32 v213, v213, v214
	s_mov_b64 exec, 0xffff
	global_atomic_add_f32 v208, v213, s[14:15] offset:704
	s_mov_b64 exec, -1
	s_branch .LBB0_496

.LBB0_599:
	ds_read_b128 v[140:143], v149
	ds_read_b128 v[154:157], v144
	ds_read_b128 v[158:161], v149 offset:2048
	ds_read_b128 v[176:179], v144 offset:2048
	s_add_u32 s28, s26, 0xfff80080
	s_addc_u32 s29, s27, -1
	s_cmp_eq_u32 s49, 28
	s_cselect_b32 s31, s1, s29
	s_cselect_b32 s30, s13, s28
	s_cselect_b32 s29, s19, s48
	s_cselect_b32 s28, s21, s33
	s_add_i32 m0, s37, 0xc000
	ds_read_b128 v[180:183], v150
	ds_read_b128 v[184:187], v145
	ds_read_b128 v[188:191], v150 offset:2048
	ds_read_b128 v[192:195], v145 offset:2048
	ds_read_b128 v[196:199], v150 offset:4096
	ds_read_b128 v[200:203], v145 offset:4096
	ds_read_b128 v[204:207], v150 offset:6144
	ds_read_b128 v[208:211], v145 offset:6144
	global_load_lds_dwordx4 v132, s[26:27]
	s_add_i32 m0, s37, 0xe000
	s_nop 0
	global_load_lds_dwordx4 v134, s[26:27]
	s_waitcnt lgkmcnt(8)
	s_barrier
	s_waitcnt lgkmcnt(0)
	s_waitcnt lgkmcnt(0)
	v_mfma_f32_16x16x32_bf16 v[124:127], v[140:143], v[180:183], v[124:127]
	v_mfma_f32_16x16x32_bf16 v[124:127], v[154:157], v[184:187], v[124:127]
	v_mfma_f32_16x16x32_bf16 v[120:123], v[176:179], v[184:187], v[120:123]
	v_mfma_f32_16x16x32_bf16 v[120:123], v[158:161], v[180:183], v[120:123]
	v_mfma_f32_16x16x32_bf16 v[104:107], v[158:161], v[188:191], v[104:107]
	v_mfma_f32_16x16x32_bf16 v[104:107], v[176:179], v[192:195], v[104:107]
	v_mfma_f32_16x16x32_bf16 v[108:111], v[154:157], v[192:195], v[108:111]
	v_mfma_f32_16x16x32_bf16 v[108:111], v[140:143], v[188:191], v[108:111]
	v_mfma_f32_16x16x32_bf16 v[92:95], v[140:143], v[196:199], v[92:95]
	v_mfma_f32_16x16x32_bf16 v[92:95], v[154:157], v[200:203], v[92:95]
	v_mfma_f32_16x16x32_bf16 v[88:91], v[176:179], v[200:203], v[88:91]
	v_mfma_f32_16x16x32_bf16 v[88:91], v[158:161], v[196:199], v[88:91]
	v_mfma_f32_16x16x32_bf16 v[72:75], v[158:161], v[204:207], v[72:75]
	v_mfma_f32_16x16x32_bf16 v[72:75], v[176:179], v[208:211], v[72:75]
	v_mfma_f32_16x16x32_bf16 v[76:79], v[154:157], v[208:211], v[76:79]
	v_mfma_f32_16x16x32_bf16 v[76:79], v[140:143], v[204:207], v[76:79]
	s_barrier
	s_add_i32 s52, s46, s36
	s_add_u32 s98, s28, s16
	s_addc_u32 s99, s29, s17
	s_mov_b32 m0, s52
	ds_read_b128 v[212:215], v151
	ds_read_b128 v[240:243], v216
	ds_read_b128 v[244:247], v151 offset:2048
	ds_read_b128 v[248:251], v216 offset:2048
	global_load_lds_dwordx4 v164, s[28:29]
	s_add_i32 m0, s52, 0x2000
	s_nop 0
	global_load_lds_dwordx4 v166, s[28:29]
	s_barrier
	s_waitcnt lgkmcnt(0)
	s_waitcnt lgkmcnt(0)
	v_mfma_f32_16x16x32_bf16 v[116:119], v[212:215], v[180:183], v[116:119]
	v_mfma_f32_16x16x32_bf16 v[116:119], v[240:243], v[184:187], v[116:119]
	v_mfma_f32_16x16x32_bf16 v[112:115], v[248:251], v[184:187], v[112:115]
	v_mfma_f32_16x16x32_bf16 v[112:115], v[244:247], v[180:183], v[112:115]
	v_mfma_f32_16x16x32_bf16 v[96:99], v[244:247], v[188:191], v[96:99]
	v_mfma_f32_16x16x32_bf16 v[96:99], v[248:251], v[192:195], v[96:99]
	v_mfma_f32_16x16x32_bf16 v[100:103], v[240:243], v[192:195], v[100:103]
	v_mfma_f32_16x16x32_bf16 v[100:103], v[212:215], v[188:191], v[100:103]
	v_mfma_f32_16x16x32_bf16 v[84:87], v[212:215], v[196:199], v[84:87]
	v_mfma_f32_16x16x32_bf16 v[84:87], v[240:243], v[200:203], v[84:87]
	v_mfma_f32_16x16x32_bf16 v[80:83], v[248:251], v[200:203], v[80:83]
	v_mfma_f32_16x16x32_bf16 v[80:83], v[244:247], v[196:199], v[80:83]
	v_mfma_f32_16x16x32_bf16 v[64:67], v[244:247], v[204:207], v[64:67]
	v_mfma_f32_16x16x32_bf16 v[64:67], v[248:251], v[208:211], v[64:67]
	v_mfma_f32_16x16x32_bf16 v[68:71], v[240:243], v[208:211], v[68:71]
	v_mfma_f32_16x16x32_bf16 v[68:71], v[212:215], v[204:207], v[68:71]
	s_mov_b32 m0, s37
	s_add_u32 s100, s30, s16
	s_addc_u32 s101, s31, s17
	s_barrier
	ds_read_b128 v[180:183], v150 offset:16384
	ds_read_b128 v[184:187], v145 offset:16384
	ds_read_b128 v[188:191], v150 offset:18432
	ds_read_b128 v[192:195], v145 offset:18432
	ds_read_b128 v[196:199], v150 offset:20480
	ds_read_b128 v[200:203], v145 offset:20480
	ds_read_b128 v[204:207], v150 offset:22528
	ds_read_b128 v[208:211], v145 offset:22528
	global_load_lds_dwordx4 v128, s[30:31]
	s_mov_b32 m0, s38
	s_nop 0
	global_load_lds_dwordx4 v130, s[30:31]
	s_barrier
	s_waitcnt lgkmcnt(0)
	s_waitcnt lgkmcnt(0)
	v_mfma_f32_16x16x32_bf16 v[60:63], v[140:143], v[180:183], v[60:63]
	v_mfma_f32_16x16x32_bf16 v[60:63], v[154:157], v[184:187], v[60:63]
	v_mfma_f32_16x16x32_bf16 v[56:59], v[176:179], v[184:187], v[56:59]
	v_mfma_f32_16x16x32_bf16 v[56:59], v[158:161], v[180:183], v[56:59]
	v_mfma_f32_16x16x32_bf16 v[40:43], v[158:161], v[188:191], v[40:43]
	v_mfma_f32_16x16x32_bf16 v[40:43], v[176:179], v[192:195], v[40:43]
	v_mfma_f32_16x16x32_bf16 v[44:47], v[154:157], v[192:195], v[44:47]
	v_mfma_f32_16x16x32_bf16 v[44:47], v[140:143], v[188:191], v[44:47]
	v_mfma_f32_16x16x32_bf16 v[28:31], v[140:143], v[196:199], v[28:31]
	v_mfma_f32_16x16x32_bf16 v[28:31], v[154:157], v[200:203], v[28:31]
	v_mfma_f32_16x16x32_bf16 v[24:27], v[176:179], v[200:203], v[24:27]
	v_mfma_f32_16x16x32_bf16 v[24:27], v[158:161], v[196:199], v[24:27]
	v_mfma_f32_16x16x32_bf16 v[8:11], v[158:161], v[204:207], v[8:11]
	v_mfma_f32_16x16x32_bf16 v[8:11], v[176:179], v[208:211], v[8:11]
	v_mfma_f32_16x16x32_bf16 v[12:15], v[154:157], v[208:211], v[12:15]
	v_mfma_f32_16x16x32_bf16 v[12:15], v[140:143], v[204:207], v[12:15]
	s_barrier
	s_add_u32 s52, s28, 0x80000
	s_addc_u32 s53, s29, 0
	s_add_i32 s54, s47, s36
	s_mov_b32 m0, s54
	s_nop 0
	global_load_lds_dwordx4 v164, s[52:53]
	s_add_i32 m0, s54, 0x2000
	s_nop 0
	global_load_lds_dwordx4 v166, s[52:53]
	s_waitcnt vmcnt(6)
	s_barrier
	v_mfma_f32_16x16x32_bf16 v[52:55], v[212:215], v[180:183], v[52:55]
	v_mfma_f32_16x16x32_bf16 v[52:55], v[240:243], v[184:187], v[52:55]
	v_mfma_f32_16x16x32_bf16 v[48:51], v[248:251], v[184:187], v[48:51]
	v_mfma_f32_16x16x32_bf16 v[48:51], v[244:247], v[180:183], v[48:51]
	v_mfma_f32_16x16x32_bf16 v[32:35], v[244:247], v[188:191], v[32:35]
	v_mfma_f32_16x16x32_bf16 v[32:35], v[248:251], v[192:195], v[32:35]
	v_mfma_f32_16x16x32_bf16 v[36:39], v[240:243], v[192:195], v[36:39]
	v_mfma_f32_16x16x32_bf16 v[36:39], v[212:215], v[188:191], v[36:39]
	v_mfma_f32_16x16x32_bf16 v[20:23], v[212:215], v[196:199], v[20:23]
	v_mfma_f32_16x16x32_bf16 v[20:23], v[240:243], v[200:203], v[20:23]
	v_mfma_f32_16x16x32_bf16 v[16:19], v[248:251], v[200:203], v[16:19]
	v_mfma_f32_16x16x32_bf16 v[16:19], v[244:247], v[196:199], v[16:19]
	v_mfma_f32_16x16x32_bf16 v[0:3], v[244:247], v[204:207], v[0:3]
	v_mfma_f32_16x16x32_bf16 v[0:3], v[248:251], v[208:211], v[0:3]
	v_mfma_f32_16x16x32_bf16 v[4:7], v[240:243], v[208:211], v[4:7]
	v_mfma_f32_16x16x32_bf16 v[4:7], v[212:215], v[204:207], v[4:7]
	s_add_i32 s52, 0, 0x18000
	s_barrier
	ds_read_b128 v[140:143], v217
	ds_read_b128 v[154:157], v234
	ds_read_b128 v[158:161], v217 offset:2048
	ds_read_b128 v[176:179], v234 offset:2048
	s_add_u32 s30, s30, 0x80000
	s_addc_u32 s31, s31, 0
	s_mov_b32 m0, s39
	ds_read_b128 v[180:183], v150 offset:32768
	ds_read_b128 v[184:187], v145 offset:32768
	ds_read_b128 v[188:191], v150 offset:34816
	ds_read_b128 v[192:195], v145 offset:34816
	ds_read_b128 v[196:199], v150 offset:36864
	ds_read_b128 v[200:203], v145 offset:36864
	ds_read_b128 v[204:207], v150 offset:38912
	ds_read_b128 v[208:211], v145 offset:38912
	global_load_lds_dwordx4 v128, s[30:31]
	s_mov_b32 m0, s40
	s_nop 0
	global_load_lds_dwordx4 v130, s[30:31]
	s_waitcnt lgkmcnt(8)
	s_barrier
	s_waitcnt lgkmcnt(0)
	s_waitcnt lgkmcnt(0)
	v_mfma_f32_16x16x32_bf16 v[124:127], v[140:143], v[180:183], v[124:127]
	v_mfma_f32_16x16x32_bf16 v[124:127], v[154:157], v[184:187], v[124:127]
	v_mfma_f32_16x16x32_bf16 v[120:123], v[176:179], v[184:187], v[120:123]
	v_mfma_f32_16x16x32_bf16 v[120:123], v[158:161], v[180:183], v[120:123]
	v_mfma_f32_16x16x32_bf16 v[104:107], v[158:161], v[188:191], v[104:107]
	v_mfma_f32_16x16x32_bf16 v[104:107], v[176:179], v[192:195], v[104:107]
	v_mfma_f32_16x16x32_bf16 v[108:111], v[154:157], v[192:195], v[108:111]
	v_mfma_f32_16x16x32_bf16 v[108:111], v[140:143], v[188:191], v[108:111]
	v_mfma_f32_16x16x32_bf16 v[92:95], v[140:143], v[196:199], v[92:95]
	v_mfma_f32_16x16x32_bf16 v[92:95], v[154:157], v[200:203], v[92:95]
	v_mfma_f32_16x16x32_bf16 v[88:91], v[176:179], v[200:203], v[88:91]
	v_mfma_f32_16x16x32_bf16 v[88:91], v[158:161], v[196:199], v[88:91]
	v_mfma_f32_16x16x32_bf16 v[72:75], v[158:161], v[204:207], v[72:75]
	v_mfma_f32_16x16x32_bf16 v[72:75], v[176:179], v[208:211], v[72:75]
	v_mfma_f32_16x16x32_bf16 v[76:79], v[154:157], v[208:211], v[76:79]
	v_mfma_f32_16x16x32_bf16 v[76:79], v[140:143], v[204:207], v[76:79]
	s_barrier
	s_add_i32 s30, 0, 0x1c000
	s_add_i32 s31, s52, s36
	s_mov_b32 m0, s31
	ds_read_b128 v[212:215], v235
	ds_read_b128 v[240:243], v252
	ds_read_b128 v[244:247], v235 offset:2048
	ds_read_b128 v[248:251], v252 offset:2048
	global_load_lds_dwordx4 v164, s[98:99]
	s_add_i32 m0, s31, 0x2000
	s_nop 0
	global_load_lds_dwordx4 v166, s[98:99]
	s_barrier
	s_waitcnt lgkmcnt(0)
	s_waitcnt lgkmcnt(0)
	v_mfma_f32_16x16x32_bf16 v[116:119], v[212:215], v[180:183], v[116:119]
	v_mfma_f32_16x16x32_bf16 v[116:119], v[240:243], v[184:187], v[116:119]
	v_mfma_f32_16x16x32_bf16 v[112:115], v[248:251], v[184:187], v[112:115]
	v_mfma_f32_16x16x32_bf16 v[112:115], v[244:247], v[180:183], v[112:115]
	v_mfma_f32_16x16x32_bf16 v[96:99], v[244:247], v[188:191], v[96:99]
	v_mfma_f32_16x16x32_bf16 v[96:99], v[248:251], v[192:195], v[96:99]
	v_mfma_f32_16x16x32_bf16 v[100:103], v[240:243], v[192:195], v[100:103]
	v_mfma_f32_16x16x32_bf16 v[100:103], v[212:215], v[188:191], v[100:103]
	v_mfma_f32_16x16x32_bf16 v[84:87], v[212:215], v[196:199], v[84:87]
	v_mfma_f32_16x16x32_bf16 v[84:87], v[240:243], v[200:203], v[84:87]
	v_mfma_f32_16x16x32_bf16 v[80:83], v[248:251], v[200:203], v[80:83]
	v_mfma_f32_16x16x32_bf16 v[80:83], v[244:247], v[196:199], v[80:83]
	v_mfma_f32_16x16x32_bf16 v[64:67], v[244:247], v[204:207], v[64:67]
	v_mfma_f32_16x16x32_bf16 v[64:67], v[248:251], v[208:211], v[64:67]
	v_mfma_f32_16x16x32_bf16 v[68:71], v[240:243], v[208:211], v[68:71]
	v_mfma_f32_16x16x32_bf16 v[68:71], v[212:215], v[204:207], v[68:71]
	s_mov_b32 m0, s42
	s_barrier
	ds_read_b128 v[180:183], v150 offset:49152
	ds_read_b128 v[184:187], v145 offset:49152
	ds_read_b128 v[188:191], v150 offset:51200
	ds_read_b128 v[192:195], v145 offset:51200
	ds_read_b128 v[196:199], v150 offset:53248
	ds_read_b128 v[200:203], v145 offset:53248
	ds_read_b128 v[204:207], v150 offset:55296
	ds_read_b128 v[208:211], v145 offset:55296
	global_load_lds_dwordx4 v128, s[100:101]
	s_mov_b32 m0, s43
	s_nop 0
	global_load_lds_dwordx4 v130, s[100:101]
	s_barrier
	s_waitcnt lgkmcnt(0)
	s_waitcnt lgkmcnt(0)
	v_mfma_f32_16x16x32_bf16 v[60:63], v[140:143], v[180:183], v[60:63]
	v_mfma_f32_16x16x32_bf16 v[60:63], v[154:157], v[184:187], v[60:63]
	v_mfma_f32_16x16x32_bf16 v[56:59], v[176:179], v[184:187], v[56:59]
	v_mfma_f32_16x16x32_bf16 v[56:59], v[158:161], v[180:183], v[56:59]
	v_mfma_f32_16x16x32_bf16 v[40:43], v[158:161], v[188:191], v[40:43]
	v_mfma_f32_16x16x32_bf16 v[40:43], v[176:179], v[192:195], v[40:43]
	v_mfma_f32_16x16x32_bf16 v[44:47], v[154:157], v[192:195], v[44:47]
	v_mfma_f32_16x16x32_bf16 v[44:47], v[140:143], v[188:191], v[44:47]
	v_mfma_f32_16x16x32_bf16 v[28:31], v[140:143], v[196:199], v[28:31]
	v_mfma_f32_16x16x32_bf16 v[28:31], v[154:157], v[200:203], v[28:31]
	v_mfma_f32_16x16x32_bf16 v[24:27], v[176:179], v[200:203], v[24:27]
	v_mfma_f32_16x16x32_bf16 v[24:27], v[158:161], v[196:199], v[24:27]
	v_mfma_f32_16x16x32_bf16 v[8:11], v[158:161], v[204:207], v[8:11]
	v_mfma_f32_16x16x32_bf16 v[8:11], v[176:179], v[208:211], v[8:11]
	v_mfma_f32_16x16x32_bf16 v[12:15], v[154:157], v[208:211], v[12:15]
	v_mfma_f32_16x16x32_bf16 v[12:15], v[140:143], v[204:207], v[12:15]
	s_barrier
	s_add_u32 s28, s28, 0x80080
	s_addc_u32 s29, s29, 0
	s_add_i32 s30, s30, s36
	s_mov_b32 m0, s30
	s_nop 0
	global_load_lds_dwordx4 v164, s[28:29]
	s_add_i32 m0, s30, 0x2000
	s_nop 0
	global_load_lds_dwordx4 v166, s[28:29]
	s_waitcnt vmcnt(6)
	s_barrier
	v_mfma_f32_16x16x32_bf16 v[52:55], v[212:215], v[180:183], v[52:55]
	v_mfma_f32_16x16x32_bf16 v[52:55], v[240:243], v[184:187], v[52:55]
	v_mfma_f32_16x16x32_bf16 v[48:51], v[248:251], v[184:187], v[48:51]
	v_mfma_f32_16x16x32_bf16 v[48:51], v[244:247], v[180:183], v[48:51]
	v_mfma_f32_16x16x32_bf16 v[32:35], v[244:247], v[188:191], v[32:35]
	v_mfma_f32_16x16x32_bf16 v[32:35], v[248:251], v[192:195], v[32:35]
	v_mfma_f32_16x16x32_bf16 v[36:39], v[240:243], v[192:195], v[36:39]
	v_mfma_f32_16x16x32_bf16 v[36:39], v[212:215], v[188:191], v[36:39]
	v_mfma_f32_16x16x32_bf16 v[20:23], v[212:215], v[196:199], v[20:23]
	v_mfma_f32_16x16x32_bf16 v[20:23], v[240:243], v[200:203], v[20:23]
	v_mfma_f32_16x16x32_bf16 v[16:19], v[248:251], v[200:203], v[16:19]
	v_mfma_f32_16x16x32_bf16 v[16:19], v[244:247], v[196:199], v[16:19]
	v_mfma_f32_16x16x32_bf16 v[0:3], v[244:247], v[204:207], v[0:3]
	v_mfma_f32_16x16x32_bf16 v[0:3], v[248:251], v[208:211], v[0:3]
	v_mfma_f32_16x16x32_bf16 v[4:7], v[240:243], v[208:211], v[4:7]
	v_mfma_f32_16x16x32_bf16 v[4:7], v[212:215], v[204:207], v[4:7]
	s_add_i32 s49, s49, 2
	s_add_u32 s26, s26, 0x100
	s_addc_u32 s27, s27, 0
	s_add_u32 s33, s33, 0x100
	s_addc_u32 s48, s48, 0
	s_cmp_gt_u32 s49, 29
	s_barrier
	s_cbranch_scc0 .LBB0_599
	v_lshl_add_u32 v143, s12, 8, v146
	v_lshlrev_b32_e32 v145, 2, v143
	global_load_dword v154, v145, s[14:15]
	global_load_dword v155, v145, s[14:15] offset:64
	global_load_dword v156, v145, s[14:15] offset:128
	global_load_dword v157, v145, s[14:15] offset:192
	global_load_dword v158, v145, s[14:15] offset:512
	global_load_dword v159, v145, s[14:15] offset:576
	global_load_dword v160, v145, s[14:15] offset:640
	global_load_dword v161, v145, s[14:15] offset:704
	v_lshlrev_b32_e32 v141, 13, v143
	v_lshl_or_b32 v143, s0, 8, v148
	v_lshl_add_u32 v141, v143, 1, v141
	v_xor_b32_e32 v169, 16, v153
	v_lshlrev_b32_e32 v169, 2, v169
	v_xor_b32_e32 v171, 32, v153
	v_lshlrev_b32_e32 v171, 2, v171
	v_mov_b32_e32 v140, 0xbdd2d3e8
	v_mov_b32_e32 v142, 0xc0135761
	v_mov_b32_e32 v144, 1.0
	s_waitcnt vmcnt(0)
	v_fmamk_f32 v154, v154, 0x3a000000, v152
	v_fmamk_f32 v155, v155, 0x3a000000, v152
	v_fmamk_f32 v156, v156, 0x3a000000, v152
	v_fmamk_f32 v157, v157, 0x3a000000, v152
	v_fmamk_f32 v158, v158, 0x3a000000, v152
	v_fmamk_f32 v159, v159, 0x3a000000, v152
	v_fmamk_f32 v160, v160, 0x3a000000, v152
	v_fmamk_f32 v161, v161, 0x3a000000, v152
	v_rsq_f32_e32 v154, v154
	v_rsq_f32_e32 v155, v155
	v_rsq_f32_e32 v156, v156
	v_rsq_f32_e32 v157, v157
	v_rsq_f32_e32 v158, v158
	v_rsq_f32_e32 v159, v159
	v_rsq_f32_e32 v160, v160
	v_rsq_f32_e32 v161, v161
	v_pk_mul_f32 v[124:125], v[124:125], v[154:155] op_sel:[0,0] op_sel_hi:[1,0]
	v_pk_mul_f32 v[126:127], v[126:127], v[154:155] op_sel:[0,0] op_sel_hi:[1,0]
	v_pk_mul_f32 v[120:121], v[120:121], v[154:155] op_sel:[0,0] op_sel_hi:[1,0]
	v_pk_mul_f32 v[122:123], v[122:123], v[154:155] op_sel:[0,0] op_sel_hi:[1,0]
	v_pk_mul_f32 v[176:177], v[124:125], v[124:125]
	v_pk_mul_f32 v[178:179], v[126:127], v[126:127]
	v_pk_mul_f32 v[180:181], v[120:121], v[120:121]
	v_pk_mul_f32 v[182:183], v[122:123], v[122:123]
	v_pk_fma_f32 v[176:177], v[176:177], v[140:141], v[142:143] op_sel_hi:[1,0,0]
	v_pk_fma_f32 v[178:179], v[178:179], v[140:141], v[142:143] op_sel_hi:[1,0,0]
	v_pk_fma_f32 v[180:181], v[180:181], v[140:141], v[142:143] op_sel_hi:[1,0,0]
	v_pk_fma_f32 v[182:183], v[182:183], v[140:141], v[142:143] op_sel_hi:[1,0,0]
	v_pk_mul_f32 v[176:177], v[124:125], v[176:177]
	v_pk_mul_f32 v[178:179], v[126:127], v[178:179]
	v_pk_mul_f32 v[180:181], v[120:121], v[180:181]
	v_pk_mul_f32 v[182:183], v[122:123], v[182:183]
	v_exp_f32_e32 v176, v176
	v_exp_f32_e32 v177, v177
	v_exp_f32_e32 v178, v178
	v_exp_f32_e32 v179, v179
	v_exp_f32_e32 v180, v180
	v_exp_f32_e32 v181, v181
	v_exp_f32_e32 v182, v182
	v_exp_f32_e32 v183, v183
	v_pk_add_f32 v[176:177], v[176:177], v[144:145] op_sel_hi:[1,0]
	v_pk_add_f32 v[178:179], v[178:179], v[144:145] op_sel_hi:[1,0]
	v_pk_add_f32 v[180:181], v[180:181], v[144:145] op_sel_hi:[1,0]
	v_pk_add_f32 v[182:183], v[182:183], v[144:145] op_sel_hi:[1,0]
	v_rcp_f32_e32 v176, v176
	v_rcp_f32_e32 v177, v177
	v_rcp_f32_e32 v178, v178
	v_rcp_f32_e32 v179, v179
	v_rcp_f32_e32 v180, v180
	v_rcp_f32_e32 v181, v181
	v_rcp_f32_e32 v182, v182
	v_rcp_f32_e32 v183, v183
	v_pk_mul_f32 v[124:125], v[124:125], v[176:177]
	v_pk_mul_f32 v[126:127], v[126:127], v[178:179]
	v_pk_mul_f32 v[120:121], v[120:121], v[180:181]
	v_pk_mul_f32 v[122:123], v[122:123], v[182:183]
	v_pk_mul_f32 v[184:185], v[124:125], v[124:125]
	v_pk_fma_f32 v[184:185], v[126:127], v[126:127], v[184:185]
	v_pk_fma_f32 v[184:185], v[120:121], v[120:121], v[184:185]
	v_pk_fma_f32 v[184:185], v[122:123], v[122:123], v[184:185]
	v_cvt_pk_bf16_f32 v124, v124, v125
	v_cvt_pk_bf16_f32 v125, v126, v127
	v_cvt_pk_bf16_f32 v126, v120, v121
	v_cvt_pk_bf16_f32 v127, v122, v123
	global_store_dwordx4 v141, v[124:127], s[96:97]
	v_pk_mul_f32 v[116:117], v[116:117], v[154:155] op_sel:[0,0] op_sel_hi:[1,0]
	v_pk_mul_f32 v[118:119], v[118:119], v[154:155] op_sel:[0,0] op_sel_hi:[1,0]
	v_pk_mul_f32 v[112:113], v[112:113], v[154:155] op_sel:[0,0] op_sel_hi:[1,0]
	v_pk_mul_f32 v[114:115], v[114:115], v[154:155] op_sel:[0,0] op_sel_hi:[1,0]
	v_pk_mul_f32 v[176:177], v[116:117], v[116:117]
	v_pk_mul_f32 v[178:179], v[118:119], v[118:119]
	v_pk_mul_f32 v[180:181], v[112:113], v[112:113]
	v_pk_mul_f32 v[182:183], v[114:115], v[114:115]
	v_pk_fma_f32 v[176:177], v[176:177], v[140:141], v[142:143] op_sel_hi:[1,0,0]
	v_pk_fma_f32 v[178:179], v[178:179], v[140:141], v[142:143] op_sel_hi:[1,0,0]
	v_pk_fma_f32 v[180:181], v[180:181], v[140:141], v[142:143] op_sel_hi:[1,0,0]
	v_pk_fma_f32 v[182:183], v[182:183], v[140:141], v[142:143] op_sel_hi:[1,0,0]
	v_pk_mul_f32 v[176:177], v[116:117], v[176:177]
	v_pk_mul_f32 v[178:179], v[118:119], v[178:179]
	v_pk_mul_f32 v[180:181], v[112:113], v[180:181]
	v_pk_mul_f32 v[182:183], v[114:115], v[182:183]
	v_exp_f32_e32 v176, v176
	v_exp_f32_e32 v177, v177
	v_exp_f32_e32 v178, v178
	v_exp_f32_e32 v179, v179
	v_exp_f32_e32 v180, v180
	v_exp_f32_e32 v181, v181
	v_exp_f32_e32 v182, v182
	v_exp_f32_e32 v183, v183
	v_pk_add_f32 v[176:177], v[176:177], v[144:145] op_sel_hi:[1,0]
	v_pk_add_f32 v[178:179], v[178:179], v[144:145] op_sel_hi:[1,0]
	v_pk_add_f32 v[180:181], v[180:181], v[144:145] op_sel_hi:[1,0]
	v_pk_add_f32 v[182:183], v[182:183], v[144:145] op_sel_hi:[1,0]
	v_rcp_f32_e32 v176, v176
	v_rcp_f32_e32 v177, v177
	v_rcp_f32_e32 v178, v178
	v_rcp_f32_e32 v179, v179
	v_rcp_f32_e32 v180, v180
	v_rcp_f32_e32 v181, v181
	v_rcp_f32_e32 v182, v182
	v_rcp_f32_e32 v183, v183
	v_pk_mul_f32 v[116:117], v[116:117], v[176:177]
	v_pk_mul_f32 v[118:119], v[118:119], v[178:179]
	v_pk_mul_f32 v[112:113], v[112:113], v[180:181]
	v_pk_mul_f32 v[114:115], v[114:115], v[182:183]
	v_pk_fma_f32 v[184:185], v[116:117], v[116:117], v[184:185]
	v_pk_fma_f32 v[184:185], v[118:119], v[118:119], v[184:185]
	v_pk_fma_f32 v[184:185], v[112:113], v[112:113], v[184:185]
	v_pk_fma_f32 v[184:185], v[114:115], v[114:115], v[184:185]
	v_cvt_pk_bf16_f32 v116, v116, v117
	v_cvt_pk_bf16_f32 v117, v118, v119
	v_cvt_pk_bf16_f32 v118, v112, v113
	v_cvt_pk_bf16_f32 v119, v114, v115
	global_store_dwordx4 v141, v[116:119], s[96:97] offset:256
	s_cmp_lt_i32 s0, 8
	s_cbranch_scc1 .Le2_skip0
	v_add_f32_e32 v184, v184, v185
	ds_bpermute_b32 v173, v169, v184
	s_waitcnt lgkmcnt(0)
	v_add_f32_e32 v184, v184, v173
	ds_bpermute_b32 v173, v171, v184
	s_waitcnt lgkmcnt(0)
	v_add_f32_e32 v184, v184, v173
	s_mov_b64 exec, s[8:9]
	global_atomic_add_f32 v145, v184, s[4:5]
	s_mov_b64 exec, -1

.LBB0_760:
	ds_read_b128 v[140:143], v145
	ds_read_b128 v[150:153], v216
	ds_read_b128 v[154:157], v145 offset:2048
	ds_read_b128 v[158:161], v216 offset:2048
	s_add_u32 s22, s20, 0xfff00080
	s_addc_u32 s23, s21, -1
	s_cmp_eq_u32 s45, 28
	s_cselect_b32 s25, s1, s23
	s_cselect_b32 s24, s9, s22
	s_cselect_b32 s23, s13, s44
	s_cselect_b32 s22, s15, s43
	s_add_i32 m0, s29, 0xc000
	ds_read_b128 v[176:179], v146
	ds_read_b128 v[180:183], v217
	ds_read_b128 v[184:187], v146 offset:2048
	ds_read_b128 v[188:191], v217 offset:2048
	ds_read_b128 v[192:195], v146 offset:4096
	ds_read_b128 v[196:199], v217 offset:4096
	ds_read_b128 v[200:203], v146 offset:6144
	ds_read_b128 v[204:207], v217 offset:6144
	global_load_lds_dwordx4 v132, s[20:21]
	s_add_i32 m0, s29, 0xe000
	s_nop 0
	global_load_lds_dwordx4 v134, s[20:21]
	s_waitcnt lgkmcnt(8)
	s_barrier
	s_waitcnt lgkmcnt(0)
	s_waitcnt lgkmcnt(0)
	v_mfma_f32_16x16x32_bf16 v[124:127], v[140:143], v[176:179], v[124:127]
	v_mfma_f32_16x16x32_bf16 v[124:127], v[150:153], v[180:183], v[124:127]
	v_mfma_f32_16x16x32_bf16 v[120:123], v[158:161], v[180:183], v[120:123]
	v_mfma_f32_16x16x32_bf16 v[120:123], v[154:157], v[176:179], v[120:123]
	v_mfma_f32_16x16x32_bf16 v[104:107], v[154:157], v[184:187], v[104:107]
	v_mfma_f32_16x16x32_bf16 v[104:107], v[158:161], v[188:191], v[104:107]
	v_mfma_f32_16x16x32_bf16 v[108:111], v[150:153], v[188:191], v[108:111]
	v_mfma_f32_16x16x32_bf16 v[108:111], v[140:143], v[184:187], v[108:111]
	v_mfma_f32_16x16x32_bf16 v[92:95], v[140:143], v[192:195], v[92:95]
	v_mfma_f32_16x16x32_bf16 v[92:95], v[150:153], v[196:199], v[92:95]
	v_mfma_f32_16x16x32_bf16 v[88:91], v[158:161], v[196:199], v[88:91]
	v_mfma_f32_16x16x32_bf16 v[88:91], v[154:157], v[192:195], v[88:91]
	v_mfma_f32_16x16x32_bf16 v[72:75], v[154:157], v[200:203], v[72:75]
	v_mfma_f32_16x16x32_bf16 v[72:75], v[158:161], v[204:207], v[72:75]
	v_mfma_f32_16x16x32_bf16 v[76:79], v[150:153], v[204:207], v[76:79]
	v_mfma_f32_16x16x32_bf16 v[76:79], v[140:143], v[200:203], v[76:79]
	s_barrier
	s_add_i32 s46, s41, s28
	s_add_u32 s98, s22, s10
	s_addc_u32 s99, s23, s11
	s_mov_b32 m0, s46
	ds_read_b128 v[208:211], v147
	ds_read_b128 v[212:215], v234
	ds_read_b128 v[236:239], v147 offset:2048
	ds_read_b128 v[240:243], v234 offset:2048
	global_load_lds_dwordx4 v164, s[22:23]
	s_add_i32 m0, s46, 0x2000
	s_nop 0
	global_load_lds_dwordx4 v166, s[22:23]
	s_barrier
	s_waitcnt lgkmcnt(0)
	s_waitcnt lgkmcnt(0)
	v_mfma_f32_16x16x32_bf16 v[116:119], v[208:211], v[176:179], v[116:119]
	v_mfma_f32_16x16x32_bf16 v[116:119], v[212:215], v[180:183], v[116:119]
	v_mfma_f32_16x16x32_bf16 v[112:115], v[240:243], v[180:183], v[112:115]
	v_mfma_f32_16x16x32_bf16 v[112:115], v[236:239], v[176:179], v[112:115]
	v_mfma_f32_16x16x32_bf16 v[96:99], v[236:239], v[184:187], v[96:99]
	v_mfma_f32_16x16x32_bf16 v[96:99], v[240:243], v[188:191], v[96:99]
	v_mfma_f32_16x16x32_bf16 v[100:103], v[212:215], v[188:191], v[100:103]
	v_mfma_f32_16x16x32_bf16 v[100:103], v[208:211], v[184:187], v[100:103]
	v_mfma_f32_16x16x32_bf16 v[84:87], v[208:211], v[192:195], v[84:87]
	v_mfma_f32_16x16x32_bf16 v[84:87], v[212:215], v[196:199], v[84:87]
	v_mfma_f32_16x16x32_bf16 v[80:83], v[240:243], v[196:199], v[80:83]
	v_mfma_f32_16x16x32_bf16 v[80:83], v[236:239], v[192:195], v[80:83]
	v_mfma_f32_16x16x32_bf16 v[64:67], v[236:239], v[200:203], v[64:67]
	v_mfma_f32_16x16x32_bf16 v[64:67], v[240:243], v[204:207], v[64:67]
	v_mfma_f32_16x16x32_bf16 v[68:71], v[212:215], v[204:207], v[68:71]
	v_mfma_f32_16x16x32_bf16 v[68:71], v[208:211], v[200:203], v[68:71]
	s_mov_b32 m0, s29
	s_add_u32 s100, s24, s10
	s_addc_u32 s101, s25, s11
	s_barrier
	ds_read_b128 v[176:179], v146 offset:16384
	ds_read_b128 v[180:183], v217 offset:16384
	ds_read_b128 v[184:187], v146 offset:18432
	ds_read_b128 v[188:191], v217 offset:18432
	ds_read_b128 v[192:195], v146 offset:20480
	ds_read_b128 v[196:199], v217 offset:20480
	ds_read_b128 v[200:203], v146 offset:22528
	ds_read_b128 v[204:207], v217 offset:22528
	global_load_lds_dwordx4 v128, s[24:25]
	s_mov_b32 m0, s30
	s_nop 0
	global_load_lds_dwordx4 v130, s[24:25]
	s_barrier
	s_waitcnt lgkmcnt(0)
	s_waitcnt lgkmcnt(0)
	v_mfma_f32_16x16x32_bf16 v[60:63], v[140:143], v[176:179], v[60:63]
	v_mfma_f32_16x16x32_bf16 v[60:63], v[150:153], v[180:183], v[60:63]
	v_mfma_f32_16x16x32_bf16 v[56:59], v[158:161], v[180:183], v[56:59]
	v_mfma_f32_16x16x32_bf16 v[56:59], v[154:157], v[176:179], v[56:59]
	v_mfma_f32_16x16x32_bf16 v[40:43], v[154:157], v[184:187], v[40:43]
	v_mfma_f32_16x16x32_bf16 v[40:43], v[158:161], v[188:191], v[40:43]
	v_mfma_f32_16x16x32_bf16 v[44:47], v[150:153], v[188:191], v[44:47]
	v_mfma_f32_16x16x32_bf16 v[44:47], v[140:143], v[184:187], v[44:47]
	v_mfma_f32_16x16x32_bf16 v[28:31], v[140:143], v[192:195], v[28:31]
	v_mfma_f32_16x16x32_bf16 v[28:31], v[150:153], v[196:199], v[28:31]
	v_mfma_f32_16x16x32_bf16 v[24:27], v[158:161], v[196:199], v[24:27]
	v_mfma_f32_16x16x32_bf16 v[24:27], v[154:157], v[192:195], v[24:27]
	v_mfma_f32_16x16x32_bf16 v[8:11], v[154:157], v[200:203], v[8:11]
	v_mfma_f32_16x16x32_bf16 v[8:11], v[158:161], v[204:207], v[8:11]
	v_mfma_f32_16x16x32_bf16 v[12:15], v[150:153], v[204:207], v[12:15]
	v_mfma_f32_16x16x32_bf16 v[12:15], v[140:143], v[200:203], v[12:15]
	s_barrier
	s_add_u32 s46, s22, 0x80000
	s_addc_u32 s47, s23, 0
	s_add_i32 s48, s42, s28
	s_mov_b32 m0, s48
	s_nop 0
	global_load_lds_dwordx4 v164, s[46:47]
	s_add_i32 m0, s48, 0x2000
	s_nop 0
	global_load_lds_dwordx4 v166, s[46:47]
	s_waitcnt vmcnt(6)
	s_barrier
	v_mfma_f32_16x16x32_bf16 v[52:55], v[208:211], v[176:179], v[52:55]
	v_mfma_f32_16x16x32_bf16 v[52:55], v[212:215], v[180:183], v[52:55]
	v_mfma_f32_16x16x32_bf16 v[48:51], v[240:243], v[180:183], v[48:51]
	v_mfma_f32_16x16x32_bf16 v[48:51], v[236:239], v[176:179], v[48:51]
	v_mfma_f32_16x16x32_bf16 v[32:35], v[236:239], v[184:187], v[32:35]
	v_mfma_f32_16x16x32_bf16 v[32:35], v[240:243], v[188:191], v[32:35]
	v_mfma_f32_16x16x32_bf16 v[36:39], v[212:215], v[188:191], v[36:39]
	v_mfma_f32_16x16x32_bf16 v[36:39], v[208:211], v[184:187], v[36:39]
	v_mfma_f32_16x16x32_bf16 v[20:23], v[208:211], v[192:195], v[20:23]
	v_mfma_f32_16x16x32_bf16 v[20:23], v[212:215], v[196:199], v[20:23]
	v_mfma_f32_16x16x32_bf16 v[16:19], v[240:243], v[196:199], v[16:19]
	v_mfma_f32_16x16x32_bf16 v[16:19], v[236:239], v[192:195], v[16:19]
	v_mfma_f32_16x16x32_bf16 v[0:3], v[236:239], v[200:203], v[0:3]
	v_mfma_f32_16x16x32_bf16 v[0:3], v[240:243], v[204:207], v[0:3]
	v_mfma_f32_16x16x32_bf16 v[4:7], v[212:215], v[204:207], v[4:7]
	v_mfma_f32_16x16x32_bf16 v[4:7], v[208:211], v[200:203], v[4:7]
	s_add_i32 s46, 0, 0x18000
	s_barrier
	ds_read_b128 v[140:143], v235
	ds_read_b128 v[150:153], v244
	ds_read_b128 v[154:157], v235 offset:2048
	ds_read_b128 v[158:161], v244 offset:2048
	s_add_u32 s24, s24, 0x100000
	s_addc_u32 s25, s25, 0
	s_mov_b32 m0, s31
	ds_read_b128 v[176:179], v146 offset:32768
	ds_read_b128 v[180:183], v217 offset:32768
	ds_read_b128 v[184:187], v146 offset:34816
	ds_read_b128 v[188:191], v217 offset:34816
	ds_read_b128 v[192:195], v146 offset:36864
	ds_read_b128 v[196:199], v217 offset:36864
	ds_read_b128 v[200:203], v146 offset:38912
	ds_read_b128 v[204:207], v217 offset:38912
	global_load_lds_dwordx4 v128, s[24:25]
	s_mov_b32 m0, s33
	s_nop 0
	global_load_lds_dwordx4 v130, s[24:25]
	s_waitcnt lgkmcnt(8)
	s_barrier
	s_waitcnt lgkmcnt(0)
	s_waitcnt lgkmcnt(0)
	v_mfma_f32_16x16x32_bf16 v[124:127], v[140:143], v[176:179], v[124:127]
	v_mfma_f32_16x16x32_bf16 v[124:127], v[150:153], v[180:183], v[124:127]
	v_mfma_f32_16x16x32_bf16 v[120:123], v[158:161], v[180:183], v[120:123]
	v_mfma_f32_16x16x32_bf16 v[120:123], v[154:157], v[176:179], v[120:123]
	v_mfma_f32_16x16x32_bf16 v[104:107], v[154:157], v[184:187], v[104:107]
	v_mfma_f32_16x16x32_bf16 v[104:107], v[158:161], v[188:191], v[104:107]
	v_mfma_f32_16x16x32_bf16 v[108:111], v[150:153], v[188:191], v[108:111]
	v_mfma_f32_16x16x32_bf16 v[108:111], v[140:143], v[184:187], v[108:111]
	v_mfma_f32_16x16x32_bf16 v[92:95], v[140:143], v[192:195], v[92:95]
	v_mfma_f32_16x16x32_bf16 v[92:95], v[150:153], v[196:199], v[92:95]
	v_mfma_f32_16x16x32_bf16 v[88:91], v[158:161], v[196:199], v[88:91]
	v_mfma_f32_16x16x32_bf16 v[88:91], v[154:157], v[192:195], v[88:91]
	v_mfma_f32_16x16x32_bf16 v[72:75], v[154:157], v[200:203], v[72:75]
	v_mfma_f32_16x16x32_bf16 v[72:75], v[158:161], v[204:207], v[72:75]
	v_mfma_f32_16x16x32_bf16 v[76:79], v[150:153], v[204:207], v[76:79]
	v_mfma_f32_16x16x32_bf16 v[76:79], v[140:143], v[200:203], v[76:79]
	s_barrier
	s_add_i32 s24, 0, 0x1c000
	s_add_i32 s25, s46, s28
	v_add_u32_e32 v149, s24, v144
	s_mov_b32 m0, s25
	ds_read_b128 v[208:211], v149
	v_xor_b32_e32 v243, 64, v149
	ds_read_b128 v[212:215], v243
	ds_read_b128 v[236:239], v149 offset:2048
	ds_read_b128 v[240:243], v243 offset:2048
	global_load_lds_dwordx4 v164, s[98:99]
	s_add_i32 m0, s25, 0x2000
	s_nop 0
	global_load_lds_dwordx4 v166, s[98:99]
	s_barrier
	s_waitcnt lgkmcnt(0)
	s_waitcnt lgkmcnt(0)
	v_mfma_f32_16x16x32_bf16 v[116:119], v[208:211], v[176:179], v[116:119]
	v_mfma_f32_16x16x32_bf16 v[116:119], v[212:215], v[180:183], v[116:119]
	v_mfma_f32_16x16x32_bf16 v[112:115], v[240:243], v[180:183], v[112:115]
	v_mfma_f32_16x16x32_bf16 v[112:115], v[236:239], v[176:179], v[112:115]
	v_mfma_f32_16x16x32_bf16 v[96:99], v[236:239], v[184:187], v[96:99]
	v_mfma_f32_16x16x32_bf16 v[96:99], v[240:243], v[188:191], v[96:99]
	v_mfma_f32_16x16x32_bf16 v[100:103], v[212:215], v[188:191], v[100:103]
	v_mfma_f32_16x16x32_bf16 v[100:103], v[208:211], v[184:187], v[100:103]
	v_mfma_f32_16x16x32_bf16 v[84:87], v[208:211], v[192:195], v[84:87]
	v_mfma_f32_16x16x32_bf16 v[84:87], v[212:215], v[196:199], v[84:87]
	v_mfma_f32_16x16x32_bf16 v[80:83], v[240:243], v[196:199], v[80:83]
	v_mfma_f32_16x16x32_bf16 v[80:83], v[236:239], v[192:195], v[80:83]
	v_mfma_f32_16x16x32_bf16 v[64:67], v[236:239], v[200:203], v[64:67]
	v_mfma_f32_16x16x32_bf16 v[64:67], v[240:243], v[204:207], v[64:67]
	v_mfma_f32_16x16x32_bf16 v[68:71], v[212:215], v[204:207], v[68:71]
	v_mfma_f32_16x16x32_bf16 v[68:71], v[208:211], v[200:203], v[68:71]
	s_mov_b32 m0, s37
	s_barrier
	ds_read_b128 v[176:179], v146 offset:49152
	ds_read_b128 v[180:183], v217 offset:49152
	ds_read_b128 v[184:187], v146 offset:51200
	ds_read_b128 v[188:191], v217 offset:51200
	ds_read_b128 v[192:195], v146 offset:53248
	ds_read_b128 v[196:199], v217 offset:53248
	ds_read_b128 v[200:203], v146 offset:55296
	ds_read_b128 v[204:207], v217 offset:55296
	global_load_lds_dwordx4 v128, s[100:101]
	s_mov_b32 m0, s38
	s_nop 0
	global_load_lds_dwordx4 v130, s[100:101]
	s_barrier
	s_waitcnt lgkmcnt(0)
	s_waitcnt lgkmcnt(0)
	v_mfma_f32_16x16x32_bf16 v[60:63], v[140:143], v[176:179], v[60:63]
	v_mfma_f32_16x16x32_bf16 v[60:63], v[150:153], v[180:183], v[60:63]
	v_mfma_f32_16x16x32_bf16 v[56:59], v[158:161], v[180:183], v[56:59]
	v_mfma_f32_16x16x32_bf16 v[56:59], v[154:157], v[176:179], v[56:59]
	v_mfma_f32_16x16x32_bf16 v[40:43], v[154:157], v[184:187], v[40:43]
	v_mfma_f32_16x16x32_bf16 v[40:43], v[158:161], v[188:191], v[40:43]
	v_mfma_f32_16x16x32_bf16 v[44:47], v[150:153], v[188:191], v[44:47]
	v_mfma_f32_16x16x32_bf16 v[44:47], v[140:143], v[184:187], v[44:47]
	v_mfma_f32_16x16x32_bf16 v[28:31], v[140:143], v[192:195], v[28:31]
	v_mfma_f32_16x16x32_bf16 v[28:31], v[150:153], v[196:199], v[28:31]
	v_mfma_f32_16x16x32_bf16 v[24:27], v[158:161], v[196:199], v[24:27]
	v_mfma_f32_16x16x32_bf16 v[24:27], v[154:157], v[192:195], v[24:27]
	v_mfma_f32_16x16x32_bf16 v[8:11], v[154:157], v[200:203], v[8:11]
	v_mfma_f32_16x16x32_bf16 v[8:11], v[158:161], v[204:207], v[8:11]
	v_mfma_f32_16x16x32_bf16 v[12:15], v[150:153], v[204:207], v[12:15]
	v_mfma_f32_16x16x32_bf16 v[12:15], v[140:143], v[200:203], v[12:15]
	s_barrier
	s_add_u32 s22, s22, 0x80080
	s_addc_u32 s23, s23, 0
	s_add_i32 s24, s24, s28
	s_mov_b32 m0, s24
	s_nop 0
	global_load_lds_dwordx4 v164, s[22:23]
	s_add_i32 m0, s24, 0x2000
	s_nop 0
	global_load_lds_dwordx4 v166, s[22:23]
	s_waitcnt vmcnt(6)
	s_barrier
	v_mfma_f32_16x16x32_bf16 v[52:55], v[208:211], v[176:179], v[52:55]
	v_mfma_f32_16x16x32_bf16 v[52:55], v[212:215], v[180:183], v[52:55]
	v_mfma_f32_16x16x32_bf16 v[48:51], v[240:243], v[180:183], v[48:51]
	v_mfma_f32_16x16x32_bf16 v[48:51], v[236:239], v[176:179], v[48:51]
	v_mfma_f32_16x16x32_bf16 v[32:35], v[236:239], v[184:187], v[32:35]
	v_mfma_f32_16x16x32_bf16 v[32:35], v[240:243], v[188:191], v[32:35]
	v_mfma_f32_16x16x32_bf16 v[36:39], v[212:215], v[188:191], v[36:39]
	v_mfma_f32_16x16x32_bf16 v[36:39], v[208:211], v[184:187], v[36:39]
	v_mfma_f32_16x16x32_bf16 v[20:23], v[208:211], v[192:195], v[20:23]
	v_mfma_f32_16x16x32_bf16 v[20:23], v[212:215], v[196:199], v[20:23]
	v_mfma_f32_16x16x32_bf16 v[16:19], v[240:243], v[196:199], v[16:19]
	v_mfma_f32_16x16x32_bf16 v[16:19], v[236:239], v[192:195], v[16:19]
	v_mfma_f32_16x16x32_bf16 v[0:3], v[236:239], v[200:203], v[0:3]
	v_mfma_f32_16x16x32_bf16 v[0:3], v[240:243], v[204:207], v[0:3]
	v_mfma_f32_16x16x32_bf16 v[4:7], v[212:215], v[204:207], v[4:7]
	v_mfma_f32_16x16x32_bf16 v[4:7], v[208:211], v[200:203], v[4:7]
	s_add_i32 s45, s45, 2
	s_add_u32 s20, s20, 0x100
	s_addc_u32 s21, s21, 0
	s_add_u32 s43, s43, 0x100
	s_addc_u32 s44, s44, 0
	s_cmp_gt_u32 s45, 29
	s_barrier
	s_cbranch_scc0 .LBB0_760
	v_lshl_add_u32 v217, s8, 8, v163
	v_add_u32_e32 v217, s35, v217
	v_lshlrev_b32_e32 v208, 2, v217
	v_lshl_add_u32 v214, v225, 3, s36
	v_lshl_add_u32 v214, s0, 8, v214
	v_lshl_add_u32 v209, v217, 11, v214
	v_lshlrev_b32_e32 v209, 1, v209
	v_lshlrev_b32_e32 v210, 1, v209
	v_lshl_add_u32 v217, v225, 4, v163
	v_xor_b32_e32 v215, 16, v217
	v_lshlrev_b32_e32 v215, 2, v215
	v_xor_b32_e32 v216, 32, v217
	v_lshlrev_b32_e32 v216, 2, v216
	v_add_u32_e32 v211, 0x0, v209
	global_load_dwordx4 v[176:179], v211, s[80:81]
	global_load_dwordx4 v[180:183], v211, s[80:81] offset:256
	v_add_u32_e32 v211, 0x10000, v209
	global_load_dwordx4 v[192:195], v211, s[80:81]
	global_load_dwordx4 v[196:199], v211, s[80:81] offset:256
	s_waitcnt vmcnt(2)
	v_lshlrev_b32_e32 v184, 16, v176
	v_and_b32_e32 v185, 0xffff0000, v176
	v_lshlrev_b32_e32 v186, 16, v177
	v_and_b32_e32 v187, 0xffff0000, v177
	v_lshlrev_b32_e32 v188, 16, v178
	v_and_b32_e32 v189, 0xffff0000, v178
	v_lshlrev_b32_e32 v190, 16, v179
	v_and_b32_e32 v191, 0xffff0000, v179
	v_pk_add_f32 v[124:125], v[124:125], v[184:185]
	v_pk_add_f32 v[126:127], v[126:127], v[186:187]
	v_pk_add_f32 v[120:121], v[120:121], v[188:189]
	v_pk_add_f32 v[122:123], v[122:123], v[190:191]
	v_mul_f32_e32 v213, v124, v124
	v_fmac_f32_e32 v213, v125, v125
	v_fmac_f32_e32 v213, v126, v126
	v_fmac_f32_e32 v213, v127, v127
	v_fmac_f32_e32 v213, v120, v120
	v_fmac_f32_e32 v213, v121, v121
	v_fmac_f32_e32 v213, v122, v122
	v_fmac_f32_e32 v213, v123, v123
	v_cvt_pk_bf16_f32 v176, v124, v125
	v_cvt_pk_bf16_f32 v177, v126, v127
	v_cvt_pk_bf16_f32 v178, v120, v121
	v_cvt_pk_bf16_f32 v179, v122, v123
	v_add_u32_e32 v217, 0x0, v209
	global_store_dwordx4 v217, v[176:179], s[80:81]
	v_lshlrev_b32_e32 v184, 16, v180
	v_and_b32_e32 v185, 0xffff0000, v180
	v_lshlrev_b32_e32 v186, 16, v181
	v_and_b32_e32 v187, 0xffff0000, v181
	v_lshlrev_b32_e32 v188, 16, v182
	v_and_b32_e32 v189, 0xffff0000, v182
	v_lshlrev_b32_e32 v190, 16, v183
	v_and_b32_e32 v191, 0xffff0000, v183
	v_pk_add_f32 v[116:117], v[116:117], v[184:185]
	v_pk_add_f32 v[118:119], v[118:119], v[186:187]
	v_pk_add_f32 v[112:113], v[112:113], v[188:189]
	v_pk_add_f32 v[114:115], v[114:115], v[190:191]
	v_fmac_f32_e32 v213, v116, v116
	v_fmac_f32_e32 v213, v117, v117
	v_fmac_f32_e32 v213, v118, v118
	v_fmac_f32_e32 v213, v119, v119
	v_fmac_f32_e32 v213, v112, v112
	v_fmac_f32_e32 v213, v113, v113
	v_fmac_f32_e32 v213, v114, v114
	v_fmac_f32_e32 v213, v115, v115
	v_cvt_pk_bf16_f32 v180, v116, v117
	v_cvt_pk_bf16_f32 v181, v118, v119
	v_cvt_pk_bf16_f32 v182, v112, v113
	v_cvt_pk_bf16_f32 v183, v114, v115
	global_store_dwordx4 v217, v[180:183], s[80:81] offset:256
	ds_bpermute_b32 v214, v215, v213
	s_waitcnt lgkmcnt(0)
	v_add_f32_e32 v213, v213, v214
	ds_bpermute_b32 v214, v216, v213
	s_waitcnt lgkmcnt(0)
	v_add_f32_e32 v213, v213, v214
	s_mov_b64 exec, 0xffff
	global_atomic_add_f32 v208, v213, s[4:5]
	s_mov_b64 exec, -1
	v_add_u32_e32 v211, 0x20000, v209
	global_load_dwordx4 v[176:179], v211, s[80:81]
	global_load_dwordx4 v[180:183], v211, s[80:81] offset:256
	s_waitcnt vmcnt(5)
	v_lshlrev_b32_e32 v200, 16, v192
	v_and_b32_e32 v201, 0xffff0000, v192
	v_lshlrev_b32_e32 v202, 16, v193
	v_and_b32_e32 v203, 0xffff0000, v193
	v_lshlrev_b32_e32 v204, 16, v194
	v_and_b32_e32 v205, 0xffff0000, v194
	v_lshlrev_b32_e32 v206, 16, v195
	v_and_b32_e32 v207, 0xffff0000, v195
	v_pk_add_f32 v[108:109], v[108:109], v[200:201]
	v_pk_add_f32 v[110:111], v[110:111], v[202:203]
	v_pk_add_f32 v[104:105], v[104:105], v[204:205]
	v_pk_add_f32 v[106:107], v[106:107], v[206:207]
	v_mul_f32_e32 v213, v108, v108
	v_fmac_f32_e32 v213, v109, v109
	v_fmac_f32_e32 v213, v110, v110
	v_fmac_f32_e32 v213, v111, v111
	v_fmac_f32_e32 v213, v104, v104
	v_fmac_f32_e32 v213, v105, v105
	v_fmac_f32_e32 v213, v106, v106
	v_fmac_f32_e32 v213, v107, v107
	v_cvt_pk_bf16_f32 v192, v108, v109
	v_cvt_pk_bf16_f32 v193, v110, v111
	v_cvt_pk_bf16_f32 v194, v104, v105
	v_cvt_pk_bf16_f32 v195, v106, v107
	v_add_u32_e32 v217, 0x10000, v209
	global_store_dwordx4 v217, v[192:195], s[80:81]
	v_lshlrev_b32_e32 v200, 16, v196
	v_and_b32_e32 v201, 0xffff0000, v196
	v_lshlrev_b32_e32 v202, 16, v197
	v_and_b32_e32 v203, 0xffff0000, v197
	v_lshlrev_b32_e32 v204, 16, v198
	v_and_b32_e32 v205, 0xffff0000, v198
	v_lshlrev_b32_e32 v206, 16, v199
	v_and_b32_e32 v207, 0xffff0000, v199
	v_pk_add_f32 v[100:101], v[100:101], v[200:201]
	v_pk_add_f32 v[102:103], v[102:103], v[202:203]
	v_pk_add_f32 v[96:97], v[96:97], v[204:205]
	v_pk_add_f32 v[98:99], v[98:99], v[206:207]
	v_fmac_f32_e32 v213, v100, v100
	v_fmac_f32_e32 v213, v101, v101
	v_fmac_f32_e32 v213, v102, v102
	v_fmac_f32_e32 v213, v103, v103
	v_fmac_f32_e32 v213, v96, v96
	v_fmac_f32_e32 v213, v97, v97
	v_fmac_f32_e32 v213, v98, v98
	v_fmac_f32_e32 v213, v99, v99
	v_cvt_pk_bf16_f32 v196, v100, v101
	v_cvt_pk_bf16_f32 v197, v102, v103
	v_cvt_pk_bf16_f32 v198, v96, v97
	v_cvt_pk_bf16_f32 v199, v98, v99
	global_store_dwordx4 v217, v[196:199], s[80:81] offset:256
	ds_bpermute_b32 v214, v215, v213
	s_waitcnt lgkmcnt(0)
	v_add_f32_e32 v213, v213, v214
	ds_bpermute_b32 v214, v216, v213
	s_waitcnt lgkmcnt(0)
	v_add_f32_e32 v213, v213, v214
	s_mov_b64 exec, 0xffff
	global_atomic_add_f32 v208, v213, s[4:5] offset:64
	s_mov_b64 exec, -1
	v_add_u32_e32 v211, 0x30000, v209
	global_load_dwordx4 v[192:195], v211, s[80:81]
	global_load_dwordx4 v[196:199], v211, s[80:81] offset:256
	s_waitcnt vmcnt(5)
	v_lshlrev_b32_e32 v184, 16, v176
	v_and_b32_e32 v185, 0xffff0000, v176
	v_lshlrev_b32_e32 v186, 16, v177
	v_and_b32_e32 v187, 0xffff0000, v177
	v_lshlrev_b32_e32 v188, 16, v178
	v_and_b32_e32 v189, 0xffff0000, v178
	v_lshlrev_b32_e32 v190, 16, v179
	v_and_b32_e32 v191, 0xffff0000, v179
	v_pk_add_f32 v[92:93], v[92:93], v[184:185]
	v_pk_add_f32 v[94:95], v[94:95], v[186:187]
	v_pk_add_f32 v[88:89], v[88:89], v[188:189]
	v_pk_add_f32 v[90:91], v[90:91], v[190:191]
	v_mul_f32_e32 v213, v92, v92
	v_fmac_f32_e32 v213, v93, v93
	v_fmac_f32_e32 v213, v94, v94
	v_fmac_f32_e32 v213, v95, v95
	v_fmac_f32_e32 v213, v88, v88
	v_fmac_f32_e32 v213, v89, v89
	v_fmac_f32_e32 v213, v90, v90
	v_fmac_f32_e32 v213, v91, v91
	v_cvt_pk_bf16_f32 v176, v92, v93
	v_cvt_pk_bf16_f32 v177, v94, v95
	v_cvt_pk_bf16_f32 v178, v88, v89
	v_cvt_pk_bf16_f32 v179, v90, v91
	v_add_u32_e32 v217, 0x20000, v209
	global_store_dwordx4 v217, v[176:179], s[80:81]
	v_lshlrev_b32_e32 v184, 16, v180
	v_and_b32_e32 v185, 0xffff0000, v180
	v_lshlrev_b32_e32 v186, 16, v181
	v_and_b32_e32 v187, 0xffff0000, v181
	v_lshlrev_b32_e32 v188, 16, v182
	v_and_b32_e32 v189, 0xffff0000, v182
	v_lshlrev_b32_e32 v190, 16, v183
	v_and_b32_e32 v191, 0xffff0000, v183
	v_pk_add_f32 v[84:85], v[84:85], v[184:185]
	v_pk_add_f32 v[86:87], v[86:87], v[186:187]
	v_pk_add_f32 v[80:81], v[80:81], v[188:189]
	v_pk_add_f32 v[82:83], v[82:83], v[190:191]
	v_fmac_f32_e32 v213, v84, v84
	v_fmac_f32_e32 v213, v85, v85
	v_fmac_f32_e32 v213, v86, v86
	v_fmac_f32_e32 v213, v87, v87
	v_fmac_f32_e32 v213, v80, v80
	v_fmac_f32_e32 v213, v81, v81
	v_fmac_f32_e32 v213, v82, v82
	v_fmac_f32_e32 v213, v83, v83
	v_cvt_pk_bf16_f32 v180, v84, v85
	v_cvt_pk_bf16_f32 v181, v86, v87
	v_cvt_pk_bf16_f32 v182, v80, v81
	v_cvt_pk_bf16_f32 v183, v82, v83
	global_store_dwordx4 v217, v[180:183], s[80:81] offset:256
	ds_bpermute_b32 v214, v215, v213
	s_waitcnt lgkmcnt(0)
	v_add_f32_e32 v213, v213, v214
	ds_bpermute_b32 v214, v216, v213
	s_waitcnt lgkmcnt(0)
	v_add_f32_e32 v213, v213, v214
	s_mov_b64 exec, 0xffff
	global_atomic_add_f32 v208, v213, s[4:5] offset:128
	s_mov_b64 exec, -1
	v_add_u32_e32 v211, 0x80000, v209
	global_load_dwordx4 v[176:179], v211, s[80:81]
	global_load_dwordx4 v[180:183], v211, s[80:81] offset:256
	s_waitcnt vmcnt(5)
	v_lshlrev_b32_e32 v200, 16, v192
	v_and_b32_e32 v201, 0xffff0000, v192
	v_lshlrev_b32_e32 v202, 16, v193
	v_and_b32_e32 v203, 0xffff0000, v193
	v_lshlrev_b32_e32 v204, 16, v194
	v_and_b32_e32 v205, 0xffff0000, v194
	v_lshlrev_b32_e32 v206, 16, v195
	v_and_b32_e32 v207, 0xffff0000, v195
	v_pk_add_f32 v[76:77], v[76:77], v[200:201]
	v_pk_add_f32 v[78:79], v[78:79], v[202:203]
	v_pk_add_f32 v[72:73], v[72:73], v[204:205]
	v_pk_add_f32 v[74:75], v[74:75], v[206:207]
	v_mul_f32_e32 v213, v76, v76
	v_fmac_f32_e32 v213, v77, v77
	v_fmac_f32_e32 v213, v78, v78
	v_fmac_f32_e32 v213, v79, v79
	v_fmac_f32_e32 v213, v72, v72
	v_fmac_f32_e32 v213, v73, v73
	v_fmac_f32_e32 v213, v74, v74
	v_fmac_f32_e32 v213, v75, v75
	v_cvt_pk_bf16_f32 v192, v76, v77
	v_cvt_pk_bf16_f32 v193, v78, v79
	v_cvt_pk_bf16_f32 v194, v72, v73
	v_cvt_pk_bf16_f32 v195, v74, v75
	v_add_u32_e32 v217, 0x30000, v209
	global_store_dwordx4 v217, v[192:195], s[80:81]
	v_lshlrev_b32_e32 v200, 16, v196
	v_and_b32_e32 v201, 0xffff0000, v196
	v_lshlrev_b32_e32 v202, 16, v197
	v_and_b32_e32 v203, 0xffff0000, v197
	v_lshlrev_b32_e32 v204, 16, v198
	v_and_b32_e32 v205, 0xffff0000, v198
	v_lshlrev_b32_e32 v206, 16, v199
	v_and_b32_e32 v207, 0xffff0000, v199
	v_pk_add_f32 v[68:69], v[68:69], v[200:201]
	v_pk_add_f32 v[70:71], v[70:71], v[202:203]
	v_pk_add_f32 v[64:65], v[64:65], v[204:205]
	v_pk_add_f32 v[66:67], v[66:67], v[206:207]
	v_fmac_f32_e32 v213, v68, v68
	v_fmac_f32_e32 v213, v69, v69
	v_fmac_f32_e32 v213, v70, v70
	v_fmac_f32_e32 v213, v71, v71
	v_fmac_f32_e32 v213, v64, v64
	v_fmac_f32_e32 v213, v65, v65
	v_fmac_f32_e32 v213, v66, v66
	v_fmac_f32_e32 v213, v67, v67
	v_cvt_pk_bf16_f32 v196, v68, v69
	v_cvt_pk_bf16_f32 v197, v70, v71
	v_cvt_pk_bf16_f32 v198, v64, v65
	v_cvt_pk_bf16_f32 v199, v66, v67
	global_store_dwordx4 v217, v[196:199], s[80:81] offset:256
	ds_bpermute_b32 v214, v215, v213
	s_waitcnt lgkmcnt(0)
	v_add_f32_e32 v213, v213, v214
	ds_bpermute_b32 v214, v216, v213
	s_waitcnt lgkmcnt(0)
	v_add_f32_e32 v213, v213, v214
	s_mov_b64 exec, 0xffff
	global_atomic_add_f32 v208, v213, s[4:5] offset:192
	s_mov_b64 exec, -1
	v_add_u32_e32 v211, 0x90000, v209
	global_load_dwordx4 v[192:195], v211, s[80:81]
	global_load_dwordx4 v[196:199], v211, s[80:81] offset:256
	s_waitcnt vmcnt(5)
	v_lshlrev_b32_e32 v184, 16, v176
	v_and_b32_e32 v185, 0xffff0000, v176
	v_lshlrev_b32_e32 v186, 16, v177
	v_and_b32_e32 v187, 0xffff0000, v177
	v_lshlrev_b32_e32 v188, 16, v178
	v_and_b32_e32 v189, 0xffff0000, v178
	v_lshlrev_b32_e32 v190, 16, v179
	v_and_b32_e32 v191, 0xffff0000, v179
	v_pk_add_f32 v[60:61], v[60:61], v[184:185]
	v_pk_add_f32 v[62:63], v[62:63], v[186:187]
	v_pk_add_f32 v[56:57], v[56:57], v[188:189]
	v_pk_add_f32 v[58:59], v[58:59], v[190:191]
	v_mul_f32_e32 v213, v60, v60
	v_fmac_f32_e32 v213, v61, v61
	v_fmac_f32_e32 v213, v62, v62
	v_fmac_f32_e32 v213, v63, v63
	v_fmac_f32_e32 v213, v56, v56
	v_fmac_f32_e32 v213, v57, v57
	v_fmac_f32_e32 v213, v58, v58
	v_fmac_f32_e32 v213, v59, v59
	v_cvt_pk_bf16_f32 v176, v60, v61
	v_cvt_pk_bf16_f32 v177, v62, v63
	v_cvt_pk_bf16_f32 v178, v56, v57
	v_cvt_pk_bf16_f32 v179, v58, v59
	v_add_u32_e32 v217, 0x80000, v209
	global_store_dwordx4 v217, v[176:179], s[80:81]
	v_lshlrev_b32_e32 v184, 16, v180
	v_and_b32_e32 v185, 0xffff0000, v180
	v_lshlrev_b32_e32 v186, 16, v181
	v_and_b32_e32 v187, 0xffff0000, v181
	v_lshlrev_b32_e32 v188, 16, v182
	v_and_b32_e32 v189, 0xffff0000, v182
	v_lshlrev_b32_e32 v190, 16, v183
	v_and_b32_e32 v191, 0xffff0000, v183
	v_pk_add_f32 v[52:53], v[52:53], v[184:185]
	v_pk_add_f32 v[54:55], v[54:55], v[186:187]
	v_pk_add_f32 v[48:49], v[48:49], v[188:189]
	v_pk_add_f32 v[50:51], v[50:51], v[190:191]
	v_fmac_f32_e32 v213, v52, v52
	v_fmac_f32_e32 v213, v53, v53
	v_fmac_f32_e32 v213, v54, v54
	v_fmac_f32_e32 v213, v55, v55
	v_fmac_f32_e32 v213, v48, v48
	v_fmac_f32_e32 v213, v49, v49
	v_fmac_f32_e32 v213, v50, v50
	v_fmac_f32_e32 v213, v51, v51
	v_cvt_pk_bf16_f32 v180, v52, v53
	v_cvt_pk_bf16_f32 v181, v54, v55
	v_cvt_pk_bf16_f32 v182, v48, v49
	v_cvt_pk_bf16_f32 v183, v50, v51
	global_store_dwordx4 v217, v[180:183], s[80:81] offset:256
	ds_bpermute_b32 v214, v215, v213
	s_waitcnt lgkmcnt(0)
	v_add_f32_e32 v213, v213, v214
	ds_bpermute_b32 v214, v216, v213
	s_waitcnt lgkmcnt(0)
	v_add_f32_e32 v213, v213, v214
	s_mov_b64 exec, 0xffff
	global_atomic_add_f32 v208, v213, s[4:5] offset:512
	s_mov_b64 exec, -1
	v_add_u32_e32 v211, 0xa0000, v209
	global_load_dwordx4 v[176:179], v211, s[80:81]
	global_load_dwordx4 v[180:183], v211, s[80:81] offset:256
	s_waitcnt vmcnt(5)
	v_lshlrev_b32_e32 v200, 16, v192
	v_and_b32_e32 v201, 0xffff0000, v192
	v_lshlrev_b32_e32 v202, 16, v193
	v_and_b32_e32 v203, 0xffff0000, v193
	v_lshlrev_b32_e32 v204, 16, v194
	v_and_b32_e32 v205, 0xffff0000, v194
	v_lshlrev_b32_e32 v206, 16, v195
	v_and_b32_e32 v207, 0xffff0000, v195
	v_pk_add_f32 v[44:45], v[44:45], v[200:201]
	v_pk_add_f32 v[46:47], v[46:47], v[202:203]
	v_pk_add_f32 v[40:41], v[40:41], v[204:205]
	v_pk_add_f32 v[42:43], v[42:43], v[206:207]
	v_mul_f32_e32 v213, v44, v44
	v_fmac_f32_e32 v213, v45, v45
	v_fmac_f32_e32 v213, v46, v46
	v_fmac_f32_e32 v213, v47, v47
	v_fmac_f32_e32 v213, v40, v40
	v_fmac_f32_e32 v213, v41, v41
	v_fmac_f32_e32 v213, v42, v42
	v_fmac_f32_e32 v213, v43, v43
	v_cvt_pk_bf16_f32 v192, v44, v45
	v_cvt_pk_bf16_f32 v193, v46, v47
	v_cvt_pk_bf16_f32 v194, v40, v41
	v_cvt_pk_bf16_f32 v195, v42, v43
	v_add_u32_e32 v217, 0x90000, v209
	global_store_dwordx4 v217, v[192:195], s[80:81]
	v_lshlrev_b32_e32 v200, 16, v196
	v_and_b32_e32 v201, 0xffff0000, v196
	v_lshlrev_b32_e32 v202, 16, v197
	v_and_b32_e32 v203, 0xffff0000, v197
	v_lshlrev_b32_e32 v204, 16, v198
	v_and_b32_e32 v205, 0xffff0000, v198
	v_lshlrev_b32_e32 v206, 16, v199
	v_and_b32_e32 v207, 0xffff0000, v199
	v_pk_add_f32 v[36:37], v[36:37], v[200:201]
	v_pk_add_f32 v[38:39], v[38:39], v[202:203]
	v_pk_add_f32 v[32:33], v[32:33], v[204:205]
	v_pk_add_f32 v[34:35], v[34:35], v[206:207]
	v_fmac_f32_e32 v213, v36, v36
	v_fmac_f32_e32 v213, v37, v37
	v_fmac_f32_e32 v213, v38, v38
	v_fmac_f32_e32 v213, v39, v39
	v_fmac_f32_e32 v213, v32, v32
	v_fmac_f32_e32 v213, v33, v33
	v_fmac_f32_e32 v213, v34, v34
	v_fmac_f32_e32 v213, v35, v35
	v_cvt_pk_bf16_f32 v196, v36, v37
	v_cvt_pk_bf16_f32 v197, v38, v39
	v_cvt_pk_bf16_f32 v198, v32, v33
	v_cvt_pk_bf16_f32 v199, v34, v35
	global_store_dwordx4 v217, v[196:199], s[80:81] offset:256
	ds_bpermute_b32 v214, v215, v213
	s_waitcnt lgkmcnt(0)
	v_add_f32_e32 v213, v213, v214
	ds_bpermute_b32 v214, v216, v213
	s_waitcnt lgkmcnt(0)
	v_add_f32_e32 v213, v213, v214
	s_mov_b64 exec, 0xffff
	global_atomic_add_f32 v208, v213, s[4:5] offset:576
	s_mov_b64 exec, -1
	v_add_u32_e32 v211, 0xb0000, v209
	global_load_dwordx4 v[192:195], v211, s[80:81]
	global_load_dwordx4 v[196:199], v211, s[80:81] offset:256
	s_waitcnt vmcnt(5)
	v_lshlrev_b32_e32 v184, 16, v176
	v_and_b32_e32 v185, 0xffff0000, v176
	v_lshlrev_b32_e32 v186, 16, v177
	v_and_b32_e32 v187, 0xffff0000, v177
	v_lshlrev_b32_e32 v188, 16, v178
	v_and_b32_e32 v189, 0xffff0000, v178
	v_lshlrev_b32_e32 v190, 16, v179
	v_and_b32_e32 v191, 0xffff0000, v179
	v_pk_add_f32 v[28:29], v[28:29], v[184:185]
	v_pk_add_f32 v[30:31], v[30:31], v[186:187]
	v_pk_add_f32 v[24:25], v[24:25], v[188:189]
	v_pk_add_f32 v[26:27], v[26:27], v[190:191]
	v_mul_f32_e32 v213, v28, v28
	v_fmac_f32_e32 v213, v29, v29
	v_fmac_f32_e32 v213, v30, v30
	v_fmac_f32_e32 v213, v31, v31
	v_fmac_f32_e32 v213, v24, v24
	v_fmac_f32_e32 v213, v25, v25
	v_fmac_f32_e32 v213, v26, v26
	v_fmac_f32_e32 v213, v27, v27
	v_cvt_pk_bf16_f32 v176, v28, v29
	v_cvt_pk_bf16_f32 v177, v30, v31
	v_cvt_pk_bf16_f32 v178, v24, v25
	v_cvt_pk_bf16_f32 v179, v26, v27
	v_add_u32_e32 v217, 0xa0000, v209
	global_store_dwordx4 v217, v[176:179], s[80:81]
	v_lshlrev_b32_e32 v184, 16, v180
	v_and_b32_e32 v185, 0xffff0000, v180
	v_lshlrev_b32_e32 v186, 16, v181
	v_and_b32_e32 v187, 0xffff0000, v181
	v_lshlrev_b32_e32 v188, 16, v182
	v_and_b32_e32 v189, 0xffff0000, v182
	v_lshlrev_b32_e32 v190, 16, v183
	v_and_b32_e32 v191, 0xffff0000, v183
	v_pk_add_f32 v[20:21], v[20:21], v[184:185]
	v_pk_add_f32 v[22:23], v[22:23], v[186:187]
	v_pk_add_f32 v[16:17], v[16:17], v[188:189]
	v_pk_add_f32 v[18:19], v[18:19], v[190:191]
	v_fmac_f32_e32 v213, v20, v20
	v_fmac_f32_e32 v213, v21, v21
	v_fmac_f32_e32 v213, v22, v22
	v_fmac_f32_e32 v213, v23, v23
	v_fmac_f32_e32 v213, v16, v16
	v_fmac_f32_e32 v213, v17, v17
	v_fmac_f32_e32 v213, v18, v18
	v_fmac_f32_e32 v213, v19, v19
	v_cvt_pk_bf16_f32 v180, v20, v21
	v_cvt_pk_bf16_f32 v181, v22, v23
	v_cvt_pk_bf16_f32 v182, v16, v17
	v_cvt_pk_bf16_f32 v183, v18, v19
	global_store_dwordx4 v217, v[180:183], s[80:81] offset:256
	ds_bpermute_b32 v214, v215, v213
	s_waitcnt lgkmcnt(0)
	v_add_f32_e32 v213, v213, v214
	ds_bpermute_b32 v214, v216, v213
	s_waitcnt lgkmcnt(0)
	v_add_f32_e32 v213, v213, v214
	s_mov_b64 exec, 0xffff
	global_atomic_add_f32 v208, v213, s[4:5] offset:640
	s_mov_b64 exec, -1
	s_waitcnt vmcnt(3)
	v_lshlrev_b32_e32 v200, 16, v192
	v_and_b32_e32 v201, 0xffff0000, v192
	v_lshlrev_b32_e32 v202, 16, v193
	v_and_b32_e32 v203, 0xffff0000, v193
	v_lshlrev_b32_e32 v204, 16, v194
	v_and_b32_e32 v205, 0xffff0000, v194
	v_lshlrev_b32_e32 v206, 16, v195
	v_and_b32_e32 v207, 0xffff0000, v195
	v_pk_add_f32 v[12:13], v[12:13], v[200:201]
	v_pk_add_f32 v[14:15], v[14:15], v[202:203]
	v_pk_add_f32 v[8:9], v[8:9], v[204:205]
	v_pk_add_f32 v[10:11], v[10:11], v[206:207]
	v_mul_f32_e32 v213, v12, v12
	v_fmac_f32_e32 v213, v13, v13
	v_fmac_f32_e32 v213, v14, v14
	v_fmac_f32_e32 v213, v15, v15
	v_fmac_f32_e32 v213, v8, v8
	v_fmac_f32_e32 v213, v9, v9
	v_fmac_f32_e32 v213, v10, v10
	v_fmac_f32_e32 v213, v11, v11
	v_cvt_pk_bf16_f32 v192, v12, v13
	v_cvt_pk_bf16_f32 v193, v14, v15
	v_cvt_pk_bf16_f32 v194, v8, v9
	v_cvt_pk_bf16_f32 v195, v10, v11
	v_add_u32_e32 v217, 0xb0000, v209
	global_store_dwordx4 v217, v[192:195], s[80:81]
	v_lshlrev_b32_e32 v200, 16, v196
	v_and_b32_e32 v201, 0xffff0000, v196
	v_lshlrev_b32_e32 v202, 16, v197
	v_and_b32_e32 v203, 0xffff0000, v197
	v_lshlrev_b32_e32 v204, 16, v198
	v_and_b32_e32 v205, 0xffff0000, v198
	v_lshlrev_b32_e32 v206, 16, v199
	v_and_b32_e32 v207, 0xffff0000, v199
	v_pk_add_f32 v[4:5], v[4:5], v[200:201]
	v_pk_add_f32 v[6:7], v[6:7], v[202:203]
	v_pk_add_f32 v[0:1], v[0:1], v[204:205]
	v_pk_add_f32 v[2:3], v[2:3], v[206:207]
	v_fmac_f32_e32 v213, v4, v4
	v_fmac_f32_e32 v213, v5, v5
	v_fmac_f32_e32 v213, v6, v6
	v_fmac_f32_e32 v213, v7, v7
	v_fmac_f32_e32 v213, v0, v0
	v_fmac_f32_e32 v213, v1, v1
	v_fmac_f32_e32 v213, v2, v2
	v_fmac_f32_e32 v213, v3, v3
	v_cvt_pk_bf16_f32 v196, v4, v5
	v_cvt_pk_bf16_f32 v197, v6, v7
	v_cvt_pk_bf16_f32 v198, v0, v1
	v_cvt_pk_bf16_f32 v199, v2, v3
	global_store_dwordx4 v217, v[196:199], s[80:81] offset:256
	ds_bpermute_b32 v214, v215, v213
	s_waitcnt lgkmcnt(0)
	v_add_f32_e32 v213, v213, v214
	ds_bpermute_b32 v214, v216, v213
	s_waitcnt lgkmcnt(0)
	v_add_f32_e32 v213, v213, v214
	s_mov_b64 exec, 0xffff
	global_atomic_add_f32 v208, v213, s[4:5] offset:704
	s_mov_b64 exec, -1
	s_branch .LBB0_752

.LBB0_840:
	ds_read_b128 v[76:79], v171
	ds_read_b128 v[80:83], v220
	ds_read_b128 v[84:87], v171 offset:2048
	ds_read_b128 v[88:91], v220 offset:2048
	s_add_u32 s10, s8, 0x100
	s_addc_u32 s11, s9, 0
	s_cmp_eq_u32 s67, 28
	s_cselect_b32 s43, s33, s11
	s_cselect_b32 s42, s37, s10
	s_cselect_b32 s13, s35, s66
	s_cselect_b32 s12, s64, s65
	s_add_i32 m0, s48, 0xc000
	ds_read_b128 v[92:95], v173
	ds_read_b128 v[96:99], v221
	ds_read_b128 v[100:103], v173 offset:2048
	ds_read_b128 v[104:107], v221 offset:2048
	ds_read_b128 v[188:191], v173 offset:4096
	ds_read_b128 v[192:195], v221 offset:4096
	ds_read_b128 v[196:199], v173 offset:6144
	ds_read_b128 v[200:203], v221 offset:6144
	global_load_lds_dwordx4 v180, s[8:9]
	s_add_i32 m0, s48, 0xe000
	s_nop 0
	global_load_lds_dwordx4 v182, s[8:9]
	s_waitcnt lgkmcnt(8)
	s_barrier
	s_waitcnt lgkmcnt(0)
	s_waitcnt lgkmcnt(0)
	v_mfma_f32_16x16x32_bf16 v[158:161], v[76:79], v[92:95], v[158:161]
	v_mfma_f32_16x16x32_bf16 v[158:161], v[80:83], v[96:99], v[158:161]
	v_mfma_f32_16x16x32_bf16 v[60:63], v[88:91], v[96:99], v[60:63]
	v_mfma_f32_16x16x32_bf16 v[60:63], v[84:87], v[92:95], v[60:63]
	v_mfma_f32_16x16x32_bf16 v[52:55], v[84:87], v[100:103], v[52:55]
	v_mfma_f32_16x16x32_bf16 v[52:55], v[88:91], v[104:107], v[52:55]
	v_mfma_f32_16x16x32_bf16 v[150:153], v[80:83], v[104:107], v[150:153]
	v_mfma_f32_16x16x32_bf16 v[150:153], v[76:79], v[100:103], v[150:153]
	v_mfma_f32_16x16x32_bf16 v[146:149], v[76:79], v[188:191], v[146:149]
	v_mfma_f32_16x16x32_bf16 v[146:149], v[80:83], v[192:195], v[146:149]
	v_mfma_f32_16x16x32_bf16 v[48:51], v[88:91], v[192:195], v[48:51]
	v_mfma_f32_16x16x32_bf16 v[48:51], v[84:87], v[188:191], v[48:51]
	v_mfma_f32_16x16x32_bf16 v[40:43], v[84:87], v[196:199], v[40:43]
	v_mfma_f32_16x16x32_bf16 v[40:43], v[88:91], v[200:203], v[40:43]
	v_mfma_f32_16x16x32_bf16 v[138:141], v[80:83], v[200:203], v[138:141]
	v_mfma_f32_16x16x32_bf16 v[138:141], v[76:79], v[196:199], v[138:141]
	s_barrier
	s_add_i32 s8, s60, s46
	s_add_u32 s98, s12, s18
	s_addc_u32 s99, s13, s19
	s_mov_b32 m0, s8
	ds_read_b128 v[204:207], v175
	ds_read_b128 v[208:211], v238
	ds_read_b128 v[212:215], v175 offset:2048
	ds_read_b128 v[216:219], v238 offset:2048
	global_load_lds_dwordx4 v164, s[12:13]
	s_add_i32 m0, s8, 0x2000
	s_nop 0
	global_load_lds_dwordx4 v166, s[12:13]
	s_barrier
	s_waitcnt lgkmcnt(0)
	s_waitcnt lgkmcnt(0)
	v_mfma_f32_16x16x32_bf16 v[154:157], v[204:207], v[92:95], v[154:157]
	v_mfma_f32_16x16x32_bf16 v[154:157], v[208:211], v[96:99], v[154:157]
	v_mfma_f32_16x16x32_bf16 v[56:59], v[216:219], v[96:99], v[56:59]
	v_mfma_f32_16x16x32_bf16 v[56:59], v[212:215], v[92:95], v[56:59]
	v_mfma_f32_16x16x32_bf16 v[44:47], v[212:215], v[100:103], v[44:47]
	v_mfma_f32_16x16x32_bf16 v[44:47], v[216:219], v[104:107], v[44:47]
	v_mfma_f32_16x16x32_bf16 v[36:39], v[216:219], v[192:195], v[36:39]
	v_mfma_f32_16x16x32_bf16 v[36:39], v[212:215], v[188:191], v[36:39]
	v_mfma_f32_16x16x32_bf16 v[32:35], v[212:215], v[196:199], v[32:35]
	v_mfma_f32_16x16x32_bf16 v[32:35], v[216:219], v[200:203], v[32:35]
	v_mfma_f32_16x16x32_bf16 v[92:95], v[204:207], v[100:103], v[142:145]
	v_mfma_f32_16x16x32_bf16 v[92:95], v[208:211], v[104:107], v[92:95]
	v_mfma_f32_16x16x32_bf16 v[96:99], v[208:211], v[192:195], v[134:137]
	v_mfma_f32_16x16x32_bf16 v[96:99], v[204:207], v[188:191], v[96:99]
	v_mfma_f32_16x16x32_bf16 v[100:103], v[204:207], v[196:199], v[130:133]
	v_mfma_f32_16x16x32_bf16 v[100:103], v[208:211], v[200:203], v[100:103]
	s_mov_b32 m0, s48
	s_add_u32 s100, s42, s18
	s_addc_u32 s101, s43, s19
	s_barrier
	ds_read_b128 v[104:107], v173 offset:16384
	ds_read_b128 v[130:133], v221 offset:16384
	ds_read_b128 v[134:137], v173 offset:18432
	ds_read_b128 v[142:145], v221 offset:18432
	ds_read_b128 v[188:191], v173 offset:20480
	ds_read_b128 v[192:195], v221 offset:20480
	ds_read_b128 v[196:199], v173 offset:22528
	ds_read_b128 v[200:203], v221 offset:22528
	global_load_lds_dwordx4 v178, s[42:43]
	s_mov_b32 m0, s49
	s_nop 0
	global_load_lds_dwordx4 v176, s[42:43]
	s_barrier
	s_waitcnt lgkmcnt(0)
	s_waitcnt lgkmcnt(0)
	v_mfma_f32_16x16x32_bf16 v[126:129], v[76:79], v[104:107], v[126:129]
	v_mfma_f32_16x16x32_bf16 v[126:129], v[80:83], v[130:133], v[126:129]
	v_mfma_f32_16x16x32_bf16 v[28:31], v[88:91], v[130:133], v[28:31]
	v_mfma_f32_16x16x32_bf16 v[28:31], v[84:87], v[104:107], v[28:31]
	v_mfma_f32_16x16x32_bf16 v[24:27], v[84:87], v[134:137], v[24:27]
	v_mfma_f32_16x16x32_bf16 v[24:27], v[88:91], v[142:145], v[24:27]
	v_mfma_f32_16x16x32_bf16 v[122:125], v[80:83], v[142:145], v[122:125]
	v_mfma_f32_16x16x32_bf16 v[122:125], v[76:79], v[134:137], v[122:125]
	v_mfma_f32_16x16x32_bf16 v[114:117], v[76:79], v[188:191], v[114:117]
	v_mfma_f32_16x16x32_bf16 v[114:117], v[80:83], v[192:195], v[114:117]
	v_mfma_f32_16x16x32_bf16 v[20:23], v[88:91], v[192:195], v[20:23]
	v_mfma_f32_16x16x32_bf16 v[20:23], v[84:87], v[188:191], v[20:23]
	v_mfma_f32_16x16x32_bf16 v[4:7], v[84:87], v[196:199], v[4:7]
	v_mfma_f32_16x16x32_bf16 v[4:7], v[88:91], v[200:203], v[4:7]
	v_mfma_f32_16x16x32_bf16 v[72:75], v[80:83], v[200:203], v[72:75]
	v_mfma_f32_16x16x32_bf16 v[72:75], v[76:79], v[196:199], v[72:75]
	s_barrier
	s_add_u32 s8, s12, 0x1600000
	s_addc_u32 s9, s13, 0
	s_add_i32 s68, s61, s46
	s_mov_b32 m0, s68
	s_nop 0
	global_load_lds_dwordx4 v164, s[8:9]
	s_add_i32 m0, s68, 0x2000
	s_nop 0
	global_load_lds_dwordx4 v166, s[8:9]
	s_waitcnt vmcnt(6)
	s_barrier
	v_mfma_f32_16x16x32_bf16 v[16:19], v[212:215], v[104:107], v[16:19]
	v_mfma_f32_16x16x32_bf16 v[16:19], v[216:219], v[130:133], v[16:19]
	v_mfma_f32_16x16x32_bf16 v[12:15], v[216:219], v[142:145], v[12:15]
	v_mfma_f32_16x16x32_bf16 v[12:15], v[212:215], v[134:137], v[12:15]
	v_mfma_f32_16x16x32_bf16 v[8:11], v[212:215], v[188:191], v[8:11]
	v_mfma_f32_16x16x32_bf16 v[8:11], v[216:219], v[192:195], v[8:11]
	v_mfma_f32_16x16x32_bf16 v[68:71], v[208:211], v[192:195], v[68:71]
	v_mfma_f32_16x16x32_bf16 v[68:71], v[204:207], v[188:191], v[68:71]
	v_mfma_f32_16x16x32_bf16 v[64:67], v[204:207], v[196:199], v[64:67]
	v_mfma_f32_16x16x32_bf16 v[64:67], v[208:211], v[200:203], v[64:67]
	v_mfma_f32_16x16x32_bf16 v[0:3], v[216:219], v[200:203], v[0:3]
	v_mfma_f32_16x16x32_bf16 v[0:3], v[212:215], v[196:199], v[0:3]
	v_mfma_f32_16x16x32_bf16 v[76:79], v[204:207], v[104:107], v[118:121]
	v_mfma_f32_16x16x32_bf16 v[76:79], v[208:211], v[130:133], v[76:79]
	v_mfma_f32_16x16x32_bf16 v[80:83], v[208:211], v[142:145], v[110:113]
	v_mfma_f32_16x16x32_bf16 v[80:83], v[204:207], v[134:137], v[80:83]
	s_add_i32 s68, 0, 0x18000
	s_barrier
	ds_read_b128 v[84:87], v239
	ds_read_b128 v[88:91], v240
	ds_read_b128 v[104:107], v239 offset:2048
	ds_read_b128 v[108:111], v240 offset:2048
	s_add_u32 s8, s42, 0x40000
	s_addc_u32 s9, s43, 0
	s_mov_b32 m0, s50
	ds_read_b128 v[118:121], v173 offset:32768
	ds_read_b128 v[130:133], v221 offset:32768
	ds_read_b128 v[134:137], v173 offset:34816
	ds_read_b128 v[188:191], v221 offset:34816
	ds_read_b128 v[192:195], v173 offset:36864
	ds_read_b128 v[196:199], v221 offset:36864
	ds_read_b128 v[200:203], v173 offset:38912
	ds_read_b128 v[204:207], v221 offset:38912
	global_load_lds_dwordx4 v178, s[8:9]
	s_mov_b32 m0, s51
	s_nop 0
	global_load_lds_dwordx4 v176, s[8:9]
	s_waitcnt lgkmcnt(8)
	s_barrier
	s_waitcnt lgkmcnt(0)
	s_waitcnt lgkmcnt(0)
	v_mfma_f32_16x16x32_bf16 v[142:145], v[84:87], v[118:121], v[158:161]
	v_mfma_f32_16x16x32_bf16 v[158:161], v[88:91], v[130:133], v[142:145]
	v_mfma_f32_16x16x32_bf16 v[60:63], v[108:111], v[130:133], v[60:63]
	v_mfma_f32_16x16x32_bf16 v[60:63], v[104:107], v[118:121], v[60:63]
	v_mfma_f32_16x16x32_bf16 v[52:55], v[104:107], v[134:137], v[52:55]
	v_mfma_f32_16x16x32_bf16 v[52:55], v[108:111], v[188:191], v[52:55]
	v_mfma_f32_16x16x32_bf16 v[48:51], v[108:111], v[196:199], v[48:51]
	v_mfma_f32_16x16x32_bf16 v[48:51], v[104:107], v[192:195], v[48:51]
	v_mfma_f32_16x16x32_bf16 v[40:43], v[104:107], v[200:203], v[40:43]
	v_mfma_f32_16x16x32_bf16 v[40:43], v[108:111], v[204:207], v[40:43]
	v_mfma_f32_16x16x32_bf16 v[138:141], v[88:91], v[204:207], v[138:141]
	v_mfma_f32_16x16x32_bf16 v[138:141], v[84:87], v[200:203], v[138:141]
	v_mfma_f32_16x16x32_bf16 v[142:145], v[84:87], v[134:137], v[150:153]
	v_mfma_f32_16x16x32_bf16 v[150:153], v[88:91], v[188:191], v[142:145]
	v_mfma_f32_16x16x32_bf16 v[142:145], v[84:87], v[192:195], v[146:149]
	v_mfma_f32_16x16x32_bf16 v[146:149], v[88:91], v[196:199], v[142:145]
	s_barrier
	s_add_i32 s42, 0, 0x1c000
	s_add_i32 s8, s68, s46
	ds_read_b128 v[208:211], v241
	ds_read_b128 v[212:215], v242
	ds_read_b128 v[216:219], v241 offset:2048
	ds_read_b128 v[234:237], v242 offset:2048
	s_mov_b32 m0, s8
	s_nop 0
	global_load_lds_dwordx4 v164, s[98:99]
	s_add_i32 m0, s8, 0x2000
	s_nop 0
	global_load_lds_dwordx4 v166, s[98:99]
	s_barrier
	s_waitcnt lgkmcnt(0)
	s_waitcnt lgkmcnt(0)
	v_mfma_f32_16x16x32_bf16 v[142:145], v[208:211], v[118:121], v[154:157]
	v_mfma_f32_16x16x32_bf16 v[154:157], v[212:215], v[130:133], v[142:145]
	v_mfma_f32_16x16x32_bf16 v[56:59], v[234:237], v[130:133], v[56:59]
	v_mfma_f32_16x16x32_bf16 v[56:59], v[216:219], v[118:121], v[56:59]
	v_mfma_f32_16x16x32_bf16 v[44:47], v[216:219], v[134:137], v[44:47]
	v_mfma_f32_16x16x32_bf16 v[44:47], v[234:237], v[188:191], v[44:47]
	v_mfma_f32_16x16x32_bf16 v[36:39], v[234:237], v[196:199], v[36:39]
	v_mfma_f32_16x16x32_bf16 v[36:39], v[216:219], v[192:195], v[36:39]
	v_mfma_f32_16x16x32_bf16 v[32:35], v[216:219], v[200:203], v[32:35]
	v_mfma_f32_16x16x32_bf16 v[32:35], v[234:237], v[204:207], v[32:35]
	v_mfma_f32_16x16x32_bf16 v[92:95], v[208:211], v[134:137], v[92:95]
	v_mfma_f32_16x16x32_bf16 v[142:145], v[212:215], v[188:191], v[92:95]
	v_mfma_f32_16x16x32_bf16 v[92:95], v[208:211], v[192:195], v[96:99]
	v_mfma_f32_16x16x32_bf16 v[134:137], v[212:215], v[196:199], v[92:95]
	v_mfma_f32_16x16x32_bf16 v[92:95], v[208:211], v[200:203], v[100:103]
	v_mfma_f32_16x16x32_bf16 v[130:133], v[212:215], v[204:207], v[92:95]
	s_mov_b32 m0, s54
	s_barrier
	ds_read_b128 v[92:95], v173 offset:49152
	ds_read_b128 v[96:99], v221 offset:49152
	ds_read_b128 v[100:103], v173 offset:51200
	ds_read_b128 v[188:191], v221 offset:51200
	ds_read_b128 v[192:195], v173 offset:53248
	ds_read_b128 v[196:199], v221 offset:53248
	ds_read_b128 v[200:203], v173 offset:55296
	ds_read_b128 v[204:207], v221 offset:55296
	global_load_lds_dwordx4 v178, s[100:101]
	s_mov_b32 m0, s55
	s_nop 0
	global_load_lds_dwordx4 v176, s[100:101]
	s_barrier
	s_waitcnt lgkmcnt(0)
	s_waitcnt lgkmcnt(0)
	v_mfma_f32_16x16x32_bf16 v[118:121], v[84:87], v[92:95], v[126:129]
	v_mfma_f32_16x16x32_bf16 v[126:129], v[88:91], v[96:99], v[118:121]
	v_mfma_f32_16x16x32_bf16 v[28:31], v[108:111], v[96:99], v[28:31]
	v_mfma_f32_16x16x32_bf16 v[28:31], v[104:107], v[92:95], v[28:31]
	v_mfma_f32_16x16x32_bf16 v[24:27], v[104:107], v[100:103], v[24:27]
	v_mfma_f32_16x16x32_bf16 v[24:27], v[108:111], v[188:191], v[24:27]
	v_mfma_f32_16x16x32_bf16 v[20:23], v[108:111], v[196:199], v[20:23]
	v_mfma_f32_16x16x32_bf16 v[20:23], v[104:107], v[192:195], v[20:23]
	v_mfma_f32_16x16x32_bf16 v[112:115], v[84:87], v[192:195], v[114:117]
	v_mfma_f32_16x16x32_bf16 v[114:117], v[88:91], v[196:199], v[112:115]
	v_mfma_f32_16x16x32_bf16 v[72:75], v[88:91], v[204:207], v[72:75]
	v_mfma_f32_16x16x32_bf16 v[72:75], v[84:87], v[200:203], v[72:75]
	v_mfma_f32_16x16x32_bf16 v[118:121], v[84:87], v[100:103], v[122:125]
	v_mfma_f32_16x16x32_bf16 v[122:125], v[88:91], v[188:191], v[118:121]
	v_mfma_f32_16x16x32_bf16 v[4:7], v[104:107], v[200:203], v[4:7]
	v_mfma_f32_16x16x32_bf16 v[4:7], v[108:111], v[204:207], v[4:7]
	s_barrier
	s_add_u32 s8, s12, 0x1600080
	s_addc_u32 s9, s13, 0
	s_add_i32 s12, s42, s46
	s_mov_b32 m0, s12
	s_nop 0
	global_load_lds_dwordx4 v164, s[8:9]
	s_add_i32 m0, s12, 0x2000
	s_nop 0
	global_load_lds_dwordx4 v166, s[8:9]
	s_waitcnt vmcnt(6)
	s_barrier
	v_mfma_f32_16x16x32_bf16 v[76:79], v[208:211], v[92:95], v[76:79]
	v_mfma_f32_16x16x32_bf16 v[118:121], v[212:215], v[96:99], v[76:79]
	v_mfma_f32_16x16x32_bf16 v[16:19], v[234:237], v[96:99], v[16:19]
	v_mfma_f32_16x16x32_bf16 v[16:19], v[216:219], v[92:95], v[16:19]
	v_mfma_f32_16x16x32_bf16 v[12:15], v[216:219], v[100:103], v[12:15]
	v_mfma_f32_16x16x32_bf16 v[12:15], v[234:237], v[188:191], v[12:15]
	v_mfma_f32_16x16x32_bf16 v[8:11], v[234:237], v[196:199], v[8:11]
	v_mfma_f32_16x16x32_bf16 v[8:11], v[216:219], v[192:195], v[8:11]
	v_mfma_f32_16x16x32_bf16 v[68:71], v[208:211], v[192:195], v[68:71]
	v_mfma_f32_16x16x32_bf16 v[68:71], v[212:215], v[196:199], v[68:71]
	v_mfma_f32_16x16x32_bf16 v[64:67], v[212:215], v[204:207], v[64:67]
	v_mfma_f32_16x16x32_bf16 v[64:67], v[208:211], v[200:203], v[64:67]
	v_mfma_f32_16x16x32_bf16 v[76:79], v[208:211], v[100:103], v[80:83]
	v_mfma_f32_16x16x32_bf16 v[110:113], v[212:215], v[188:191], v[76:79]
	v_mfma_f32_16x16x32_bf16 v[0:3], v[216:219], v[200:203], v[0:3]
	v_mfma_f32_16x16x32_bf16 v[0:3], v[234:237], v[204:207], v[0:3]
	s_add_i32 s67, s67, 2
	s_add_u32 s65, s65, 0x100
	s_addc_u32 s66, s66, 0
	s_cmp_gt_u32 s67, 29
	s_mov_b64 s[8:9], s[10:11]
	s_barrier
	s_cbranch_scc0 .LBB0_840
	s_lshl_b32 s8, s0, 8
	s_add_i32 s8, s8, s58
	s_lshl_b32 s9, s1, 7
	s_add_i32 s9, s9, s53
	s_lshl_b32 s10, s0, 3
	s_lshr_b32 s11, s58, 5
	s_add_i32 s10, s10, s11
	v_add_u32_e32 v200, s8, v163
	v_lshlrev_b32_e32 v213, 2, v200
	global_load_dword v188, v213, s[4:5]
	global_load_dword v189, v213, s[4:5] offset:64
	global_load_dword v190, v213, s[4:5] offset:128
	global_load_dword v191, v213, s[4:5] offset:192
	global_load_dword v192, v213, s[4:5] offset:256
	global_load_dword v193, v213, s[4:5] offset:320
	global_load_dword v194, v213, s[4:5] offset:384
	global_load_dword v195, v213, s[4:5] offset:448
	v_lshl_add_u32 v201, v225, 3, s9
	v_lshlrev_b32_e32 v212, 2, v201
	v_add_u32_e32 v213, 0x21000, v212
	global_load_dwordx4 v[76:79], v213, s[82:83]
	v_add_u32_e32 v213, 0x2c000, v212
	global_load_dwordx4 v[80:83], v213, s[82:83]
	v_add_u32_e32 v213, 0x37000, v212
	global_load_dwordx4 v[84:87], v213, s[82:83]
	v_add_u32_e32 v213, 0xb000, v212
	global_load_dwordx4 v[88:91], v213, s[84:85]
	v_add_u32_e32 v213, 0x26800, v212
	global_load_dwordx4 v[92:95], v213, s[82:83]
	v_add_u32_e32 v213, 0x31800, v212
	global_load_dwordx4 v[96:99], v213, s[82:83]
	v_add_u32_e32 v213, 0x3c800, v212
	global_load_dwordx4 v[100:103], v213, s[82:83]
	v_add_u32_e32 v213, 0x10800, v212
	global_load_dwordx4 v[104:107], v213, s[84:85]
	v_mul_u32_u24_e32 v215, 0x2c00, v200
	v_lshl_add_u32 v215, v201, 1, v215
	v_add_u32_e32 v213, s10, v163
	v_mul_u32_u24_e32 v217, 0xb000, v213
	v_add_u32_e32 v217, v217, v212
	v_cmp_gt_u32_e64 s[8:9], 2, v163
	v_cmp_lt_u32_e64 s[10:11], 13, v163
	v_cmp_lt_u32_e32 vcc, 1, v163
	v_mov_b32_e32 v214, 1.0
	v_mov_b32_e32 v216, 0xbfb8aa3b
	v_mov_b32_e32 v108, 0x3727c5ac
	s_waitcnt vmcnt(8)
	v_fmamk_f32 v188, v188, 0x3a000000, v108
	v_fmamk_f32 v189, v189, 0x3a000000, v108
	v_fmamk_f32 v190, v190, 0x3a000000, v108
	v_fmamk_f32 v191, v191, 0x3a000000, v108
	v_fmamk_f32 v192, v192, 0x3a000000, v108
	v_fmamk_f32 v193, v193, 0x3a000000, v108
	v_fmamk_f32 v194, v194, 0x3a000000, v108
	v_fmamk_f32 v195, v195, 0x3a000000, v108
	v_rsq_f32_e32 v188, v188
	v_rsq_f32_e32 v189, v189
	v_rsq_f32_e32 v190, v190
	v_rsq_f32_e32 v191, v191
	v_rsq_f32_e32 v192, v192
	v_rsq_f32_e32 v193, v193
	v_rsq_f32_e32 v194, v194
	v_rsq_f32_e32 v195, v195
	v_pk_mul_f32 v[158:159], v[158:159], v[188:189] op_sel_hi:[1,0]
	v_pk_mul_f32 v[160:161], v[160:161], v[188:189] op_sel_hi:[1,0]
	v_pk_mul_f32 v[60:61], v[60:61], v[188:189] op_sel_hi:[1,0]
	v_pk_mul_f32 v[62:63], v[62:63], v[188:189] op_sel_hi:[1,0]
	v_pk_mul_f32 v[154:155], v[154:155], v[188:189] op_sel_hi:[1,0]
	v_pk_mul_f32 v[156:157], v[156:157], v[188:189] op_sel_hi:[1,0]
	v_pk_mul_f32 v[56:57], v[56:57], v[188:189] op_sel_hi:[1,0]
	v_pk_mul_f32 v[58:59], v[58:59], v[188:189] op_sel_hi:[1,0]
	v_pk_mul_f32 v[150:151], v[150:151], v[188:189] op_sel:[0,1] op_sel_hi:[1,1]
	v_pk_mul_f32 v[152:153], v[152:153], v[188:189] op_sel:[0,1] op_sel_hi:[1,1]
	v_pk_mul_f32 v[52:53], v[52:53], v[188:189] op_sel:[0,1] op_sel_hi:[1,1]
	v_pk_mul_f32 v[54:55], v[54:55], v[188:189] op_sel:[0,1] op_sel_hi:[1,1]
	v_pk_mul_f32 v[142:143], v[142:143], v[188:189] op_sel:[0,1] op_sel_hi:[1,1]
	v_pk_mul_f32 v[144:145], v[144:145], v[188:189] op_sel:[0,1] op_sel_hi:[1,1]
	v_pk_mul_f32 v[44:45], v[44:45], v[188:189] op_sel:[0,1] op_sel_hi:[1,1]
	v_pk_mul_f32 v[46:47], v[46:47], v[188:189] op_sel:[0,1] op_sel_hi:[1,1]
	v_pk_mul_f32 v[146:147], v[146:147], v[190:191] op_sel_hi:[1,0]
	v_pk_mul_f32 v[148:149], v[148:149], v[190:191] op_sel_hi:[1,0]
	v_pk_mul_f32 v[48:49], v[48:49], v[190:191] op_sel_hi:[1,0]
	v_pk_mul_f32 v[50:51], v[50:51], v[190:191] op_sel_hi:[1,0]
	v_pk_mul_f32 v[134:135], v[134:135], v[190:191] op_sel_hi:[1,0]
	v_pk_mul_f32 v[136:137], v[136:137], v[190:191] op_sel_hi:[1,0]
	v_pk_mul_f32 v[36:37], v[36:37], v[190:191] op_sel_hi:[1,0]
	v_pk_mul_f32 v[38:39], v[38:39], v[190:191] op_sel_hi:[1,0]
	v_pk_mul_f32 v[138:139], v[138:139], v[190:191] op_sel:[0,1] op_sel_hi:[1,1]
	v_pk_mul_f32 v[140:141], v[140:141], v[190:191] op_sel:[0,1] op_sel_hi:[1,1]
	v_pk_mul_f32 v[40:41], v[40:41], v[190:191] op_sel:[0,1] op_sel_hi:[1,1]
	v_pk_mul_f32 v[42:43], v[42:43], v[190:191] op_sel:[0,1] op_sel_hi:[1,1]
	v_pk_mul_f32 v[130:131], v[130:131], v[190:191] op_sel:[0,1] op_sel_hi:[1,1]
	v_pk_mul_f32 v[132:133], v[132:133], v[190:191] op_sel:[0,1] op_sel_hi:[1,1]
	v_pk_mul_f32 v[32:33], v[32:33], v[190:191] op_sel:[0,1] op_sel_hi:[1,1]
	v_pk_mul_f32 v[34:35], v[34:35], v[190:191] op_sel:[0,1] op_sel_hi:[1,1]
	v_pk_mul_f32 v[126:127], v[126:127], v[192:193] op_sel_hi:[1,0]
	v_pk_mul_f32 v[128:129], v[128:129], v[192:193] op_sel_hi:[1,0]
	v_pk_mul_f32 v[28:29], v[28:29], v[192:193] op_sel_hi:[1,0]
	v_pk_mul_f32 v[30:31], v[30:31], v[192:193] op_sel_hi:[1,0]
	v_pk_mul_f32 v[118:119], v[118:119], v[192:193] op_sel_hi:[1,0]
	v_pk_mul_f32 v[120:121], v[120:121], v[192:193] op_sel_hi:[1,0]
	v_pk_mul_f32 v[16:17], v[16:17], v[192:193] op_sel_hi:[1,0]
	v_pk_mul_f32 v[18:19], v[18:19], v[192:193] op_sel_hi:[1,0]
	v_pk_mul_f32 v[122:123], v[122:123], v[192:193] op_sel:[0,1] op_sel_hi:[1,1]
	v_pk_mul_f32 v[124:125], v[124:125], v[192:193] op_sel:[0,1] op_sel_hi:[1,1]
	v_pk_mul_f32 v[24:25], v[24:25], v[192:193] op_sel:[0,1] op_sel_hi:[1,1]
	v_pk_mul_f32 v[26:27], v[26:27], v[192:193] op_sel:[0,1] op_sel_hi:[1,1]
	v_pk_mul_f32 v[110:111], v[110:111], v[192:193] op_sel:[0,1] op_sel_hi:[1,1]
	v_pk_mul_f32 v[112:113], v[112:113], v[192:193] op_sel:[0,1] op_sel_hi:[1,1]
	v_pk_mul_f32 v[12:13], v[12:13], v[192:193] op_sel:[0,1] op_sel_hi:[1,1]
	v_pk_mul_f32 v[14:15], v[14:15], v[192:193] op_sel:[0,1] op_sel_hi:[1,1]
	v_pk_mul_f32 v[114:115], v[114:115], v[194:195] op_sel_hi:[1,0]
	v_pk_mul_f32 v[116:117], v[116:117], v[194:195] op_sel_hi:[1,0]
	v_pk_mul_f32 v[20:21], v[20:21], v[194:195] op_sel_hi:[1,0]
	v_pk_mul_f32 v[22:23], v[22:23], v[194:195] op_sel_hi:[1,0]
	v_pk_mul_f32 v[68:69], v[68:69], v[194:195] op_sel_hi:[1,0]
	v_pk_mul_f32 v[70:71], v[70:71], v[194:195] op_sel_hi:[1,0]
	v_pk_mul_f32 v[8:9], v[8:9], v[194:195] op_sel_hi:[1,0]
	v_pk_mul_f32 v[10:11], v[10:11], v[194:195] op_sel_hi:[1,0]
	v_pk_mul_f32 v[72:73], v[72:73], v[194:195] op_sel:[0,1] op_sel_hi:[1,1]
	v_pk_mul_f32 v[74:75], v[74:75], v[194:195] op_sel:[0,1] op_sel_hi:[1,1]
	v_pk_mul_f32 v[4:5], v[4:5], v[194:195] op_sel:[0,1] op_sel_hi:[1,1]
	v_pk_mul_f32 v[6:7], v[6:7], v[194:195] op_sel:[0,1] op_sel_hi:[1,1]
	v_pk_mul_f32 v[64:65], v[64:65], v[194:195] op_sel:[0,1] op_sel_hi:[1,1]
	v_pk_mul_f32 v[66:67], v[66:67], v[194:195] op_sel:[0,1] op_sel_hi:[1,1]
	v_pk_mul_f32 v[0:1], v[0:1], v[194:195] op_sel:[0,1] op_sel_hi:[1,1]
	v_pk_mul_f32 v[2:3], v[2:3], v[194:195] op_sel:[0,1] op_sel_hi:[1,1]
	s_nop 1
	s_mov_b64 exec, s[8:9]
	v_add_u32_e32 v213, 0x5800, v217
	global_store_dwordx4 v217, v[158:161], s[70:71]
	global_store_dwordx4 v213, v[154:157], s[70:71]
	global_store_dwordx4 v217, v[60:63], s[70:71] offset:16
	global_store_dwordx4 v213, v[56:59], s[70:71] offset:16
	s_mov_b64 exec, s[10:11]
	v_add_u32_e32 v213, 0xfff7c000, v217
	global_store_dwordx4 v213, v[72:75], s[70:71]
	global_store_dwordx4 v213, v[4:7], s[70:71] offset:16
	v_add_u32_e32 v213, 0xfff81800, v217
	global_store_dwordx4 v213, v[64:67], s[70:71]
	global_store_dwordx4 v213, v[0:3], s[70:71] offset:16
	s_mov_b64 exec, -1
	v_add_u32_e32 v213, 0x3c800, v212
	global_load_dwordx4 v[204:207], v213, s[82:83] offset:16
	v_add_u32_e32 v213, 0x10800, v212
	global_load_dwordx4 v[208:211], v213, s[84:85] offset:16
	s_waitcnt vmcnt(10)
	v_pk_fma_f32 v[188:189], v[158:159], v[84:85], v[88:89]
	v_pk_fma_f32 v[190:191], v[160:161], v[86:87], v[90:91]
	v_pk_fma_f32 v[192:193], v[154:155], v[100:101], v[104:105]
	v_pk_fma_f32 v[194:195], v[156:157], v[102:103], v[106:107]
	v_fmac_f32_dpp v188, v158, v80 row_shr:1 row_mask:0xf bank_mask:0xf
	v_fmac_f32_dpp v189, v159, v81 row_shr:1 row_mask:0xf bank_mask:0xf
	v_fmac_f32_dpp v190, v160, v82 row_shr:1 row_mask:0xf bank_mask:0xf
	v_fmac_f32_dpp v191, v161, v83 row_shr:1 row_mask:0xf bank_mask:0xf
	v_fmac_f32_dpp v192, v154, v96 row_shr:1 row_mask:0xf bank_mask:0xf
	v_fmac_f32_dpp v193, v155, v97 row_shr:1 row_mask:0xf bank_mask:0xf
	v_fmac_f32_dpp v194, v156, v98 row_shr:1 row_mask:0xf bank_mask:0xf
	v_fmac_f32_dpp v195, v157, v99 row_shr:1 row_mask:0xf bank_mask:0xf
	v_fmac_f32_dpp v188, v158, v76 row_shr:2 row_mask:0xf bank_mask:0xf
	v_fmac_f32_dpp v189, v159, v77 row_shr:2 row_mask:0xf bank_mask:0xf
	v_fmac_f32_dpp v190, v160, v78 row_shr:2 row_mask:0xf bank_mask:0xf
	v_fmac_f32_dpp v191, v161, v79 row_shr:2 row_mask:0xf bank_mask:0xf
	v_fmac_f32_dpp v192, v154, v92 row_shr:2 row_mask:0xf bank_mask:0xf
	v_fmac_f32_dpp v193, v155, v93 row_shr:2 row_mask:0xf bank_mask:0xf
	v_fmac_f32_dpp v194, v156, v94 row_shr:2 row_mask:0xf bank_mask:0xf
	v_fmac_f32_dpp v195, v157, v95 row_shr:2 row_mask:0xf bank_mask:0xf
	v_pk_mul_f32 v[196:197], v[188:189], v[216:217] op_sel_hi:[1,0]
	v_pk_mul_f32 v[198:199], v[190:191], v[216:217] op_sel_hi:[1,0]
	v_exp_f32_e32 v196, v196
	v_exp_f32_e32 v197, v197
	v_exp_f32_e32 v198, v198
	v_exp_f32_e32 v199, v199
	v_pk_add_f32 v[196:197], v[196:197], v[214:215] op_sel_hi:[1,0]
	v_pk_add_f32 v[198:199], v[198:199], v[214:215] op_sel_hi:[1,0]
	v_rcp_f32_e32 v196, v196
	v_rcp_f32_e32 v197, v197
	v_rcp_f32_e32 v198, v198
	v_rcp_f32_e32 v199, v199
	v_pk_mul_f32 v[188:189], v[188:189], v[196:197]
	v_pk_mul_f32 v[190:191], v[190:191], v[198:199]
	v_pk_mul_f32 v[188:189], v[188:189], v[192:193]
	v_pk_mul_f32 v[190:191], v[190:191], v[194:195]
	v_cvt_pk_bf16_f32 v200, v188, v189
	v_cvt_pk_bf16_f32 v201, v190, v191
	v_pk_fma_f32 v[188:189], v[150:151], v[84:85], v[88:89]
	v_pk_fma_f32 v[190:191], v[152:153], v[86:87], v[90:91]
	v_pk_fma_f32 v[192:193], v[142:143], v[100:101], v[104:105]
	v_pk_fma_f32 v[194:195], v[144:145], v[102:103], v[106:107]
	v_fmac_f32_dpp v188, v150, v80 row_shr:1 row_mask:0xf bank_mask:0xf
	v_fmac_f32_dpp v189, v151, v81 row_shr:1 row_mask:0xf bank_mask:0xf
	v_fmac_f32_dpp v190, v152, v82 row_shr:1 row_mask:0xf bank_mask:0xf
	v_fmac_f32_dpp v191, v153, v83 row_shr:1 row_mask:0xf bank_mask:0xf
	v_fmac_f32_dpp v192, v142, v96 row_shr:1 row_mask:0xf bank_mask:0xf
	v_fmac_f32_dpp v193, v143, v97 row_shr:1 row_mask:0xf bank_mask:0xf
	v_fmac_f32_dpp v194, v144, v98 row_shr:1 row_mask:0xf bank_mask:0xf
	v_fmac_f32_dpp v195, v145, v99 row_shr:1 row_mask:0xf bank_mask:0xf
	v_fmac_f32_dpp v188, v150, v76 row_shr:2 row_mask:0xf bank_mask:0xf
	v_fmac_f32_dpp v189, v151, v77 row_shr:2 row_mask:0xf bank_mask:0xf
	v_fmac_f32_dpp v190, v152, v78 row_shr:2 row_mask:0xf bank_mask:0xf
	v_fmac_f32_dpp v191, v153, v79 row_shr:2 row_mask:0xf bank_mask:0xf
	v_fmac_f32_dpp v192, v142, v92 row_shr:2 row_mask:0xf bank_mask:0xf
	v_fmac_f32_dpp v193, v143, v93 row_shr:2 row_mask:0xf bank_mask:0xf
	v_fmac_f32_dpp v194, v144, v94 row_shr:2 row_mask:0xf bank_mask:0xf
	v_fmac_f32_dpp v195, v145, v95 row_shr:2 row_mask:0xf bank_mask:0xf
	v_fmac_f32_dpp v188, v158, v80 row_shl:15 row_mask:0xf bank_mask:0xf
	v_fmac_f32_dpp v189, v159, v81 row_shl:15 row_mask:0xf bank_mask:0xf
	v_fmac_f32_dpp v190, v160, v82 row_shl:15 row_mask:0xf bank_mask:0xf
	v_fmac_f32_dpp v191, v161, v83 row_shl:15 row_mask:0xf bank_mask:0xf
	v_fmac_f32_dpp v192, v154, v96 row_shl:15 row_mask:0xf bank_mask:0xf
	v_fmac_f32_dpp v193, v155, v97 row_shl:15 row_mask:0xf bank_mask:0xf
	v_fmac_f32_dpp v194, v156, v98 row_shl:15 row_mask:0xf bank_mask:0xf
	v_fmac_f32_dpp v195, v157, v99 row_shl:15 row_mask:0xf bank_mask:0xf
	v_fmac_f32_dpp v188, v158, v76 row_shl:14 row_mask:0xf bank_mask:0xf
	v_fmac_f32_dpp v189, v159, v77 row_shl:14 row_mask:0xf bank_mask:0xf
	v_fmac_f32_dpp v190, v160, v78 row_shl:14 row_mask:0xf bank_mask:0xf
	v_fmac_f32_dpp v191, v161, v79 row_shl:14 row_mask:0xf bank_mask:0xf
	v_fmac_f32_dpp v192, v154, v92 row_shl:14 row_mask:0xf bank_mask:0xf
	v_fmac_f32_dpp v193, v155, v93 row_shl:14 row_mask:0xf bank_mask:0xf
	v_fmac_f32_dpp v194, v156, v94 row_shl:14 row_mask:0xf bank_mask:0xf
	v_fmac_f32_dpp v195, v157, v95 row_shl:14 row_mask:0xf bank_mask:0xf
	v_pk_mul_f32 v[196:197], v[188:189], v[216:217] op_sel_hi:[1,0]
	v_pk_mul_f32 v[198:199], v[190:191], v[216:217] op_sel_hi:[1,0]
	v_exp_f32_e32 v196, v196
	v_exp_f32_e32 v197, v197
	v_exp_f32_e32 v198, v198
	v_exp_f32_e32 v199, v199
	v_pk_add_f32 v[196:197], v[196:197], v[214:215] op_sel_hi:[1,0]
	v_pk_add_f32 v[198:199], v[198:199], v[214:215] op_sel_hi:[1,0]
	v_rcp_f32_e32 v196, v196
	v_rcp_f32_e32 v197, v197
	v_rcp_f32_e32 v198, v198
	v_rcp_f32_e32 v199, v199
	v_pk_mul_f32 v[188:189], v[188:189], v[196:197]
	v_pk_mul_f32 v[190:191], v[190:191], v[198:199]
	v_pk_mul_f32 v[188:189], v[188:189], v[192:193]
	v_pk_mul_f32 v[190:191], v[190:191], v[194:195]
	v_cvt_pk_bf16_f32 v158, v188, v189
	v_cvt_pk_bf16_f32 v159, v190, v191
	v_add_u32_e32 v213, 0x21000, v212
	global_load_dwordx4 v[154:157], v213, s[82:83] offset:16
	v_pk_fma_f32 v[188:189], v[146:147], v[84:85], v[88:89]
	v_pk_fma_f32 v[190:191], v[148:149], v[86:87], v[90:91]
	v_pk_fma_f32 v[192:193], v[134:135], v[100:101], v[104:105]
	v_pk_fma_f32 v[194:195], v[136:137], v[102:103], v[106:107]
	v_fmac_f32_dpp v188, v146, v80 row_shr:1 row_mask:0xf bank_mask:0xf
	v_fmac_f32_dpp v189, v147, v81 row_shr:1 row_mask:0xf bank_mask:0xf
	v_fmac_f32_dpp v190, v148, v82 row_shr:1 row_mask:0xf bank_mask:0xf
	v_fmac_f32_dpp v191, v149, v83 row_shr:1 row_mask:0xf bank_mask:0xf
	v_fmac_f32_dpp v192, v134, v96 row_shr:1 row_mask:0xf bank_mask:0xf
	v_fmac_f32_dpp v193, v135, v97 row_shr:1 row_mask:0xf bank_mask:0xf
	v_fmac_f32_dpp v194, v136, v98 row_shr:1 row_mask:0xf bank_mask:0xf
	v_fmac_f32_dpp v195, v137, v99 row_shr:1 row_mask:0xf bank_mask:0xf
	v_fmac_f32_dpp v188, v146, v76 row_shr:2 row_mask:0xf bank_mask:0xf
	v_fmac_f32_dpp v189, v147, v77 row_shr:2 row_mask:0xf bank_mask:0xf
	v_fmac_f32_dpp v190, v148, v78 row_shr:2 row_mask:0xf bank_mask:0xf
	v_fmac_f32_dpp v191, v149, v79 row_shr:2 row_mask:0xf bank_mask:0xf
	v_fmac_f32_dpp v192, v134, v92 row_shr:2 row_mask:0xf bank_mask:0xf
	v_fmac_f32_dpp v193, v135, v93 row_shr:2 row_mask:0xf bank_mask:0xf
	v_fmac_f32_dpp v194, v136, v94 row_shr:2 row_mask:0xf bank_mask:0xf
	v_fmac_f32_dpp v195, v137, v95 row_shr:2 row_mask:0xf bank_mask:0xf
	v_fmac_f32_dpp v188, v150, v80 row_shl:15 row_mask:0xf bank_mask:0xf
	v_fmac_f32_dpp v189, v151, v81 row_shl:15 row_mask:0xf bank_mask:0xf
	v_fmac_f32_dpp v190, v152, v82 row_shl:15 row_mask:0xf bank_mask:0xf
	v_fmac_f32_dpp v191, v153, v83 row_shl:15 row_mask:0xf bank_mask:0xf
	v_fmac_f32_dpp v192, v142, v96 row_shl:15 row_mask:0xf bank_mask:0xf
	v_fmac_f32_dpp v193, v143, v97 row_shl:15 row_mask:0xf bank_mask:0xf
	v_fmac_f32_dpp v194, v144, v98 row_shl:15 row_mask:0xf bank_mask:0xf
	v_fmac_f32_dpp v195, v145, v99 row_shl:15 row_mask:0xf bank_mask:0xf
	v_fmac_f32_dpp v188, v150, v76 row_shl:14 row_mask:0xf bank_mask:0xf
	v_fmac_f32_dpp v189, v151, v77 row_shl:14 row_mask:0xf bank_mask:0xf
	v_fmac_f32_dpp v190, v152, v78 row_shl:14 row_mask:0xf bank_mask:0xf
	v_fmac_f32_dpp v191, v153, v79 row_shl:14 row_mask:0xf bank_mask:0xf
	v_fmac_f32_dpp v192, v142, v92 row_shl:14 row_mask:0xf bank_mask:0xf
	v_fmac_f32_dpp v193, v143, v93 row_shl:14 row_mask:0xf bank_mask:0xf
	v_fmac_f32_dpp v194, v144, v94 row_shl:14 row_mask:0xf bank_mask:0xf
	v_fmac_f32_dpp v195, v145, v95 row_shl:14 row_mask:0xf bank_mask:0xf
	v_pk_mul_f32 v[196:197], v[188:189], v[216:217] op_sel_hi:[1,0]
	v_pk_mul_f32 v[198:199], v[190:191], v[216:217] op_sel_hi:[1,0]
	v_exp_f32_e32 v196, v196
	v_exp_f32_e32 v197, v197
	v_exp_f32_e32 v198, v198
	v_exp_f32_e32 v199, v199
	v_pk_add_f32 v[196:197], v[196:197], v[214:215] op_sel_hi:[1,0]
	v_pk_add_f32 v[198:199], v[198:199], v[214:215] op_sel_hi:[1,0]
	v_rcp_f32_e32 v196, v196
	v_rcp_f32_e32 v197, v197
	v_rcp_f32_e32 v198, v198
	v_rcp_f32_e32 v199, v199
	v_pk_mul_f32 v[188:189], v[188:189], v[196:197]
	v_pk_mul_f32 v[190:191], v[190:191], v[198:199]
	v_pk_mul_f32 v[188:189], v[188:189], v[192:193]
	v_pk_mul_f32 v[190:191], v[190:191], v[194:195]
	v_cvt_pk_bf16_f32 v150, v188, v189
	v_cvt_pk_bf16_f32 v151, v190, v191
	v_add_u32_e32 v213, 0x2c000, v212
	global_load_dwordx4 v[142:145], v213, s[82:83] offset:16
	v_pk_fma_f32 v[188:189], v[138:139], v[84:85], v[88:89]
	v_pk_fma_f32 v[190:191], v[140:141], v[86:87], v[90:91]
	v_pk_fma_f32 v[192:193], v[130:131], v[100:101], v[104:105]
	v_pk_fma_f32 v[194:195], v[132:133], v[102:103], v[106:107]
	v_fmac_f32_dpp v188, v138, v80 row_shr:1 row_mask:0xf bank_mask:0xf
	v_fmac_f32_dpp v189, v139, v81 row_shr:1 row_mask:0xf bank_mask:0xf
	v_fmac_f32_dpp v190, v140, v82 row_shr:1 row_mask:0xf bank_mask:0xf
	v_fmac_f32_dpp v191, v141, v83 row_shr:1 row_mask:0xf bank_mask:0xf
	v_fmac_f32_dpp v192, v130, v96 row_shr:1 row_mask:0xf bank_mask:0xf
	v_fmac_f32_dpp v193, v131, v97 row_shr:1 row_mask:0xf bank_mask:0xf
	v_fmac_f32_dpp v194, v132, v98 row_shr:1 row_mask:0xf bank_mask:0xf
	v_fmac_f32_dpp v195, v133, v99 row_shr:1 row_mask:0xf bank_mask:0xf
	v_fmac_f32_dpp v188, v138, v76 row_shr:2 row_mask:0xf bank_mask:0xf
	v_fmac_f32_dpp v189, v139, v77 row_shr:2 row_mask:0xf bank_mask:0xf
	v_fmac_f32_dpp v190, v140, v78 row_shr:2 row_mask:0xf bank_mask:0xf
	v_fmac_f32_dpp v191, v141, v79 row_shr:2 row_mask:0xf bank_mask:0xf
	v_fmac_f32_dpp v192, v130, v92 row_shr:2 row_mask:0xf bank_mask:0xf
	v_fmac_f32_dpp v193, v131, v93 row_shr:2 row_mask:0xf bank_mask:0xf
	v_fmac_f32_dpp v194, v132, v94 row_shr:2 row_mask:0xf bank_mask:0xf
	v_fmac_f32_dpp v195, v133, v95 row_shr:2 row_mask:0xf bank_mask:0xf
	v_fmac_f32_dpp v188, v146, v80 row_shl:15 row_mask:0xf bank_mask:0xf
	v_fmac_f32_dpp v189, v147, v81 row_shl:15 row_mask:0xf bank_mask:0xf
	v_fmac_f32_dpp v190, v148, v82 row_shl:15 row_mask:0xf bank_mask:0xf
	v_fmac_f32_dpp v191, v149, v83 row_shl:15 row_mask:0xf bank_mask:0xf
	v_fmac_f32_dpp v192, v134, v96 row_shl:15 row_mask:0xf bank_mask:0xf
	v_fmac_f32_dpp v193, v135, v97 row_shl:15 row_mask:0xf bank_mask:0xf
	v_fmac_f32_dpp v194, v136, v98 row_shl:15 row_mask:0xf bank_mask:0xf
	v_fmac_f32_dpp v195, v137, v99 row_shl:15 row_mask:0xf bank_mask:0xf
	v_fmac_f32_dpp v188, v146, v76 row_shl:14 row_mask:0xf bank_mask:0xf
	v_fmac_f32_dpp v189, v147, v77 row_shl:14 row_mask:0xf bank_mask:0xf
	v_fmac_f32_dpp v190, v148, v78 row_shl:14 row_mask:0xf bank_mask:0xf
	v_fmac_f32_dpp v191, v149, v79 row_shl:14 row_mask:0xf bank_mask:0xf
	v_fmac_f32_dpp v192, v134, v92 row_shl:14 row_mask:0xf bank_mask:0xf
	v_fmac_f32_dpp v193, v135, v93 row_shl:14 row_mask:0xf bank_mask:0xf
	v_fmac_f32_dpp v194, v136, v94 row_shl:14 row_mask:0xf bank_mask:0xf
	v_fmac_f32_dpp v195, v137, v95 row_shl:14 row_mask:0xf bank_mask:0xf
	v_pk_mul_f32 v[196:197], v[188:189], v[216:217] op_sel_hi:[1,0]
	v_pk_mul_f32 v[198:199], v[190:191], v[216:217] op_sel_hi:[1,0]
	v_exp_f32_e32 v196, v196
	v_exp_f32_e32 v197, v197
	v_exp_f32_e32 v198, v198
	v_exp_f32_e32 v199, v199
	v_pk_add_f32 v[196:197], v[196:197], v[214:215] op_sel_hi:[1,0]
	v_pk_add_f32 v[198:199], v[198:199], v[214:215] op_sel_hi:[1,0]
	v_rcp_f32_e32 v196, v196
	v_rcp_f32_e32 v197, v197
	v_rcp_f32_e32 v198, v198
	v_rcp_f32_e32 v199, v199
	v_pk_mul_f32 v[188:189], v[188:189], v[196:197]
	v_pk_mul_f32 v[190:191], v[190:191], v[198:199]
	v_pk_mul_f32 v[188:189], v[188:189], v[192:193]
	v_pk_mul_f32 v[190:191], v[190:191], v[194:195]
	v_cvt_pk_bf16_f32 v146, v188, v189
	v_cvt_pk_bf16_f32 v147, v190, v191
	v_add_u32_e32 v213, 0x37000, v212
	global_load_dwordx4 v[134:137], v213, s[82:83] offset:16
	v_pk_fma_f32 v[188:189], v[126:127], v[84:85], v[88:89]
	v_pk_fma_f32 v[190:191], v[128:129], v[86:87], v[90:91]
	v_pk_fma_f32 v[192:193], v[118:119], v[100:101], v[104:105]
	v_pk_fma_f32 v[194:195], v[120:121], v[102:103], v[106:107]
	v_fmac_f32_dpp v188, v126, v80 row_shr:1 row_mask:0xf bank_mask:0xf
	v_fmac_f32_dpp v189, v127, v81 row_shr:1 row_mask:0xf bank_mask:0xf
	v_fmac_f32_dpp v190, v128, v82 row_shr:1 row_mask:0xf bank_mask:0xf
	v_fmac_f32_dpp v191, v129, v83 row_shr:1 row_mask:0xf bank_mask:0xf
	v_fmac_f32_dpp v192, v118, v96 row_shr:1 row_mask:0xf bank_mask:0xf
	v_fmac_f32_dpp v193, v119, v97 row_shr:1 row_mask:0xf bank_mask:0xf
	v_fmac_f32_dpp v194, v120, v98 row_shr:1 row_mask:0xf bank_mask:0xf
	v_fmac_f32_dpp v195, v121, v99 row_shr:1 row_mask:0xf bank_mask:0xf
	v_fmac_f32_dpp v188, v126, v76 row_shr:2 row_mask:0xf bank_mask:0xf
	v_fmac_f32_dpp v189, v127, v77 row_shr:2 row_mask:0xf bank_mask:0xf
	v_fmac_f32_dpp v190, v128, v78 row_shr:2 row_mask:0xf bank_mask:0xf
	v_fmac_f32_dpp v191, v129, v79 row_shr:2 row_mask:0xf bank_mask:0xf
	v_fmac_f32_dpp v192, v118, v92 row_shr:2 row_mask:0xf bank_mask:0xf
	v_fmac_f32_dpp v193, v119, v93 row_shr:2 row_mask:0xf bank_mask:0xf
	v_fmac_f32_dpp v194, v120, v94 row_shr:2 row_mask:0xf bank_mask:0xf
	v_fmac_f32_dpp v195, v121, v95 row_shr:2 row_mask:0xf bank_mask:0xf
	v_fmac_f32_dpp v188, v138, v80 row_shl:15 row_mask:0xf bank_mask:0xf
	v_fmac_f32_dpp v189, v139, v81 row_shl:15 row_mask:0xf bank_mask:0xf
	v_fmac_f32_dpp v190, v140, v82 row_shl:15 row_mask:0xf bank_mask:0xf
	v_fmac_f32_dpp v191, v141, v83 row_shl:15 row_mask:0xf bank_mask:0xf
	v_fmac_f32_dpp v192, v130, v96 row_shl:15 row_mask:0xf bank_mask:0xf
	v_fmac_f32_dpp v193, v131, v97 row_shl:15 row_mask:0xf bank_mask:0xf
	v_fmac_f32_dpp v194, v132, v98 row_shl:15 row_mask:0xf bank_mask:0xf
	v_fmac_f32_dpp v195, v133, v99 row_shl:15 row_mask:0xf bank_mask:0xf
	v_fmac_f32_dpp v188, v138, v76 row_shl:14 row_mask:0xf bank_mask:0xf
	v_fmac_f32_dpp v189, v139, v77 row_shl:14 row_mask:0xf bank_mask:0xf
	v_fmac_f32_dpp v190, v140, v78 row_shl:14 row_mask:0xf bank_mask:0xf
	v_fmac_f32_dpp v191, v141, v79 row_shl:14 row_mask:0xf bank_mask:0xf
	v_fmac_f32_dpp v192, v130, v92 row_shl:14 row_mask:0xf bank_mask:0xf
	v_fmac_f32_dpp v193, v131, v93 row_shl:14 row_mask:0xf bank_mask:0xf
	v_fmac_f32_dpp v194, v132, v94 row_shl:14 row_mask:0xf bank_mask:0xf
	v_fmac_f32_dpp v195, v133, v95 row_shl:14 row_mask:0xf bank_mask:0xf
	v_pk_mul_f32 v[196:197], v[188:189], v[216:217] op_sel_hi:[1,0]
	v_pk_mul_f32 v[198:199], v[190:191], v[216:217] op_sel_hi:[1,0]
	v_exp_f32_e32 v196, v196
	v_exp_f32_e32 v197, v197
	v_exp_f32_e32 v198, v198
	v_exp_f32_e32 v199, v199
	v_pk_add_f32 v[196:197], v[196:197], v[214:215] op_sel_hi:[1,0]
	v_pk_add_f32 v[198:199], v[198:199], v[214:215] op_sel_hi:[1,0]
	v_rcp_f32_e32 v196, v196
	v_rcp_f32_e32 v197, v197
	v_rcp_f32_e32 v198, v198
	v_rcp_f32_e32 v199, v199
	v_pk_mul_f32 v[188:189], v[188:189], v[196:197]
	v_pk_mul_f32 v[190:191], v[190:191], v[198:199]
	v_pk_mul_f32 v[188:189], v[188:189], v[192:193]
	v_pk_mul_f32 v[190:191], v[190:191], v[194:195]
	v_cvt_pk_bf16_f32 v138, v188, v189
	v_cvt_pk_bf16_f32 v139, v190, v191
	v_add_u32_e32 v213, 0xb000, v212
	global_load_dwordx4 v[130:133], v213, s[84:85] offset:16
	v_pk_fma_f32 v[188:189], v[122:123], v[84:85], v[88:89]
	v_pk_fma_f32 v[190:191], v[124:125], v[86:87], v[90:91]
	v_pk_fma_f32 v[192:193], v[110:111], v[100:101], v[104:105]
	v_pk_fma_f32 v[194:195], v[112:113], v[102:103], v[106:107]
	v_fmac_f32_dpp v188, v122, v80 row_shr:1 row_mask:0xf bank_mask:0xf
	v_fmac_f32_dpp v189, v123, v81 row_shr:1 row_mask:0xf bank_mask:0xf
	v_fmac_f32_dpp v190, v124, v82 row_shr:1 row_mask:0xf bank_mask:0xf
	v_fmac_f32_dpp v191, v125, v83 row_shr:1 row_mask:0xf bank_mask:0xf
	v_fmac_f32_dpp v192, v110, v96 row_shr:1 row_mask:0xf bank_mask:0xf
	v_fmac_f32_dpp v193, v111, v97 row_shr:1 row_mask:0xf bank_mask:0xf
	v_fmac_f32_dpp v194, v112, v98 row_shr:1 row_mask:0xf bank_mask:0xf
	v_fmac_f32_dpp v195, v113, v99 row_shr:1 row_mask:0xf bank_mask:0xf
	v_fmac_f32_dpp v188, v122, v76 row_shr:2 row_mask:0xf bank_mask:0xf
	v_fmac_f32_dpp v189, v123, v77 row_shr:2 row_mask:0xf bank_mask:0xf
	v_fmac_f32_dpp v190, v124, v78 row_shr:2 row_mask:0xf bank_mask:0xf
	v_fmac_f32_dpp v191, v125, v79 row_shr:2 row_mask:0xf bank_mask:0xf
	v_fmac_f32_dpp v192, v110, v92 row_shr:2 row_mask:0xf bank_mask:0xf
	v_fmac_f32_dpp v193, v111, v93 row_shr:2 row_mask:0xf bank_mask:0xf
	v_fmac_f32_dpp v194, v112, v94 row_shr:2 row_mask:0xf bank_mask:0xf
	v_fmac_f32_dpp v195, v113, v95 row_shr:2 row_mask:0xf bank_mask:0xf
	v_fmac_f32_dpp v188, v126, v80 row_shl:15 row_mask:0xf bank_mask:0xf
	v_fmac_f32_dpp v189, v127, v81 row_shl:15 row_mask:0xf bank_mask:0xf
	v_fmac_f32_dpp v190, v128, v82 row_shl:15 row_mask:0xf bank_mask:0xf
	v_fmac_f32_dpp v191, v129, v83 row_shl:15 row_mask:0xf bank_mask:0xf
	v_fmac_f32_dpp v192, v118, v96 row_shl:15 row_mask:0xf bank_mask:0xf
	v_fmac_f32_dpp v193, v119, v97 row_shl:15 row_mask:0xf bank_mask:0xf
	v_fmac_f32_dpp v194, v120, v98 row_shl:15 row_mask:0xf bank_mask:0xf
	v_fmac_f32_dpp v195, v121, v99 row_shl:15 row_mask:0xf bank_mask:0xf
	v_fmac_f32_dpp v188, v126, v76 row_shl:14 row_mask:0xf bank_mask:0xf
	v_fmac_f32_dpp v189, v127, v77 row_shl:14 row_mask:0xf bank_mask:0xf
	v_fmac_f32_dpp v190, v128, v78 row_shl:14 row_mask:0xf bank_mask:0xf
	v_fmac_f32_dpp v191, v129, v79 row_shl:14 row_mask:0xf bank_mask:0xf
	v_fmac_f32_dpp v192, v118, v92 row_shl:14 row_mask:0xf bank_mask:0xf
	v_fmac_f32_dpp v193, v119, v93 row_shl:14 row_mask:0xf bank_mask:0xf
	v_fmac_f32_dpp v194, v120, v94 row_shl:14 row_mask:0xf bank_mask:0xf
	v_fmac_f32_dpp v195, v121, v95 row_shl:14 row_mask:0xf bank_mask:0xf
	v_pk_mul_f32 v[196:197], v[188:189], v[216:217] op_sel_hi:[1,0]
	v_pk_mul_f32 v[198:199], v[190:191], v[216:217] op_sel_hi:[1,0]
	v_exp_f32_e32 v196, v196
	v_exp_f32_e32 v197, v197
	v_exp_f32_e32 v198, v198
	v_exp_f32_e32 v199, v199
	v_pk_add_f32 v[196:197], v[196:197], v[214:215] op_sel_hi:[1,0]
	v_pk_add_f32 v[198:199], v[198:199], v[214:215] op_sel_hi:[1,0]
	v_rcp_f32_e32 v196, v196
	v_rcp_f32_e32 v197, v197
	v_rcp_f32_e32 v198, v198
	v_rcp_f32_e32 v199, v199
	v_pk_mul_f32 v[188:189], v[188:189], v[196:197]
	v_pk_mul_f32 v[190:191], v[190:191], v[198:199]
	v_pk_mul_f32 v[188:189], v[188:189], v[192:193]
	v_pk_mul_f32 v[190:191], v[190:191], v[194:195]
	v_cvt_pk_bf16_f32 v126, v188, v189
	v_cvt_pk_bf16_f32 v127, v190, v191
	v_add_u32_e32 v213, 0x26800, v212
	global_load_dwordx4 v[118:121], v213, s[82:83] offset:16
	v_pk_fma_f32 v[188:189], v[114:115], v[84:85], v[88:89]
	v_pk_fma_f32 v[190:191], v[116:117], v[86:87], v[90:91]
	v_pk_fma_f32 v[192:193], v[68:69], v[100:101], v[104:105]
	v_pk_fma_f32 v[194:195], v[70:71], v[102:103], v[106:107]
	v_fmac_f32_dpp v188, v114, v80 row_shr:1 row_mask:0xf bank_mask:0xf
	v_fmac_f32_dpp v189, v115, v81 row_shr:1 row_mask:0xf bank_mask:0xf
	v_fmac_f32_dpp v190, v116, v82 row_shr:1 row_mask:0xf bank_mask:0xf
	v_fmac_f32_dpp v191, v117, v83 row_shr:1 row_mask:0xf bank_mask:0xf
	v_fmac_f32_dpp v192, v68, v96 row_shr:1 row_mask:0xf bank_mask:0xf
	v_fmac_f32_dpp v193, v69, v97 row_shr:1 row_mask:0xf bank_mask:0xf
	v_fmac_f32_dpp v194, v70, v98 row_shr:1 row_mask:0xf bank_mask:0xf
	v_fmac_f32_dpp v195, v71, v99 row_shr:1 row_mask:0xf bank_mask:0xf
	v_fmac_f32_dpp v188, v114, v76 row_shr:2 row_mask:0xf bank_mask:0xf
	v_fmac_f32_dpp v189, v115, v77 row_shr:2 row_mask:0xf bank_mask:0xf
	v_fmac_f32_dpp v190, v116, v78 row_shr:2 row_mask:0xf bank_mask:0xf
	v_fmac_f32_dpp v191, v117, v79 row_shr:2 row_mask:0xf bank_mask:0xf
	v_fmac_f32_dpp v192, v68, v92 row_shr:2 row_mask:0xf bank_mask:0xf
	v_fmac_f32_dpp v193, v69, v93 row_shr:2 row_mask:0xf bank_mask:0xf
	v_fmac_f32_dpp v194, v70, v94 row_shr:2 row_mask:0xf bank_mask:0xf
	v_fmac_f32_dpp v195, v71, v95 row_shr:2 row_mask:0xf bank_mask:0xf
	v_fmac_f32_dpp v188, v122, v80 row_shl:15 row_mask:0xf bank_mask:0xf
	v_fmac_f32_dpp v189, v123, v81 row_shl:15 row_mask:0xf bank_mask:0xf
	v_fmac_f32_dpp v190, v124, v82 row_shl:15 row_mask:0xf bank_mask:0xf
	v_fmac_f32_dpp v191, v125, v83 row_shl:15 row_mask:0xf bank_mask:0xf
	v_fmac_f32_dpp v192, v110, v96 row_shl:15 row_mask:0xf bank_mask:0xf
	v_fmac_f32_dpp v193, v111, v97 row_shl:15 row_mask:0xf bank_mask:0xf
	v_fmac_f32_dpp v194, v112, v98 row_shl:15 row_mask:0xf bank_mask:0xf
	v_fmac_f32_dpp v195, v113, v99 row_shl:15 row_mask:0xf bank_mask:0xf
	v_fmac_f32_dpp v188, v122, v76 row_shl:14 row_mask:0xf bank_mask:0xf
	v_fmac_f32_dpp v189, v123, v77 row_shl:14 row_mask:0xf bank_mask:0xf
	v_fmac_f32_dpp v190, v124, v78 row_shl:14 row_mask:0xf bank_mask:0xf
	v_fmac_f32_dpp v191, v125, v79 row_shl:14 row_mask:0xf bank_mask:0xf
	v_fmac_f32_dpp v192, v110, v92 row_shl:14 row_mask:0xf bank_mask:0xf
	v_fmac_f32_dpp v193, v111, v93 row_shl:14 row_mask:0xf bank_mask:0xf
	v_fmac_f32_dpp v194, v112, v94 row_shl:14 row_mask:0xf bank_mask:0xf
	v_fmac_f32_dpp v195, v113, v95 row_shl:14 row_mask:0xf bank_mask:0xf
	v_pk_mul_f32 v[196:197], v[188:189], v[216:217] op_sel_hi:[1,0]
	v_pk_mul_f32 v[198:199], v[190:191], v[216:217] op_sel_hi:[1,0]
	v_exp_f32_e32 v196, v196
	v_exp_f32_e32 v197, v197
	v_exp_f32_e32 v198, v198
	v_exp_f32_e32 v199, v199
	v_pk_add_f32 v[196:197], v[196:197], v[214:215] op_sel_hi:[1,0]
	v_pk_add_f32 v[198:199], v[198:199], v[214:215] op_sel_hi:[1,0]
	v_rcp_f32_e32 v196, v196
	v_rcp_f32_e32 v197, v197
	v_rcp_f32_e32 v198, v198
	v_rcp_f32_e32 v199, v199
	v_pk_mul_f32 v[188:189], v[188:189], v[196:197]
	v_pk_mul_f32 v[190:191], v[190:191], v[198:199]
	v_pk_mul_f32 v[188:189], v[188:189], v[192:193]
	v_pk_mul_f32 v[190:191], v[190:191], v[194:195]
	v_cvt_pk_bf16_f32 v122, v188, v189
	v_cvt_pk_bf16_f32 v123, v190, v191
	v_add_u32_e32 v213, 0x31800, v212
	global_load_dwordx4 v[110:113], v213, s[82:83] offset:16
	v_pk_fma_f32 v[188:189], v[72:73], v[84:85], v[88:89]
	v_pk_fma_f32 v[190:191], v[74:75], v[86:87], v[90:91]
	v_pk_fma_f32 v[192:193], v[64:65], v[100:101], v[104:105]
	v_pk_fma_f32 v[194:195], v[66:67], v[102:103], v[106:107]
	v_fmac_f32_dpp v188, v72, v80 row_shr:1 row_mask:0xf bank_mask:0xf
	v_fmac_f32_dpp v189, v73, v81 row_shr:1 row_mask:0xf bank_mask:0xf
	v_fmac_f32_dpp v190, v74, v82 row_shr:1 row_mask:0xf bank_mask:0xf
	v_fmac_f32_dpp v191, v75, v83 row_shr:1 row_mask:0xf bank_mask:0xf
	v_fmac_f32_dpp v192, v64, v96 row_shr:1 row_mask:0xf bank_mask:0xf
	v_fmac_f32_dpp v193, v65, v97 row_shr:1 row_mask:0xf bank_mask:0xf
	v_fmac_f32_dpp v194, v66, v98 row_shr:1 row_mask:0xf bank_mask:0xf
	v_fmac_f32_dpp v195, v67, v99 row_shr:1 row_mask:0xf bank_mask:0xf
	v_fmac_f32_dpp v188, v72, v76 row_shr:2 row_mask:0xf bank_mask:0xf
	v_fmac_f32_dpp v189, v73, v77 row_shr:2 row_mask:0xf bank_mask:0xf
	v_fmac_f32_dpp v190, v74, v78 row_shr:2 row_mask:0xf bank_mask:0xf
	v_fmac_f32_dpp v191, v75, v79 row_shr:2 row_mask:0xf bank_mask:0xf
	v_fmac_f32_dpp v192, v64, v92 row_shr:2 row_mask:0xf bank_mask:0xf
	v_fmac_f32_dpp v193, v65, v93 row_shr:2 row_mask:0xf bank_mask:0xf
	v_fmac_f32_dpp v194, v66, v94 row_shr:2 row_mask:0xf bank_mask:0xf
	v_fmac_f32_dpp v195, v67, v95 row_shr:2 row_mask:0xf bank_mask:0xf
	v_fmac_f32_dpp v188, v114, v80 row_shl:15 row_mask:0xf bank_mask:0xf
	v_fmac_f32_dpp v189, v115, v81 row_shl:15 row_mask:0xf bank_mask:0xf
	v_fmac_f32_dpp v190, v116, v82 row_shl:15 row_mask:0xf bank_mask:0xf
	v_fmac_f32_dpp v191, v117, v83 row_shl:15 row_mask:0xf bank_mask:0xf
	v_fmac_f32_dpp v192, v68, v96 row_shl:15 row_mask:0xf bank_mask:0xf
	v_fmac_f32_dpp v193, v69, v97 row_shl:15 row_mask:0xf bank_mask:0xf
	v_fmac_f32_dpp v194, v70, v98 row_shl:15 row_mask:0xf bank_mask:0xf
	v_fmac_f32_dpp v195, v71, v99 row_shl:15 row_mask:0xf bank_mask:0xf
	v_fmac_f32_dpp v188, v114, v76 row_shl:14 row_mask:0xf bank_mask:0xf
	v_fmac_f32_dpp v189, v115, v77 row_shl:14 row_mask:0xf bank_mask:0xf
	v_fmac_f32_dpp v190, v116, v78 row_shl:14 row_mask:0xf bank_mask:0xf
	v_fmac_f32_dpp v191, v117, v79 row_shl:14 row_mask:0xf bank_mask:0xf
	v_fmac_f32_dpp v192, v68, v92 row_shl:14 row_mask:0xf bank_mask:0xf
	v_fmac_f32_dpp v193, v69, v93 row_shl:14 row_mask:0xf bank_mask:0xf
	v_fmac_f32_dpp v194, v70, v94 row_shl:14 row_mask:0xf bank_mask:0xf
	v_fmac_f32_dpp v195, v71, v95 row_shl:14 row_mask:0xf bank_mask:0xf
	v_pk_mul_f32 v[196:197], v[188:189], v[216:217] op_sel_hi:[1,0]
	v_pk_mul_f32 v[198:199], v[190:191], v[216:217] op_sel_hi:[1,0]
	v_exp_f32_e32 v196, v196
	v_exp_f32_e32 v197, v197
	v_exp_f32_e32 v198, v198
	v_exp_f32_e32 v199, v199
	v_pk_add_f32 v[196:197], v[196:197], v[214:215] op_sel_hi:[1,0]
	v_pk_add_f32 v[198:199], v[198:199], v[214:215] op_sel_hi:[1,0]
	v_rcp_f32_e32 v196, v196
	v_rcp_f32_e32 v197, v197
	v_rcp_f32_e32 v198, v198
	v_rcp_f32_e32 v199, v199
	v_pk_mul_f32 v[188:189], v[188:189], v[196:197]
	v_pk_mul_f32 v[190:191], v[190:191], v[198:199]
	v_pk_mul_f32 v[188:189], v[188:189], v[192:193]
	v_pk_mul_f32 v[190:191], v[190:191], v[194:195]
	v_cvt_pk_bf16_f32 v114, v188, v189
	v_cvt_pk_bf16_f32 v115, v190, v191
	s_waitcnt vmcnt(0)
	v_pk_fma_f32 v[188:189], v[60:61], v[134:135], v[130:131]
	v_pk_fma_f32 v[190:191], v[62:63], v[136:137], v[132:133]
	v_pk_fma_f32 v[192:193], v[56:57], v[204:205], v[208:209]
	v_pk_fma_f32 v[194:195], v[58:59], v[206:207], v[210:211]
	v_fmac_f32_dpp v188, v60, v142 row_shr:1 row_mask:0xf bank_mask:0xf
	v_fmac_f32_dpp v189, v61, v143 row_shr:1 row_mask:0xf bank_mask:0xf
	v_fmac_f32_dpp v190, v62, v144 row_shr:1 row_mask:0xf bank_mask:0xf
	v_fmac_f32_dpp v191, v63, v145 row_shr:1 row_mask:0xf bank_mask:0xf
	v_fmac_f32_dpp v192, v56, v110 row_shr:1 row_mask:0xf bank_mask:0xf
	v_fmac_f32_dpp v193, v57, v111 row_shr:1 row_mask:0xf bank_mask:0xf
	v_fmac_f32_dpp v194, v58, v112 row_shr:1 row_mask:0xf bank_mask:0xf
	v_fmac_f32_dpp v195, v59, v113 row_shr:1 row_mask:0xf bank_mask:0xf
	v_fmac_f32_dpp v188, v60, v154 row_shr:2 row_mask:0xf bank_mask:0xf
	v_fmac_f32_dpp v189, v61, v155 row_shr:2 row_mask:0xf bank_mask:0xf
	v_fmac_f32_dpp v190, v62, v156 row_shr:2 row_mask:0xf bank_mask:0xf
	v_fmac_f32_dpp v191, v63, v157 row_shr:2 row_mask:0xf bank_mask:0xf
	v_fmac_f32_dpp v192, v56, v118 row_shr:2 row_mask:0xf bank_mask:0xf
	v_fmac_f32_dpp v193, v57, v119 row_shr:2 row_mask:0xf bank_mask:0xf
	v_fmac_f32_dpp v194, v58, v120 row_shr:2 row_mask:0xf bank_mask:0xf
	v_fmac_f32_dpp v195, v59, v121 row_shr:2 row_mask:0xf bank_mask:0xf
	v_pk_mul_f32 v[196:197], v[188:189], v[216:217] op_sel_hi:[1,0]
	v_pk_mul_f32 v[198:199], v[190:191], v[216:217] op_sel_hi:[1,0]
	v_exp_f32_e32 v196, v196
	v_exp_f32_e32 v197, v197
	v_exp_f32_e32 v198, v198
	v_exp_f32_e32 v199, v199
	v_pk_add_f32 v[196:197], v[196:197], v[214:215] op_sel_hi:[1,0]
	v_pk_add_f32 v[198:199], v[198:199], v[214:215] op_sel_hi:[1,0]
	v_rcp_f32_e32 v196, v196
	v_rcp_f32_e32 v197, v197
	v_rcp_f32_e32 v198, v198
	v_rcp_f32_e32 v199, v199
	v_pk_mul_f32 v[188:189], v[188:189], v[196:197]
	v_pk_mul_f32 v[190:191], v[190:191], v[198:199]
	v_pk_mul_f32 v[188:189], v[188:189], v[192:193]
	v_pk_mul_f32 v[190:191], v[190:191], v[194:195]
	v_cvt_pk_bf16_f32 v202, v188, v189
	v_cvt_pk_bf16_f32 v203, v190, v191
	s_mov_b64 exec, vcc
	global_store_dwordx4 v215, v[200:203], s[96:97]
	s_mov_b64 exec, -1
	v_pk_fma_f32 v[188:189], v[52:53], v[134:135], v[130:131]
	v_pk_fma_f32 v[190:191], v[54:55], v[136:137], v[132:133]
	v_pk_fma_f32 v[192:193], v[44:45], v[204:205], v[208:209]
	v_pk_fma_f32 v[194:195], v[46:47], v[206:207], v[210:211]
	v_fmac_f32_dpp v188, v52, v142 row_shr:1 row_mask:0xf bank_mask:0xf
	v_fmac_f32_dpp v189, v53, v143 row_shr:1 row_mask:0xf bank_mask:0xf
	v_fmac_f32_dpp v190, v54, v144 row_shr:1 row_mask:0xf bank_mask:0xf
	v_fmac_f32_dpp v191, v55, v145 row_shr:1 row_mask:0xf bank_mask:0xf
	v_fmac_f32_dpp v192, v44, v110 row_shr:1 row_mask:0xf bank_mask:0xf
	v_fmac_f32_dpp v193, v45, v111 row_shr:1 row_mask:0xf bank_mask:0xf
	v_fmac_f32_dpp v194, v46, v112 row_shr:1 row_mask:0xf bank_mask:0xf
	v_fmac_f32_dpp v195, v47, v113 row_shr:1 row_mask:0xf bank_mask:0xf
	v_fmac_f32_dpp v188, v52, v154 row_shr:2 row_mask:0xf bank_mask:0xf
	v_fmac_f32_dpp v189, v53, v155 row_shr:2 row_mask:0xf bank_mask:0xf
	v_fmac_f32_dpp v190, v54, v156 row_shr:2 row_mask:0xf bank_mask:0xf
	v_fmac_f32_dpp v191, v55, v157 row_shr:2 row_mask:0xf bank_mask:0xf
	v_fmac_f32_dpp v192, v44, v118 row_shr:2 row_mask:0xf bank_mask:0xf
	v_fmac_f32_dpp v193, v45, v119 row_shr:2 row_mask:0xf bank_mask:0xf
	v_fmac_f32_dpp v194, v46, v120 row_shr:2 row_mask:0xf bank_mask:0xf
	v_fmac_f32_dpp v195, v47, v121 row_shr:2 row_mask:0xf bank_mask:0xf
	v_fmac_f32_dpp v188, v60, v142 row_shl:15 row_mask:0xf bank_mask:0xf
	v_fmac_f32_dpp v189, v61, v143 row_shl:15 row_mask:0xf bank_mask:0xf
	v_fmac_f32_dpp v190, v62, v144 row_shl:15 row_mask:0xf bank_mask:0xf
	v_fmac_f32_dpp v191, v63, v145 row_shl:15 row_mask:0xf bank_mask:0xf
	v_fmac_f32_dpp v192, v56, v110 row_shl:15 row_mask:0xf bank_mask:0xf
	v_fmac_f32_dpp v193, v57, v111 row_shl:15 row_mask:0xf bank_mask:0xf
	v_fmac_f32_dpp v194, v58, v112 row_shl:15 row_mask:0xf bank_mask:0xf
	v_fmac_f32_dpp v195, v59, v113 row_shl:15 row_mask:0xf bank_mask:0xf
	v_fmac_f32_dpp v188, v60, v154 row_shl:14 row_mask:0xf bank_mask:0xf
	v_fmac_f32_dpp v189, v61, v155 row_shl:14 row_mask:0xf bank_mask:0xf
	v_fmac_f32_dpp v190, v62, v156 row_shl:14 row_mask:0xf bank_mask:0xf
	v_fmac_f32_dpp v191, v63, v157 row_shl:14 row_mask:0xf bank_mask:0xf
	v_fmac_f32_dpp v192, v56, v118 row_shl:14 row_mask:0xf bank_mask:0xf
	v_fmac_f32_dpp v193, v57, v119 row_shl:14 row_mask:0xf bank_mask:0xf
	v_fmac_f32_dpp v194, v58, v120 row_shl:14 row_mask:0xf bank_mask:0xf
	v_fmac_f32_dpp v195, v59, v121 row_shl:14 row_mask:0xf bank_mask:0xf
	v_pk_mul_f32 v[196:197], v[188:189], v[216:217] op_sel_hi:[1,0]
	v_pk_mul_f32 v[198:199], v[190:191], v[216:217] op_sel_hi:[1,0]
	v_exp_f32_e32 v196, v196
	v_exp_f32_e32 v197, v197
	v_exp_f32_e32 v198, v198
	v_exp_f32_e32 v199, v199
	v_pk_add_f32 v[196:197], v[196:197], v[214:215] op_sel_hi:[1,0]
	v_pk_add_f32 v[198:199], v[198:199], v[214:215] op_sel_hi:[1,0]
	v_rcp_f32_e32 v196, v196
	v_rcp_f32_e32 v197, v197
	v_rcp_f32_e32 v198, v198
	v_rcp_f32_e32 v199, v199
	v_pk_mul_f32 v[188:189], v[188:189], v[196:197]
	v_pk_mul_f32 v[190:191], v[190:191], v[198:199]
	v_pk_mul_f32 v[188:189], v[188:189], v[192:193]
	v_pk_mul_f32 v[190:191], v[190:191], v[194:195]
	v_cvt_pk_bf16_f32 v160, v188, v189
	v_cvt_pk_bf16_f32 v161, v190, v191
	v_add_u32_e32 v213, 0x2c000, v215
	global_store_dwordx4 v213, v[158:161], s[96:97]
	v_pk_fma_f32 v[188:189], v[48:49], v[134:135], v[130:131]
	v_pk_fma_f32 v[190:191], v[50:51], v[136:137], v[132:133]
	v_pk_fma_f32 v[192:193], v[36:37], v[204:205], v[208:209]
	v_pk_fma_f32 v[194:195], v[38:39], v[206:207], v[210:211]
	v_fmac_f32_dpp v188, v48, v142 row_shr:1 row_mask:0xf bank_mask:0xf
	v_fmac_f32_dpp v189, v49, v143 row_shr:1 row_mask:0xf bank_mask:0xf
	v_fmac_f32_dpp v190, v50, v144 row_shr:1 row_mask:0xf bank_mask:0xf
	v_fmac_f32_dpp v191, v51, v145 row_shr:1 row_mask:0xf bank_mask:0xf
	v_fmac_f32_dpp v192, v36, v110 row_shr:1 row_mask:0xf bank_mask:0xf
	v_fmac_f32_dpp v193, v37, v111 row_shr:1 row_mask:0xf bank_mask:0xf
	v_fmac_f32_dpp v194, v38, v112 row_shr:1 row_mask:0xf bank_mask:0xf
	v_fmac_f32_dpp v195, v39, v113 row_shr:1 row_mask:0xf bank_mask:0xf
	v_fmac_f32_dpp v188, v48, v154 row_shr:2 row_mask:0xf bank_mask:0xf
	v_fmac_f32_dpp v189, v49, v155 row_shr:2 row_mask:0xf bank_mask:0xf
	v_fmac_f32_dpp v190, v50, v156 row_shr:2 row_mask:0xf bank_mask:0xf
	v_fmac_f32_dpp v191, v51, v157 row_shr:2 row_mask:0xf bank_mask:0xf
	v_fmac_f32_dpp v192, v36, v118 row_shr:2 row_mask:0xf bank_mask:0xf
	v_fmac_f32_dpp v193, v37, v119 row_shr:2 row_mask:0xf bank_mask:0xf
	v_fmac_f32_dpp v194, v38, v120 row_shr:2 row_mask:0xf bank_mask:0xf
	v_fmac_f32_dpp v195, v39, v121 row_shr:2 row_mask:0xf bank_mask:0xf
	v_fmac_f32_dpp v188, v52, v142 row_shl:15 row_mask:0xf bank_mask:0xf
	v_fmac_f32_dpp v189, v53, v143 row_shl:15 row_mask:0xf bank_mask:0xf
	v_fmac_f32_dpp v190, v54, v144 row_shl:15 row_mask:0xf bank_mask:0xf
	v_fmac_f32_dpp v191, v55, v145 row_shl:15 row_mask:0xf bank_mask:0xf
	v_fmac_f32_dpp v192, v44, v110 row_shl:15 row_mask:0xf bank_mask:0xf
	v_fmac_f32_dpp v193, v45, v111 row_shl:15 row_mask:0xf bank_mask:0xf
	v_fmac_f32_dpp v194, v46, v112 row_shl:15 row_mask:0xf bank_mask:0xf
	v_fmac_f32_dpp v195, v47, v113 row_shl:15 row_mask:0xf bank_mask:0xf
	v_fmac_f32_dpp v188, v52, v154 row_shl:14 row_mask:0xf bank_mask:0xf
	v_fmac_f32_dpp v189, v53, v155 row_shl:14 row_mask:0xf bank_mask:0xf
	v_fmac_f32_dpp v190, v54, v156 row_shl:14 row_mask:0xf bank_mask:0xf
	v_fmac_f32_dpp v191, v55, v157 row_shl:14 row_mask:0xf bank_mask:0xf
	v_fmac_f32_dpp v192, v44, v118 row_shl:14 row_mask:0xf bank_mask:0xf
	v_fmac_f32_dpp v193, v45, v119 row_shl:14 row_mask:0xf bank_mask:0xf
	v_fmac_f32_dpp v194, v46, v120 row_shl:14 row_mask:0xf bank_mask:0xf
	v_fmac_f32_dpp v195, v47, v121 row_shl:14 row_mask:0xf bank_mask:0xf
	v_pk_mul_f32 v[196:197], v[188:189], v[216:217] op_sel_hi:[1,0]
	v_pk_mul_f32 v[198:199], v[190:191], v[216:217] op_sel_hi:[1,0]
	v_exp_f32_e32 v196, v196
	v_exp_f32_e32 v197, v197
	v_exp_f32_e32 v198, v198
	v_exp_f32_e32 v199, v199
	v_pk_add_f32 v[196:197], v[196:197], v[214:215] op_sel_hi:[1,0]
	v_pk_add_f32 v[198:199], v[198:199], v[214:215] op_sel_hi:[1,0]
	v_rcp_f32_e32 v196, v196
	v_rcp_f32_e32 v197, v197
	v_rcp_f32_e32 v198, v198
	v_rcp_f32_e32 v199, v199
	v_pk_mul_f32 v[188:189], v[188:189], v[196:197]
	v_pk_mul_f32 v[190:191], v[190:191], v[198:199]
	v_pk_mul_f32 v[188:189], v[188:189], v[192:193]
	v_pk_mul_f32 v[190:191], v[190:191], v[194:195]
	v_cvt_pk_bf16_f32 v152, v188, v189
	v_cvt_pk_bf16_f32 v153, v190, v191
	v_add_u32_e32 v213, 0x58000, v215
	global_store_dwordx4 v213, v[150:153], s[96:97]
	v_pk_fma_f32 v[188:189], v[40:41], v[134:135], v[130:131]
	v_pk_fma_f32 v[190:191], v[42:43], v[136:137], v[132:133]
	v_pk_fma_f32 v[192:193], v[32:33], v[204:205], v[208:209]
	v_pk_fma_f32 v[194:195], v[34:35], v[206:207], v[210:211]
	v_fmac_f32_dpp v188, v40, v142 row_shr:1 row_mask:0xf bank_mask:0xf
	v_fmac_f32_dpp v189, v41, v143 row_shr:1 row_mask:0xf bank_mask:0xf
	v_fmac_f32_dpp v190, v42, v144 row_shr:1 row_mask:0xf bank_mask:0xf
	v_fmac_f32_dpp v191, v43, v145 row_shr:1 row_mask:0xf bank_mask:0xf
	v_fmac_f32_dpp v192, v32, v110 row_shr:1 row_mask:0xf bank_mask:0xf
	v_fmac_f32_dpp v193, v33, v111 row_shr:1 row_mask:0xf bank_mask:0xf
	v_fmac_f32_dpp v194, v34, v112 row_shr:1 row_mask:0xf bank_mask:0xf
	v_fmac_f32_dpp v195, v35, v113 row_shr:1 row_mask:0xf bank_mask:0xf
	v_fmac_f32_dpp v188, v40, v154 row_shr:2 row_mask:0xf bank_mask:0xf
	v_fmac_f32_dpp v189, v41, v155 row_shr:2 row_mask:0xf bank_mask:0xf
	v_fmac_f32_dpp v190, v42, v156 row_shr:2 row_mask:0xf bank_mask:0xf
	v_fmac_f32_dpp v191, v43, v157 row_shr:2 row_mask:0xf bank_mask:0xf
	v_fmac_f32_dpp v192, v32, v118 row_shr:2 row_mask:0xf bank_mask:0xf
	v_fmac_f32_dpp v193, v33, v119 row_shr:2 row_mask:0xf bank_mask:0xf
	v_fmac_f32_dpp v194, v34, v120 row_shr:2 row_mask:0xf bank_mask:0xf
	v_fmac_f32_dpp v195, v35, v121 row_shr:2 row_mask:0xf bank_mask:0xf
	v_fmac_f32_dpp v188, v48, v142 row_shl:15 row_mask:0xf bank_mask:0xf
	v_fmac_f32_dpp v189, v49, v143 row_shl:15 row_mask:0xf bank_mask:0xf
	v_fmac_f32_dpp v190, v50, v144 row_shl:15 row_mask:0xf bank_mask:0xf
	v_fmac_f32_dpp v191, v51, v145 row_shl:15 row_mask:0xf bank_mask:0xf
	v_fmac_f32_dpp v192, v36, v110 row_shl:15 row_mask:0xf bank_mask:0xf
	v_fmac_f32_dpp v193, v37, v111 row_shl:15 row_mask:0xf bank_mask:0xf
	v_fmac_f32_dpp v194, v38, v112 row_shl:15 row_mask:0xf bank_mask:0xf
	v_fmac_f32_dpp v195, v39, v113 row_shl:15 row_mask:0xf bank_mask:0xf
	v_fmac_f32_dpp v188, v48, v154 row_shl:14 row_mask:0xf bank_mask:0xf
	v_fmac_f32_dpp v189, v49, v155 row_shl:14 row_mask:0xf bank_mask:0xf
	v_fmac_f32_dpp v190, v50, v156 row_shl:14 row_mask:0xf bank_mask:0xf
	v_fmac_f32_dpp v191, v51, v157 row_shl:14 row_mask:0xf bank_mask:0xf
	v_fmac_f32_dpp v192, v36, v118 row_shl:14 row_mask:0xf bank_mask:0xf
	v_fmac_f32_dpp v193, v37, v119 row_shl:14 row_mask:0xf bank_mask:0xf
	v_fmac_f32_dpp v194, v38, v120 row_shl:14 row_mask:0xf bank_mask:0xf
	v_fmac_f32_dpp v195, v39, v121 row_shl:14 row_mask:0xf bank_mask:0xf
	v_pk_mul_f32 v[196:197], v[188:189], v[216:217] op_sel_hi:[1,0]
	v_pk_mul_f32 v[198:199], v[190:191], v[216:217] op_sel_hi:[1,0]
	v_exp_f32_e32 v196, v196
	v_exp_f32_e32 v197, v197
	v_exp_f32_e32 v198, v198
	v_exp_f32_e32 v199, v199
	v_pk_add_f32 v[196:197], v[196:197], v[214:215] op_sel_hi:[1,0]
	v_pk_add_f32 v[198:199], v[198:199], v[214:215] op_sel_hi:[1,0]
	v_rcp_f32_e32 v196, v196
	v_rcp_f32_e32 v197, v197
	v_rcp_f32_e32 v198, v198
	v_rcp_f32_e32 v199, v199
	v_pk_mul_f32 v[188:189], v[188:189], v[196:197]
	v_pk_mul_f32 v[190:191], v[190:191], v[198:199]
	v_pk_mul_f32 v[188:189], v[188:189], v[192:193]
	v_pk_mul_f32 v[190:191], v[190:191], v[194:195]
	v_cvt_pk_bf16_f32 v148, v188, v189
	v_cvt_pk_bf16_f32 v149, v190, v191
	v_add_u32_e32 v213, 0x84000, v215
	global_store_dwordx4 v213, v[146:149], s[96:97]
	v_pk_fma_f32 v[188:189], v[28:29], v[134:135], v[130:131]
	v_pk_fma_f32 v[190:191], v[30:31], v[136:137], v[132:133]
	v_pk_fma_f32 v[192:193], v[16:17], v[204:205], v[208:209]
	v_pk_fma_f32 v[194:195], v[18:19], v[206:207], v[210:211]
	v_fmac_f32_dpp v188, v28, v142 row_shr:1 row_mask:0xf bank_mask:0xf
	v_fmac_f32_dpp v189, v29, v143 row_shr:1 row_mask:0xf bank_mask:0xf
	v_fmac_f32_dpp v190, v30, v144 row_shr:1 row_mask:0xf bank_mask:0xf
	v_fmac_f32_dpp v191, v31, v145 row_shr:1 row_mask:0xf bank_mask:0xf
	v_fmac_f32_dpp v192, v16, v110 row_shr:1 row_mask:0xf bank_mask:0xf
	v_fmac_f32_dpp v193, v17, v111 row_shr:1 row_mask:0xf bank_mask:0xf
	v_fmac_f32_dpp v194, v18, v112 row_shr:1 row_mask:0xf bank_mask:0xf
	v_fmac_f32_dpp v195, v19, v113 row_shr:1 row_mask:0xf bank_mask:0xf
	v_fmac_f32_dpp v188, v28, v154 row_shr:2 row_mask:0xf bank_mask:0xf
	v_fmac_f32_dpp v189, v29, v155 row_shr:2 row_mask:0xf bank_mask:0xf
	v_fmac_f32_dpp v190, v30, v156 row_shr:2 row_mask:0xf bank_mask:0xf
	v_fmac_f32_dpp v191, v31, v157 row_shr:2 row_mask:0xf bank_mask:0xf
	v_fmac_f32_dpp v192, v16, v118 row_shr:2 row_mask:0xf bank_mask:0xf
	v_fmac_f32_dpp v193, v17, v119 row_shr:2 row_mask:0xf bank_mask:0xf
	v_fmac_f32_dpp v194, v18, v120 row_shr:2 row_mask:0xf bank_mask:0xf
	v_fmac_f32_dpp v195, v19, v121 row_shr:2 row_mask:0xf bank_mask:0xf
	v_fmac_f32_dpp v188, v40, v142 row_shl:15 row_mask:0xf bank_mask:0xf
	v_fmac_f32_dpp v189, v41, v143 row_shl:15 row_mask:0xf bank_mask:0xf
	v_fmac_f32_dpp v190, v42, v144 row_shl:15 row_mask:0xf bank_mask:0xf
	v_fmac_f32_dpp v191, v43, v145 row_shl:15 row_mask:0xf bank_mask:0xf
	v_fmac_f32_dpp v192, v32, v110 row_shl:15 row_mask:0xf bank_mask:0xf
	v_fmac_f32_dpp v193, v33, v111 row_shl:15 row_mask:0xf bank_mask:0xf
	v_fmac_f32_dpp v194, v34, v112 row_shl:15 row_mask:0xf bank_mask:0xf
	v_fmac_f32_dpp v195, v35, v113 row_shl:15 row_mask:0xf bank_mask:0xf
	v_fmac_f32_dpp v188, v40, v154 row_shl:14 row_mask:0xf bank_mask:0xf
	v_fmac_f32_dpp v189, v41, v155 row_shl:14 row_mask:0xf bank_mask:0xf
	v_fmac_f32_dpp v190, v42, v156 row_shl:14 row_mask:0xf bank_mask:0xf
	v_fmac_f32_dpp v191, v43, v157 row_shl:14 row_mask:0xf bank_mask:0xf
	v_fmac_f32_dpp v192, v32, v118 row_shl:14 row_mask:0xf bank_mask:0xf
	v_fmac_f32_dpp v193, v33, v119 row_shl:14 row_mask:0xf bank_mask:0xf
	v_fmac_f32_dpp v194, v34, v120 row_shl:14 row_mask:0xf bank_mask:0xf
	v_fmac_f32_dpp v195, v35, v121 row_shl:14 row_mask:0xf bank_mask:0xf
	v_pk_mul_f32 v[196:197], v[188:189], v[216:217] op_sel_hi:[1,0]
	v_pk_mul_f32 v[198:199], v[190:191], v[216:217] op_sel_hi:[1,0]
	v_exp_f32_e32 v196, v196
	v_exp_f32_e32 v197, v197
	v_exp_f32_e32 v198, v198
	v_exp_f32_e32 v199, v199
	v_pk_add_f32 v[196:197], v[196:197], v[214:215] op_sel_hi:[1,0]
	v_pk_add_f32 v[198:199], v[198:199], v[214:215] op_sel_hi:[1,0]
	v_rcp_f32_e32 v196, v196
	v_rcp_f32_e32 v197, v197
	v_rcp_f32_e32 v198, v198
	v_rcp_f32_e32 v199, v199
	v_pk_mul_f32 v[188:189], v[188:189], v[196:197]
	v_pk_mul_f32 v[190:191], v[190:191], v[198:199]
	v_pk_mul_f32 v[188:189], v[188:189], v[192:193]
	v_pk_mul_f32 v[190:191], v[190:191], v[194:195]
	v_cvt_pk_bf16_f32 v140, v188, v189
	v_cvt_pk_bf16_f32 v141, v190, v191
	v_add_u32_e32 v213, 0xb0000, v215
	global_store_dwordx4 v213, v[138:141], s[96:97]
	v_pk_fma_f32 v[188:189], v[24:25], v[134:135], v[130:131]
	v_pk_fma_f32 v[190:191], v[26:27], v[136:137], v[132:133]
	v_pk_fma_f32 v[192:193], v[12:13], v[204:205], v[208:209]
	v_pk_fma_f32 v[194:195], v[14:15], v[206:207], v[210:211]
	v_fmac_f32_dpp v188, v24, v142 row_shr:1 row_mask:0xf bank_mask:0xf
	v_fmac_f32_dpp v189, v25, v143 row_shr:1 row_mask:0xf bank_mask:0xf
	v_fmac_f32_dpp v190, v26, v144 row_shr:1 row_mask:0xf bank_mask:0xf
	v_fmac_f32_dpp v191, v27, v145 row_shr:1 row_mask:0xf bank_mask:0xf
	v_fmac_f32_dpp v192, v12, v110 row_shr:1 row_mask:0xf bank_mask:0xf
	v_fmac_f32_dpp v193, v13, v111 row_shr:1 row_mask:0xf bank_mask:0xf
	v_fmac_f32_dpp v194, v14, v112 row_shr:1 row_mask:0xf bank_mask:0xf
	v_fmac_f32_dpp v195, v15, v113 row_shr:1 row_mask:0xf bank_mask:0xf
	v_fmac_f32_dpp v188, v24, v154 row_shr:2 row_mask:0xf bank_mask:0xf
	v_fmac_f32_dpp v189, v25, v155 row_shr:2 row_mask:0xf bank_mask:0xf
	v_fmac_f32_dpp v190, v26, v156 row_shr:2 row_mask:0xf bank_mask:0xf
	v_fmac_f32_dpp v191, v27, v157 row_shr:2 row_mask:0xf bank_mask:0xf
	v_fmac_f32_dpp v192, v12, v118 row_shr:2 row_mask:0xf bank_mask:0xf
	v_fmac_f32_dpp v193, v13, v119 row_shr:2 row_mask:0xf bank_mask:0xf
	v_fmac_f32_dpp v194, v14, v120 row_shr:2 row_mask:0xf bank_mask:0xf
	v_fmac_f32_dpp v195, v15, v121 row_shr:2 row_mask:0xf bank_mask:0xf
	v_fmac_f32_dpp v188, v28, v142 row_shl:15 row_mask:0xf bank_mask:0xf
	v_fmac_f32_dpp v189, v29, v143 row_shl:15 row_mask:0xf bank_mask:0xf
	v_fmac_f32_dpp v190, v30, v144 row_shl:15 row_mask:0xf bank_mask:0xf
	v_fmac_f32_dpp v191, v31, v145 row_shl:15 row_mask:0xf bank_mask:0xf
	v_fmac_f32_dpp v192, v16, v110 row_shl:15 row_mask:0xf bank_mask:0xf
	v_fmac_f32_dpp v193, v17, v111 row_shl:15 row_mask:0xf bank_mask:0xf
	v_fmac_f32_dpp v194, v18, v112 row_shl:15 row_mask:0xf bank_mask:0xf
	v_fmac_f32_dpp v195, v19, v113 row_shl:15 row_mask:0xf bank_mask:0xf
	v_fmac_f32_dpp v188, v28, v154 row_shl:14 row_mask:0xf bank_mask:0xf
	v_fmac_f32_dpp v189, v29, v155 row_shl:14 row_mask:0xf bank_mask:0xf
	v_fmac_f32_dpp v190, v30, v156 row_shl:14 row_mask:0xf bank_mask:0xf
	v_fmac_f32_dpp v191, v31, v157 row_shl:14 row_mask:0xf bank_mask:0xf
	v_fmac_f32_dpp v192, v16, v118 row_shl:14 row_mask:0xf bank_mask:0xf
	v_fmac_f32_dpp v193, v17, v119 row_shl:14 row_mask:0xf bank_mask:0xf
	v_fmac_f32_dpp v194, v18, v120 row_shl:14 row_mask:0xf bank_mask:0xf
	v_fmac_f32_dpp v195, v19, v121 row_shl:14 row_mask:0xf bank_mask:0xf
	v_pk_mul_f32 v[196:197], v[188:189], v[216:217] op_sel_hi:[1,0]
	v_pk_mul_f32 v[198:199], v[190:191], v[216:217] op_sel_hi:[1,0]
	v_exp_f32_e32 v196, v196
	v_exp_f32_e32 v197, v197
	v_exp_f32_e32 v198, v198
	v_exp_f32_e32 v199, v199
	v_pk_add_f32 v[196:197], v[196:197], v[214:215] op_sel_hi:[1,0]
	v_pk_add_f32 v[198:199], v[198:199], v[214:215] op_sel_hi:[1,0]
	v_rcp_f32_e32 v196, v196
	v_rcp_f32_e32 v197, v197
	v_rcp_f32_e32 v198, v198
	v_rcp_f32_e32 v199, v199
	v_pk_mul_f32 v[188:189], v[188:189], v[196:197]
	v_pk_mul_f32 v[190:191], v[190:191], v[198:199]
	v_pk_mul_f32 v[188:189], v[188:189], v[192:193]
	v_pk_mul_f32 v[190:191], v[190:191], v[194:195]
	v_cvt_pk_bf16_f32 v128, v188, v189
	v_cvt_pk_bf16_f32 v129, v190, v191
	v_add_u32_e32 v213, 0xdc000, v215
	global_store_dwordx4 v213, v[126:129], s[96:97]
	v_pk_fma_f32 v[188:189], v[20:21], v[134:135], v[130:131]
	v_pk_fma_f32 v[190:191], v[22:23], v[136:137], v[132:133]
	v_pk_fma_f32 v[192:193], v[8:9], v[204:205], v[208:209]
	v_pk_fma_f32 v[194:195], v[10:11], v[206:207], v[210:211]
	v_fmac_f32_dpp v188, v20, v142 row_shr:1 row_mask:0xf bank_mask:0xf
	v_fmac_f32_dpp v189, v21, v143 row_shr:1 row_mask:0xf bank_mask:0xf
	v_fmac_f32_dpp v190, v22, v144 row_shr:1 row_mask:0xf bank_mask:0xf
	v_fmac_f32_dpp v191, v23, v145 row_shr:1 row_mask:0xf bank_mask:0xf
	v_fmac_f32_dpp v192, v8, v110 row_shr:1 row_mask:0xf bank_mask:0xf
	v_fmac_f32_dpp v193, v9, v111 row_shr:1 row_mask:0xf bank_mask:0xf
	v_fmac_f32_dpp v194, v10, v112 row_shr:1 row_mask:0xf bank_mask:0xf
	v_fmac_f32_dpp v195, v11, v113 row_shr:1 row_mask:0xf bank_mask:0xf
	v_fmac_f32_dpp v188, v20, v154 row_shr:2 row_mask:0xf bank_mask:0xf
	v_fmac_f32_dpp v189, v21, v155 row_shr:2 row_mask:0xf bank_mask:0xf
	v_fmac_f32_dpp v190, v22, v156 row_shr:2 row_mask:0xf bank_mask:0xf
	v_fmac_f32_dpp v191, v23, v157 row_shr:2 row_mask:0xf bank_mask:0xf
	v_fmac_f32_dpp v192, v8, v118 row_shr:2 row_mask:0xf bank_mask:0xf
	v_fmac_f32_dpp v193, v9, v119 row_shr:2 row_mask:0xf bank_mask:0xf
	v_fmac_f32_dpp v194, v10, v120 row_shr:2 row_mask:0xf bank_mask:0xf
	v_fmac_f32_dpp v195, v11, v121 row_shr:2 row_mask:0xf bank_mask:0xf
	v_fmac_f32_dpp v188, v24, v142 row_shl:15 row_mask:0xf bank_mask:0xf
	v_fmac_f32_dpp v189, v25, v143 row_shl:15 row_mask:0xf bank_mask:0xf
	v_fmac_f32_dpp v190, v26, v144 row_shl:15 row_mask:0xf bank_mask:0xf
	v_fmac_f32_dpp v191, v27, v145 row_shl:15 row_mask:0xf bank_mask:0xf
	v_fmac_f32_dpp v192, v12, v110 row_shl:15 row_mask:0xf bank_mask:0xf
	v_fmac_f32_dpp v193, v13, v111 row_shl:15 row_mask:0xf bank_mask:0xf
	v_fmac_f32_dpp v194, v14, v112 row_shl:15 row_mask:0xf bank_mask:0xf
	v_fmac_f32_dpp v195, v15, v113 row_shl:15 row_mask:0xf bank_mask:0xf
	v_fmac_f32_dpp v188, v24, v154 row_shl:14 row_mask:0xf bank_mask:0xf
	v_fmac_f32_dpp v189, v25, v155 row_shl:14 row_mask:0xf bank_mask:0xf
	v_fmac_f32_dpp v190, v26, v156 row_shl:14 row_mask:0xf bank_mask:0xf
	v_fmac_f32_dpp v191, v27, v157 row_shl:14 row_mask:0xf bank_mask:0xf
	v_fmac_f32_dpp v192, v12, v118 row_shl:14 row_mask:0xf bank_mask:0xf
	v_fmac_f32_dpp v193, v13, v119 row_shl:14 row_mask:0xf bank_mask:0xf
	v_fmac_f32_dpp v194, v14, v120 row_shl:14 row_mask:0xf bank_mask:0xf
	v_fmac_f32_dpp v195, v15, v121 row_shl:14 row_mask:0xf bank_mask:0xf
	v_pk_mul_f32 v[196:197], v[188:189], v[216:217] op_sel_hi:[1,0]
	v_pk_mul_f32 v[198:199], v[190:191], v[216:217] op_sel_hi:[1,0]
	v_exp_f32_e32 v196, v196
	v_exp_f32_e32 v197, v197
	v_exp_f32_e32 v198, v198
	v_exp_f32_e32 v199, v199
	v_pk_add_f32 v[196:197], v[196:197], v[214:215] op_sel_hi:[1,0]
	v_pk_add_f32 v[198:199], v[198:199], v[214:215] op_sel_hi:[1,0]
	v_rcp_f32_e32 v196, v196
	v_rcp_f32_e32 v197, v197
	v_rcp_f32_e32 v198, v198
	v_rcp_f32_e32 v199, v199
	v_pk_mul_f32 v[188:189], v[188:189], v[196:197]
	v_pk_mul_f32 v[190:191], v[190:191], v[198:199]
	v_pk_mul_f32 v[188:189], v[188:189], v[192:193]
	v_pk_mul_f32 v[190:191], v[190:191], v[194:195]
	v_cvt_pk_bf16_f32 v124, v188, v189
	v_cvt_pk_bf16_f32 v125, v190, v191
	v_add_u32_e32 v213, 0x108000, v215
	global_store_dwordx4 v213, v[122:125], s[96:97]
	v_pk_fma_f32 v[188:189], v[4:5], v[134:135], v[130:131]
	v_pk_fma_f32 v[190:191], v[6:7], v[136:137], v[132:133]
	v_pk_fma_f32 v[192:193], v[0:1], v[204:205], v[208:209]
	v_pk_fma_f32 v[194:195], v[2:3], v[206:207], v[210:211]
	v_fmac_f32_dpp v188, v4, v142 row_shr:1 row_mask:0xf bank_mask:0xf
	v_fmac_f32_dpp v189, v5, v143 row_shr:1 row_mask:0xf bank_mask:0xf
	v_fmac_f32_dpp v190, v6, v144 row_shr:1 row_mask:0xf bank_mask:0xf
	v_fmac_f32_dpp v191, v7, v145 row_shr:1 row_mask:0xf bank_mask:0xf
	v_fmac_f32_dpp v192, v0, v110 row_shr:1 row_mask:0xf bank_mask:0xf
	v_fmac_f32_dpp v193, v1, v111 row_shr:1 row_mask:0xf bank_mask:0xf
	v_fmac_f32_dpp v194, v2, v112 row_shr:1 row_mask:0xf bank_mask:0xf
	v_fmac_f32_dpp v195, v3, v113 row_shr:1 row_mask:0xf bank_mask:0xf
	v_fmac_f32_dpp v188, v4, v154 row_shr:2 row_mask:0xf bank_mask:0xf
	v_fmac_f32_dpp v189, v5, v155 row_shr:2 row_mask:0xf bank_mask:0xf
	v_fmac_f32_dpp v190, v6, v156 row_shr:2 row_mask:0xf bank_mask:0xf
	v_fmac_f32_dpp v191, v7, v157 row_shr:2 row_mask:0xf bank_mask:0xf
	v_fmac_f32_dpp v192, v0, v118 row_shr:2 row_mask:0xf bank_mask:0xf
	v_fmac_f32_dpp v193, v1, v119 row_shr:2 row_mask:0xf bank_mask:0xf
	v_fmac_f32_dpp v194, v2, v120 row_shr:2 row_mask:0xf bank_mask:0xf
	v_fmac_f32_dpp v195, v3, v121 row_shr:2 row_mask:0xf bank_mask:0xf
	v_fmac_f32_dpp v188, v20, v142 row_shl:15 row_mask:0xf bank_mask:0xf
	v_fmac_f32_dpp v189, v21, v143 row_shl:15 row_mask:0xf bank_mask:0xf
	v_fmac_f32_dpp v190, v22, v144 row_shl:15 row_mask:0xf bank_mask:0xf
	v_fmac_f32_dpp v191, v23, v145 row_shl:15 row_mask:0xf bank_mask:0xf
	v_fmac_f32_dpp v192, v8, v110 row_shl:15 row_mask:0xf bank_mask:0xf
	v_fmac_f32_dpp v193, v9, v111 row_shl:15 row_mask:0xf bank_mask:0xf
	v_fmac_f32_dpp v194, v10, v112 row_shl:15 row_mask:0xf bank_mask:0xf
	v_fmac_f32_dpp v195, v11, v113 row_shl:15 row_mask:0xf bank_mask:0xf
	v_fmac_f32_dpp v188, v20, v154 row_shl:14 row_mask:0xf bank_mask:0xf
	v_fmac_f32_dpp v189, v21, v155 row_shl:14 row_mask:0xf bank_mask:0xf
	v_fmac_f32_dpp v190, v22, v156 row_shl:14 row_mask:0xf bank_mask:0xf
	v_fmac_f32_dpp v191, v23, v157 row_shl:14 row_mask:0xf bank_mask:0xf
	v_fmac_f32_dpp v192, v8, v118 row_shl:14 row_mask:0xf bank_mask:0xf
	v_fmac_f32_dpp v193, v9, v119 row_shl:14 row_mask:0xf bank_mask:0xf
	v_fmac_f32_dpp v194, v10, v120 row_shl:14 row_mask:0xf bank_mask:0xf
	v_fmac_f32_dpp v195, v11, v121 row_shl:14 row_mask:0xf bank_mask:0xf
	v_pk_mul_f32 v[196:197], v[188:189], v[216:217] op_sel_hi:[1,0]
	v_pk_mul_f32 v[198:199], v[190:191], v[216:217] op_sel_hi:[1,0]
	v_exp_f32_e32 v196, v196
	v_exp_f32_e32 v197, v197
	v_exp_f32_e32 v198, v198
	v_exp_f32_e32 v199, v199
	v_pk_add_f32 v[196:197], v[196:197], v[214:215] op_sel_hi:[1,0]
	v_pk_add_f32 v[198:199], v[198:199], v[214:215] op_sel_hi:[1,0]
	v_rcp_f32_e32 v196, v196
	v_rcp_f32_e32 v197, v197
	v_rcp_f32_e32 v198, v198
	v_rcp_f32_e32 v199, v199
	v_pk_mul_f32 v[188:189], v[188:189], v[196:197]
	v_pk_mul_f32 v[190:191], v[190:191], v[198:199]
	v_pk_mul_f32 v[188:189], v[188:189], v[192:193]
	v_pk_mul_f32 v[190:191], v[190:191], v[194:195]
	v_cvt_pk_bf16_f32 v116, v188, v189
	v_cvt_pk_bf16_f32 v117, v190, v191
	v_add_u32_e32 v213, 0x134000, v215
	global_store_dwordx4 v213, v[114:117], s[96:97]
	s_branch .LBB0_836

.LBB0_985:
	ds_read_b128 v[136:139], v141
	ds_read_b128 v[146:149], v216
	ds_read_b128 v[150:153], v141 offset:2048
	ds_read_b128 v[154:157], v216 offset:2048
	s_add_u32 s14, s0, 0xffea0080
	s_addc_u32 s15, s1, -1
	s_cmpk_eq_i32 s41, 0x54
	s_cselect_b32 s17, s5, s15
	s_cselect_b32 s16, s4, s14
	s_cselect_b32 s15, s7, s40
	s_cselect_b32 s14, s6, s39
	s_add_i32 m0, s21, 0xc000
	ds_read_b128 v[158:161], v142
	ds_read_b128 v[164:167], v217
	ds_read_b128 v[176:179], v142 offset:2048
	ds_read_b128 v[180:183], v217 offset:2048
	ds_read_b128 v[184:187], v142 offset:4096
	ds_read_b128 v[188:191], v217 offset:4096
	ds_read_b128 v[192:195], v142 offset:6144
	ds_read_b128 v[196:199], v217 offset:6144
	global_load_lds_dwordx4 v128, s[0:1]
	s_add_i32 m0, s21, 0xe000
	s_nop 0
	global_load_lds_dwordx4 v130, s[0:1]
	s_waitcnt lgkmcnt(8)
	s_barrier
	s_waitcnt lgkmcnt(0)
	s_waitcnt lgkmcnt(0)
	v_mfma_f32_16x16x32_bf16 v[124:127], v[136:139], v[158:161], v[124:127]
	v_mfma_f32_16x16x32_bf16 v[124:127], v[146:149], v[164:167], v[124:127]
	v_mfma_f32_16x16x32_bf16 v[120:123], v[154:157], v[164:167], v[120:123]
	v_mfma_f32_16x16x32_bf16 v[120:123], v[150:153], v[158:161], v[120:123]
	v_mfma_f32_16x16x32_bf16 v[104:107], v[150:153], v[176:179], v[104:107]
	v_mfma_f32_16x16x32_bf16 v[104:107], v[154:157], v[180:183], v[104:107]
	v_mfma_f32_16x16x32_bf16 v[108:111], v[146:149], v[180:183], v[108:111]
	v_mfma_f32_16x16x32_bf16 v[108:111], v[136:139], v[176:179], v[108:111]
	v_mfma_f32_16x16x32_bf16 v[92:95], v[136:139], v[184:187], v[92:95]
	v_mfma_f32_16x16x32_bf16 v[92:95], v[146:149], v[188:191], v[92:95]
	v_mfma_f32_16x16x32_bf16 v[88:91], v[154:157], v[188:191], v[88:91]
	v_mfma_f32_16x16x32_bf16 v[88:91], v[150:153], v[184:187], v[88:91]
	v_mfma_f32_16x16x32_bf16 v[72:75], v[150:153], v[192:195], v[72:75]
	v_mfma_f32_16x16x32_bf16 v[72:75], v[154:157], v[196:199], v[72:75]
	v_mfma_f32_16x16x32_bf16 v[76:79], v[146:149], v[196:199], v[76:79]
	v_mfma_f32_16x16x32_bf16 v[76:79], v[136:139], v[192:195], v[76:79]
	s_barrier
	s_add_i32 s42, s33, s20
	s_add_u32 s98, s14, s12
	s_addc_u32 s99, s15, s13
	s_mov_b32 m0, s42
	ds_read_b128 v[200:203], v143
	ds_read_b128 v[204:207], v218
	ds_read_b128 v[208:211], v143 offset:2048
	ds_read_b128 v[212:215], v218 offset:2048
	global_load_lds_dwordx4 v170, s[14:15]
	s_add_i32 m0, s42, 0x2000
	s_nop 0
	global_load_lds_dwordx4 v174, s[14:15]
	s_barrier
	s_waitcnt lgkmcnt(0)
	s_waitcnt lgkmcnt(0)
	v_mfma_f32_16x16x32_bf16 v[116:119], v[200:203], v[158:161], v[116:119]
	v_mfma_f32_16x16x32_bf16 v[116:119], v[204:207], v[164:167], v[116:119]
	v_mfma_f32_16x16x32_bf16 v[112:115], v[212:215], v[164:167], v[112:115]
	v_mfma_f32_16x16x32_bf16 v[112:115], v[208:211], v[158:161], v[112:115]
	v_mfma_f32_16x16x32_bf16 v[96:99], v[208:211], v[176:179], v[96:99]
	v_mfma_f32_16x16x32_bf16 v[96:99], v[212:215], v[180:183], v[96:99]
	v_mfma_f32_16x16x32_bf16 v[100:103], v[204:207], v[180:183], v[100:103]
	v_mfma_f32_16x16x32_bf16 v[100:103], v[200:203], v[176:179], v[100:103]
	v_mfma_f32_16x16x32_bf16 v[84:87], v[200:203], v[184:187], v[84:87]
	v_mfma_f32_16x16x32_bf16 v[84:87], v[204:207], v[188:191], v[84:87]
	v_mfma_f32_16x16x32_bf16 v[80:83], v[212:215], v[188:191], v[80:83]
	v_mfma_f32_16x16x32_bf16 v[80:83], v[208:211], v[184:187], v[80:83]
	v_mfma_f32_16x16x32_bf16 v[64:67], v[208:211], v[192:195], v[64:67]
	v_mfma_f32_16x16x32_bf16 v[64:67], v[212:215], v[196:199], v[64:67]
	v_mfma_f32_16x16x32_bf16 v[68:71], v[204:207], v[196:199], v[68:71]
	v_mfma_f32_16x16x32_bf16 v[68:71], v[200:203], v[192:195], v[68:71]
	s_mov_b32 m0, s21
	s_add_u32 s100, s16, s12
	s_addc_u32 s101, s17, s13
	s_barrier
	ds_read_b128 v[158:161], v142 offset:16384
	ds_read_b128 v[164:167], v217 offset:16384
	ds_read_b128 v[176:179], v142 offset:18432
	ds_read_b128 v[180:183], v217 offset:18432
	ds_read_b128 v[184:187], v142 offset:20480
	ds_read_b128 v[188:191], v217 offset:20480
	ds_read_b128 v[192:195], v142 offset:22528
	ds_read_b128 v[196:199], v217 offset:22528
	global_load_lds_dwordx4 v168, s[16:17]
	s_mov_b32 m0, s22
	s_nop 0
	global_load_lds_dwordx4 v172, s[16:17]
	s_barrier
	s_waitcnt lgkmcnt(0)
	s_waitcnt lgkmcnt(0)
	v_mfma_f32_16x16x32_bf16 v[60:63], v[136:139], v[158:161], v[60:63]
	v_mfma_f32_16x16x32_bf16 v[60:63], v[146:149], v[164:167], v[60:63]
	v_mfma_f32_16x16x32_bf16 v[56:59], v[154:157], v[164:167], v[56:59]
	v_mfma_f32_16x16x32_bf16 v[56:59], v[150:153], v[158:161], v[56:59]
	v_mfma_f32_16x16x32_bf16 v[40:43], v[150:153], v[176:179], v[40:43]
	v_mfma_f32_16x16x32_bf16 v[40:43], v[154:157], v[180:183], v[40:43]
	v_mfma_f32_16x16x32_bf16 v[44:47], v[146:149], v[180:183], v[44:47]
	v_mfma_f32_16x16x32_bf16 v[44:47], v[136:139], v[176:179], v[44:47]
	v_mfma_f32_16x16x32_bf16 v[28:31], v[136:139], v[184:187], v[28:31]
	v_mfma_f32_16x16x32_bf16 v[28:31], v[146:149], v[188:191], v[28:31]
	v_mfma_f32_16x16x32_bf16 v[24:27], v[154:157], v[188:191], v[24:27]
	v_mfma_f32_16x16x32_bf16 v[24:27], v[150:153], v[184:187], v[24:27]
	v_mfma_f32_16x16x32_bf16 v[8:11], v[150:153], v[192:195], v[8:11]
	v_mfma_f32_16x16x32_bf16 v[8:11], v[154:157], v[196:199], v[8:11]
	v_mfma_f32_16x16x32_bf16 v[12:15], v[146:149], v[196:199], v[12:15]
	v_mfma_f32_16x16x32_bf16 v[12:15], v[136:139], v[192:195], v[12:15]
	s_barrier
	s_add_u32 s42, s14, 0x160000
	s_addc_u32 s43, s15, 0
	s_add_i32 s44, s34, s20
	s_mov_b32 m0, s44
	s_nop 0
	global_load_lds_dwordx4 v170, s[42:43]
	s_add_i32 m0, s44, 0x2000
	s_nop 0
	global_load_lds_dwordx4 v174, s[42:43]
	s_waitcnt vmcnt(6)
	s_barrier
	v_mfma_f32_16x16x32_bf16 v[52:55], v[200:203], v[158:161], v[52:55]
	v_mfma_f32_16x16x32_bf16 v[52:55], v[204:207], v[164:167], v[52:55]
	v_mfma_f32_16x16x32_bf16 v[48:51], v[212:215], v[164:167], v[48:51]
	v_mfma_f32_16x16x32_bf16 v[48:51], v[208:211], v[158:161], v[48:51]
	v_mfma_f32_16x16x32_bf16 v[32:35], v[208:211], v[176:179], v[32:35]
	v_mfma_f32_16x16x32_bf16 v[32:35], v[212:215], v[180:183], v[32:35]
	v_mfma_f32_16x16x32_bf16 v[36:39], v[204:207], v[180:183], v[36:39]
	v_mfma_f32_16x16x32_bf16 v[36:39], v[200:203], v[176:179], v[36:39]
	v_mfma_f32_16x16x32_bf16 v[20:23], v[200:203], v[184:187], v[20:23]
	v_mfma_f32_16x16x32_bf16 v[20:23], v[204:207], v[188:191], v[20:23]
	v_mfma_f32_16x16x32_bf16 v[16:19], v[212:215], v[188:191], v[16:19]
	v_mfma_f32_16x16x32_bf16 v[16:19], v[208:211], v[184:187], v[16:19]
	v_mfma_f32_16x16x32_bf16 v[0:3], v[208:211], v[192:195], v[0:3]
	v_mfma_f32_16x16x32_bf16 v[0:3], v[212:215], v[196:199], v[0:3]
	v_mfma_f32_16x16x32_bf16 v[4:7], v[204:207], v[196:199], v[4:7]
	v_mfma_f32_16x16x32_bf16 v[4:7], v[200:203], v[192:195], v[4:7]
	s_add_i32 s42, 0, 0x18000
	s_barrier
	ds_read_b128 v[136:139], v219
	ds_read_b128 v[146:149], v220
	ds_read_b128 v[150:153], v219 offset:2048
	ds_read_b128 v[154:157], v220 offset:2048
	s_add_u32 s16, s16, 0x160000
	s_addc_u32 s17, s17, 0
	s_mov_b32 m0, s23
	ds_read_b128 v[158:161], v142 offset:32768
	ds_read_b128 v[164:167], v217 offset:32768
	ds_read_b128 v[176:179], v142 offset:34816
	ds_read_b128 v[180:183], v217 offset:34816
	ds_read_b128 v[184:187], v142 offset:36864
	ds_read_b128 v[188:191], v217 offset:36864
	ds_read_b128 v[192:195], v142 offset:38912
	ds_read_b128 v[196:199], v217 offset:38912
	global_load_lds_dwordx4 v168, s[16:17]
	s_mov_b32 m0, s24
	s_nop 0
	global_load_lds_dwordx4 v172, s[16:17]
	s_waitcnt lgkmcnt(8)
	s_barrier
	s_waitcnt lgkmcnt(0)
	s_waitcnt lgkmcnt(0)
	v_mfma_f32_16x16x32_bf16 v[124:127], v[136:139], v[158:161], v[124:127]
	v_mfma_f32_16x16x32_bf16 v[124:127], v[146:149], v[164:167], v[124:127]
	v_mfma_f32_16x16x32_bf16 v[120:123], v[154:157], v[164:167], v[120:123]
	v_mfma_f32_16x16x32_bf16 v[120:123], v[150:153], v[158:161], v[120:123]
	v_mfma_f32_16x16x32_bf16 v[104:107], v[150:153], v[176:179], v[104:107]
	v_mfma_f32_16x16x32_bf16 v[104:107], v[154:157], v[180:183], v[104:107]
	v_mfma_f32_16x16x32_bf16 v[108:111], v[146:149], v[180:183], v[108:111]
	v_mfma_f32_16x16x32_bf16 v[108:111], v[136:139], v[176:179], v[108:111]
	v_mfma_f32_16x16x32_bf16 v[92:95], v[136:139], v[184:187], v[92:95]
	v_mfma_f32_16x16x32_bf16 v[92:95], v[146:149], v[188:191], v[92:95]
	v_mfma_f32_16x16x32_bf16 v[88:91], v[154:157], v[188:191], v[88:91]
	v_mfma_f32_16x16x32_bf16 v[88:91], v[150:153], v[184:187], v[88:91]
	v_mfma_f32_16x16x32_bf16 v[72:75], v[150:153], v[192:195], v[72:75]
	v_mfma_f32_16x16x32_bf16 v[72:75], v[154:157], v[196:199], v[72:75]
	v_mfma_f32_16x16x32_bf16 v[76:79], v[146:149], v[196:199], v[76:79]
	v_mfma_f32_16x16x32_bf16 v[76:79], v[136:139], v[192:195], v[76:79]
	s_barrier
	s_add_i32 s16, 0, 0x1c000
	s_add_i32 s17, s42, s20
	v_add_u32_e32 v145, s16, v140
	s_mov_b32 m0, s17
	ds_read_b128 v[200:203], v145
	v_xor_b32_e32 v215, 64, v145
	ds_read_b128 v[204:207], v215
	ds_read_b128 v[208:211], v145 offset:2048
	ds_read_b128 v[212:215], v215 offset:2048
	global_load_lds_dwordx4 v170, s[98:99]
	s_add_i32 m0, s17, 0x2000
	s_nop 0
	global_load_lds_dwordx4 v174, s[98:99]
	s_barrier
	s_waitcnt lgkmcnt(0)
	s_waitcnt lgkmcnt(0)
	v_mfma_f32_16x16x32_bf16 v[116:119], v[200:203], v[158:161], v[116:119]
	v_mfma_f32_16x16x32_bf16 v[116:119], v[204:207], v[164:167], v[116:119]
	v_mfma_f32_16x16x32_bf16 v[112:115], v[212:215], v[164:167], v[112:115]
	v_mfma_f32_16x16x32_bf16 v[112:115], v[208:211], v[158:161], v[112:115]
	v_mfma_f32_16x16x32_bf16 v[96:99], v[208:211], v[176:179], v[96:99]
	v_mfma_f32_16x16x32_bf16 v[96:99], v[212:215], v[180:183], v[96:99]
	v_mfma_f32_16x16x32_bf16 v[100:103], v[204:207], v[180:183], v[100:103]
	v_mfma_f32_16x16x32_bf16 v[100:103], v[200:203], v[176:179], v[100:103]
	v_mfma_f32_16x16x32_bf16 v[84:87], v[200:203], v[184:187], v[84:87]
	v_mfma_f32_16x16x32_bf16 v[84:87], v[204:207], v[188:191], v[84:87]
	v_mfma_f32_16x16x32_bf16 v[80:83], v[212:215], v[188:191], v[80:83]
	v_mfma_f32_16x16x32_bf16 v[80:83], v[208:211], v[184:187], v[80:83]
	v_mfma_f32_16x16x32_bf16 v[64:67], v[208:211], v[192:195], v[64:67]
	v_mfma_f32_16x16x32_bf16 v[64:67], v[212:215], v[196:199], v[64:67]
	v_mfma_f32_16x16x32_bf16 v[68:71], v[204:207], v[196:199], v[68:71]
	v_mfma_f32_16x16x32_bf16 v[68:71], v[200:203], v[192:195], v[68:71]
	s_mov_b32 m0, s28
	s_barrier
	ds_read_b128 v[158:161], v142 offset:49152
	ds_read_b128 v[164:167], v217 offset:49152
	ds_read_b128 v[176:179], v142 offset:51200
	ds_read_b128 v[180:183], v217 offset:51200
	ds_read_b128 v[184:187], v142 offset:53248
	ds_read_b128 v[188:191], v217 offset:53248
	ds_read_b128 v[192:195], v142 offset:55296
	ds_read_b128 v[196:199], v217 offset:55296
	global_load_lds_dwordx4 v168, s[100:101]
	s_mov_b32 m0, s29
	s_nop 0
	global_load_lds_dwordx4 v172, s[100:101]
	s_barrier
	s_waitcnt lgkmcnt(0)
	s_waitcnt lgkmcnt(0)
	v_mfma_f32_16x16x32_bf16 v[60:63], v[136:139], v[158:161], v[60:63]
	v_mfma_f32_16x16x32_bf16 v[60:63], v[146:149], v[164:167], v[60:63]
	v_mfma_f32_16x16x32_bf16 v[56:59], v[154:157], v[164:167], v[56:59]
	v_mfma_f32_16x16x32_bf16 v[56:59], v[150:153], v[158:161], v[56:59]
	v_mfma_f32_16x16x32_bf16 v[40:43], v[150:153], v[176:179], v[40:43]
	v_mfma_f32_16x16x32_bf16 v[40:43], v[154:157], v[180:183], v[40:43]
	v_mfma_f32_16x16x32_bf16 v[44:47], v[146:149], v[180:183], v[44:47]
	v_mfma_f32_16x16x32_bf16 v[44:47], v[136:139], v[176:179], v[44:47]
	v_mfma_f32_16x16x32_bf16 v[28:31], v[136:139], v[184:187], v[28:31]
	v_mfma_f32_16x16x32_bf16 v[28:31], v[146:149], v[188:191], v[28:31]
	v_mfma_f32_16x16x32_bf16 v[24:27], v[154:157], v[188:191], v[24:27]
	v_mfma_f32_16x16x32_bf16 v[24:27], v[150:153], v[184:187], v[24:27]
	v_mfma_f32_16x16x32_bf16 v[8:11], v[150:153], v[192:195], v[8:11]
	v_mfma_f32_16x16x32_bf16 v[8:11], v[154:157], v[196:199], v[8:11]
	v_mfma_f32_16x16x32_bf16 v[12:15], v[146:149], v[196:199], v[12:15]
	v_mfma_f32_16x16x32_bf16 v[12:15], v[136:139], v[192:195], v[12:15]
	s_barrier
	s_add_u32 s14, s14, 0x160080
	s_addc_u32 s15, s15, 0
	s_add_i32 s16, s16, s20
	s_mov_b32 m0, s16
	s_nop 0
	global_load_lds_dwordx4 v170, s[14:15]
	s_add_i32 m0, s16, 0x2000
	s_nop 0
	global_load_lds_dwordx4 v174, s[14:15]
	s_waitcnt vmcnt(6)
	s_barrier
	v_mfma_f32_16x16x32_bf16 v[52:55], v[200:203], v[158:161], v[52:55]
	v_mfma_f32_16x16x32_bf16 v[52:55], v[204:207], v[164:167], v[52:55]
	v_mfma_f32_16x16x32_bf16 v[48:51], v[212:215], v[164:167], v[48:51]
	v_mfma_f32_16x16x32_bf16 v[48:51], v[208:211], v[158:161], v[48:51]
	v_mfma_f32_16x16x32_bf16 v[32:35], v[208:211], v[176:179], v[32:35]
	v_mfma_f32_16x16x32_bf16 v[32:35], v[212:215], v[180:183], v[32:35]
	v_mfma_f32_16x16x32_bf16 v[36:39], v[204:207], v[180:183], v[36:39]
	v_mfma_f32_16x16x32_bf16 v[36:39], v[200:203], v[176:179], v[36:39]
	v_mfma_f32_16x16x32_bf16 v[20:23], v[200:203], v[184:187], v[20:23]
	v_mfma_f32_16x16x32_bf16 v[20:23], v[204:207], v[188:191], v[20:23]
	v_mfma_f32_16x16x32_bf16 v[16:19], v[212:215], v[188:191], v[16:19]
	v_mfma_f32_16x16x32_bf16 v[16:19], v[208:211], v[184:187], v[16:19]
	v_mfma_f32_16x16x32_bf16 v[0:3], v[208:211], v[192:195], v[0:3]
	v_mfma_f32_16x16x32_bf16 v[0:3], v[212:215], v[196:199], v[0:3]
	v_mfma_f32_16x16x32_bf16 v[4:7], v[204:207], v[196:199], v[4:7]
	v_mfma_f32_16x16x32_bf16 v[4:7], v[200:203], v[192:195], v[4:7]
	s_add_i32 s41, s41, 2
	s_add_u32 s0, s0, 0x100
	s_addc_u32 s1, s1, 0
	s_add_u32 s39, s39, 0x100
	s_addc_u32 s40, s40, 0
	s_cmpk_gt_u32 s41, 0x55
	s_barrier
	s_cbranch_scc0 .LBB0_985
	v_lshl_add_u32 v217, s38, 8, v163
	v_add_u32_e32 v217, s26, v217
	v_lshlrev_b32_e32 v208, 2, v217
	v_lshl_add_u32 v214, v225, 3, s27
	v_lshl_add_u32 v214, s37, 8, v214
	v_lshl_add_u32 v209, v217, 11, v214
	v_lshlrev_b32_e32 v209, 1, v209
	v_lshlrev_b32_e32 v210, 1, v209
	v_lshl_add_u32 v217, v225, 4, v163
	v_xor_b32_e32 v215, 16, v217
	v_lshlrev_b32_e32 v215, 2, v215
	v_xor_b32_e32 v216, 32, v217
	v_lshlrev_b32_e32 v216, 2, v216
	v_add_u32_e32 v211, 0x0, v209
	global_load_dwordx4 v[176:179], v211, s[80:81]
	global_load_dwordx4 v[180:183], v211, s[80:81] offset:256
	v_add_u32_e32 v211, 0x10000, v209
	global_load_dwordx4 v[192:195], v211, s[80:81]
	global_load_dwordx4 v[196:199], v211, s[80:81] offset:256
	s_waitcnt vmcnt(2)
	v_lshlrev_b32_e32 v184, 16, v176
	v_and_b32_e32 v185, 0xffff0000, v176
	v_lshlrev_b32_e32 v186, 16, v177
	v_and_b32_e32 v187, 0xffff0000, v177
	v_lshlrev_b32_e32 v188, 16, v178
	v_and_b32_e32 v189, 0xffff0000, v178
	v_lshlrev_b32_e32 v190, 16, v179
	v_and_b32_e32 v191, 0xffff0000, v179
	v_pk_add_f32 v[124:125], v[124:125], v[184:185]
	v_pk_add_f32 v[126:127], v[126:127], v[186:187]
	v_pk_add_f32 v[120:121], v[120:121], v[188:189]
	v_pk_add_f32 v[122:123], v[122:123], v[190:191]
	v_mul_f32_e32 v213, v124, v124
	v_fmac_f32_e32 v213, v125, v125
	v_fmac_f32_e32 v213, v126, v126
	v_fmac_f32_e32 v213, v127, v127
	v_fmac_f32_e32 v213, v120, v120
	v_fmac_f32_e32 v213, v121, v121
	v_fmac_f32_e32 v213, v122, v122
	v_fmac_f32_e32 v213, v123, v123
	v_add_u32_e32 v212, 0x0, v210
	global_store_dwordx4 v212, v[124:127], s[90:91]
	global_store_dwordx4 v212, v[120:123], s[90:91] offset:16
	v_lshlrev_b32_e32 v184, 16, v180
	v_and_b32_e32 v185, 0xffff0000, v180
	v_lshlrev_b32_e32 v186, 16, v181
	v_and_b32_e32 v187, 0xffff0000, v181
	v_lshlrev_b32_e32 v188, 16, v182
	v_and_b32_e32 v189, 0xffff0000, v182
	v_lshlrev_b32_e32 v190, 16, v183
	v_and_b32_e32 v191, 0xffff0000, v183
	v_pk_add_f32 v[116:117], v[116:117], v[184:185]
	v_pk_add_f32 v[118:119], v[118:119], v[186:187]
	v_pk_add_f32 v[112:113], v[112:113], v[188:189]
	v_pk_add_f32 v[114:115], v[114:115], v[190:191]
	v_fmac_f32_e32 v213, v116, v116
	v_fmac_f32_e32 v213, v117, v117
	v_fmac_f32_e32 v213, v118, v118
	v_fmac_f32_e32 v213, v119, v119
	v_fmac_f32_e32 v213, v112, v112
	v_fmac_f32_e32 v213, v113, v113
	v_fmac_f32_e32 v213, v114, v114
	v_fmac_f32_e32 v213, v115, v115
	global_store_dwordx4 v212, v[116:119], s[90:91] offset:512
	global_store_dwordx4 v212, v[112:115], s[90:91] offset:528
	ds_bpermute_b32 v214, v215, v213
	s_waitcnt lgkmcnt(0)
	v_add_f32_e32 v213, v213, v214
	ds_bpermute_b32 v214, v216, v213
	s_waitcnt lgkmcnt(0)
	v_add_f32_e32 v213, v213, v214
	s_mov_b64 exec, 0xffff
	global_atomic_add_f32 v208, v213, s[10:11]
	s_mov_b64 exec, -1
	v_add_u32_e32 v211, 0x20000, v209
	global_load_dwordx4 v[176:179], v211, s[80:81]
	global_load_dwordx4 v[180:183], v211, s[80:81] offset:256
	s_waitcnt vmcnt(7)
	v_lshlrev_b32_e32 v200, 16, v192
	v_and_b32_e32 v201, 0xffff0000, v192
	v_lshlrev_b32_e32 v202, 16, v193
	v_and_b32_e32 v203, 0xffff0000, v193
	v_lshlrev_b32_e32 v204, 16, v194
	v_and_b32_e32 v205, 0xffff0000, v194
	v_lshlrev_b32_e32 v206, 16, v195
	v_and_b32_e32 v207, 0xffff0000, v195
	v_pk_add_f32 v[108:109], v[108:109], v[200:201]
	v_pk_add_f32 v[110:111], v[110:111], v[202:203]
	v_pk_add_f32 v[104:105], v[104:105], v[204:205]
	v_pk_add_f32 v[106:107], v[106:107], v[206:207]
	v_mul_f32_e32 v213, v108, v108
	v_fmac_f32_e32 v213, v109, v109
	v_fmac_f32_e32 v213, v110, v110
	v_fmac_f32_e32 v213, v111, v111
	v_fmac_f32_e32 v213, v104, v104
	v_fmac_f32_e32 v213, v105, v105
	v_fmac_f32_e32 v213, v106, v106
	v_fmac_f32_e32 v213, v107, v107
	v_add_u32_e32 v212, 0x20000, v210
	global_store_dwordx4 v212, v[108:111], s[90:91]
	global_store_dwordx4 v212, v[104:107], s[90:91] offset:16
	v_lshlrev_b32_e32 v200, 16, v196
	v_and_b32_e32 v201, 0xffff0000, v196
	v_lshlrev_b32_e32 v202, 16, v197
	v_and_b32_e32 v203, 0xffff0000, v197
	v_lshlrev_b32_e32 v204, 16, v198
	v_and_b32_e32 v205, 0xffff0000, v198
	v_lshlrev_b32_e32 v206, 16, v199
	v_and_b32_e32 v207, 0xffff0000, v199
	v_pk_add_f32 v[100:101], v[100:101], v[200:201]
	v_pk_add_f32 v[102:103], v[102:103], v[202:203]
	v_pk_add_f32 v[96:97], v[96:97], v[204:205]
	v_pk_add_f32 v[98:99], v[98:99], v[206:207]
	v_fmac_f32_e32 v213, v100, v100
	v_fmac_f32_e32 v213, v101, v101
	v_fmac_f32_e32 v213, v102, v102
	v_fmac_f32_e32 v213, v103, v103
	v_fmac_f32_e32 v213, v96, v96
	v_fmac_f32_e32 v213, v97, v97
	v_fmac_f32_e32 v213, v98, v98
	v_fmac_f32_e32 v213, v99, v99
	global_store_dwordx4 v212, v[100:103], s[90:91] offset:512
	global_store_dwordx4 v212, v[96:99], s[90:91] offset:528
	ds_bpermute_b32 v214, v215, v213
	s_waitcnt lgkmcnt(0)
	v_add_f32_e32 v213, v213, v214
	ds_bpermute_b32 v214, v216, v213
	s_waitcnt lgkmcnt(0)
	v_add_f32_e32 v213, v213, v214
	s_mov_b64 exec, 0xffff
	global_atomic_add_f32 v208, v213, s[10:11] offset:64
	s_mov_b64 exec, -1
	v_add_u32_e32 v211, 0x30000, v209
	global_load_dwordx4 v[192:195], v211, s[80:81]
	global_load_dwordx4 v[196:199], v211, s[80:81] offset:256
	s_waitcnt vmcnt(7)
	v_lshlrev_b32_e32 v184, 16, v176
	v_and_b32_e32 v185, 0xffff0000, v176
	v_lshlrev_b32_e32 v186, 16, v177
	v_and_b32_e32 v187, 0xffff0000, v177
	v_lshlrev_b32_e32 v188, 16, v178
	v_and_b32_e32 v189, 0xffff0000, v178
	v_lshlrev_b32_e32 v190, 16, v179
	v_and_b32_e32 v191, 0xffff0000, v179
	v_pk_add_f32 v[92:93], v[92:93], v[184:185]
	v_pk_add_f32 v[94:95], v[94:95], v[186:187]
	v_pk_add_f32 v[88:89], v[88:89], v[188:189]
	v_pk_add_f32 v[90:91], v[90:91], v[190:191]
	v_mul_f32_e32 v213, v92, v92
	v_fmac_f32_e32 v213, v93, v93
	v_fmac_f32_e32 v213, v94, v94
	v_fmac_f32_e32 v213, v95, v95
	v_fmac_f32_e32 v213, v88, v88
	v_fmac_f32_e32 v213, v89, v89
	v_fmac_f32_e32 v213, v90, v90
	v_fmac_f32_e32 v213, v91, v91
	v_add_u32_e32 v212, 0x40000, v210
	global_store_dwordx4 v212, v[92:95], s[90:91]
	global_store_dwordx4 v212, v[88:91], s[90:91] offset:16
	v_lshlrev_b32_e32 v184, 16, v180
	v_and_b32_e32 v185, 0xffff0000, v180
	v_lshlrev_b32_e32 v186, 16, v181
	v_and_b32_e32 v187, 0xffff0000, v181
	v_lshlrev_b32_e32 v188, 16, v182
	v_and_b32_e32 v189, 0xffff0000, v182
	v_lshlrev_b32_e32 v190, 16, v183
	v_and_b32_e32 v191, 0xffff0000, v183
	v_pk_add_f32 v[84:85], v[84:85], v[184:185]
	v_pk_add_f32 v[86:87], v[86:87], v[186:187]
	v_pk_add_f32 v[80:81], v[80:81], v[188:189]
	v_pk_add_f32 v[82:83], v[82:83], v[190:191]
	v_fmac_f32_e32 v213, v84, v84
	v_fmac_f32_e32 v213, v85, v85
	v_fmac_f32_e32 v213, v86, v86
	v_fmac_f32_e32 v213, v87, v87
	v_fmac_f32_e32 v213, v80, v80
	v_fmac_f32_e32 v213, v81, v81
	v_fmac_f32_e32 v213, v82, v82
	v_fmac_f32_e32 v213, v83, v83
	global_store_dwordx4 v212, v[84:87], s[90:91] offset:512
	global_store_dwordx4 v212, v[80:83], s[90:91] offset:528
	ds_bpermute_b32 v214, v215, v213
	s_waitcnt lgkmcnt(0)
	v_add_f32_e32 v213, v213, v214
	ds_bpermute_b32 v214, v216, v213
	s_waitcnt lgkmcnt(0)
	v_add_f32_e32 v213, v213, v214
	s_mov_b64 exec, 0xffff
	global_atomic_add_f32 v208, v213, s[10:11] offset:128
	s_mov_b64 exec, -1
	v_add_u32_e32 v211, 0x80000, v209
	global_load_dwordx4 v[176:179], v211, s[80:81]
	global_load_dwordx4 v[180:183], v211, s[80:81] offset:256
	s_waitcnt vmcnt(7)
	v_lshlrev_b32_e32 v200, 16, v192
	v_and_b32_e32 v201, 0xffff0000, v192
	v_lshlrev_b32_e32 v202, 16, v193
	v_and_b32_e32 v203, 0xffff0000, v193
	v_lshlrev_b32_e32 v204, 16, v194
	v_and_b32_e32 v205, 0xffff0000, v194
	v_lshlrev_b32_e32 v206, 16, v195
	v_and_b32_e32 v207, 0xffff0000, v195
	v_pk_add_f32 v[76:77], v[76:77], v[200:201]
	v_pk_add_f32 v[78:79], v[78:79], v[202:203]
	v_pk_add_f32 v[72:73], v[72:73], v[204:205]
	v_pk_add_f32 v[74:75], v[74:75], v[206:207]
	v_mul_f32_e32 v213, v76, v76
	v_fmac_f32_e32 v213, v77, v77
	v_fmac_f32_e32 v213, v78, v78
	v_fmac_f32_e32 v213, v79, v79
	v_fmac_f32_e32 v213, v72, v72
	v_fmac_f32_e32 v213, v73, v73
	v_fmac_f32_e32 v213, v74, v74
	v_fmac_f32_e32 v213, v75, v75
	v_add_u32_e32 v212, 0x60000, v210
	global_store_dwordx4 v212, v[76:79], s[90:91]
	global_store_dwordx4 v212, v[72:75], s[90:91] offset:16
	v_lshlrev_b32_e32 v200, 16, v196
	v_and_b32_e32 v201, 0xffff0000, v196
	v_lshlrev_b32_e32 v202, 16, v197
	v_and_b32_e32 v203, 0xffff0000, v197
	v_lshlrev_b32_e32 v204, 16, v198
	v_and_b32_e32 v205, 0xffff0000, v198
	v_lshlrev_b32_e32 v206, 16, v199
	v_and_b32_e32 v207, 0xffff0000, v199
	v_pk_add_f32 v[68:69], v[68:69], v[200:201]
	v_pk_add_f32 v[70:71], v[70:71], v[202:203]
	v_pk_add_f32 v[64:65], v[64:65], v[204:205]
	v_pk_add_f32 v[66:67], v[66:67], v[206:207]
	v_fmac_f32_e32 v213, v68, v68
	v_fmac_f32_e32 v213, v69, v69
	v_fmac_f32_e32 v213, v70, v70
	v_fmac_f32_e32 v213, v71, v71
	v_fmac_f32_e32 v213, v64, v64
	v_fmac_f32_e32 v213, v65, v65
	v_fmac_f32_e32 v213, v66, v66
	v_fmac_f32_e32 v213, v67, v67
	global_store_dwordx4 v212, v[68:71], s[90:91] offset:512
	global_store_dwordx4 v212, v[64:67], s[90:91] offset:528
	ds_bpermute_b32 v214, v215, v213
	s_waitcnt lgkmcnt(0)
	v_add_f32_e32 v213, v213, v214
	ds_bpermute_b32 v214, v216, v213
	s_waitcnt lgkmcnt(0)
	v_add_f32_e32 v213, v213, v214
	s_mov_b64 exec, 0xffff
	global_atomic_add_f32 v208, v213, s[10:11] offset:192
	s_mov_b64 exec, -1
	v_add_u32_e32 v211, 0x90000, v209
	global_load_dwordx4 v[192:195], v211, s[80:81]
	global_load_dwordx4 v[196:199], v211, s[80:81] offset:256
	s_waitcnt vmcnt(7)
	v_lshlrev_b32_e32 v184, 16, v176
	v_and_b32_e32 v185, 0xffff0000, v176
	v_lshlrev_b32_e32 v186, 16, v177
	v_and_b32_e32 v187, 0xffff0000, v177
	v_lshlrev_b32_e32 v188, 16, v178
	v_and_b32_e32 v189, 0xffff0000, v178
	v_lshlrev_b32_e32 v190, 16, v179
	v_and_b32_e32 v191, 0xffff0000, v179
	v_pk_add_f32 v[60:61], v[60:61], v[184:185]
	v_pk_add_f32 v[62:63], v[62:63], v[186:187]
	v_pk_add_f32 v[56:57], v[56:57], v[188:189]
	v_pk_add_f32 v[58:59], v[58:59], v[190:191]
	v_mul_f32_e32 v213, v60, v60
	v_fmac_f32_e32 v213, v61, v61
	v_fmac_f32_e32 v213, v62, v62
	v_fmac_f32_e32 v213, v63, v63
	v_fmac_f32_e32 v213, v56, v56
	v_fmac_f32_e32 v213, v57, v57
	v_fmac_f32_e32 v213, v58, v58
	v_fmac_f32_e32 v213, v59, v59
	v_add_u32_e32 v212, 0x100000, v210
	global_store_dwordx4 v212, v[60:63], s[90:91]
	global_store_dwordx4 v212, v[56:59], s[90:91] offset:16
	v_lshlrev_b32_e32 v184, 16, v180
	v_and_b32_e32 v185, 0xffff0000, v180
	v_lshlrev_b32_e32 v186, 16, v181
	v_and_b32_e32 v187, 0xffff0000, v181
	v_lshlrev_b32_e32 v188, 16, v182
	v_and_b32_e32 v189, 0xffff0000, v182
	v_lshlrev_b32_e32 v190, 16, v183
	v_and_b32_e32 v191, 0xffff0000, v183
	v_pk_add_f32 v[52:53], v[52:53], v[184:185]
	v_pk_add_f32 v[54:55], v[54:55], v[186:187]
	v_pk_add_f32 v[48:49], v[48:49], v[188:189]
	v_pk_add_f32 v[50:51], v[50:51], v[190:191]
	v_fmac_f32_e32 v213, v52, v52
	v_fmac_f32_e32 v213, v53, v53
	v_fmac_f32_e32 v213, v54, v54
	v_fmac_f32_e32 v213, v55, v55
	v_fmac_f32_e32 v213, v48, v48
	v_fmac_f32_e32 v213, v49, v49
	v_fmac_f32_e32 v213, v50, v50
	v_fmac_f32_e32 v213, v51, v51
	global_store_dwordx4 v212, v[52:55], s[90:91] offset:512
	global_store_dwordx4 v212, v[48:51], s[90:91] offset:528
	ds_bpermute_b32 v214, v215, v213
	s_waitcnt lgkmcnt(0)
	v_add_f32_e32 v213, v213, v214
	ds_bpermute_b32 v214, v216, v213
	s_waitcnt lgkmcnt(0)
	v_add_f32_e32 v213, v213, v214
	s_mov_b64 exec, 0xffff
	global_atomic_add_f32 v208, v213, s[10:11] offset:512
	s_mov_b64 exec, -1
	v_add_u32_e32 v211, 0xa0000, v209
	global_load_dwordx4 v[176:179], v211, s[80:81]
	global_load_dwordx4 v[180:183], v211, s[80:81] offset:256
	s_waitcnt vmcnt(7)
	v_lshlrev_b32_e32 v200, 16, v192
	v_and_b32_e32 v201, 0xffff0000, v192
	v_lshlrev_b32_e32 v202, 16, v193
	v_and_b32_e32 v203, 0xffff0000, v193
	v_lshlrev_b32_e32 v204, 16, v194
	v_and_b32_e32 v205, 0xffff0000, v194
	v_lshlrev_b32_e32 v206, 16, v195
	v_and_b32_e32 v207, 0xffff0000, v195
	v_pk_add_f32 v[44:45], v[44:45], v[200:201]
	v_pk_add_f32 v[46:47], v[46:47], v[202:203]
	v_pk_add_f32 v[40:41], v[40:41], v[204:205]
	v_pk_add_f32 v[42:43], v[42:43], v[206:207]
	v_mul_f32_e32 v213, v44, v44
	v_fmac_f32_e32 v213, v45, v45
	v_fmac_f32_e32 v213, v46, v46
	v_fmac_f32_e32 v213, v47, v47
	v_fmac_f32_e32 v213, v40, v40
	v_fmac_f32_e32 v213, v41, v41
	v_fmac_f32_e32 v213, v42, v42
	v_fmac_f32_e32 v213, v43, v43
	v_add_u32_e32 v212, 0x120000, v210
	global_store_dwordx4 v212, v[44:47], s[90:91]
	global_store_dwordx4 v212, v[40:43], s[90:91] offset:16
	v_lshlrev_b32_e32 v200, 16, v196
	v_and_b32_e32 v201, 0xffff0000, v196
	v_lshlrev_b32_e32 v202, 16, v197
	v_and_b32_e32 v203, 0xffff0000, v197
	v_lshlrev_b32_e32 v204, 16, v198
	v_and_b32_e32 v205, 0xffff0000, v198
	v_lshlrev_b32_e32 v206, 16, v199
	v_and_b32_e32 v207, 0xffff0000, v199
	v_pk_add_f32 v[36:37], v[36:37], v[200:201]
	v_pk_add_f32 v[38:39], v[38:39], v[202:203]
	v_pk_add_f32 v[32:33], v[32:33], v[204:205]
	v_pk_add_f32 v[34:35], v[34:35], v[206:207]
	v_fmac_f32_e32 v213, v36, v36
	v_fmac_f32_e32 v213, v37, v37
	v_fmac_f32_e32 v213, v38, v38
	v_fmac_f32_e32 v213, v39, v39
	v_fmac_f32_e32 v213, v32, v32
	v_fmac_f32_e32 v213, v33, v33
	v_fmac_f32_e32 v213, v34, v34
	v_fmac_f32_e32 v213, v35, v35
	global_store_dwordx4 v212, v[36:39], s[90:91] offset:512
	global_store_dwordx4 v212, v[32:35], s[90:91] offset:528
	ds_bpermute_b32 v214, v215, v213
	s_waitcnt lgkmcnt(0)
	v_add_f32_e32 v213, v213, v214
	ds_bpermute_b32 v214, v216, v213
	s_waitcnt lgkmcnt(0)
	v_add_f32_e32 v213, v213, v214
	s_mov_b64 exec, 0xffff
	global_atomic_add_f32 v208, v213, s[10:11] offset:576
	s_mov_b64 exec, -1
	v_add_u32_e32 v211, 0xb0000, v209
	global_load_dwordx4 v[192:195], v211, s[80:81]
	global_load_dwordx4 v[196:199], v211, s[80:81] offset:256
	s_waitcnt vmcnt(7)
	v_lshlrev_b32_e32 v184, 16, v176
	v_and_b32_e32 v185, 0xffff0000, v176
	v_lshlrev_b32_e32 v186, 16, v177
	v_and_b32_e32 v187, 0xffff0000, v177
	v_lshlrev_b32_e32 v188, 16, v178
	v_and_b32_e32 v189, 0xffff0000, v178
	v_lshlrev_b32_e32 v190, 16, v179
	v_and_b32_e32 v191, 0xffff0000, v179
	v_pk_add_f32 v[28:29], v[28:29], v[184:185]
	v_pk_add_f32 v[30:31], v[30:31], v[186:187]
	v_pk_add_f32 v[24:25], v[24:25], v[188:189]
	v_pk_add_f32 v[26:27], v[26:27], v[190:191]
	v_mul_f32_e32 v213, v28, v28
	v_fmac_f32_e32 v213, v29, v29
	v_fmac_f32_e32 v213, v30, v30
	v_fmac_f32_e32 v213, v31, v31
	v_fmac_f32_e32 v213, v24, v24
	v_fmac_f32_e32 v213, v25, v25
	v_fmac_f32_e32 v213, v26, v26
	v_fmac_f32_e32 v213, v27, v27
	v_add_u32_e32 v212, 0x140000, v210
	global_store_dwordx4 v212, v[28:31], s[90:91]
	global_store_dwordx4 v212, v[24:27], s[90:91] offset:16
	v_lshlrev_b32_e32 v184, 16, v180
	v_and_b32_e32 v185, 0xffff0000, v180
	v_lshlrev_b32_e32 v186, 16, v181
	v_and_b32_e32 v187, 0xffff0000, v181
	v_lshlrev_b32_e32 v188, 16, v182
	v_and_b32_e32 v189, 0xffff0000, v182
	v_lshlrev_b32_e32 v190, 16, v183
	v_and_b32_e32 v191, 0xffff0000, v183
	v_pk_add_f32 v[20:21], v[20:21], v[184:185]
	v_pk_add_f32 v[22:23], v[22:23], v[186:187]
	v_pk_add_f32 v[16:17], v[16:17], v[188:189]
	v_pk_add_f32 v[18:19], v[18:19], v[190:191]
	v_fmac_f32_e32 v213, v20, v20
	v_fmac_f32_e32 v213, v21, v21
	v_fmac_f32_e32 v213, v22, v22
	v_fmac_f32_e32 v213, v23, v23
	v_fmac_f32_e32 v213, v16, v16
	v_fmac_f32_e32 v213, v17, v17
	v_fmac_f32_e32 v213, v18, v18
	v_fmac_f32_e32 v213, v19, v19
	global_store_dwordx4 v212, v[20:23], s[90:91] offset:512
	global_store_dwordx4 v212, v[16:19], s[90:91] offset:528
	ds_bpermute_b32 v214, v215, v213
	s_waitcnt lgkmcnt(0)
	v_add_f32_e32 v213, v213, v214
	ds_bpermute_b32 v214, v216, v213
	s_waitcnt lgkmcnt(0)
	v_add_f32_e32 v213, v213, v214
	s_mov_b64 exec, 0xffff
	global_atomic_add_f32 v208, v213, s[10:11] offset:640
	s_mov_b64 exec, -1
	s_waitcnt vmcnt(5)
	v_lshlrev_b32_e32 v200, 16, v192
	v_and_b32_e32 v201, 0xffff0000, v192
	v_lshlrev_b32_e32 v202, 16, v193
	v_and_b32_e32 v203, 0xffff0000, v193
	v_lshlrev_b32_e32 v204, 16, v194
	v_and_b32_e32 v205, 0xffff0000, v194
	v_lshlrev_b32_e32 v206, 16, v195
	v_and_b32_e32 v207, 0xffff0000, v195
	v_pk_add_f32 v[12:13], v[12:13], v[200:201]
	v_pk_add_f32 v[14:15], v[14:15], v[202:203]
	v_pk_add_f32 v[8:9], v[8:9], v[204:205]
	v_pk_add_f32 v[10:11], v[10:11], v[206:207]
	v_mul_f32_e32 v213, v12, v12
	v_fmac_f32_e32 v213, v13, v13
	v_fmac_f32_e32 v213, v14, v14
	v_fmac_f32_e32 v213, v15, v15
	v_fmac_f32_e32 v213, v8, v8
	v_fmac_f32_e32 v213, v9, v9
	v_fmac_f32_e32 v213, v10, v10
	v_fmac_f32_e32 v213, v11, v11
	v_add_u32_e32 v212, 0x160000, v210
	global_store_dwordx4 v212, v[12:15], s[90:91]
	global_store_dwordx4 v212, v[8:11], s[90:91] offset:16
	v_lshlrev_b32_e32 v200, 16, v196
	v_and_b32_e32 v201, 0xffff0000, v196
	v_lshlrev_b32_e32 v202, 16, v197
	v_and_b32_e32 v203, 0xffff0000, v197
	v_lshlrev_b32_e32 v204, 16, v198
	v_and_b32_e32 v205, 0xffff0000, v198
	v_lshlrev_b32_e32 v206, 16, v199
	v_and_b32_e32 v207, 0xffff0000, v199
	v_pk_add_f32 v[4:5], v[4:5], v[200:201]
	v_pk_add_f32 v[6:7], v[6:7], v[202:203]
	v_pk_add_f32 v[0:1], v[0:1], v[204:205]
	v_pk_add_f32 v[2:3], v[2:3], v[206:207]
	v_fmac_f32_e32 v213, v4, v4
	v_fmac_f32_e32 v213, v5, v5
	v_fmac_f32_e32 v213, v6, v6
	v_fmac_f32_e32 v213, v7, v7
	v_fmac_f32_e32 v213, v0, v0
	v_fmac_f32_e32 v213, v1, v1
	v_fmac_f32_e32 v213, v2, v2
	v_fmac_f32_e32 v213, v3, v3
	global_store_dwordx4 v212, v[4:7], s[90:91] offset:512
	global_store_dwordx4 v212, v[0:3], s[90:91] offset:528
	ds_bpermute_b32 v214, v215, v213
	s_waitcnt lgkmcnt(0)
	v_add_f32_e32 v213, v213, v214
	ds_bpermute_b32 v214, v216, v213
	s_waitcnt lgkmcnt(0)
	v_add_f32_e32 v213, v213, v214
	s_mov_b64 exec, 0xffff
	global_atomic_add_f32 v208, v213, s[10:11] offset:704
	s_mov_b64 exec, -1
	s_branch .LBB0_973
